# plus: PEER table conversion stores one 8-byte piece per lane (quad transpose) instead of four 2-byte stores; u-phase as rolling row prefetch with VALU lane reduction
# speedup vs baseline: 1.0107x; 1.0025x over previous
; __global__ void __launch_bounds__(NTHR, 2) k_main(Args a) {
;     ...
;         if (bid >= cfirst) for (int rr0 = ((bid - cfirst) * 8 + wave) * 4; rr0 < 2 * 16384; rr0 += (nb - cfirst) * 8 * 4) {
;             float4 v[4][4];
; #pragma unroll
;             for (int q = 0; q < 4; ++q) { const int rr = rr0 + q, which = rr >> 14, row = rr & 16383;
;                 typedef float f4v __attribute__((ext_vector_type(4))); const f4v* src4 = (const f4v*)((which ? a.peer_v : a.peer_u) + (size_t)row * D) + lane;
; #pragma unroll
;                 for (int jq = 0; jq < 4; ++jq) { const f4v t4 = __builtin_nontemporal_load(src4 + 64 * jq); v[q][jq] = make_float4(t4.x, t4.y, t4.z, t4.w); } }
; #pragma unroll
;             for (int q = 0; q < 4; ++q) { const int rr = rr0 + q, which = rr >> 14, row = rr & 16383;
;                 float ss = 0.f;
; #pragma unroll
;                 for (int jq = 0; jq < 4; ++jq) ss += v[q][jq].x * v[q][jq].x + v[q][jq].y * v[q][jq].y + v[q][jq].z * v[q][jq].z + v[q][jq].w * v[q][jq].w;
;                 ss = wave_sum(ss);
;                 const float step = ss > 0.f ? 0.335f * sqrtf(ss * (1.f / D)) : 1.f, inv = 1.f / step;
;                 unsigned short* dst = (unsigned short*)((which ? V8 : U8) + (size_t)row * 128) + lane;
; #pragma unroll
;                 for (int jq = 0; jq < 4; ++jq) { const float e4[4] = {v[q][jq].x, v[q][jq].y, v[q][jq].z, v[q][jq].w}; unsigned w4 = 0u;
; #pragma unroll
;                     for (int i = 0; i < 4; ++i) { const int qi = (int)fminf(fmaxf(floorf(e4[i] * inv), -8.f), 7.f); w4 |= ((unsigned)qi & 15u) << (4 * i); }
;                     dst[(size_t)jq * (16384 * 64)] = (unsigned short)w4; }
.LBB0_123:
	s_and_b64 s[0:1], s[0:1], exec
	s_cselect_b32 s3, 0xc0, 0
	s_cmp_lt_i32 s2, s3
	s_cbranch_scc1 .LBB0_146
	s_sub_i32 s10, s2, s3
	s_lshl_b32 s0, s10, 5
	s_lshl_b32 s1, s95, 2
	s_add_i32 s11, s0, s1
	s_mov_b64 s[28:29], s[62:63]
	s_cmpk_gt_i32 s11, 0x7fff
	v_and_b32_e32 v62, 63, v1
	s_cbranch_scc1 .LBB0_135
	v_and_b32_e32 v240, 1, v62
	v_cmp_ne_u32_e64 s[44:45], 0, v240
	v_and_b32_e32 v240, 2, v62
	v_cmp_ne_u32_e64 s[46:47], 0, v240
	s_mov_b32 s48, 0x5040100
	v_and_b32_e32 v244, 3, v62
	v_lshlrev_b32_e32 v244, 21, v244
	v_lshrrev_b32_e32 v240, 2, v62
	v_lshl_add_u32 v244, v240, 3, v244
	v_lshlrev_b32_e32 v240, 1, v62
	v_sub_u32_e32 v244, v244, v240
	v_mov_b32_e32 v245, 0
	v_mov_b32_e32 v65, 0
	s_sub_i32 s0, s33, s3
	s_mov_b32 s7, 0
	v_cmp_eq_u32_e64 s[4:5], 0, v62
	s_lshl_b32 s12, s0, 5
	v_lshlrev_b32_e32 v64, 4, v62
	s_movk_i32 s13, 0x1000
	s_movk_i32 s14, 0x2000
	s_movk_i32 s15, 0x3000
	v_lshlrev_b32_e32 v66, 1, v62
	v_mov_b32_e32 v67, v65
	s_mov_b32 s16, 0xf800000
	v_mov_b32_e32 v63, 0x260
	s_mov_b32 s17, 0xc1000000
	v_mov_b32_e32 v70, 0x40e00000
	s_movk_i32 s18, 0xf0
	s_movk_i32 s19, 0xf00
	s_mov_b32 s20, 0x200000
	s_mov_b32 s21, 0x400000
	s_branch .LBB0_127

; __global__ void __launch_bounds__(NTHR, 2) k_main(Args a) {
;     ...
;         if (bid >= cfirst) for (int rr0 = ((bid - cfirst) * 8 + wave) * 4; rr0 < 2 * 16384; rr0 += (nb - cfirst) * 8 * 4) {
;             float4 v[4][4];
; #pragma unroll
;             for (int q = 0; q < 4; ++q) { const int rr = rr0 + q, which = rr >> 14, row = rr & 16383;
;                 typedef float f4v __attribute__((ext_vector_type(4))); const f4v* src4 = (const f4v*)((which ? a.peer_v : a.peer_u) + (size_t)row * D) + lane;
; #pragma unroll
;                 for (int jq = 0; jq < 4; ++jq) { const f4v t4 = __builtin_nontemporal_load(src4 + 64 * jq); v[q][jq] = make_float4(t4.x, t4.y, t4.z, t4.w); } }
; #pragma unroll
;             for (int q = 0; q < 4; ++q) { const int rr = rr0 + q, which = rr >> 14, row = rr & 16383;
;                 float ss = 0.f;
; #pragma unroll
;                 for (int jq = 0; jq < 4; ++jq) ss += v[q][jq].x * v[q][jq].x + v[q][jq].y * v[q][jq].y + v[q][jq].z * v[q][jq].z + v[q][jq].w * v[q][jq].w;
;                 ss = wave_sum(ss);
;                 const float step = ss > 0.f ? 0.335f * sqrtf(ss * (1.f / D)) : 1.f, inv = 1.f / step;
;                 unsigned short* dst = (unsigned short*)((which ? V8 : U8) + (size_t)row * 128) + lane;
.LBB0_127:
	s_and_b32 s22, s11, 0x3ffc
	s_mov_b64 s[26:27], s[60:61]
	s_lshl_b32 s6, s22, 12
	v_readlane_b32 s60, v235, 16
	s_cmpk_lt_u32 s11, 0x4000
	v_readlane_b32 s74, v235, 30
	v_readlane_b32 s75, v235, 31
	s_cselect_b32 s1, s75, s85
	s_cselect_b32 s0, s74, s84
	v_lshl_add_u64 v[2:3], s[0:1], 0, v[64:65]
	v_lshl_add_u64 v[2:3], v[2:3], 0, s[6:7]
	global_load_dwordx4 v[72:75], v[2:3], off nt
	global_load_dwordx4 v[54:57], v[2:3], off offset:1024 nt
	global_load_dwordx4 v[50:53], v[2:3], off offset:2048 nt
	global_load_dwordx4 v[46:49], v[2:3], off offset:3072 nt
	v_readlane_b32 s8, v235, 36
	v_readlane_b32 s24, v235, 38
	v_add_co_u32_e32 v4, vcc, s13, v2
	s_cselect_b32 s1, s97, s51
	s_cselect_b32 s0, s96, s50
	s_cselect_b32 s8, s8, s24
	v_addc_co_u32_e32 v5, vcc, 0, v3, vcc
	v_lshl_add_u64 v[68:69], s[0:1], 0, v[66:67]
	v_add_co_u32_e32 v58, vcc, s14, v2
	global_load_dwordx4 v[42:45], v[4:5], off offset:1024 nt
	global_load_dwordx4 v[34:37], v[4:5], off offset:2048 nt
	v_addc_co_u32_e32 v59, vcc, 0, v3, vcc
	v_add_co_u32_e32 v2, vcc, s15, v2
	global_load_dwordx4 v[30:33], v[58:59], off nt
	global_load_dwordx4 v[26:29], v[58:59], off offset:1024 nt
	global_load_dwordx4 v[22:25], v[58:59], off offset:2048 nt
	global_load_dwordx4 v[18:21], v[58:59], off offset:3072 nt
	v_addc_co_u32_e32 v3, vcc, 0, v3, vcc
	v_readlane_b32 s9, v235, 37
	v_readlane_b32 s25, v235, 39
	s_cselect_b32 s9, s9, s25
	s_lshl_b32 s6, s22, 7
	v_lshl_add_u64 v[76:77], v[68:69], 0, s[6:7]
	v_readlane_b32 s61, v235, 17
	v_readlane_b32 s62, v235, 18
	v_readlane_b32 s63, v235, 19
	v_readlane_b32 s64, v235, 20
	v_readlane_b32 s65, v235, 21
	v_readlane_b32 s66, v235, 22
	v_readlane_b32 s67, v235, 23
	v_readlane_b32 s68, v235, 24
	v_readlane_b32 s69, v235, 25
	v_readlane_b32 s70, v235, 26
	v_readlane_b32 s71, v235, 27
	v_readlane_b32 s72, v235, 28
	v_readlane_b32 s73, v235, 29
	s_waitcnt vmcnt(9)
	v_mov_b32_e32 v8, v73
	s_waitcnt vmcnt(8)
	v_mov_b32_e32 v9, v55
	v_mov_b32_e32 v6, v72
	v_mov_b32_e32 v7, v54
	s_waitcnt vmcnt(7)
	v_mov_b32_e32 v16, v51
	s_waitcnt vmcnt(6)
	v_mov_b32_e32 v17, v47
	v_pk_mul_f32 v[8:9], v[8:9], v[8:9]
	v_mov_b32_e32 v10, v74
	v_mov_b32_e32 v11, v56
	v_mov_b32_e32 v14, v50
	v_mov_b32_e32 v15, v46
	v_pk_mul_f32 v[16:17], v[16:17], v[16:17]
	v_pk_fma_f32 v[6:7], v[6:7], v[6:7], v[8:9]
	v_mov_b32_e32 v12, v75
	v_mov_b32_e32 v13, v57
	v_mov_b32_e32 v38, v52
	v_mov_b32_e32 v39, v48
	v_pk_fma_f32 v[8:9], v[14:15], v[14:15], v[16:17]
	v_pk_fma_f32 v[6:7], v[10:11], v[10:11], v[6:7]
	v_mov_b32_e32 v40, v53
	v_mov_b32_e32 v41, v49
	v_pk_fma_f32 v[8:9], v[38:39], v[38:39], v[8:9]
	v_pk_fma_f32 v[6:7], v[12:13], v[12:13], v[6:7]
	v_pk_fma_f32 v[8:9], v[40:41], v[40:41], v[8:9]
	v_add_f32_e32 v6, v6, v7
	v_add_f32_e32 v6, v6, v8
	v_add_f32_e32 v6, v6, v9
	s_nop 1
	v_add_f32_dpp v6, v6, v6 quad_perm:[1,0,3,2] row_mask:0xf bank_mask:0xf bound_ctrl:1
	s_nop 1
	v_add_f32_dpp v6, v6, v6 quad_perm:[2,3,0,1] row_mask:0xf bank_mask:0xf bound_ctrl:1
	s_nop 1
	v_add_f32_dpp v6, v6, v6 row_half_mirror row_mask:0xf bank_mask:0xf bound_ctrl:1
	s_nop 1
	v_add_f32_dpp v6, v6, v6 row_mirror row_mask:0xf bank_mask:0xf bound_ctrl:1
	s_nop 0
	v_readlane_b32 s23, v6, 16
	v_readlane_b32 s24, v6, 48
	v_readlane_b32 s0, v6, 0
	v_readlane_b32 s1, v6, 32
	v_mov_b32_e32 v6, s23
	v_mov_b32_e32 v7, s24
	v_pk_add_f32 v[6:7], s[0:1], v[6:7]
	s_nop 0
	v_add_f32_e32 v60, v6, v7
	v_mul_f32_e32 v6, 0x3a800000, v60
	v_mul_f32_e32 v7, 0x4f800000, v6
	v_cmp_gt_f32_e32 vcc, s16, v6
	s_nop 1
	v_cndmask_b32_e32 v61, v6, v7, vcc
	v_sqrt_f32_e32 v71, v61
	global_load_dwordx4 v[38:41], v[4:5], off offset:3072 nt
	global_load_dwordx4 v[14:17], v[2:3], off nt
	global_load_dwordx4 v[10:13], v[2:3], off offset:1024 nt
	global_load_dwordx4 v[6:9], v[2:3], off offset:2048 nt
	v_add_u32_e32 v4, -1, v71
	v_add_u32_e32 v5, 1, v71
	v_fma_f32 v78, -v4, v71, v61
	v_fma_f32 v79, -v5, v71, v61
	v_cmp_ge_f32_e64 s[0:1], 0, v78
	s_nop 1
	v_cndmask_b32_e64 v4, v71, v4, s[0:1]
	v_cmp_lt_f32_e64 s[0:1], 0, v79
	s_nop 1
	v_cndmask_b32_e64 v4, v4, v5, s[0:1]
	v_mul_f32_e32 v5, 0x37800000, v4
	v_cndmask_b32_e32 v4, v4, v5, vcc
	v_cmp_class_f32_e32 vcc, v61, v63
	s_nop 1
	v_cndmask_b32_e32 v4, v4, v61, vcc
	v_mul_f32_e32 v4, 0x3eab851f, v4
	v_cmp_lt_f32_e32 vcc, 0, v60
	s_nop 1
	v_cndmask_b32_e32 v71, 1.0, v4, vcc
	global_load_dwordx4 v[58:61], v[58:59], off offset:-4096 nt
	s_nop 0
	global_load_dwordx4 v[2:5], v[2:3], off offset:3072 nt
	v_div_scale_f32 v78, s[0:1], v71, v71, 1.0
	v_rcp_f32_e32 v79, v78
	v_div_scale_f32 v80, vcc, 1.0, v71, 1.0
	v_fma_f32 v81, -v78, v79, 1.0
	v_fmac_f32_e32 v79, v81, v79
	v_mul_f32_e32 v81, v80, v79
	v_fma_f32 v82, -v78, v81, v80
	v_fmac_f32_e32 v81, v82, v79
	v_fma_f32 v78, -v78, v81, v80
	v_div_fmas_f32 v78, v78, v79, v81
	v_div_fixup_f32 v78, v78, v71, 1.0
	v_mul_f32_e32 v54, v78, v54
	v_mul_f32_e32 v55, v78, v55
	v_floor_f32_e32 v54, v54
	v_floor_f32_e32 v55, v55
	v_mul_f32_e32 v56, v78, v56
	v_med3_f32 v54, v54, s17, v70
	v_med3_f32 v55, v55, s17, v70
	v_floor_f32_e32 v56, v56
	v_cvt_i32_f32_e32 v54, v54
	v_cvt_i32_f32_e32 v55, v55
	v_med3_f32 v56, v56, s17, v70
	v_cvt_i32_f32_e32 v56, v56
	v_mul_f32_e32 v50, v78, v50
	v_and_b32_e32 v54, 15, v54
	v_lshlrev_b32_e32 v55, 4, v55
	v_floor_f32_e32 v50, v50
	v_mul_f32_e32 v57, v78, v57
	v_and_or_b32 v54, v55, s18, v54
	v_lshlrev_b32_e32 v55, 8, v56
	v_med3_f32 v50, v50, s17, v70
	v_floor_f32_e32 v57, v57
	v_and_or_b32 v54, v55, s19, v54
	v_cvt_i32_f32_e32 v55, v50
	v_mul_f32_e32 v50, v78, v51
	v_med3_f32 v57, v57, s17, v70
	v_floor_f32_e32 v50, v50
	v_mul_f32_e32 v52, v78, v52
	v_cvt_i32_f32_e32 v57, v57
	v_med3_f32 v50, v50, s17, v70
; __global__ void __launch_bounds__(NTHR, 2) k_main(Args a) {
;     ...
;                 const float step = ss > 0.f ? 0.335f * sqrtf(ss * (1.f / D)) : 1.f, inv = 1.f / step;
;                 unsigned short* dst = (unsigned short*)((which ? V8 : U8) + (size_t)row * 128) + lane;
; #pragma unroll
;                 for (int jq = 0; jq < 4; ++jq) { const float e4[4] = {v[q][jq].x, v[q][jq].y, v[q][jq].z, v[q][jq].w}; unsigned w4 = 0u;
; #pragma unroll
;                     for (int i = 0; i < 4; ++i) { const int qi = (int)fminf(fmaxf(floorf(e4[i] * inv), -8.f), 7.f); w4 |= ((unsigned)qi & 15u) << (4 * i); }
;                     dst[(size_t)jq * (16384 * 64)] = (unsigned short)w4; }
;                 if (lane == 0) (which ? SV : SU)[row] = 0.5f * step;
	v_floor_f32_e32 v52, v52
	v_cvt_i32_f32_e32 v56, v50
	v_med3_f32 v52, v52, s17, v70
	v_cvt_i32_f32_e32 v52, v52
	v_add_co_u32_e32 v50, vcc, s20, v76
	v_lshl_or_b32 v54, v57, 12, v54
	s_nop 0
	v_addc_co_u32_e32 v51, vcc, 0, v77, vcc
	v_mul_f32_e32 v46, v78, v46
	v_mov_b32_e32 v237, v54
	v_and_b32_e32 v50, 15, v55
	v_lshlrev_b32_e32 v51, 4, v56
	v_floor_f32_e32 v46, v46
	v_mul_f32_e32 v53, v78, v53
	v_and_or_b32 v50, v51, s18, v50
	v_lshlrev_b32_e32 v51, 8, v52
	v_med3_f32 v46, v46, s17, v70
	v_floor_f32_e32 v53, v53
	v_and_or_b32 v50, v51, s19, v50
	v_cvt_i32_f32_e32 v51, v46
	v_mul_f32_e32 v46, v78, v47
	v_mul_f32_e32 v72, v78, v72
	v_mul_f32_e32 v73, v78, v73
	v_med3_f32 v53, v53, s17, v70
	v_floor_f32_e32 v46, v46
	v_mul_f32_e32 v48, v78, v48
	v_mul_f32_e32 v74, v78, v74
	v_floor_f32_e32 v72, v72
	v_floor_f32_e32 v73, v73
	v_cvt_i32_f32_e32 v53, v53
	v_med3_f32 v46, v46, s17, v70
	v_floor_f32_e32 v48, v48
	v_floor_f32_e32 v74, v74
	v_med3_f32 v72, v72, s17, v70
	v_med3_f32 v73, v73, s17, v70
	v_cvt_i32_f32_e32 v52, v46
	v_med3_f32 v48, v48, s17, v70
	v_mul_f32_e32 v49, v78, v49
	v_mul_f32_e32 v75, v78, v75
	v_med3_f32 v74, v74, s17, v70
	v_cvt_i32_f32_e32 v72, v72
	v_cvt_i32_f32_e32 v73, v73
	v_cvt_i32_f32_e32 v48, v48
	v_floor_f32_e32 v49, v49
	v_floor_f32_e32 v75, v75
	v_cvt_i32_f32_e32 v74, v74
	v_add_co_u32_e32 v46, vcc, s21, v76
	v_med3_f32 v49, v49, s17, v70
	v_med3_f32 v75, v75, s17, v70
	v_lshl_or_b32 v50, v53, 12, v50
	v_addc_co_u32_e32 v47, vcc, 0, v77, vcc
	v_cvt_i32_f32_e32 v49, v49
	v_cvt_i32_f32_e32 v75, v75
	v_mov_b32_e32 v238, v50
	v_and_b32_e32 v46, 15, v51
	v_lshlrev_b32_e32 v47, 4, v52
	v_and_b32_e32 v72, 15, v72
	v_lshlrev_b32_e32 v73, 4, v73
	v_and_or_b32 v46, v47, s18, v46
	v_lshlrev_b32_e32 v47, 8, v48
	v_lshlrev_b32_e32 v74, 8, v74
	v_and_or_b32 v72, v73, s18, v72
	v_and_or_b32 v46, v47, s19, v46
	v_and_or_b32 v72, v74, s19, v72
	v_lshl_or_b32 v48, v49, 12, v46
	v_add_co_u32_e32 v46, vcc, 0x600000, v76
	v_lshl_or_b32 v72, v75, 12, v72
	s_nop 0
	v_addc_co_u32_e32 v47, vcc, 0, v77, vcc
	v_mov_b32_e32 v236, v72
	v_mov_b32_e32 v239, v48
	v_cndmask_b32_e64 v240, v237, v236, s[44:45]
	v_cndmask_b32_e64 v241, v239, v238, s[44:45]
	s_nop 1
	v_mov_b32_dpp v242, v240 quad_perm:[1,0,3,2] row_mask:0xf bank_mask:0xf
	v_mov_b32_dpp v243, v241 quad_perm:[1,0,3,2] row_mask:0xf bank_mask:0xf
	v_cndmask_b32_e64 v236, v236, v242, s[44:45]
	v_cndmask_b32_e64 v237, v242, v237, s[44:45]
	v_cndmask_b32_e64 v238, v238, v243, s[44:45]
	v_cndmask_b32_e64 v239, v243, v239, s[44:45]
	v_cndmask_b32_e64 v240, v238, v236, s[46:47]
	v_cndmask_b32_e64 v241, v239, v237, s[46:47]
	s_nop 1
	v_mov_b32_dpp v242, v240 quad_perm:[2,3,0,1] row_mask:0xf bank_mask:0xf
	v_mov_b32_dpp v243, v241 quad_perm:[2,3,0,1] row_mask:0xf bank_mask:0xf
	v_cndmask_b32_e64 v236, v236, v242, s[46:47]
	v_cndmask_b32_e64 v238, v242, v238, s[46:47]
	v_cndmask_b32_e64 v237, v237, v243, s[46:47]
	v_cndmask_b32_e64 v239, v243, v239, s[46:47]
	v_perm_b32 v248, v237, v236, s48
	v_perm_b32 v249, v239, v238, s48
	v_lshl_add_u64 v[246:247], v[76:77], 0, v[244:245]
	global_store_dwordx2 v[246:247], v[248:249], off
	s_and_saveexec_b64 s[0:1], s[4:5]
	s_cbranch_execz .LBB0_129
	s_lshl_b32 s23, s22, 2
	v_mul_f32_e32 v46, 0.5, v71
	v_mov_b32_e32 v47, s23
	global_store_dword v47, v46, s[8:9]
.LBB0_129:
	s_or_b64 exec, exec, s[0:1]
	s_waitcnt vmcnt(2)
	v_mov_b32_e32 v48, v59
	v_mov_b32_e32 v49, v43
	v_mov_b32_e32 v46, v58
	v_mov_b32_e32 v47, v42
	v_pk_mul_f32 v[48:49], v[48:49], v[48:49]
	v_mov_b32_e32 v50, v60
	v_mov_b32_e32 v51, v44
	v_pk_fma_f32 v[46:47], v[46:47], v[46:47], v[48:49]
	v_mov_b32_e32 v52, v61
	v_pk_fma_f32 v[46:47], v[50:51], v[50:51], v[46:47]
	v_mov_b32_e32 v50, v35
	v_mov_b32_e32 v51, v39
	v_mov_b32_e32 v53, v45
	v_mov_b32_e32 v48, v34
	v_mov_b32_e32 v49, v38
	v_pk_mul_f32 v[50:51], v[50:51], v[50:51]
	v_pk_fma_f32 v[46:47], v[52:53], v[52:53], v[46:47]
	v_mov_b32_e32 v52, v36
	v_mov_b32_e32 v53, v40
	v_pk_fma_f32 v[48:49], v[48:49], v[48:49], v[50:51]
	v_mov_b32_e32 v54, v37
	v_mov_b32_e32 v55, v41
	v_pk_fma_f32 v[48:49], v[52:53], v[52:53], v[48:49]
	v_add_f32_e32 v46, v46, v47
	v_pk_fma_f32 v[48:49], v[54:55], v[54:55], v[48:49]
	s_nop 0
	v_add_f32_e32 v46, v46, v48
	v_add_f32_e32 v46, v46, v49
	s_nop 1
	v_add_f32_dpp v46, v46, v46 quad_perm:[1,0,3,2] row_mask:0xf bank_mask:0xf bound_ctrl:1
	s_nop 1
	v_add_f32_dpp v46, v46, v46 quad_perm:[2,3,0,1] row_mask:0xf bank_mask:0xf bound_ctrl:1
	s_nop 1
	v_add_f32_dpp v46, v46, v46 row_half_mirror row_mask:0xf bank_mask:0xf bound_ctrl:1
	s_nop 1
	v_add_f32_dpp v46, v46, v46 row_mirror row_mask:0xf bank_mask:0xf bound_ctrl:1
	s_nop 0
	v_readlane_b32 s23, v46, 16
	v_readlane_b32 s24, v46, 48
	v_readlane_b32 s0, v46, 0
	v_readlane_b32 s1, v46, 32
	v_mov_b32_e32 v46, s23
	v_mov_b32_e32 v47, s24
	v_pk_add_f32 v[46:47], s[0:1], v[46:47]
	s_nop 0
	v_add_f32_e32 v46, v46, v47
	v_mul_f32_e32 v47, 0x3a800000, v46
	v_mul_f32_e32 v48, 0x4f800000, v47
	v_cmp_gt_f32_e32 vcc, s16, v47
	s_nop 1
	v_cndmask_b32_e32 v47, v47, v48, vcc
	v_sqrt_f32_e32 v48, v47
	s_nop 0
	v_add_u32_e32 v49, -1, v48
	v_fma_f32 v50, -v49, v48, v47
	v_cmp_ge_f32_e64 s[0:1], 0, v50
	v_add_u32_e32 v50, 1, v48
	s_nop 0
	v_cndmask_b32_e64 v49, v48, v49, s[0:1]
	v_fma_f32 v48, -v50, v48, v47
	v_cmp_lt_f32_e64 s[0:1], 0, v48
	s_nop 1
	v_cndmask_b32_e64 v48, v49, v50, s[0:1]
	v_mul_f32_e32 v49, 0x37800000, v48
	v_cndmask_b32_e32 v48, v48, v49, vcc
	v_cmp_class_f32_e32 vcc, v47, v63
	s_nop 1
	v_cndmask_b32_e32 v47, v48, v47, vcc
	v_mul_f32_e32 v47, 0x3eab851f, v47
	v_cmp_lt_f32_e32 vcc, 0, v46
	s_nop 1
	v_cndmask_b32_e32 v46, 1.0, v47, vcc
	v_div_scale_f32 v47, s[0:1], v46, v46, 1.0
; __global__ void __launch_bounds__(NTHR, 2) k_main(Args a) {
;     ...
;             for (int q = 0; q < 4; ++q) { const int rr = rr0 + q, which = rr >> 14, row = rr & 16383;
;                 float ss = 0.f;
; #pragma unroll
;                 for (int jq = 0; jq < 4; ++jq) ss += v[q][jq].x * v[q][jq].x + v[q][jq].y * v[q][jq].y + v[q][jq].z * v[q][jq].z + v[q][jq].w * v[q][jq].w;
;                 ss = wave_sum(ss);
;                 const float step = ss > 0.f ? 0.335f * sqrtf(ss * (1.f / D)) : 1.f, inv = 1.f / step;
;                 unsigned short* dst = (unsigned short*)((which ? V8 : U8) + (size_t)row * 128) + lane;
; #pragma unroll
;                 for (int jq = 0; jq < 4; ++jq) { const float e4[4] = {v[q][jq].x, v[q][jq].y, v[q][jq].z, v[q][jq].w}; unsigned w4 = 0u;
; #pragma unroll
;                     for (int i = 0; i < 4; ++i) { const int qi = (int)fminf(fmaxf(floorf(e4[i] * inv), -8.f), 7.f); w4 |= ((unsigned)qi & 15u) << (4 * i); }
;                     dst[(size_t)jq * (16384 * 64)] = (unsigned short)w4; }
;                 if (lane == 0) (which ? SV : SU)[row] = 0.5f * step;
	v_rcp_f32_e32 v48, v47
	s_or_b32 s0, s6, 0x80
	s_mov_b32 s1, s7
	v_fma_f32 v49, -v47, v48, 1.0
	v_fmac_f32_e32 v48, v49, v48
	v_div_scale_f32 v49, vcc, 1.0, v46, 1.0
	v_mul_f32_e32 v50, v49, v48
	v_fma_f32 v51, -v47, v50, v49
	v_fmac_f32_e32 v50, v51, v48
	v_fma_f32 v47, -v47, v50, v49
	v_div_fmas_f32 v47, v47, v48, v50
	v_div_fixup_f32 v47, v47, v46, 1.0
	v_mul_f32_e32 v42, v47, v42
	v_mul_f32_e32 v43, v47, v43
	v_floor_f32_e32 v42, v42
	v_floor_f32_e32 v43, v43
	v_mul_f32_e32 v44, v47, v44
	v_med3_f32 v42, v42, s17, v70
	v_med3_f32 v43, v43, s17, v70
	v_floor_f32_e32 v44, v44
	v_cvt_i32_f32_e32 v42, v42
	v_cvt_i32_f32_e32 v43, v43
	v_med3_f32 v44, v44, s17, v70
	v_cvt_i32_f32_e32 v44, v44
	v_mul_f32_e32 v34, v47, v34
	v_and_b32_e32 v42, 15, v42
	v_lshlrev_b32_e32 v43, 4, v43
	v_floor_f32_e32 v34, v34
	v_mul_f32_e32 v45, v47, v45
	v_and_or_b32 v42, v43, s18, v42
	v_lshlrev_b32_e32 v43, 8, v44
	v_med3_f32 v34, v34, s17, v70
	v_floor_f32_e32 v45, v45
	v_and_or_b32 v42, v43, s19, v42
	v_cvt_i32_f32_e32 v43, v34
	v_mul_f32_e32 v34, v47, v35
	v_med3_f32 v45, v45, s17, v70
	v_floor_f32_e32 v34, v34
	v_mul_f32_e32 v36, v47, v36
	v_cvt_i32_f32_e32 v45, v45
	v_med3_f32 v34, v34, s17, v70
	v_floor_f32_e32 v36, v36
	v_cvt_i32_f32_e32 v44, v34
	v_med3_f32 v36, v36, s17, v70
	v_mul_f32_e32 v37, v47, v37
	v_lshl_add_u64 v[48:49], v[68:69], 0, s[0:1]
	v_cvt_i32_f32_e32 v36, v36
	v_floor_f32_e32 v37, v37
	v_add_co_u32_e32 v34, vcc, s20, v48
	v_med3_f32 v37, v37, s17, v70
	v_lshl_or_b32 v42, v45, 12, v42
	v_addc_co_u32_e32 v35, vcc, 0, v49, vcc
	v_cvt_i32_f32_e32 v37, v37
	v_mov_b32_e32 v237, v42
	v_and_b32_e32 v34, 15, v43
	v_lshlrev_b32_e32 v35, 4, v44
	v_and_or_b32 v34, v35, s18, v34
	v_lshlrev_b32_e32 v35, 8, v36
	v_and_or_b32 v34, v35, s19, v34
	v_lshl_or_b32 v36, v37, 12, v34
	v_mul_f32_e32 v34, v47, v38
	v_floor_f32_e32 v34, v34
	v_mul_f32_e32 v50, v47, v58
	v_mul_f32_e32 v51, v47, v59
	v_med3_f32 v34, v34, s17, v70
	v_floor_f32_e32 v50, v50
	v_floor_f32_e32 v51, v51
	v_mul_f32_e32 v52, v47, v60
	v_cvt_i32_f32_e32 v37, v34
	v_mul_f32_e32 v34, v47, v39
	v_med3_f32 v50, v50, s17, v70
	v_med3_f32 v51, v51, s17, v70
	v_floor_f32_e32 v52, v52
	v_floor_f32_e32 v34, v34
	v_cvt_i32_f32_e32 v50, v50
	v_cvt_i32_f32_e32 v51, v51
	v_med3_f32 v52, v52, s17, v70
	v_med3_f32 v34, v34, s17, v70
	v_cvt_i32_f32_e32 v52, v52
	v_cvt_i32_f32_e32 v38, v34
	v_add_co_u32_e32 v34, vcc, s21, v48
	v_and_b32_e32 v50, 15, v50
	s_nop 0
	v_addc_co_u32_e32 v35, vcc, 0, v49, vcc
	v_mov_b32_e32 v238, v36
	v_mul_f32_e32 v36, v47, v40
	v_lshlrev_b32_e32 v51, 4, v51
	v_floor_f32_e32 v36, v36
	v_and_or_b32 v50, v51, s18, v50
	v_lshlrev_b32_e32 v51, 8, v52
	v_and_b32_e32 v34, 15, v37
	v_med3_f32 v36, v36, s17, v70
	v_mul_f32_e32 v37, v47, v41
	v_and_or_b32 v50, v51, s19, v50
	v_mul_f32_e32 v51, v47, v61
	v_cvt_i32_f32_e32 v36, v36
	v_floor_f32_e32 v37, v37
	v_floor_f32_e32 v51, v51
	v_med3_f32 v37, v37, s17, v70
	v_med3_f32 v51, v51, s17, v70
	v_cvt_i32_f32_e32 v37, v37
	v_cvt_i32_f32_e32 v51, v51
	v_lshlrev_b32_e32 v35, 4, v38
	v_and_or_b32 v34, v35, s18, v34
	v_lshlrev_b32_e32 v35, 8, v36
	v_and_or_b32 v34, v35, s19, v34
	v_lshl_or_b32 v36, v37, 12, v34
	v_add_co_u32_e32 v34, vcc, 0x600000, v48
	v_lshl_or_b32 v50, v51, 12, v50
	s_nop 0
	v_addc_co_u32_e32 v35, vcc, 0, v49, vcc
	v_mov_b32_e32 v236, v50
	v_mov_b32_e32 v239, v36
	v_cndmask_b32_e64 v240, v237, v236, s[44:45]
	v_cndmask_b32_e64 v241, v239, v238, s[44:45]
	s_nop 1
	v_mov_b32_dpp v242, v240 quad_perm:[1,0,3,2] row_mask:0xf bank_mask:0xf
	v_mov_b32_dpp v243, v241 quad_perm:[1,0,3,2] row_mask:0xf bank_mask:0xf
	v_cndmask_b32_e64 v236, v236, v242, s[44:45]
	v_cndmask_b32_e64 v237, v242, v237, s[44:45]
	v_cndmask_b32_e64 v238, v238, v243, s[44:45]
	v_cndmask_b32_e64 v239, v243, v239, s[44:45]
	v_cndmask_b32_e64 v240, v238, v236, s[46:47]
	v_cndmask_b32_e64 v241, v239, v237, s[46:47]
	s_nop 1
	v_mov_b32_dpp v242, v240 quad_perm:[2,3,0,1] row_mask:0xf bank_mask:0xf
	v_mov_b32_dpp v243, v241 quad_perm:[2,3,0,1] row_mask:0xf bank_mask:0xf
	v_cndmask_b32_e64 v236, v236, v242, s[46:47]
	v_cndmask_b32_e64 v238, v242, v238, s[46:47]
	v_cndmask_b32_e64 v237, v237, v243, s[46:47]
	v_cndmask_b32_e64 v239, v243, v239, s[46:47]
	v_perm_b32 v248, v237, v236, s48
	v_perm_b32 v249, v239, v238, s48
	v_lshl_add_u64 v[246:247], v[48:49], 0, v[244:245]
	global_store_dwordx2 v[246:247], v[248:249], off
	s_and_saveexec_b64 s[0:1], s[4:5]
	s_cbranch_execz .LBB0_131
	s_lshl_b32 s23, s22, 2
	v_mul_f32_e32 v34, 0.5, v46
	v_mov_b32_e32 v35, s23
	global_store_dword v35, v34, s[8:9] offset:4
; __global__ void __launch_bounds__(NTHR, 2) k_main(Args a) {
;     ...
;             for (int q = 0; q < 4; ++q) { const int rr = rr0 + q, which = rr >> 14, row = rr & 16383;
;                 float ss = 0.f;
; #pragma unroll
;                 for (int jq = 0; jq < 4; ++jq) ss += v[q][jq].x * v[q][jq].x + v[q][jq].y * v[q][jq].y + v[q][jq].z * v[q][jq].z + v[q][jq].w * v[q][jq].w;
;                 ss = wave_sum(ss);
;                 const float step = ss > 0.f ? 0.335f * sqrtf(ss * (1.f / D)) : 1.f, inv = 1.f / step;
;                 unsigned short* dst = (unsigned short*)((which ? V8 : U8) + (size_t)row * 128) + lane;
; #pragma unroll
;                 for (int jq = 0; jq < 4; ++jq) { const float e4[4] = {v[q][jq].x, v[q][jq].y, v[q][jq].z, v[q][jq].w}; unsigned w4 = 0u;
; #pragma unroll
;                     for (int i = 0; i < 4; ++i) { const int qi = (int)fminf(fmaxf(floorf(e4[i] * inv), -8.f), 7.f); w4 |= ((unsigned)qi & 15u) << (4 * i); }
;                     dst[(size_t)jq * (16384 * 64)] = (unsigned short)w4; }
;                 if (lane == 0) (which ? SV : SU)[row] = 0.5f * step;
.LBB0_131:
	s_or_b64 exec, exec, s[0:1]
	v_mov_b32_e32 v36, v31
	v_mov_b32_e32 v37, v27
	v_mov_b32_e32 v34, v30
	v_mov_b32_e32 v35, v26
	v_pk_mul_f32 v[36:37], v[36:37], v[36:37]
	v_mov_b32_e32 v38, v32
	v_mov_b32_e32 v39, v28
	v_pk_fma_f32 v[34:35], v[34:35], v[34:35], v[36:37]
	v_mov_b32_e32 v40, v33
	v_pk_fma_f32 v[34:35], v[38:39], v[38:39], v[34:35]
	v_mov_b32_e32 v38, v23
	v_mov_b32_e32 v39, v19
	v_mov_b32_e32 v41, v29
	v_mov_b32_e32 v36, v22
	v_mov_b32_e32 v37, v18
	v_pk_mul_f32 v[38:39], v[38:39], v[38:39]
	v_pk_fma_f32 v[34:35], v[40:41], v[40:41], v[34:35]
	v_mov_b32_e32 v40, v24
	v_mov_b32_e32 v41, v20
	v_pk_fma_f32 v[36:37], v[36:37], v[36:37], v[38:39]
	v_mov_b32_e32 v42, v25
	v_mov_b32_e32 v43, v21
	v_pk_fma_f32 v[36:37], v[40:41], v[40:41], v[36:37]
	v_add_f32_e32 v34, v34, v35
	v_pk_fma_f32 v[36:37], v[42:43], v[42:43], v[36:37]
	s_nop 0
	v_add_f32_e32 v34, v34, v36
	v_add_f32_e32 v34, v34, v37
	s_nop 1
	v_add_f32_dpp v34, v34, v34 quad_perm:[1,0,3,2] row_mask:0xf bank_mask:0xf bound_ctrl:1
	s_nop 1
	v_add_f32_dpp v34, v34, v34 quad_perm:[2,3,0,1] row_mask:0xf bank_mask:0xf bound_ctrl:1
	s_nop 1
	v_add_f32_dpp v34, v34, v34 row_half_mirror row_mask:0xf bank_mask:0xf bound_ctrl:1
	s_nop 1
	v_add_f32_dpp v34, v34, v34 row_mirror row_mask:0xf bank_mask:0xf bound_ctrl:1
	s_nop 0
	v_readlane_b32 s23, v34, 16
	v_readlane_b32 s24, v34, 48
	v_readlane_b32 s0, v34, 0
	v_readlane_b32 s1, v34, 32
	v_mov_b32_e32 v34, s23
	v_mov_b32_e32 v35, s24
	v_pk_add_f32 v[34:35], s[0:1], v[34:35]
	s_nop 0
	v_add_f32_e32 v34, v34, v35
	v_mul_f32_e32 v35, 0x3a800000, v34
	v_mul_f32_e32 v36, 0x4f800000, v35
	v_cmp_gt_f32_e32 vcc, s16, v35
	s_nop 1
	v_cndmask_b32_e32 v35, v35, v36, vcc
	v_sqrt_f32_e32 v36, v35
	s_nop 0
	v_add_u32_e32 v37, -1, v36
	v_fma_f32 v38, -v37, v36, v35
	v_cmp_ge_f32_e64 s[0:1], 0, v38
	v_add_u32_e32 v38, 1, v36
	s_nop 0
	v_cndmask_b32_e64 v37, v36, v37, s[0:1]
	v_fma_f32 v36, -v38, v36, v35
	v_cmp_lt_f32_e64 s[0:1], 0, v36
	s_nop 1
	v_cndmask_b32_e64 v36, v37, v38, s[0:1]
	v_mul_f32_e32 v37, 0x37800000, v36
	v_cndmask_b32_e32 v36, v36, v37, vcc
	v_cmp_class_f32_e32 vcc, v35, v63
	s_nop 1
	v_cndmask_b32_e32 v35, v36, v35, vcc
	v_mul_f32_e32 v35, 0x3eab851f, v35
	v_cmp_lt_f32_e32 vcc, 0, v34
	s_nop 1
	v_cndmask_b32_e32 v34, 1.0, v35, vcc
	v_div_scale_f32 v35, s[0:1], v34, v34, 1.0
	v_rcp_f32_e32 v36, v35
	s_or_b32 s0, s6, 0x100
	s_mov_b32 s1, s7
	v_fma_f32 v37, -v35, v36, 1.0
	v_fmac_f32_e32 v36, v37, v36
	v_div_scale_f32 v37, vcc, 1.0, v34, 1.0
	v_mul_f32_e32 v38, v37, v36
	v_fma_f32 v39, -v35, v38, v37
	v_fmac_f32_e32 v38, v39, v36
	v_fma_f32 v35, -v35, v38, v37
	v_div_fmas_f32 v35, v35, v36, v38
	v_div_fixup_f32 v35, v35, v34, 1.0
	v_mul_f32_e32 v26, v35, v26
	v_mul_f32_e32 v27, v35, v27
	v_floor_f32_e32 v26, v26
	v_floor_f32_e32 v27, v27
	v_mul_f32_e32 v28, v35, v28
	v_med3_f32 v26, v26, s17, v70
	v_med3_f32 v27, v27, s17, v70
	v_floor_f32_e32 v28, v28
	v_cvt_i32_f32_e32 v26, v26
	v_cvt_i32_f32_e32 v27, v27
	v_med3_f32 v28, v28, s17, v70
	v_cvt_i32_f32_e32 v28, v28
	v_mul_f32_e32 v22, v35, v22
	v_and_b32_e32 v26, 15, v26
	v_lshlrev_b32_e32 v27, 4, v27
	v_floor_f32_e32 v22, v22
	v_mul_f32_e32 v29, v35, v29
	v_and_or_b32 v26, v27, s18, v26
	v_lshlrev_b32_e32 v27, 8, v28
	v_med3_f32 v22, v22, s17, v70
	v_floor_f32_e32 v29, v29
	v_and_or_b32 v26, v27, s19, v26
	v_cvt_i32_f32_e32 v27, v22
	v_mul_f32_e32 v22, v35, v23
	v_med3_f32 v29, v29, s17, v70
	v_floor_f32_e32 v22, v22
	v_mul_f32_e32 v24, v35, v24
	v_cvt_i32_f32_e32 v29, v29
	v_med3_f32 v22, v22, s17, v70
	v_floor_f32_e32 v24, v24
	v_cvt_i32_f32_e32 v28, v22
	v_med3_f32 v24, v24, s17, v70
	v_lshl_add_u64 v[36:37], v[68:69], 0, s[0:1]
	v_mul_f32_e32 v30, v35, v30
	v_mul_f32_e32 v31, v35, v31
	v_cvt_i32_f32_e32 v24, v24
	v_floor_f32_e32 v30, v30
	v_floor_f32_e32 v31, v31
	v_mul_f32_e32 v32, v35, v32
	v_add_co_u32_e32 v22, vcc, s20, v36
	v_med3_f32 v30, v30, s17, v70
	v_med3_f32 v31, v31, s17, v70
	v_floor_f32_e32 v32, v32
	v_lshl_or_b32 v26, v29, 12, v26
	v_addc_co_u32_e32 v23, vcc, 0, v37, vcc
	v_mul_f32_e32 v18, v35, v18
	v_cvt_i32_f32_e32 v30, v30
	v_cvt_i32_f32_e32 v31, v31
	v_med3_f32 v32, v32, s17, v70
	v_mov_b32_e32 v237, v26
	v_and_b32_e32 v22, 15, v27
	v_lshlrev_b32_e32 v23, 4, v28
	v_floor_f32_e32 v18, v18
	v_cvt_i32_f32_e32 v32, v32
	v_mul_f32_e32 v25, v35, v25
	v_and_or_b32 v22, v23, s18, v22
	v_lshlrev_b32_e32 v23, 8, v24
	v_med3_f32 v18, v18, s17, v70
	v_floor_f32_e32 v25, v25
	v_and_or_b32 v22, v23, s19, v22
	v_cvt_i32_f32_e32 v23, v18
	v_mul_f32_e32 v18, v35, v19
	v_med3_f32 v25, v25, s17, v70
	v_floor_f32_e32 v18, v18
	v_mul_f32_e32 v20, v35, v20
	v_and_b32_e32 v30, 15, v30
	v_lshlrev_b32_e32 v31, 4, v31
	v_cvt_i32_f32_e32 v25, v25
	v_med3_f32 v18, v18, s17, v70
	v_floor_f32_e32 v20, v20
	v_and_or_b32 v30, v31, s18, v30
	v_lshlrev_b32_e32 v31, 8, v32
	v_cvt_i32_f32_e32 v24, v18
	v_med3_f32 v20, v20, s17, v70
	v_mul_f32_e32 v21, v35, v21
	v_and_or_b32 v30, v31, s19, v30
	v_mul_f32_e32 v31, v35, v33
	v_cvt_i32_f32_e32 v20, v20
	v_floor_f32_e32 v21, v21
	v_floor_f32_e32 v31, v31
	v_add_co_u32_e32 v18, vcc, s21, v36
	v_med3_f32 v21, v21, s17, v70
	v_med3_f32 v31, v31, s17, v70
	v_lshl_or_b32 v22, v25, 12, v22
	v_addc_co_u32_e32 v19, vcc, 0, v37, vcc
	v_cvt_i32_f32_e32 v21, v21
	v_cvt_i32_f32_e32 v31, v31
	v_mov_b32_e32 v238, v22
	v_and_b32_e32 v18, 15, v23
	v_lshlrev_b32_e32 v19, 4, v24
	v_and_or_b32 v18, v19, s18, v18
	v_lshlrev_b32_e32 v19, 8, v20
	v_and_or_b32 v18, v19, s19, v18
	v_lshl_or_b32 v20, v21, 12, v18
	v_add_co_u32_e32 v18, vcc, 0x600000, v36
	v_lshl_or_b32 v30, v31, 12, v30
	s_nop 0
	v_addc_co_u32_e32 v19, vcc, 0, v37, vcc
	v_mov_b32_e32 v236, v30
	v_mov_b32_e32 v239, v20
	v_cndmask_b32_e64 v240, v237, v236, s[44:45]
	v_cndmask_b32_e64 v241, v239, v238, s[44:45]
	s_nop 1
	v_mov_b32_dpp v242, v240 quad_perm:[1,0,3,2] row_mask:0xf bank_mask:0xf
	v_mov_b32_dpp v243, v241 quad_perm:[1,0,3,2] row_mask:0xf bank_mask:0xf
	v_cndmask_b32_e64 v236, v236, v242, s[44:45]
	v_cndmask_b32_e64 v237, v242, v237, s[44:45]
	v_cndmask_b32_e64 v238, v238, v243, s[44:45]
	v_cndmask_b32_e64 v239, v243, v239, s[44:45]
	v_cndmask_b32_e64 v240, v238, v236, s[46:47]
	v_cndmask_b32_e64 v241, v239, v237, s[46:47]
	s_nop 1
	v_mov_b32_dpp v242, v240 quad_perm:[2,3,0,1] row_mask:0xf bank_mask:0xf
	v_mov_b32_dpp v243, v241 quad_perm:[2,3,0,1] row_mask:0xf bank_mask:0xf
	v_cndmask_b32_e64 v236, v236, v242, s[46:47]
	v_cndmask_b32_e64 v238, v242, v238, s[46:47]
	v_cndmask_b32_e64 v237, v237, v243, s[46:47]
	v_cndmask_b32_e64 v239, v243, v239, s[46:47]
	v_perm_b32 v248, v237, v236, s48
	v_perm_b32 v249, v239, v238, s48
	v_lshl_add_u64 v[246:247], v[36:37], 0, v[244:245]
	global_store_dwordx2 v[246:247], v[248:249], off
	s_and_saveexec_b64 s[0:1], s[4:5]
	s_mov_b64 s[60:61], s[26:27]
	s_cbranch_execz .LBB0_133
	s_lshl_b32 s23, s22, 2
	v_mul_f32_e32 v18, 0.5, v34
	v_mov_b32_e32 v19, s23
	global_store_dword v19, v18, s[8:9] offset:8
; __global__ void __launch_bounds__(NTHR, 2) k_main(Args a) {
;     ...
;             for (int q = 0; q < 4; ++q) { const int rr = rr0 + q, which = rr >> 14, row = rr & 16383;
;                 float ss = 0.f;
; #pragma unroll
;                 for (int jq = 0; jq < 4; ++jq) ss += v[q][jq].x * v[q][jq].x + v[q][jq].y * v[q][jq].y + v[q][jq].z * v[q][jq].z + v[q][jq].w * v[q][jq].w;
;                 ss = wave_sum(ss);
;                 const float step = ss > 0.f ? 0.335f * sqrtf(ss * (1.f / D)) : 1.f, inv = 1.f / step;
;                 unsigned short* dst = (unsigned short*)((which ? V8 : U8) + (size_t)row * 128) + lane;
; #pragma unroll
;                 for (int jq = 0; jq < 4; ++jq) { const float e4[4] = {v[q][jq].x, v[q][jq].y, v[q][jq].z, v[q][jq].w}; unsigned w4 = 0u;
; #pragma unroll
;                     for (int i = 0; i < 4; ++i) { const int qi = (int)fminf(fmaxf(floorf(e4[i] * inv), -8.f), 7.f); w4 |= ((unsigned)qi & 15u) << (4 * i); }
;                     dst[(size_t)jq * (16384 * 64)] = (unsigned short)w4; }
;                 if (lane == 0) (which ? SV : SU)[row] = 0.5f * step;
.LBB0_133:
	s_or_b64 exec, exec, s[0:1]
	v_mov_b32_e32 v20, v15
	v_mov_b32_e32 v21, v11
	v_mov_b32_e32 v18, v14
	v_mov_b32_e32 v19, v10
	v_pk_mul_f32 v[20:21], v[20:21], v[20:21]
	v_mov_b32_e32 v22, v16
	v_mov_b32_e32 v23, v12
	v_pk_fma_f32 v[18:19], v[18:19], v[18:19], v[20:21]
	v_mov_b32_e32 v24, v17
	v_pk_fma_f32 v[18:19], v[22:23], v[22:23], v[18:19]
	v_mov_b32_e32 v22, v7
	s_waitcnt vmcnt(12)
	v_mov_b32_e32 v23, v3
	v_mov_b32_e32 v25, v13
	v_mov_b32_e32 v20, v6
	v_mov_b32_e32 v21, v2
	v_pk_mul_f32 v[22:23], v[22:23], v[22:23]
	v_pk_fma_f32 v[18:19], v[24:25], v[24:25], v[18:19]
	v_mov_b32_e32 v24, v8
	v_mov_b32_e32 v25, v4
	v_pk_fma_f32 v[20:21], v[20:21], v[20:21], v[22:23]
	v_mov_b32_e32 v26, v9
	v_mov_b32_e32 v27, v5
	v_pk_fma_f32 v[20:21], v[24:25], v[24:25], v[20:21]
	v_add_f32_e32 v18, v18, v19
	v_pk_fma_f32 v[20:21], v[26:27], v[26:27], v[20:21]
	s_or_b32 s6, s6, 0x180
	v_add_f32_e32 v18, v18, v20
	v_add_f32_e32 v18, v18, v21
	s_nop 1
	v_add_f32_dpp v18, v18, v18 quad_perm:[1,0,3,2] row_mask:0xf bank_mask:0xf bound_ctrl:1
	s_nop 1
	v_add_f32_dpp v18, v18, v18 quad_perm:[2,3,0,1] row_mask:0xf bank_mask:0xf bound_ctrl:1
	s_nop 1
	v_add_f32_dpp v18, v18, v18 row_half_mirror row_mask:0xf bank_mask:0xf bound_ctrl:1
	s_nop 1
	v_add_f32_dpp v18, v18, v18 row_mirror row_mask:0xf bank_mask:0xf bound_ctrl:1
	s_nop 0
	v_readlane_b32 s23, v18, 16
	v_readlane_b32 s24, v18, 48
	v_readlane_b32 s0, v18, 0
	v_readlane_b32 s1, v18, 32
	v_mov_b32_e32 v18, s23
	v_mov_b32_e32 v19, s24
	v_pk_add_f32 v[18:19], s[0:1], v[18:19]
	s_nop 0
	v_add_f32_e32 v18, v18, v19
	v_mul_f32_e32 v19, 0x3a800000, v18
	v_mul_f32_e32 v20, 0x4f800000, v19
	v_cmp_gt_f32_e32 vcc, s16, v19
	s_nop 1
	v_cndmask_b32_e32 v19, v19, v20, vcc
	v_sqrt_f32_e32 v20, v19
	s_nop 0
	v_add_u32_e32 v21, -1, v20
	v_fma_f32 v22, -v21, v20, v19
	v_cmp_ge_f32_e64 s[0:1], 0, v22
	v_add_u32_e32 v22, 1, v20
	s_nop 0
	v_cndmask_b32_e64 v21, v20, v21, s[0:1]
	v_fma_f32 v20, -v22, v20, v19
	v_cmp_lt_f32_e64 s[0:1], 0, v20
	s_nop 1
	v_cndmask_b32_e64 v20, v21, v22, s[0:1]
	v_mul_f32_e32 v21, 0x37800000, v20
	v_cndmask_b32_e32 v20, v20, v21, vcc
	v_cmp_class_f32_e32 vcc, v19, v63
	s_nop 1
	v_cndmask_b32_e32 v19, v20, v19, vcc
	v_mul_f32_e32 v19, 0x3eab851f, v19
	v_cmp_lt_f32_e32 vcc, 0, v18
	s_nop 1
	v_cndmask_b32_e32 v18, 1.0, v19, vcc
	v_div_scale_f32 v19, s[0:1], v18, v18, 1.0
	v_rcp_f32_e32 v20, v19
	s_nop 0
	v_fma_f32 v21, -v19, v20, 1.0
	v_fmac_f32_e32 v20, v21, v20
	v_div_scale_f32 v21, vcc, 1.0, v18, 1.0
	v_mul_f32_e32 v22, v21, v20
	v_fma_f32 v23, -v19, v22, v21
	v_fmac_f32_e32 v22, v23, v20
	v_fma_f32 v19, -v19, v22, v21
	v_div_fmas_f32 v19, v19, v20, v22
	v_div_fixup_f32 v19, v19, v18, 1.0
	v_mul_f32_e32 v10, v19, v10
	v_mul_f32_e32 v11, v19, v11
	v_floor_f32_e32 v10, v10
	v_floor_f32_e32 v11, v11
	v_mul_f32_e32 v12, v19, v12
	v_med3_f32 v10, v10, s17, v70
	v_med3_f32 v11, v11, s17, v70
	v_floor_f32_e32 v12, v12
	v_cvt_i32_f32_e32 v10, v10
	v_cvt_i32_f32_e32 v11, v11
	v_med3_f32 v12, v12, s17, v70
	v_cvt_i32_f32_e32 v12, v12
	v_mul_f32_e32 v6, v19, v6
	v_and_b32_e32 v10, 15, v10
	v_lshlrev_b32_e32 v11, 4, v11
	v_floor_f32_e32 v6, v6
	v_mul_f32_e32 v13, v19, v13
	v_and_or_b32 v10, v11, s18, v10
	v_lshlrev_b32_e32 v11, 8, v12
	v_med3_f32 v6, v6, s17, v70
	v_floor_f32_e32 v13, v13
	v_and_or_b32 v10, v11, s19, v10
	v_cvt_i32_f32_e32 v11, v6
	v_mul_f32_e32 v6, v19, v7
	v_med3_f32 v13, v13, s17, v70
	v_floor_f32_e32 v6, v6
	v_mul_f32_e32 v8, v19, v8
	v_cvt_i32_f32_e32 v13, v13
	v_med3_f32 v6, v6, s17, v70
	v_floor_f32_e32 v8, v8
	v_cvt_i32_f32_e32 v12, v6
	v_med3_f32 v8, v8, s17, v70
	v_lshl_add_u64 v[20:21], v[68:69], 0, s[6:7]
	v_mul_f32_e32 v14, v19, v14
	v_mul_f32_e32 v15, v19, v15
	v_cvt_i32_f32_e32 v8, v8
	v_floor_f32_e32 v14, v14
	v_floor_f32_e32 v15, v15
	v_mul_f32_e32 v16, v19, v16
	v_add_co_u32_e32 v6, vcc, s20, v20
	v_med3_f32 v14, v14, s17, v70
	v_med3_f32 v15, v15, s17, v70
	v_floor_f32_e32 v16, v16
	v_lshl_or_b32 v10, v13, 12, v10
	v_addc_co_u32_e32 v7, vcc, 0, v21, vcc
	v_mul_f32_e32 v2, v19, v2
	v_cvt_i32_f32_e32 v14, v14
	v_cvt_i32_f32_e32 v15, v15
	v_med3_f32 v16, v16, s17, v70
	v_mov_b32_e32 v237, v10
	v_and_b32_e32 v6, 15, v11
	v_lshlrev_b32_e32 v7, 4, v12
	v_floor_f32_e32 v2, v2
	v_cvt_i32_f32_e32 v16, v16
	v_mul_f32_e32 v9, v19, v9
	v_and_or_b32 v6, v7, s18, v6
	v_lshlrev_b32_e32 v7, 8, v8
	v_med3_f32 v2, v2, s17, v70
	v_floor_f32_e32 v9, v9
	v_and_or_b32 v6, v7, s19, v6
	v_cvt_i32_f32_e32 v7, v2
	v_mul_f32_e32 v2, v19, v3
	v_med3_f32 v9, v9, s17, v70
	v_floor_f32_e32 v2, v2
	v_mul_f32_e32 v4, v19, v4
	v_and_b32_e32 v14, 15, v14
	v_lshlrev_b32_e32 v15, 4, v15
	v_cvt_i32_f32_e32 v9, v9
	v_med3_f32 v2, v2, s17, v70
	v_floor_f32_e32 v4, v4
	v_and_or_b32 v14, v15, s18, v14
	v_lshlrev_b32_e32 v15, 8, v16
	v_cvt_i32_f32_e32 v8, v2
	v_med3_f32 v4, v4, s17, v70
	v_mul_f32_e32 v5, v19, v5
	v_and_or_b32 v14, v15, s19, v14
	v_mul_f32_e32 v15, v19, v17
	v_cvt_i32_f32_e32 v4, v4
	v_floor_f32_e32 v5, v5
	v_floor_f32_e32 v15, v15
	v_add_co_u32_e32 v2, vcc, s21, v20
	v_med3_f32 v5, v5, s17, v70
	v_med3_f32 v15, v15, s17, v70
	v_lshl_or_b32 v6, v9, 12, v6
	v_addc_co_u32_e32 v3, vcc, 0, v21, vcc
	v_cvt_i32_f32_e32 v5, v5
	v_cvt_i32_f32_e32 v15, v15
	v_mov_b32_e32 v238, v6
	v_and_b32_e32 v2, 15, v7
	v_lshlrev_b32_e32 v3, 4, v8
	v_and_or_b32 v2, v3, s18, v2
	v_lshlrev_b32_e32 v3, 8, v4
	v_and_or_b32 v2, v3, s19, v2
	v_lshl_or_b32 v4, v5, 12, v2
	v_add_co_u32_e32 v2, vcc, 0x600000, v20
	v_lshl_or_b32 v14, v15, 12, v14
	s_nop 0
	v_addc_co_u32_e32 v3, vcc, 0, v21, vcc
	v_mov_b32_e32 v236, v14
	v_mov_b32_e32 v239, v4
	v_cndmask_b32_e64 v240, v237, v236, s[44:45]
	v_cndmask_b32_e64 v241, v239, v238, s[44:45]
	s_nop 1
	v_mov_b32_dpp v242, v240 quad_perm:[1,0,3,2] row_mask:0xf bank_mask:0xf
	v_mov_b32_dpp v243, v241 quad_perm:[1,0,3,2] row_mask:0xf bank_mask:0xf
	v_cndmask_b32_e64 v236, v236, v242, s[44:45]
	v_cndmask_b32_e64 v237, v242, v237, s[44:45]
	v_cndmask_b32_e64 v238, v238, v243, s[44:45]
	v_cndmask_b32_e64 v239, v243, v239, s[44:45]
	v_cndmask_b32_e64 v240, v238, v236, s[46:47]
	v_cndmask_b32_e64 v241, v239, v237, s[46:47]
	s_nop 1
	v_mov_b32_dpp v242, v240 quad_perm:[2,3,0,1] row_mask:0xf bank_mask:0xf
	v_mov_b32_dpp v243, v241 quad_perm:[2,3,0,1] row_mask:0xf bank_mask:0xf
	v_cndmask_b32_e64 v236, v236, v242, s[46:47]
	v_cndmask_b32_e64 v238, v242, v238, s[46:47]
	v_cndmask_b32_e64 v237, v237, v243, s[46:47]
	v_cndmask_b32_e64 v239, v243, v239, s[46:47]
	v_perm_b32 v248, v237, v236, s48
	v_perm_b32 v249, v239, v238, s48
	v_lshl_add_u64 v[246:247], v[20:21], 0, v[244:245]
	global_store_dwordx2 v[246:247], v[248:249], off
	s_and_saveexec_b64 s[0:1], s[4:5]
	s_cbranch_execz .LBB0_126
	s_lshl_b32 s6, s22, 2
	v_mul_f32_e32 v2, 0.5, v18
	v_mov_b32_e32 v3, s6
	global_store_dword v3, v2, s[8:9] offset:12
	s_branch .LBB0_126

; #define LAS __attribute__((address_space(3)))
; #define MFMA32(a, b, c) __builtin_amdgcn_mfma_f32_32x32x16_bf16((a), (b), (c), 0, 0, 0)
; __device__ __forceinline__ void route_task(int task, int tl0, const bf16* QP  , const LAS bf16* KHL, LAS unsigned short* EL, LAS float* GL, int lane) {
;     const int r = lane & 31, hi = lane >> 5, t = 4 * task + (r >> 3), head = r & 7;
;     int top[2][16]; bf16x8 qa[2][4];
;     { unsigned qo = (unsigned)t * (unsigned)D + (unsigned)(head * 128 + 8 * hi); asm volatile("" : "+v"(qo)); const bf16* qp = QP + qo;
; #pragma unroll
;       for (int hf = 0; hf < 2; ++hf)
; #pragma unroll
;         for (int ks = 0; ks < 4; ++ks) qa[hf][ks] = ldg8(qp + 64 * hf + 16 * ks); }
; #pragma unroll
;     for (int half = 0; half < 2; ++half) {
;         int cur[16];
; #pragma unroll
;         for (int kt = 0; kt < 4; ++kt) {
;             f32x16 X;
; #pragma unroll
;             for (int i = 0; i < 16; ++i) X[i] = 8.f;
;             const LAS bf16* khp = KHL + (half * 128 + 32 * kt + r) * 72 + 8 * hi;
; #pragma unroll
;             for (int ks = 0; ks < 4; ++ks) {
;                 const bf16x8 kh = lds8(khp + 16 * ks);
;                 X = MFMA32(kh, qa[half][ks], X);
;             }
;             int grp[16];
; #pragma unroll
;             for (int i = 0; i < 16; ++i) grp[i] = (int)((__float_as_uint(X[i]) | 127u) - (unsigned)(32 * kt + (i & 3) + 8 * (i >> 2)));
;             sort16_desc(grp);
;             if (kt == 0) {
; #pragma unroll
;                 for (int i = 0; i < 16; ++i) cur[i] = grp[i];
;             } else merge16_desc(cur, grp);
; __global__ void __launch_bounds__(NTHR, 2) k_main(Args a) {
;     ...
;             __syncthreads();
;             route_task(16 * j + wave, 4 * wave, QP, KHL, EL, GL, lane);
;             route_task(16 * j + 8 + wave, 32 + 4 * wave, QP, KHL, EL, GL, lane);
.LBB0_666:
	s_or_b64 exec, exec, s[10:11]
	s_lshl_b32 s10, s2, 4
	s_add_i32 s10, s10, s95
	s_lshl_b32 s10, s10, 12
	v_or_b32_e32 v82, s10, v88
	s_waitcnt lgkmcnt(0)
	s_barrier
	s_add_i32 s11, 0, 0x12000
	v_lshl_add_u64 v[70:71], v[82:83], 1, s[80:81]
	global_load_dwordx4 v[62:65], v[70:71], off
	global_load_dwordx4 v[54:57], v[70:71], off offset:32
	global_load_dwordx4 v[58:61], v[70:71], off offset:64
	global_load_dwordx4 v[50:53], v[70:71], off offset:96
	ds_read_b128 v[34:37], v94
	ds_read_b128 v[38:41], v94 offset:32
	s_add_i32 s10, s10, 0x8000
	s_mov_b32 s41, 0
	s_waitcnt vmcnt(3) lgkmcnt(1)
	v_mfma_f32_32x32x16_bf16 v[18:33], v[34:37], v[62:65], v[2:17]
	ds_read_b128 v[34:37], v94 offset:64
	ds_read_b128 v[66:69], v94 offset:96
	s_waitcnt vmcnt(2) lgkmcnt(2)
	v_mfma_f32_32x32x16_bf16 v[18:33], v[38:41], v[54:57], v[18:33]
	v_and_b32_e32 v38, 64, v112
	v_add_u32_e32 v122, 64, v38
	v_cmp_lt_i32_e32 vcc, v113, v122
	s_waitcnt vmcnt(1) lgkmcnt(1)
	v_mfma_f32_32x32x16_bf16 v[18:33], v[34:37], v[58:61], v[18:33]
	v_cndmask_b32_e32 v34, v112, v113, vcc
	v_lshlrev_b32_e32 v123, 2, v34
	global_load_dwordx4 v[46:49], v[70:71], off offset:128
	global_load_dwordx4 v[42:45], v[70:71], off offset:160
	global_load_dwordx4 v[38:41], v[70:71], off offset:192
	global_load_dwordx4 v[34:37], v[70:71], off offset:224
	s_waitcnt vmcnt(4) lgkmcnt(0)
	v_mfma_f32_32x32x16_bf16 v[18:33], v[66:69], v[50:53], v[18:33]
	s_nop 11
	v_or_b32_e32 v21, 0x7f, v21
	v_or_b32_e32 v32, 0x7f, v32
	v_or_b32_e32 v22, 0x7f, v22
	v_or_b32_e32 v26, 0x7f, v26
	v_or_b32_e32 v31, 0x7f, v31
	v_or_b32_e32 v23, 0x7f, v23
	v_or_b32_e32 v24, 0x7f, v24
	v_or_b32_e32 v27, 0x7f, v27
	v_or_b32_e32 v28, 0x7f, v28
	v_or_b32_e32 v20, 0x7f, v20
	v_or_b32_e32 v33, 0x7f, v33
	v_or_b32_e32 v25, 0x7f, v25
	v_or_b32_e32 v29, 0x7f, v29
	v_or_b32_e32 v19, 0x7f, v19
	v_or_b32_e32 v30, 0x7f, v30
	v_or_b32_e32 v18, 0x7f, v18
	v_add_u32_e32 v21, -3, v21
	v_subrev_u32_e32 v32, 26, v32
	v_add_u32_e32 v22, -8, v22
	v_add_u32_e32 v26, -16, v26
	v_subrev_u32_e32 v31, 25, v31
	v_add_u32_e32 v23, -9, v23
	v_add_u32_e32 v24, -10, v24
	v_subrev_u32_e32 v27, 17, v27
	v_subrev_u32_e32 v28, 18, v28
	v_add_u32_e32 v20, -2, v20
	v_subrev_u32_e32 v33, 27, v33
	v_add_u32_e32 v25, -11, v25
	v_subrev_u32_e32 v29, 19, v29
	v_add_u32_e32 v19, -1, v19
	v_subrev_u32_e32 v30, 24, v30
	v_max_i32_e32 v66, v21, v32
	v_max_i32_e32 v67, v22, v26
	v_max_i32_e32 v68, v18, v31
	v_max_i32_e32 v69, v23, v24
	v_min_i32_e32 v70, v27, v28
	v_min_i32_e32 v71, v20, v33
	v_min_i32_e32 v72, v25, v29
	v_min_i32_e32 v73, v19, v30
	v_min_i32_e32 v23, v23, v24
	v_min_i32_e32 v18, v18, v31
	v_min_i32_e32 v22, v22, v26
	v_min_i32_e32 v21, v21, v32
	v_max_i32_e32 v19, v19, v30
	v_max_i32_e32 v24, v25, v29
	v_max_i32_e32 v20, v20, v33
	v_max_i32_e32 v25, v27, v28
	v_min_i32_e32 v26, v66, v67
	v_min_i32_e32 v27, v68, v69
	v_max_i32_e32 v28, v70, v71
	v_max_i32_e32 v29, v72, v73
	v_max_i32_e32 v30, v23, v18
	v_max_i32_e32 v31, v22, v21
	v_min_i32_e32 v32, v19, v24
	v_min_i32_e32 v33, v20, v25
	v_min_i32_e32 v18, v23, v18
	v_min_i32_e32 v21, v22, v21
	v_min_i32_e32 v22, v70, v71
	v_max_i32_e32 v23, v68, v69
	v_max_i32_e32 v19, v19, v24
	v_max_i32_e32 v20, v20, v25
	v_max_i32_e32 v24, v66, v67
	v_min_i32_e32 v25, v26, v27
	v_max_i32_e32 v67, v30, v31
	v_min_i32_e32 v30, v30, v31
	v_min_i32_e32 v31, v32, v33
	v_max_i32_e32 v26, v26, v27
	v_max_i32_e32 v27, v28, v29
	v_min_i32_e32 v66, v28, v29
	v_max_i32_e32 v68, v32, v33
	v_min_i32_e32 v75, v21, v22
	v_max_i32_e32 v21, v21, v22
	v_min_i32_e32 v22, v23, v19
	v_min_i32_e32 v28, v20, v24
	v_max_i32_e32 v33, v30, v31
	v_min_i32_e32 v69, v26, v27
	v_max_i32_e32 v29, v25, v66
	v_min_i32_e32 v32, v67, v68
	v_min_i32_e32 v77, v25, v66
	v_min_i32_e32 v25, v22, v28
	v_max_i32_e32 v80, v22, v28
	v_min_i32_e32 v22, v33, v69
	v_max_i32_e32 v125, v20, v24
	v_max_i32_e32 v129, v67, v68
	v_max_i32_e32 v24, v33, v69
	ds_read_b128 v[66:69], v95
	v_min_i32_e32 v72, v72, v73
	v_min_i32_e32 v74, v72, v18
	v_max_i32_e32 v18, v72, v18
	v_max_i32_e32 v124, v23, v19
	v_min_i32_e32 v76, v30, v31
	v_max_i32_e32 v78, v74, v75
	v_min_i32_e32 v79, v18, v21
	v_min_i32_e32 v126, v124, v125
	v_max_i32_e32 v128, v26, v27
	v_max_i32_e32 v18, v18, v21
	v_max_i32_e32 v81, v76, v77
	v_max_i32_e32 v82, v78, v79
	v_min_i32_e32 v127, v80, v126
	v_min_i32_e32 v130, v128, v129
	v_min_i32_e32 v21, v29, v32
	v_min_i32_e32 v28, v25, v18
	v_max_i32_e32 v18, v25, v18
	v_max_i32_e32 v30, v81, v82
	v_min_i32_e32 v19, v127, v130
	v_max_i32_e32 v23, v29, v32
	v_max_i32_e32 v25, v21, v22
	v_max_i32_e32 v31, v30, v28
	v_min_i32_e32 v20, v18, v19
	v_min_i32_e32 v26, v23, v24
	v_max_i32_e32 v70, v25, v31
	v_min_i32_e32 v27, v20, v26
	v_min_i32_e32 v131, v70, v27
	v_max_i32_e32 v143, v70, v27
	ds_read_b128 v[70:73], v95 offset:32
	v_min_i32_e32 v132, v25, v31
	v_min_i32_e32 v133, v21, v22
	v_min_i32_e32 v134, v30, v28
	v_max_i32_e32 v138, v18, v19
	v_max_i32_e32 v139, v23, v24
	v_max_i32_e32 v141, v20, v26
	s_waitcnt lgkmcnt(1)
	v_mfma_f32_32x32x16_bf16 v[18:33], v[66:69], v[62:65], v[2:17]
	ds_read_b128 v[66:69], v95 offset:64
	v_max_i32_e32 v135, v133, v134
	v_max_i32_e32 v136, v132, v135
	v_min_i32_e32 v76, v76, v77
	v_min_i32_e32 v77, v78, v79
	v_min_i32_e32 v132, v132, v135
	v_max_i32_e32 v127, v127, v130
	s_waitcnt lgkmcnt(1)
	v_mfma_f32_32x32x16_bf16 v[18:33], v[70:73], v[54:57], v[18:33]
	ds_read_b128 v[70:73], v95 offset:96
	v_max_i32_e32 v80, v80, v126
	v_min_i32_e32 v74, v74, v75
	v_min_i32_e32 v140, v138, v139
	v_max_i32_e32 v78, v76, v77
	v_min_i32_e32 v79, v81, v82
	v_min_i32_e32 v82, v133, v134
	s_waitcnt lgkmcnt(1)
; #define LAS __attribute__((address_space(3)))
; #define MFMA32(a, b, c) __builtin_amdgcn_mfma_f32_32x32x16_bf16((a), (b), (c), 0, 0, 0)
; __device__ __forceinline__ void route_task(int task, int tl0, const bf16* QP  , const LAS bf16* KHL, LAS unsigned short* EL, LAS float* GL, int lane) {
;     ...
;         for (int kt = 0; kt < 4; ++kt) {
;             f32x16 X;
; #pragma unroll
;             for (int i = 0; i < 16; ++i) X[i] = 8.f;
;             const LAS bf16* khp = KHL + (half * 128 + 32 * kt + r) * 72 + 8 * hi;
; #pragma unroll
;             for (int ks = 0; ks < 4; ++ks) {
;                 const bf16x8 kh = lds8(khp + 16 * ks);
;                 X = MFMA32(kh, qa[half][ks], X);
;             }
;             int grp[16];
; #pragma unroll
;             for (int i = 0; i < 16; ++i) grp[i] = (int)((__float_as_uint(X[i]) | 127u) - (unsigned)(32 * kt + (i & 3) + 8 * (i >> 2)));
;             sort16_desc(grp);
;             if (kt == 0) {
; #pragma unroll
;                 for (int i = 0; i < 16; ++i) cur[i] = grp[i];
;             } else merge16_desc(cur, grp);
	v_mfma_f32_32x32x16_bf16 v[18:33], v[66:69], v[58:61], v[18:33]
	v_max_i32_e32 v66, v128, v129
	v_max_i32_e32 v134, v138, v139
	v_min_i32_e32 v76, v76, v77
	v_max_i32_e32 v81, v78, v79
	v_min_i32_e32 v78, v78, v79
	v_min_i32_e32 v67, v80, v66
	v_min_i32_e32 v142, v140, v141
	s_waitcnt lgkmcnt(0)
	v_mfma_f32_32x32x16_bf16 v[18:33], v[70:73], v[50:53], v[18:33]
	v_min_i32_e32 v68, v127, v67
	v_min_i32_e32 v137, v131, v136
	v_min_i32_e32 v144, v142, v143
	v_min_i32_e32 v133, v81, v82
	v_min_i32_e32 v69, v134, v68
	s_nop 6
	v_or_b32_e32 v21, 0x7f, v21
	v_or_b32_e32 v32, 0x7f, v32
	v_or_b32_e32 v22, 0x7f, v22
	v_or_b32_e32 v26, 0x7f, v26
	v_or_b32_e32 v18, 0x7f, v18
	v_or_b32_e32 v31, 0x7f, v31
	v_or_b32_e32 v23, 0x7f, v23
	v_or_b32_e32 v24, 0x7f, v24
	v_or_b32_e32 v27, 0x7f, v27
	v_or_b32_e32 v28, 0x7f, v28
	v_or_b32_e32 v20, 0x7f, v20
	v_or_b32_e32 v33, 0x7f, v33
	v_or_b32_e32 v25, 0x7f, v25
	v_or_b32_e32 v29, 0x7f, v29
	v_or_b32_e32 v19, 0x7f, v19
	v_or_b32_e32 v30, 0x7f, v30
	v_subrev_u32_e32 v21, 35, v21
	v_subrev_u32_e32 v32, 58, v32
	v_subrev_u32_e32 v22, 40, v22
	v_subrev_u32_e32 v26, 48, v26
	v_subrev_u32_e32 v18, 32, v18
	v_subrev_u32_e32 v31, 57, v31
	v_subrev_u32_e32 v23, 41, v23
	v_subrev_u32_e32 v24, 42, v24
	v_subrev_u32_e32 v27, 49, v27
	v_subrev_u32_e32 v28, 50, v28
	v_subrev_u32_e32 v20, 34, v20
	v_subrev_u32_e32 v33, 59, v33
	v_subrev_u32_e32 v25, 43, v25
	v_subrev_u32_e32 v29, 51, v29
	v_subrev_u32_e32 v19, 33, v19
	v_subrev_u32_e32 v30, 56, v30
	v_max_i32_e32 v70, v21, v32
	v_max_i32_e32 v71, v22, v26
	v_max_i32_e32 v73, v18, v31
	v_max_i32_e32 v75, v23, v24
	v_min_i32_e32 v126, v27, v28
	v_min_i32_e32 v128, v20, v33
	v_min_i32_e32 v130, v25, v29
	v_min_i32_e32 v135, v19, v30
	v_min_i32_e32 v23, v23, v24
	v_min_i32_e32 v18, v18, v31
	v_min_i32_e32 v22, v22, v26
	v_min_i32_e32 v21, v21, v32
	v_max_i32_e32 v19, v19, v30
	v_max_i32_e32 v25, v25, v29
	v_max_i32_e32 v20, v20, v33
	v_max_i32_e32 v27, v27, v28
	v_min_i32_e32 v72, v70, v71
	v_min_i32_e32 v77, v73, v75
	v_max_i32_e32 v129, v126, v128
	v_max_i32_e32 v138, v130, v135
	v_max_i32_e32 v24, v23, v18
	v_max_i32_e32 v26, v22, v21
	v_min_i32_e32 v29, v19, v25
	v_min_i32_e32 v28, v20, v27
	v_min_i32_e32 v130, v130, v135
	v_min_i32_e32 v18, v23, v18
	v_min_i32_e32 v21, v22, v21
	v_min_i32_e32 v22, v126, v128
	v_max_i32_e32 v73, v73, v75
	v_max_i32_e32 v19, v19, v25
	v_max_i32_e32 v20, v20, v27
	v_max_i32_e32 v27, v70, v71
	v_min_i32_e32 v79, v72, v77
	v_min_i32_e32 v139, v129, v138
	v_max_i32_e32 v31, v24, v26
	v_max_i32_e32 v30, v29, v28
	v_min_i32_e32 v24, v24, v26
	v_min_i32_e32 v26, v29, v28
	v_max_i32_e32 v29, v72, v77
	v_max_i32_e32 v72, v129, v138
	v_min_i32_e32 v23, v130, v18
	v_min_i32_e32 v126, v21, v22
	v_max_i32_e32 v18, v130, v18
	v_max_i32_e32 v21, v21, v22
	v_min_i32_e32 v25, v73, v19
	v_min_i32_e32 v70, v20, v27
	v_max_i32_e32 v19, v73, v19
	v_max_i32_e32 v20, v20, v27
	v_min_i32_e32 v32, v31, v30
	v_max_i32_e32 v28, v24, v26
	v_min_i32_e32 v77, v29, v72
	v_min_i32_e32 v24, v24, v26
	v_min_i32_e32 v26, v79, v139
	v_max_i32_e32 v128, v23, v126
	v_min_i32_e32 v22, v18, v21
	v_min_i32_e32 v71, v25, v70
	v_max_i32_e32 v25, v25, v70
	v_min_i32_e32 v27, v19, v20
	v_max_i32_e32 v29, v29, v72
	v_max_i32_e32 v30, v31, v30
	v_max_i32_e32 v145, v79, v139
	v_max_i32_e32 v79, v24, v26
	v_max_i32_e32 v130, v128, v22
	v_max_i32_e32 v18, v18, v21
	v_min_i32_e32 v70, v25, v27
	v_min_i32_e32 v31, v29, v30
	v_min_i32_e32 v33, v145, v32
	v_min_i32_e32 v129, v28, v77
	v_max_i32_e32 v135, v79, v130
	v_min_i32_e32 v21, v71, v18
	v_max_i32_e32 v18, v71, v18
	v_min_i32_e32 v71, v70, v31
	v_max_i32_e32 v32, v145, v32
	v_max_i32_e32 v28, v28, v77
	v_max_i32_e32 v138, v33, v129
	v_max_i32_e32 v75, v135, v21
	v_min_i32_e32 v72, v18, v71
	v_min_i32_e32 v73, v32, v28
	v_min_i32_e32 v33, v33, v129
	v_min_i32_e32 v21, v135, v21
	v_max_i32_e32 v18, v18, v71
	v_max_i32_e32 v28, v32, v28
	v_min_i32_e32 v24, v24, v26
	v_min_i32_e32 v22, v128, v22
	v_max_i32_e32 v25, v25, v27
	v_max_i32_e32 v27, v29, v30
	v_max_i32_e32 v139, v138, v75
	v_min_i32_e32 v77, v72, v73
	v_min_i32_e32 v75, v138, v75
	v_max_i32_e32 v129, v33, v21
	v_min_i32_e32 v32, v18, v28
	v_max_i32_e32 v71, v72, v73
	v_max_i32_e32 v26, v24, v22
	v_min_i32_e32 v79, v79, v130
	v_max_i32_e32 v18, v18, v28
	v_max_i32_e32 v28, v70, v31
	v_min_i32_e32 v29, v25, v27
	v_min_i32_e32 v145, v139, v77
	v_max_i32_e32 v135, v75, v129
	v_min_i32_e32 v72, v32, v71
	v_max_i32_e32 v73, v139, v77
	v_max_i32_e32 v128, v26, v79
	v_min_i32_e32 v21, v33, v21
	v_min_i32_e32 v30, v28, v29
	v_min_i32_e32 v138, v145, v135
	v_min_i32_e32 v77, v72, v73
	v_min_i32_e32 v33, v128, v21
	v_min_i32_e32 v75, v75, v129
	v_min_i32_e32 v31, v18, v30
	v_min_i32_e32 v26, v26, v79
	v_min_i32_e32 v22, v24, v22
	v_min_i32_e32 v23, v23, v126
	v_max3_i32 v23, v124, v125, v23
	v_max3_i32 v22, v80, v66, v22
	v_max3_i32 v24, v127, v67, v26
	v_max3_i32 v26, v134, v68, v33
	v_max3_i32 v21, v69, v128, v21
	v_max3_i32 v33, v140, v141, v75
	v_max3_i32 v66, v142, v143, v138
	v_max3_i32 v67, v144, v145, v135
	v_max3_i32 v68, v131, v136, v77
	v_max3_i32 v69, v137, v72, v73
	v_max3_i32 v32, v132, v32, v71
	v_max3_i32 v31, v81, v82, v31
	v_max3_i32 v18, v133, v18, v30
	v_max3_i32 v28, v78, v28, v29
	v_max3_i32 v25, v76, v25, v27
	v_max3_i32 v19, v74, v19, v20
	v_max_i32_e32 v20, v23, v68
	v_min_i32_e32 v23, v23, v68
	v_max_i32_e32 v27, v22, v69
	v_min_i32_e32 v22, v22, v69
	v_max_i32_e32 v29, v24, v32
	v_min_i32_e32 v24, v24, v32
	v_max_i32_e32 v30, v26, v31
	v_min_i32_e32 v26, v26, v31
	v_max_i32_e32 v31, v21, v18
	v_min_i32_e32 v18, v21, v18
	v_max_i32_e32 v21, v33, v28
	v_min_i32_e32 v28, v33, v28
	v_max_i32_e32 v32, v66, v25
	v_min_i32_e32 v25, v66, v25
	v_max_i32_e32 v33, v67, v19
	v_min_i32_e32 v19, v67, v19
	ds_read_b128 v[66:69], v94 offset:9216
	v_max_i32_e32 v70, v20, v31
	v_min_i32_e32 v74, v20, v31
	v_max_i32_e32 v20, v27, v21
	v_min_i32_e32 v75, v27, v21
	v_max_i32_e32 v21, v29, v32
	v_max_i32_e32 v27, v30, v33
	v_max_i32_e32 v127, v70, v21
	v_min_i32_e32 v128, v70, v21
	ds_read_b128 v[70:73], v94 offset:9248
	v_min_i32_e32 v76, v29, v32
	v_min_i32_e32 v77, v30, v33
	v_max_i32_e32 v78, v23, v18
	v_min_i32_e32 v79, v23, v18
	v_max_i32_e32 v80, v22, v28
	v_min_i32_e32 v81, v22, v28
	v_max_i32_e32 v82, v24, v25
	v_min_i32_e32 v124, v24, v25
	v_max_i32_e32 v125, v26, v19
	v_min_i32_e32 v126, v26, v19
	v_max_i32_e32 v129, v20, v27
	v_min_i32_e32 v130, v20, v27
	s_waitcnt lgkmcnt(1)
; #define LAS __attribute__((address_space(3)))
; #define MFMA32(a, b, c) __builtin_amdgcn_mfma_f32_32x32x16_bf16((a), (b), (c), 0, 0, 0)
; __device__ __forceinline__ void route_task(int task, int tl0, const bf16* QP  , const LAS bf16* KHL, LAS unsigned short* EL, LAS float* GL, int lane) {
;     ...
;         for (int kt = 0; kt < 4; ++kt) {
;             f32x16 X;
; #pragma unroll
;             for (int i = 0; i < 16; ++i) X[i] = 8.f;
;             const LAS bf16* khp = KHL + (half * 128 + 32 * kt + r) * 72 + 8 * hi;
; #pragma unroll
;             for (int ks = 0; ks < 4; ++ks) {
;                 const bf16x8 kh = lds8(khp + 16 * ks);
;                 X = MFMA32(kh, qa[half][ks], X);
;             }
;             int grp[16];
; #pragma unroll
;             for (int i = 0; i < 16; ++i) grp[i] = (int)((__float_as_uint(X[i]) | 127u) - (unsigned)(32 * kt + (i & 3) + 8 * (i >> 2)));
;             sort16_desc(grp);
;             if (kt == 0) {
; #pragma unroll
;                 for (int i = 0; i < 16; ++i) cur[i] = grp[i];
;             } else merge16_desc(cur, grp);
	v_mfma_f32_32x32x16_bf16 v[18:33], v[66:69], v[62:65], v[2:17]
	ds_read_b128 v[66:69], v94 offset:9280
	v_max_i32_e32 v131, v74, v76
	v_min_i32_e32 v74, v74, v76
	v_max_i32_e32 v76, v75, v77
	v_min_i32_e32 v75, v75, v77
	v_max_i32_e32 v77, v78, v82
	v_min_i32_e32 v78, v78, v82
	s_waitcnt lgkmcnt(1)
	v_mfma_f32_32x32x16_bf16 v[18:33], v[70:73], v[54:57], v[18:33]
	ds_read_b128 v[70:73], v94 offset:9312
	v_max_i32_e32 v82, v80, v125
	v_min_i32_e32 v80, v80, v125
	v_max_i32_e32 v125, v79, v124
	v_min_i32_e32 v79, v79, v124
	v_max_i32_e32 v124, v81, v126
	v_min_i32_e32 v81, v81, v126
	s_waitcnt lgkmcnt(1)
	v_mfma_f32_32x32x16_bf16 v[18:33], v[66:69], v[58:61], v[18:33]
	v_min_i32_e32 v126, v127, v129
	v_min_i32_e32 v66, v128, v130
	v_min_i32_e32 v67, v131, v76
	v_min_i32_e32 v69, v77, v82
	v_min_i32_e32 v132, v78, v80
	v_min_i32_e32 v133, v125, v124
	v_min_i32_e32 v68, v74, v75
	s_waitcnt lgkmcnt(0)
	v_mfma_f32_32x32x16_bf16 v[18:33], v[70:73], v[50:53], v[18:33]
	v_min_i32_e32 v134, v79, v81
	s_nop 10
	v_or_b32_e32 v21, 0x7f, v21
	v_or_b32_e32 v32, 0x7f, v32
	v_or_b32_e32 v22, 0x7f, v22
	v_or_b32_e32 v26, 0x7f, v26
	v_or_b32_e32 v18, 0x7f, v18
	v_or_b32_e32 v31, 0x7f, v31
	v_or_b32_e32 v23, 0x7f, v23
	v_or_b32_e32 v24, 0x7f, v24
	v_or_b32_e32 v27, 0x7f, v27
	v_or_b32_e32 v28, 0x7f, v28
	v_or_b32_e32 v20, 0x7f, v20
	v_or_b32_e32 v33, 0x7f, v33
	v_or_b32_e32 v25, 0x7f, v25
	v_or_b32_e32 v29, 0x7f, v29
	v_or_b32_e32 v19, 0x7f, v19
	v_or_b32_e32 v30, 0x7f, v30
	v_add_u32_e32 v21, 0xffffffbd, v21
	v_add_u32_e32 v32, 0xffffffa6, v32
	v_add_u32_e32 v22, 0xffffffb8, v22
	v_add_u32_e32 v26, 0xffffffb0, v26
	v_subrev_u32_e32 v18, 64, v18
	v_add_u32_e32 v31, 0xffffffa7, v31
	v_add_u32_e32 v23, 0xffffffb7, v23
	v_add_u32_e32 v24, 0xffffffb6, v24
	v_add_u32_e32 v27, 0xffffffaf, v27
	v_add_u32_e32 v28, 0xffffffae, v28
	v_add_u32_e32 v20, 0xffffffbe, v20
	v_add_u32_e32 v33, 0xffffffa5, v33
	v_add_u32_e32 v25, 0xffffffb5, v25
	v_add_u32_e32 v29, 0xffffffad, v29
	v_add_u32_e32 v19, 0xffffffbf, v19
	v_add_u32_e32 v30, 0xffffffa8, v30
	v_max_i32_e32 v70, v21, v32
	v_max_i32_e32 v71, v22, v26
	v_max_i32_e32 v73, v18, v31
	v_max_i32_e32 v135, v23, v24
	v_min_i32_e32 v138, v27, v28
	v_min_i32_e32 v139, v20, v33
	v_min_i32_e32 v141, v25, v29
	v_min_i32_e32 v142, v19, v30
	v_min_i32_e32 v23, v23, v24
	v_min_i32_e32 v18, v18, v31
	v_min_i32_e32 v22, v22, v26
	v_min_i32_e32 v21, v21, v32
	v_max_i32_e32 v19, v19, v30
	v_max_i32_e32 v25, v25, v29
	v_max_i32_e32 v20, v20, v33
	v_max_i32_e32 v27, v27, v28
	v_min_i32_e32 v72, v70, v71
	v_min_i32_e32 v136, v73, v135
	v_max_i32_e32 v140, v138, v139
	v_max_i32_e32 v143, v141, v142
	v_max_i32_e32 v24, v23, v18
	v_max_i32_e32 v26, v22, v21
	v_min_i32_e32 v29, v19, v25
	v_min_i32_e32 v28, v20, v27
	v_min_i32_e32 v141, v141, v142
	v_min_i32_e32 v18, v23, v18
	v_min_i32_e32 v21, v22, v21
	v_min_i32_e32 v22, v138, v139
	v_max_i32_e32 v73, v73, v135
	v_max_i32_e32 v19, v19, v25
	v_max_i32_e32 v20, v20, v27
	v_max_i32_e32 v27, v70, v71
	v_min_i32_e32 v137, v72, v136
	v_min_i32_e32 v144, v140, v143
	v_max_i32_e32 v31, v24, v26
	v_max_i32_e32 v30, v29, v28
	v_min_i32_e32 v24, v24, v26
	v_min_i32_e32 v26, v29, v28
	v_max_i32_e32 v29, v72, v136
	v_max_i32_e32 v72, v140, v143
	v_min_i32_e32 v23, v141, v18
	v_min_i32_e32 v138, v21, v22
	v_max_i32_e32 v18, v141, v18
	v_max_i32_e32 v21, v21, v22
	v_min_i32_e32 v25, v73, v19
	v_min_i32_e32 v70, v20, v27
	v_max_i32_e32 v19, v73, v19
	v_max_i32_e32 v20, v20, v27
	v_min_i32_e32 v32, v31, v30
	v_max_i32_e32 v28, v24, v26
	v_min_i32_e32 v136, v29, v72
	v_min_i32_e32 v24, v24, v26
	v_min_i32_e32 v26, v137, v144
	v_max_i32_e32 v139, v23, v138
	v_min_i32_e32 v22, v18, v21
	v_min_i32_e32 v71, v25, v70
	v_max_i32_e32 v25, v25, v70
	v_min_i32_e32 v27, v19, v20
	v_max_i32_e32 v29, v29, v72
	v_max_i32_e32 v30, v31, v30
	v_max_i32_e32 v145, v137, v144
	v_max_i32_e32 v137, v24, v26
	v_max_i32_e32 v141, v139, v22
	v_max_i32_e32 v18, v18, v21
	v_min_i32_e32 v70, v25, v27
	v_min_i32_e32 v31, v29, v30
	v_min_i32_e32 v33, v145, v32
	v_min_i32_e32 v140, v28, v136
	v_max_i32_e32 v142, v137, v141
	v_min_i32_e32 v21, v71, v18
	v_max_i32_e32 v18, v71, v18
	v_min_i32_e32 v71, v70, v31
	v_max_i32_e32 v32, v145, v32
	v_max_i32_e32 v28, v28, v136
	v_max_i32_e32 v143, v33, v140
	v_max_i32_e32 v135, v142, v21
	v_min_i32_e32 v72, v18, v71
	v_min_i32_e32 v73, v32, v28
	v_min_i32_e32 v33, v33, v140
	v_min_i32_e32 v21, v142, v21
	v_max_i32_e32 v18, v18, v71
	v_max_i32_e32 v28, v32, v28
	v_min_i32_e32 v24, v24, v26
	v_min_i32_e32 v22, v139, v22
	v_max_i32_e32 v25, v25, v27
	v_max_i32_e32 v27, v29, v30
	v_max_i32_e32 v144, v143, v135
	v_min_i32_e32 v136, v72, v73
	v_min_i32_e32 v135, v143, v135
	v_max_i32_e32 v140, v33, v21
	v_min_i32_e32 v32, v18, v28
	v_max_i32_e32 v71, v72, v73
	v_max_i32_e32 v26, v24, v22
	v_min_i32_e32 v137, v137, v141
	v_max_i32_e32 v18, v18, v28
	v_max_i32_e32 v28, v70, v31
	v_min_i32_e32 v29, v25, v27
	v_min_i32_e32 v145, v144, v136
	v_max_i32_e32 v142, v135, v140
	v_min_i32_e32 v72, v32, v71
	v_max_i32_e32 v73, v144, v136
	v_max_i32_e32 v139, v26, v137
	v_min_i32_e32 v21, v33, v21
	v_min_i32_e32 v30, v28, v29
	v_min_i32_e32 v143, v145, v142
	v_min_i32_e32 v136, v72, v73
	v_min_i32_e32 v33, v139, v21
	v_max_i32_e32 v21, v139, v21
	v_min_i32_e32 v135, v135, v140
	v_max_i32_e32 v32, v32, v71
	v_min_i32_e32 v31, v18, v30
	v_max_i32_e32 v18, v18, v30
	v_min_i32_e32 v26, v26, v137
	v_min_i32_e32 v22, v24, v22
	v_max_i32_e32 v24, v25, v27
	v_min_i32_e32 v23, v23, v138
	v_max3_i32 v23, v127, v129, v23
	v_max_i32_e32 v22, v126, v22
	v_max3_i32 v25, v128, v130, v26
	v_max_i32_e32 v26, v66, v33
; #define LAS __attribute__((address_space(3)))
; #define MFMA32(a, b, c) __builtin_amdgcn_mfma_f32_32x32x16_bf16((a), (b), (c), 0, 0, 0)
; __device__ __forceinline__ void route_task(int task, int tl0, const bf16* QP  , const LAS bf16* KHL, LAS unsigned short* EL, LAS float* GL, int lane) {
;     ...
;         for (int kt = 0; kt < 4; ++kt) {
;             f32x16 X;
; #pragma unroll
;             for (int i = 0; i < 16; ++i) X[i] = 8.f;
;             const LAS bf16* khp = KHL + (half * 128 + 32 * kt + r) * 72 + 8 * hi;
; #pragma unroll
;             for (int ks = 0; ks < 4; ++ks) {
;                 const bf16x8 kh = lds8(khp + 16 * ks);
;                 X = MFMA32(kh, qa[half][ks], X);
;             }
;             int grp[16];
; #pragma unroll
;             for (int i = 0; i < 16; ++i) grp[i] = (int)((__float_as_uint(X[i]) | 127u) - (unsigned)(32 * kt + (i & 3) + 8 * (i >> 2)));
;             sort16_desc(grp);
;             if (kt == 0) {
; #pragma unroll
;                 for (int i = 0; i < 16; ++i) cur[i] = grp[i];
;             } else merge16_desc(cur, grp);
	v_max3_i32 v21, v131, v76, v21
	v_max_i32_e32 v27, v67, v135
	v_max3_i32 v30, v74, v75, v143
	v_max3_i32 v66, v77, v82, v136
	v_max3_i32 v67, v69, v72, v73
	v_max3_i32 v32, v78, v80, v32
	v_max_i32_e32 v31, v132, v31
	v_max3_i32 v18, v125, v124, v18
	v_max3_i32 v28, v133, v28, v29
	v_max3_i32 v24, v79, v81, v24
	v_max3_i32 v33, v68, v145, v142
	v_max3_i32 v19, v134, v19, v20
	v_max_i32_e32 v20, v23, v66
	v_min_i32_e32 v23, v23, v66
	v_max_i32_e32 v29, v22, v67
	v_max_i32_e32 v66, v25, v32
	v_min_i32_e32 v25, v25, v32
	v_max_i32_e32 v32, v26, v31
	v_min_i32_e32 v26, v26, v31
	v_max_i32_e32 v31, v21, v18
	v_min_i32_e32 v18, v21, v18
	v_max_i32_e32 v21, v27, v28
	v_min_i32_e32 v27, v27, v28
	v_max_i32_e32 v28, v30, v24
	v_min_i32_e32 v22, v22, v67
	v_min_i32_e32 v24, v30, v24
	v_max_i32_e32 v30, v33, v19
	v_min_i32_e32 v19, v33, v19
	v_max_i32_e32 v33, v20, v31
	v_min_i32_e32 v74, v20, v31
	v_max_i32_e32 v20, v29, v21
	v_min_i32_e32 v75, v29, v21
	v_max_i32_e32 v21, v66, v28
	v_min_i32_e32 v76, v66, v28
	ds_read_b128 v[66:69], v96
	ds_read_b128 v[70:73], v96 offset:32
	v_max_i32_e32 v28, v32, v30
	v_min_i32_e32 v77, v32, v30
	v_max_i32_e32 v78, v23, v18
	v_min_i32_e32 v79, v23, v18
	v_max_i32_e32 v80, v22, v27
	v_min_i32_e32 v81, v22, v27
	v_max_i32_e32 v82, v25, v24
	v_min_i32_e32 v124, v25, v24
	v_max_i32_e32 v125, v26, v19
	v_min_i32_e32 v126, v26, v19
	v_max_i32_e32 v127, v33, v21
	v_min_i32_e32 v128, v33, v21
	v_max_i32_e32 v129, v20, v28
	v_min_i32_e32 v130, v20, v28
	s_waitcnt lgkmcnt(1)
	v_mfma_f32_32x32x16_bf16 v[18:33], v[66:69], v[62:65], v[2:17]
	ds_read_b128 v[62:65], v96 offset:64
	v_max_i32_e32 v67, v75, v77
	v_min_i32_e32 v68, v75, v77
	v_max_i32_e32 v75, v80, v125
	v_max_i32_e32 v131, v74, v76
	v_min_i32_e32 v66, v74, v76
	v_max_i32_e32 v69, v78, v82
	s_waitcnt lgkmcnt(1)
	v_mfma_f32_32x32x16_bf16 v[18:33], v[70:73], v[54:57], v[18:33]
	ds_read_b128 v[54:57], v96 offset:96
	v_min_i32_e32 v70, v80, v125
	v_max_i32_e32 v71, v79, v124
	v_min_i32_e32 v72, v79, v124
	v_min_i32_e32 v74, v78, v82
	v_max_i32_e32 v73, v81, v126
	v_min_i32_e32 v76, v81, v126
	s_waitcnt lgkmcnt(1)
	v_mfma_f32_32x32x16_bf16 v[18:33], v[62:65], v[58:61], v[18:33]
	v_min_i32_e32 v77, v127, v129
	v_min_i32_e32 v58, v128, v130
	v_min_i32_e32 v59, v131, v67
	v_min_i32_e32 v60, v66, v68
	v_min_i32_e32 v61, v69, v75
	v_min_i32_e32 v62, v74, v70
	v_min_i32_e32 v63, v71, v73
	s_waitcnt lgkmcnt(0)
	v_mfma_f32_32x32x16_bf16 v[18:33], v[54:57], v[50:53], v[18:33]
	v_min_i32_e32 v64, v72, v76
	s_nop 10
	v_or_b32_e32 v25, 0x7f, v25
	v_or_b32_e32 v29, 0x7f, v29
	v_or_b32_e32 v19, 0x7f, v19
	v_or_b32_e32 v30, 0x7f, v30
	v_or_b32_e32 v23, 0x7f, v23
	v_or_b32_e32 v24, 0x7f, v24
	v_or_b32_e32 v18, 0x7f, v18
	v_or_b32_e32 v31, 0x7f, v31
	v_or_b32_e32 v22, 0x7f, v22
	v_or_b32_e32 v26, 0x7f, v26
	v_or_b32_e32 v21, 0x7f, v21
	v_or_b32_e32 v32, 0x7f, v32
	v_or_b32_e32 v27, 0x7f, v27
	v_or_b32_e32 v28, 0x7f, v28
	v_or_b32_e32 v20, 0x7f, v20
	v_or_b32_e32 v33, 0x7f, v33
	v_add_u32_e32 v25, 0xffffff95, v25
	v_add_u32_e32 v29, 0xffffff8d, v29
	v_add_u32_e32 v19, 0xffffff9f, v19
	v_add_u32_e32 v30, 0xffffff88, v30
	v_add_u32_e32 v23, 0xffffff97, v23
	v_add_u32_e32 v24, 0xffffff96, v24
	v_add_u32_e32 v18, 0xffffffa0, v18
	v_add_u32_e32 v31, 0xffffff87, v31
	v_add_u32_e32 v22, 0xffffff98, v22
	v_add_u32_e32 v26, 0xffffff90, v26
	v_add_u32_e32 v21, 0xffffff9d, v21
	v_add_u32_e32 v32, 0xffffff86, v32
	v_add_u32_e32 v27, 0xffffff8f, v27
	v_add_u32_e32 v28, 0xffffff8e, v28
	v_add_u32_e32 v20, 0xffffff9e, v20
	v_add_u32_e32 v33, 0xffffff85, v33
	v_min_i32_e32 v50, v25, v29
	v_min_i32_e32 v51, v19, v30
	v_min_i32_e32 v53, v23, v24
	v_min_i32_e32 v54, v18, v31
	v_min_i32_e32 v57, v22, v26
	v_min_i32_e32 v65, v21, v32
	v_min_i32_e32 v79, v27, v28
	v_min_i32_e32 v80, v20, v33
	v_max_i32_e32 v18, v18, v31
	v_max_i32_e32 v23, v23, v24
	v_max_i32_e32 v19, v19, v30
	v_max_i32_e32 v25, v25, v29
	v_max_i32_e32 v20, v20, v33
	v_max_i32_e32 v27, v27, v28
	v_max_i32_e32 v21, v21, v32
	v_max_i32_e32 v22, v22, v26
	v_max_i32_e32 v24, v18, v23
	v_max_i32_e32 v29, v19, v25
	v_max_i32_e32 v28, v20, v27
	v_max_i32_e32 v26, v21, v22
	v_min_i32_e32 v30, v24, v29
	v_min_i32_e32 v31, v28, v26
	v_min_i32_e32 v55, v53, v54
	v_min_i32_e32 v32, v30, v31
	v_max_i32_e32 v30, v30, v31
	v_min_i32_e32 v21, v21, v22
	v_min_i32_e32 v18, v18, v23
	v_max_i32_e32 v23, v79, v80
	v_max_i32_e32 v31, v50, v51
	v_max_i32_e32 v53, v53, v54
	v_max_i32_e32 v54, v57, v65
	v_min_i32_e32 v19, v19, v25
	v_min_i32_e32 v20, v20, v27
	v_min_i32_e32 v52, v50, v51
	v_min_i32_e32 v78, v57, v65
	v_min_i32_e32 v81, v79, v80
	v_max_i32_e32 v22, v21, v18
	v_max_i32_e32 v57, v53, v54
	v_max_i32_e32 v25, v19, v20
	v_min_i32_e32 v18, v21, v18
	v_min_i32_e32 v21, v23, v31
	v_min_i32_e32 v56, v52, v55
	v_min_i32_e32 v82, v78, v81
	v_max_i32_e32 v33, v52, v55
	v_max_i32_e32 v52, v78, v81
	v_max_i32_e32 v24, v24, v29
	v_max_i32_e32 v26, v28, v26
	v_max_i32_e32 v50, v23, v31
	v_max_i32_e32 v27, v57, v25
	v_max_i32_e32 v23, v18, v21
	v_min_i32_e32 v25, v57, v25
	v_min_i32_e32 v53, v53, v54
	v_min_i32_e32 v19, v19, v20
	v_max_i32_e32 v55, v33, v52
	v_min_i32_e32 v28, v24, v26
	v_max_i32_e32 v51, v22, v50
	v_max_i32_e32 v31, v23, v25
	v_max_i32_e32 v20, v53, v19
	v_min_i32_e32 v23, v23, v25
	v_min_i32_e32 v19, v53, v19
	v_min_i32_e32 v18, v18, v21
	v_max_i32_e32 v25, v56, v82
	v_min_i32_e32 v33, v33, v52
	v_min_i32_e32 v29, v30, v28
	v_min_i32_e32 v65, v51, v27
	v_min_i32_e32 v22, v22, v50
	v_max_i32_e32 v21, v19, v18
	v_max_i32_e32 v52, v25, v33
	v_max_i32_e32 v78, v32, v55
	v_min_i32_e32 v79, v29, v65
	v_max_i32_e32 v50, v20, v22
	v_min_i32_e32 v20, v20, v22
; __device__ __forceinline__ void route_task(int task, int tl0, const bf16* QP  , const LAS bf16* KHL, LAS unsigned short* EL, LAS float* GL, int lane) {
;     ...
;             } else merge16_desc(cur, grp);
;         }
;         { const unsigned h4 = 4u * (unsigned)hi;
; #pragma unroll
;           for (int i = 0; i < 16; ++i) cur[i] -= (int)h4; }
;         int oth[16];
; #pragma unroll
;         for (int i = 0; i < 16; ++i) oth[i] = __shfl_xor(cur[i], 32);
;         merge16_desc(cur, oth);
; #pragma unroll
;         for (int i = 0; i < 16; ++i) top[half][i] = cur[i];
	v_max_i32_e32 v53, v21, v52
	v_min_i32_e32 v32, v32, v55
	v_max_i32_e32 v80, v78, v79
	v_max_i32_e32 v54, v31, v50
	v_min_i32_e32 v78, v78, v79
	v_min_i32_e32 v31, v31, v50
	v_max_i32_e32 v22, v23, v20
	v_max_i32_e32 v55, v53, v32
	v_min_i32_e32 v18, v19, v18
	v_min_i32_e32 v19, v25, v33
	v_min_i32_e32 v20, v23, v20
	v_min_i32_e32 v23, v53, v32
	v_max_i32_e32 v28, v30, v28
	v_max_i32_e32 v27, v51, v27
	v_min_i32_e32 v124, v56, v82
	v_min_i32_e32 v57, v80, v54
	v_max_i32_e32 v50, v78, v31
	v_max_i32_e32 v56, v22, v55
	v_min_i32_e32 v31, v78, v31
	v_max_i32_e32 v25, v18, v19
	v_min_i32_e32 v21, v21, v52
	v_min_i32_e32 v32, v20, v23
	v_max_i32_e32 v29, v29, v65
	v_min_i32_e32 v30, v28, v27
	v_min_i32_e32 v22, v22, v55
	v_max_i32_e32 v20, v20, v23
	v_min_i32_e32 v79, v57, v50
	v_max_i32_e32 v78, v56, v31
	v_max_i32_e32 v33, v25, v21
	v_max_i32_e32 v53, v80, v54
	v_min_i32_e32 v51, v29, v30
	v_min_i32_e32 v31, v56, v31
	v_max_i32_e32 v23, v22, v20
	v_min_i32_e32 v81, v79, v78
	v_max_i32_e32 v52, v33, v32
	v_max_i32_e32 v54, v53, v51
	v_min_i32_e32 v21, v25, v21
	v_max_i32_e32 v25, v57, v50
	v_min_i32_e32 v55, v31, v23
	v_max_i32_e32 v27, v28, v27
	v_min_i32_e32 v18, v18, v19
	v_min_i32_e32 v20, v22, v20
	v_min_i32_e32 v32, v33, v32
	v_min_i32_e32 v33, v53, v51
	v_max3_i32 v124, v127, v129, v124
	v_max3_i32 v69, v69, v75, v81
	v_max3_i32 v52, v131, v67, v52
	v_max3_i32 v54, v71, v73, v54
	v_max3_i32 v21, v128, v130, v21
	v_max3_i32 v25, v74, v70, v25
	v_max3_i32 v55, v66, v68, v55
	v_max3_i32 v27, v72, v76, v27
	v_max_i32_e32 v18, v77, v18
	v_max3_i32 v19, v61, v79, v78
	v_max_i32_e32 v20, v59, v20
	v_max3_i32 v22, v63, v29, v30
	v_max_i32_e32 v32, v58, v32
	v_max_i32_e32 v33, v62, v33
	v_max3_i32 v23, v60, v31, v23
	v_max3_i32 v24, v64, v24, v26
	v_min_i32_e32 v65, v52, v54
	v_min_i32_e32 v50, v21, v25
	v_min_i32_e32 v61, v18, v19
	v_min_i32_e32 v29, v20, v22
	v_min_i32_e32 v26, v23, v24
	v_max_i32_e32 v59, v124, v69
	v_max_i32_e32 v52, v52, v54
	v_max_i32_e32 v21, v21, v25
	v_max_i32_e32 v25, v55, v27
	v_max_i32_e32 v18, v18, v19
	v_max_i32_e32 v19, v20, v22
	v_max_i32_e32 v22, v32, v33
	v_max_i32_e32 v23, v23, v24
	v_min_i32_e32 v28, v55, v27
	v_max_i32_e32 v54, v59, v52
	v_max_i32_e32 v27, v21, v25
	v_max_i32_e32 v20, v18, v19
	v_max_i32_e32 v24, v22, v23
	v_min_i32_e32 v51, v32, v33
	v_max_i32_e32 v55, v54, v27
	v_max_i32_e32 v32, v20, v24
	v_min_i32_e32 v27, v54, v27
	v_min_i32_e32 v20, v20, v24
	v_max_i32_e32 v24, v27, v20
	v_min_i32_e32 v20, v27, v20
	v_min_i32_e32 v27, v59, v52
	v_min_i32_e32 v21, v21, v25
	v_min_i32_e32 v18, v18, v19
	v_min_i32_e32 v19, v22, v23
	v_min_i32_e32 v75, v124, v69
	v_max_i32_e32 v25, v27, v21
	v_max_i32_e32 v22, v18, v19
	v_min_i32_e32 v21, v27, v21
	v_min_i32_e32 v18, v18, v19
	v_min_i32_e32 v56, v50, v28
	v_min_i32_e32 v31, v51, v26
	v_max_i32_e32 v23, v25, v22
	v_min_i32_e32 v22, v25, v22
	v_max_i32_e32 v19, v21, v18
	v_min_i32_e32 v18, v21, v18
	v_max_i32_e32 v21, v75, v65
	v_max_i32_e32 v25, v50, v28
	v_max_i32_e32 v28, v61, v29
	v_max_i32_e32 v26, v51, v26
	v_min_i32_e32 v67, v75, v65
	v_min_i32_e32 v30, v61, v29
	v_max_i32_e32 v27, v21, v25
	v_min_i32_e32 v21, v21, v25
	v_min_i32_e32 v25, v28, v26
	v_min_i32_e32 v57, v67, v56
	v_min_i32_e32 v53, v30, v31
	v_max_i32_e32 v29, v28, v26
	v_max_i32_e32 v26, v21, v25
	v_min_i32_e32 v21, v21, v25
	v_max_i32_e32 v25, v67, v56
	v_max_i32_e32 v28, v30, v31
	v_min_i32_e32 v58, v57, v53
	v_max_i32_e32 v33, v55, v32
	v_min_i32_e32 v32, v55, v32
	v_max_i32_e32 v50, v27, v29
	v_min_i32_e32 v27, v27, v29
	v_max_i32_e32 v29, v25, v28
	v_min_i32_e32 v25, v25, v28
	v_max_i32_e32 v28, v57, v53
	v_sub_u32_e32 v30, v33, v87
	v_sub_u32_e32 v31, v32, v87
	v_sub_u32_e32 v24, v24, v87
	v_sub_u32_e32 v20, v20, v87
	v_sub_u32_e32 v23, v23, v87
	v_sub_u32_e32 v22, v22, v87
	v_sub_u32_e32 v19, v19, v87
	v_sub_u32_e32 v18, v18, v87
	v_sub_u32_e32 v32, v50, v87
	v_sub_u32_e32 v27, v27, v87
	v_sub_u32_e32 v26, v26, v87
	v_sub_u32_e32 v21, v21, v87
	v_sub_u32_e32 v29, v29, v87
	v_sub_u32_e32 v25, v25, v87
	v_sub_u32_e32 v28, v28, v87
	v_sub_u32_e32 v33, v58, v87
	ds_bpermute_b32 v50, v123, v30
	ds_bpermute_b32 v51, v123, v31
	ds_bpermute_b32 v52, v123, v24
	ds_bpermute_b32 v53, v123, v20
	ds_bpermute_b32 v54, v123, v23
	ds_bpermute_b32 v55, v123, v22
	ds_bpermute_b32 v56, v123, v19
	ds_bpermute_b32 v57, v123, v18
	ds_bpermute_b32 v58, v123, v32
	ds_bpermute_b32 v59, v123, v27
	ds_bpermute_b32 v60, v123, v26
	ds_bpermute_b32 v61, v123, v33
	ds_bpermute_b32 v62, v123, v28
	ds_bpermute_b32 v63, v123, v25
	ds_bpermute_b32 v64, v123, v29
	ds_bpermute_b32 v65, v123, v21
	s_waitcnt lgkmcnt(4)
	v_max_i32_e32 v30, v30, v61
	s_waitcnt lgkmcnt(3)
	v_max_i32_e32 v31, v31, v62
	s_waitcnt lgkmcnt(2)
	v_max_i32_e32 v24, v24, v63
	s_waitcnt lgkmcnt(1)
	v_max_i32_e32 v20, v20, v64
	s_waitcnt lgkmcnt(0)
; #define LAS __attribute__((address_space(3)))
; #define MFMA32(a, b, c) __builtin_amdgcn_mfma_f32_32x32x16_bf16((a), (b), (c), 0, 0, 0)
; __device__ __forceinline__ void route_task(int task, int tl0, const bf16* QP  , const LAS bf16* KHL, LAS unsigned short* EL, LAS float* GL, int lane) {
;     ...
;         for (int kt = 0; kt < 4; ++kt) {
;             f32x16 X;
; #pragma unroll
;             for (int i = 0; i < 16; ++i) X[i] = 8.f;
;             const LAS bf16* khp = KHL + (half * 128 + 32 * kt + r) * 72 + 8 * hi;
; #pragma unroll
;             for (int ks = 0; ks < 4; ++ks) {
;                 const bf16x8 kh = lds8(khp + 16 * ks);
;                 X = MFMA32(kh, qa[half][ks], X);
;             }
;             int grp[16];
; #pragma unroll
;             for (int i = 0; i < 16; ++i) grp[i] = (int)((__float_as_uint(X[i]) | 127u) - (unsigned)(32 * kt + (i & 3) + 8 * (i >> 2)));
;             sort16_desc(grp);
;             if (kt == 0) {
; #pragma unroll
;                 for (int i = 0; i < 16; ++i) cur[i] = grp[i];
;             } else merge16_desc(cur, grp);
;     ...
;         int oth[16];
; #pragma unroll
;         for (int i = 0; i < 16; ++i) oth[i] = __shfl_xor(cur[i], 32);
;         merge16_desc(cur, oth);
; #pragma unroll
;         for (int i = 0; i < 16; ++i) top[half][i] = cur[i];
	v_max_i32_e32 v23, v23, v65
	v_max_i32_e32 v22, v22, v60
	v_max_i32_e32 v19, v19, v59
	v_max_i32_e32 v18, v18, v58
	v_max_i32_e32 v32, v32, v57
	v_max_i32_e32 v27, v27, v56
	v_max_i32_e32 v26, v26, v55
	v_max_i32_e32 v21, v21, v54
	v_max_i32_e32 v29, v29, v53
	v_max_i32_e32 v25, v25, v52
	v_max_i32_e32 v28, v28, v51
	v_max_i32_e32 v33, v33, v50
	v_max_i32_e32 v50, v30, v32
	v_min_i32_e32 v30, v30, v32
	v_max_i32_e32 v32, v31, v27
	v_min_i32_e32 v27, v31, v27
	v_max_i32_e32 v31, v24, v26
	v_min_i32_e32 v24, v24, v26
	v_max_i32_e32 v26, v20, v21
	v_min_i32_e32 v20, v20, v21
	v_max_i32_e32 v21, v23, v29
	v_min_i32_e32 v23, v23, v29
	v_max_i32_e32 v29, v22, v25
	v_min_i32_e32 v22, v22, v25
	v_max_i32_e32 v25, v19, v28
	v_min_i32_e32 v19, v19, v28
	v_max_i32_e32 v28, v18, v33
	v_min_i32_e32 v18, v18, v33
	v_max_i32_e32 v33, v50, v21
	v_min_i32_e32 v21, v50, v21
	v_max_i32_e32 v50, v32, v29
	v_min_i32_e32 v29, v32, v29
	v_max_i32_e32 v32, v31, v25
	v_min_i32_e32 v25, v31, v25
	v_max_i32_e32 v31, v26, v28
	v_max_i32_e32 v64, v50, v31
	v_min_i32_e32 v67, v50, v31
	ds_read_b128 v[50:53], v94 offset:18432
	ds_read_b128 v[54:57], v94 offset:18464
	v_min_i32_e32 v26, v26, v28
	v_max_i32_e32 v28, v30, v23
	v_min_i32_e32 v58, v30, v23
	v_max_i32_e32 v23, v27, v22
	v_min_i32_e32 v59, v27, v22
	v_max_i32_e32 v22, v24, v19
	v_min_i32_e32 v60, v24, v19
	v_max_i32_e32 v19, v20, v18
	v_min_i32_e32 v61, v20, v18
	v_max_i32_e32 v62, v33, v32
	v_min_i32_e32 v66, v33, v32
	v_max_i32_e32 v68, v21, v25
	v_min_i32_e32 v69, v21, v25
	v_max_i32_e32 v70, v29, v26
	v_min_i32_e32 v71, v29, v26
	v_max_i32_e32 v72, v28, v22
	v_min_i32_e32 v73, v28, v22
	v_max_i32_e32 v74, v23, v19
	v_min_i32_e32 v75, v23, v19
	s_waitcnt vmcnt(3) lgkmcnt(1)
	v_mfma_f32_32x32x16_bf16 v[18:33], v[50:53], v[46:49], v[2:17]
	ds_read_b128 v[50:53], v94 offset:18496
	v_max_i32_e32 v76, v58, v60
	v_min_i32_e32 v77, v58, v60
	v_max_i32_e32 v78, v59, v61
	v_min_i32_e32 v79, v59, v61
	v_max_i32_e32 v63, v62, v64
	v_min_i32_e32 v65, v62, v64
	s_waitcnt vmcnt(2) lgkmcnt(1)
	v_mfma_f32_32x32x16_bf16 v[18:33], v[54:57], v[42:45], v[18:33]
	v_max_i32_e32 v64, v66, v67
	v_min_i32_e32 v62, v66, v67
	v_max_i32_e32 v61, v68, v70
	v_min_i32_e32 v60, v68, v70
	v_max_i32_e32 v59, v69, v71
	v_min_i32_e32 v57, v69, v71
	ds_read_b128 v[66:69], v94 offset:18528
	s_waitcnt vmcnt(1) lgkmcnt(1)
	v_mfma_f32_32x32x16_bf16 v[18:33], v[50:53], v[38:41], v[18:33]
	v_max_i32_e32 v55, v72, v74
	v_min_i32_e32 v58, v72, v74
	v_max_i32_e32 v56, v73, v75
	v_min_i32_e32 v54, v73, v75
	v_max_i32_e32 v53, v76, v78
	v_min_i32_e32 v52, v76, v78
	v_max_i32_e32 v51, v77, v79
	s_waitcnt vmcnt(0) lgkmcnt(0)
	v_mfma_f32_32x32x16_bf16 v[18:33], v[66:69], v[34:37], v[18:33]
	v_min_i32_e32 v50, v77, v79
	s_nop 10
	v_or_b32_e32 v21, 0x7f, v21
	v_or_b32_e32 v32, 0x7f, v32
	v_or_b32_e32 v22, 0x7f, v22
	v_or_b32_e32 v26, 0x7f, v26
	v_or_b32_e32 v31, 0x7f, v31
	v_or_b32_e32 v23, 0x7f, v23
	v_or_b32_e32 v24, 0x7f, v24
	v_or_b32_e32 v27, 0x7f, v27
	v_or_b32_e32 v28, 0x7f, v28
	v_or_b32_e32 v20, 0x7f, v20
	v_or_b32_e32 v33, 0x7f, v33
	v_or_b32_e32 v25, 0x7f, v25
	v_or_b32_e32 v29, 0x7f, v29
	v_or_b32_e32 v19, 0x7f, v19
	v_or_b32_e32 v30, 0x7f, v30
	v_add_u32_e32 v21, -3, v21
	v_subrev_u32_e32 v32, 26, v32
	v_add_u32_e32 v22, -8, v22
	v_add_u32_e32 v26, -16, v26
	v_or_b32_e32 v18, 0x7f, v18
	v_subrev_u32_e32 v31, 25, v31
	v_add_u32_e32 v23, -9, v23
	v_add_u32_e32 v24, -10, v24
	v_subrev_u32_e32 v27, 17, v27
	v_subrev_u32_e32 v28, 18, v28
	v_add_u32_e32 v20, -2, v20
	v_subrev_u32_e32 v33, 27, v33
	v_add_u32_e32 v25, -11, v25
	v_subrev_u32_e32 v29, 19, v29
	v_add_u32_e32 v19, -1, v19
	v_subrev_u32_e32 v30, 24, v30
	v_max_i32_e32 v66, v21, v32
	v_max_i32_e32 v67, v22, v26
	v_max_i32_e32 v69, v18, v31
	v_max_i32_e32 v70, v23, v24
	v_min_i32_e32 v73, v27, v28
	v_min_i32_e32 v74, v20, v33
	v_min_i32_e32 v76, v25, v29
	v_min_i32_e32 v77, v19, v30
	v_min_i32_e32 v23, v23, v24
	v_min_i32_e32 v18, v18, v31
	v_min_i32_e32 v22, v22, v26
	v_min_i32_e32 v21, v21, v32
	v_max_i32_e32 v19, v19, v30
	v_max_i32_e32 v25, v25, v29
	v_max_i32_e32 v20, v20, v33
	v_max_i32_e32 v27, v27, v28
	v_max_i32_e32 v24, v23, v18
	v_max_i32_e32 v26, v22, v21
	v_min_i32_e32 v29, v19, v25
	v_min_i32_e32 v28, v20, v27
	v_max_i32_e32 v31, v24, v26
	v_min_i32_e32 v24, v24, v26
	v_min_i32_e32 v26, v29, v28
	v_min_i32_e32 v68, v66, v67
	v_min_i32_e32 v71, v69, v70
	v_max_i32_e32 v75, v73, v74
	v_max_i32_e32 v78, v76, v77
	v_max_i32_e32 v30, v29, v28
	v_max_i32_e32 v28, v24, v26
	v_min_i32_e32 v81, v24, v26
	v_min_i32_e32 v24, v76, v77
	v_min_i32_e32 v18, v23, v18
	v_min_i32_e32 v21, v22, v21
	v_min_i32_e32 v22, v73, v74
	v_min_i32_e32 v72, v68, v71
	v_min_i32_e32 v79, v75, v78
	v_min_i32_e32 v76, v24, v18
	v_min_i32_e32 v74, v21, v22
	v_max_i32_e32 v18, v24, v18
	v_max_i32_e32 v21, v21, v22
	v_max_i32_e32 v23, v69, v70
	v_max_i32_e32 v19, v19, v25
	v_max_i32_e32 v20, v20, v27
	v_max_i32_e32 v25, v66, v67
	v_max_i32_e32 v80, v72, v79
	v_max_i32_e32 v29, v68, v71
	v_max_i32_e32 v68, v75, v78
	v_min_i32_e32 v79, v72, v79
	v_max_i32_e32 v77, v76, v74
	v_min_i32_e32 v124, v18, v21
	v_min_i32_e32 v24, v23, v19
	v_min_i32_e32 v26, v20, v25
	v_min_i32_e32 v32, v31, v30
	v_min_i32_e32 v71, v29, v68
	v_max_i32_e32 v82, v81, v79
	v_max_i32_e32 v125, v77, v124
	v_min_i32_e32 v27, v24, v26
	v_max_i32_e32 v18, v18, v21
	v_min_i32_e32 v33, v80, v32
	v_min_i32_e32 v75, v28, v71
	v_max_i32_e32 v22, v82, v125
	v_min_i32_e32 v21, v27, v18
	v_max_i32_e32 v78, v33, v75
	v_max_i32_e32 v66, v22, v21
	v_max_i32_e32 v70, v78, v66
	v_max_i32_e32 v131, v29, v68
	v_min_i32_e32 v78, v78, v66
	ds_read_b128 v[66:69], v97
	v_max_i32_e32 v127, v23, v19
	v_max_i32_e32 v128, v20, v25
	v_max_i32_e32 v126, v24, v26
	v_min_i32_e32 v129, v127, v128
	v_max_i32_e32 v132, v31, v30
	v_min_i32_e32 v130, v126, v129
	v_min_i32_e32 v133, v131, v132
	v_max_i32_e32 v18, v27, v18
	v_min_i32_e32 v19, v130, v133
	v_max_i32_e32 v23, v80, v32
	v_max_i32_e32 v24, v28, v71
	v_min_i32_e32 v20, v18, v19
	v_min_i32_e32 v25, v23, v24
	v_min_i32_e32 v26, v20, v25
	v_min_i32_e32 v80, v70, v26
	v_max_i32_e32 v143, v70, v26
	ds_read_b128 v[70:73], v97 offset:32
	v_min_i32_e32 v75, v33, v75
	v_min_i32_e32 v134, v22, v21
	v_max_i32_e32 v138, v18, v19
	v_max_i32_e32 v139, v23, v24
	v_max_i32_e32 v141, v20, v25
	s_waitcnt lgkmcnt(1)
; #define LAS __attribute__((address_space(3)))
; #define MFMA32(a, b, c) __builtin_amdgcn_mfma_f32_32x32x16_bf16((a), (b), (c), 0, 0, 0)
; __device__ __forceinline__ void route_task(int task, int tl0, const bf16* QP  , const LAS bf16* KHL, LAS unsigned short* EL, LAS float* GL, int lane) {
;     ...
;         for (int kt = 0; kt < 4; ++kt) {
;             f32x16 X;
; #pragma unroll
;             for (int i = 0; i < 16; ++i) X[i] = 8.f;
;             const LAS bf16* khp = KHL + (half * 128 + 32 * kt + r) * 72 + 8 * hi;
; #pragma unroll
;             for (int ks = 0; ks < 4; ++ks) {
;                 const bf16x8 kh = lds8(khp + 16 * ks);
;                 X = MFMA32(kh, qa[half][ks], X);
;             }
;             int grp[16];
; #pragma unroll
;             for (int i = 0; i < 16; ++i) grp[i] = (int)((__float_as_uint(X[i]) | 127u) - (unsigned)(32 * kt + (i & 3) + 8 * (i >> 2)));
;             sort16_desc(grp);
;             if (kt == 0) {
; #pragma unroll
;                 for (int i = 0; i < 16; ++i) cur[i] = grp[i];
;             } else merge16_desc(cur, grp);
	v_mfma_f32_32x32x16_bf16 v[18:33], v[66:69], v[46:49], v[2:17]
	ds_read_b128 v[66:69], v97 offset:64
	v_max_i32_e32 v135, v75, v134
	v_max_i32_e32 v136, v78, v135
	v_min_i32_e32 v79, v81, v79
	v_min_i32_e32 v77, v77, v124
	v_min_i32_e32 v78, v78, v135
	v_max_i32_e32 v130, v130, v133
	s_waitcnt lgkmcnt(1)
	v_mfma_f32_32x32x16_bf16 v[18:33], v[70:73], v[42:45], v[18:33]
	ds_read_b128 v[70:73], v97 offset:96
	v_max_i32_e32 v126, v126, v129
	v_min_i32_e32 v74, v76, v74
	v_min_i32_e32 v140, v138, v139
	v_max_i32_e32 v81, v79, v77
	v_min_i32_e32 v82, v82, v125
	v_min_i32_e32 v75, v75, v134
	s_waitcnt lgkmcnt(1)
	v_mfma_f32_32x32x16_bf16 v[18:33], v[66:69], v[38:41], v[18:33]
	v_max_i32_e32 v66, v131, v132
	v_max_i32_e32 v134, v138, v139
	v_min_i32_e32 v77, v79, v77
	v_max_i32_e32 v124, v81, v82
	v_min_i32_e32 v81, v81, v82
	v_min_i32_e32 v67, v126, v66
	v_min_i32_e32 v142, v140, v141
	s_waitcnt lgkmcnt(0)
	v_mfma_f32_32x32x16_bf16 v[18:33], v[70:73], v[34:37], v[18:33]
	v_min_i32_e32 v68, v130, v67
	v_min_i32_e32 v137, v80, v136
	v_min_i32_e32 v144, v142, v143
	v_min_i32_e32 v125, v124, v75
	v_min_i32_e32 v69, v134, v68
	s_nop 6
	v_or_b32_e32 v21, 0x7f, v21
	v_or_b32_e32 v32, 0x7f, v32
	v_or_b32_e32 v22, 0x7f, v22
	v_or_b32_e32 v26, 0x7f, v26
	v_or_b32_e32 v18, 0x7f, v18
	v_or_b32_e32 v31, 0x7f, v31
	v_or_b32_e32 v23, 0x7f, v23
	v_or_b32_e32 v24, 0x7f, v24
	v_or_b32_e32 v27, 0x7f, v27
	v_or_b32_e32 v28, 0x7f, v28
	v_or_b32_e32 v20, 0x7f, v20
	v_or_b32_e32 v33, 0x7f, v33
	v_or_b32_e32 v25, 0x7f, v25
	v_or_b32_e32 v29, 0x7f, v29
	v_or_b32_e32 v19, 0x7f, v19
	v_or_b32_e32 v30, 0x7f, v30
	v_subrev_u32_e32 v21, 35, v21
	v_subrev_u32_e32 v32, 58, v32
	v_subrev_u32_e32 v22, 40, v22
	v_subrev_u32_e32 v26, 48, v26
	v_subrev_u32_e32 v18, 32, v18
	v_subrev_u32_e32 v31, 57, v31
	v_subrev_u32_e32 v23, 41, v23
	v_subrev_u32_e32 v24, 42, v24
	v_subrev_u32_e32 v27, 49, v27
	v_subrev_u32_e32 v28, 50, v28
	v_subrev_u32_e32 v20, 34, v20
	v_subrev_u32_e32 v33, 59, v33
	v_subrev_u32_e32 v25, 43, v25
	v_subrev_u32_e32 v29, 51, v29
	v_subrev_u32_e32 v19, 33, v19
	v_subrev_u32_e32 v30, 56, v30
	v_max_i32_e32 v70, v21, v32
	v_max_i32_e32 v71, v22, v26
	v_max_i32_e32 v73, v18, v31
	v_max_i32_e32 v76, v23, v24
	v_min_i32_e32 v129, v27, v28
	v_min_i32_e32 v131, v20, v33
	v_min_i32_e32 v133, v25, v29
	v_min_i32_e32 v135, v19, v30
	v_min_i32_e32 v23, v23, v24
	v_min_i32_e32 v18, v18, v31
	v_min_i32_e32 v22, v22, v26
	v_min_i32_e32 v21, v21, v32
	v_max_i32_e32 v19, v19, v30
	v_max_i32_e32 v25, v25, v29
	v_max_i32_e32 v20, v20, v33
	v_max_i32_e32 v27, v27, v28
	v_min_i32_e32 v72, v70, v71
	v_min_i32_e32 v79, v73, v76
	v_max_i32_e32 v132, v129, v131
	v_max_i32_e32 v138, v133, v135
	v_max_i32_e32 v24, v23, v18
	v_max_i32_e32 v26, v22, v21
	v_min_i32_e32 v29, v19, v25
	v_min_i32_e32 v28, v20, v27
	v_min_i32_e32 v133, v133, v135
	v_min_i32_e32 v18, v23, v18
	v_min_i32_e32 v21, v22, v21
	v_min_i32_e32 v22, v129, v131
	v_max_i32_e32 v73, v73, v76
	v_max_i32_e32 v19, v19, v25
	v_max_i32_e32 v20, v20, v27
	v_max_i32_e32 v27, v70, v71
	v_min_i32_e32 v82, v72, v79
	v_min_i32_e32 v139, v132, v138
	v_max_i32_e32 v31, v24, v26
	v_max_i32_e32 v30, v29, v28
	v_min_i32_e32 v24, v24, v26
	v_min_i32_e32 v26, v29, v28
	v_max_i32_e32 v29, v72, v79
	v_max_i32_e32 v72, v132, v138
	v_min_i32_e32 v23, v133, v18
	v_min_i32_e32 v129, v21, v22
	v_max_i32_e32 v18, v133, v18
	v_max_i32_e32 v21, v21, v22
	v_min_i32_e32 v25, v73, v19
	v_min_i32_e32 v70, v20, v27
	v_max_i32_e32 v19, v73, v19
	v_max_i32_e32 v20, v20, v27
	v_min_i32_e32 v32, v31, v30
	v_max_i32_e32 v28, v24, v26
	v_min_i32_e32 v79, v29, v72
	v_min_i32_e32 v24, v24, v26
	v_min_i32_e32 v26, v82, v139
	v_max_i32_e32 v131, v23, v129
	v_min_i32_e32 v22, v18, v21
	v_min_i32_e32 v71, v25, v70
	v_max_i32_e32 v25, v25, v70
	v_min_i32_e32 v27, v19, v20
	v_max_i32_e32 v29, v29, v72
	v_max_i32_e32 v30, v31, v30
	v_max_i32_e32 v145, v82, v139
	v_max_i32_e32 v82, v24, v26
	v_max_i32_e32 v133, v131, v22
	v_max_i32_e32 v18, v18, v21
	v_min_i32_e32 v70, v25, v27
	v_min_i32_e32 v31, v29, v30
	v_min_i32_e32 v33, v145, v32
	v_min_i32_e32 v132, v28, v79
	v_max_i32_e32 v135, v82, v133
	v_min_i32_e32 v21, v71, v18
	v_max_i32_e32 v18, v71, v18
	v_min_i32_e32 v71, v70, v31
	v_max_i32_e32 v32, v145, v32
	v_max_i32_e32 v28, v28, v79
	v_max_i32_e32 v138, v33, v132
	v_max_i32_e32 v76, v135, v21
	v_min_i32_e32 v72, v18, v71
	v_min_i32_e32 v73, v32, v28
	v_min_i32_e32 v33, v33, v132
	v_min_i32_e32 v21, v135, v21
	v_max_i32_e32 v18, v18, v71
	v_max_i32_e32 v28, v32, v28
	v_min_i32_e32 v24, v24, v26
	v_min_i32_e32 v22, v131, v22
	v_max_i32_e32 v25, v25, v27
	v_max_i32_e32 v27, v29, v30
	v_max_i32_e32 v139, v138, v76
	v_min_i32_e32 v79, v72, v73
	v_min_i32_e32 v76, v138, v76
	v_max_i32_e32 v132, v33, v21
	v_min_i32_e32 v32, v18, v28
	v_max_i32_e32 v71, v72, v73
	v_max_i32_e32 v26, v24, v22
	v_min_i32_e32 v82, v82, v133
	v_max_i32_e32 v18, v18, v28
	v_max_i32_e32 v28, v70, v31
	v_min_i32_e32 v29, v25, v27
	v_min_i32_e32 v145, v139, v79
	v_max_i32_e32 v135, v76, v132
	v_min_i32_e32 v72, v32, v71
	v_max_i32_e32 v73, v139, v79
	v_max_i32_e32 v131, v26, v82
	v_min_i32_e32 v21, v33, v21
	v_min_i32_e32 v30, v28, v29
	v_min_i32_e32 v138, v145, v135
	v_min_i32_e32 v79, v72, v73
	v_min_i32_e32 v33, v131, v21
	v_min_i32_e32 v76, v76, v132
	v_min_i32_e32 v31, v18, v30
	v_min_i32_e32 v26, v26, v82
	v_min_i32_e32 v22, v24, v22
	v_min_i32_e32 v23, v23, v129
	v_max3_i32 v23, v127, v128, v23
	v_max3_i32 v22, v126, v66, v22
	v_max3_i32 v24, v130, v67, v26
	v_max3_i32 v26, v134, v68, v33
	v_max3_i32 v21, v69, v131, v21
	v_max3_i32 v33, v140, v141, v76
	v_max3_i32 v66, v142, v143, v138
; #define LAS __attribute__((address_space(3)))
; #define MFMA32(a, b, c) __builtin_amdgcn_mfma_f32_32x32x16_bf16((a), (b), (c), 0, 0, 0)
; __device__ __forceinline__ void route_task(int task, int tl0, const bf16* QP  , const LAS bf16* KHL, LAS unsigned short* EL, LAS float* GL, int lane) {
;     ...
;         for (int kt = 0; kt < 4; ++kt) {
;             f32x16 X;
; #pragma unroll
;             for (int i = 0; i < 16; ++i) X[i] = 8.f;
;             const LAS bf16* khp = KHL + (half * 128 + 32 * kt + r) * 72 + 8 * hi;
; #pragma unroll
;             for (int ks = 0; ks < 4; ++ks) {
;                 const bf16x8 kh = lds8(khp + 16 * ks);
;                 X = MFMA32(kh, qa[half][ks], X);
;             }
;             int grp[16];
; #pragma unroll
;             for (int i = 0; i < 16; ++i) grp[i] = (int)((__float_as_uint(X[i]) | 127u) - (unsigned)(32 * kt + (i & 3) + 8 * (i >> 2)));
;             sort16_desc(grp);
;             if (kt == 0) {
; #pragma unroll
;                 for (int i = 0; i < 16; ++i) cur[i] = grp[i];
;             } else merge16_desc(cur, grp);
	v_max3_i32 v67, v144, v145, v135
	v_max3_i32 v68, v80, v136, v79
	v_max3_i32 v69, v137, v72, v73
	v_max3_i32 v32, v78, v32, v71
	v_max3_i32 v31, v124, v75, v31
	v_max3_i32 v18, v125, v18, v30
	v_max3_i32 v28, v81, v28, v29
	v_max3_i32 v25, v77, v25, v27
	v_max3_i32 v19, v74, v19, v20
	v_max_i32_e32 v20, v23, v68
	v_min_i32_e32 v23, v23, v68
	v_max_i32_e32 v27, v22, v69
	v_min_i32_e32 v22, v22, v69
	v_max_i32_e32 v29, v24, v32
	v_min_i32_e32 v24, v24, v32
	v_max_i32_e32 v30, v26, v31
	v_min_i32_e32 v26, v26, v31
	v_max_i32_e32 v31, v21, v18
	v_min_i32_e32 v18, v21, v18
	v_max_i32_e32 v21, v33, v28
	v_min_i32_e32 v28, v33, v28
	v_max_i32_e32 v32, v66, v25
	v_min_i32_e32 v25, v66, v25
	v_max_i32_e32 v33, v67, v19
	v_min_i32_e32 v19, v67, v19
	ds_read_b128 v[66:69], v94 offset:27648
	v_max_i32_e32 v70, v20, v31
	v_min_i32_e32 v74, v20, v31
	v_max_i32_e32 v20, v27, v21
	v_min_i32_e32 v75, v27, v21
	v_max_i32_e32 v21, v29, v32
	v_max_i32_e32 v27, v30, v33
	v_max_i32_e32 v127, v70, v21
	v_min_i32_e32 v128, v70, v21
	ds_read_b128 v[70:73], v94 offset:27680
	v_min_i32_e32 v76, v29, v32
	v_min_i32_e32 v77, v30, v33
	v_max_i32_e32 v78, v23, v18
	v_min_i32_e32 v79, v23, v18
	v_max_i32_e32 v80, v22, v28
	v_min_i32_e32 v81, v22, v28
	v_max_i32_e32 v82, v24, v25
	v_min_i32_e32 v124, v24, v25
	v_max_i32_e32 v125, v26, v19
	v_min_i32_e32 v126, v26, v19
	v_max_i32_e32 v129, v20, v27
	v_min_i32_e32 v130, v20, v27
	s_waitcnt lgkmcnt(1)
	v_mfma_f32_32x32x16_bf16 v[18:33], v[66:69], v[46:49], v[2:17]
	ds_read_b128 v[66:69], v94 offset:27712
	v_max_i32_e32 v131, v74, v76
	v_min_i32_e32 v74, v74, v76
	v_max_i32_e32 v76, v75, v77
	v_min_i32_e32 v75, v75, v77
	v_max_i32_e32 v77, v78, v82
	v_min_i32_e32 v78, v78, v82
	s_waitcnt lgkmcnt(1)
	v_mfma_f32_32x32x16_bf16 v[18:33], v[70:73], v[42:45], v[18:33]
	ds_read_b128 v[70:73], v94 offset:27744
	v_max_i32_e32 v82, v80, v125
	v_min_i32_e32 v80, v80, v125
	v_max_i32_e32 v125, v79, v124
	v_min_i32_e32 v79, v79, v124
	v_max_i32_e32 v124, v81, v126
	v_min_i32_e32 v81, v81, v126
	s_waitcnt lgkmcnt(1)
	v_mfma_f32_32x32x16_bf16 v[18:33], v[66:69], v[38:41], v[18:33]
	v_min_i32_e32 v126, v127, v129
	v_min_i32_e32 v66, v128, v130
	v_min_i32_e32 v67, v131, v76
	v_min_i32_e32 v69, v77, v82
	v_min_i32_e32 v132, v78, v80
	v_min_i32_e32 v133, v125, v124
	v_min_i32_e32 v68, v74, v75
	s_waitcnt lgkmcnt(0)
	v_mfma_f32_32x32x16_bf16 v[18:33], v[70:73], v[34:37], v[18:33]
	v_min_i32_e32 v134, v79, v81
	s_nop 10
	v_or_b32_e32 v21, 0x7f, v21
	v_or_b32_e32 v32, 0x7f, v32
	v_or_b32_e32 v22, 0x7f, v22
	v_or_b32_e32 v26, 0x7f, v26
	v_or_b32_e32 v18, 0x7f, v18
	v_or_b32_e32 v31, 0x7f, v31
	v_or_b32_e32 v23, 0x7f, v23
	v_or_b32_e32 v24, 0x7f, v24
	v_or_b32_e32 v27, 0x7f, v27
	v_or_b32_e32 v28, 0x7f, v28
	v_or_b32_e32 v20, 0x7f, v20
	v_or_b32_e32 v33, 0x7f, v33
	v_or_b32_e32 v25, 0x7f, v25
	v_or_b32_e32 v29, 0x7f, v29
	v_or_b32_e32 v19, 0x7f, v19
	v_or_b32_e32 v30, 0x7f, v30
	v_add_u32_e32 v21, 0xffffffbd, v21
	v_add_u32_e32 v32, 0xffffffa6, v32
	v_add_u32_e32 v22, 0xffffffb8, v22
	v_add_u32_e32 v26, 0xffffffb0, v26
	v_subrev_u32_e32 v18, 64, v18
	v_add_u32_e32 v31, 0xffffffa7, v31
	v_add_u32_e32 v23, 0xffffffb7, v23
	v_add_u32_e32 v24, 0xffffffb6, v24
	v_add_u32_e32 v27, 0xffffffaf, v27
	v_add_u32_e32 v28, 0xffffffae, v28
	v_add_u32_e32 v20, 0xffffffbe, v20
	v_add_u32_e32 v33, 0xffffffa5, v33
	v_add_u32_e32 v25, 0xffffffb5, v25
	v_add_u32_e32 v29, 0xffffffad, v29
	v_add_u32_e32 v19, 0xffffffbf, v19
	v_add_u32_e32 v30, 0xffffffa8, v30
	v_max_i32_e32 v70, v21, v32
	v_max_i32_e32 v71, v22, v26
	v_max_i32_e32 v73, v18, v31
	v_max_i32_e32 v135, v23, v24
	v_min_i32_e32 v138, v27, v28
	v_min_i32_e32 v139, v20, v33
	v_min_i32_e32 v141, v25, v29
	v_min_i32_e32 v142, v19, v30
	v_min_i32_e32 v23, v23, v24
	v_min_i32_e32 v18, v18, v31
	v_min_i32_e32 v22, v22, v26
	v_min_i32_e32 v21, v21, v32
	v_max_i32_e32 v19, v19, v30
	v_max_i32_e32 v25, v25, v29
	v_max_i32_e32 v20, v20, v33
	v_max_i32_e32 v27, v27, v28
	v_min_i32_e32 v72, v70, v71
	v_min_i32_e32 v136, v73, v135
	v_max_i32_e32 v140, v138, v139
	v_max_i32_e32 v143, v141, v142
	v_max_i32_e32 v24, v23, v18
	v_max_i32_e32 v26, v22, v21
	v_min_i32_e32 v29, v19, v25
	v_min_i32_e32 v28, v20, v27
	v_min_i32_e32 v141, v141, v142
	v_min_i32_e32 v18, v23, v18
	v_min_i32_e32 v21, v22, v21
	v_min_i32_e32 v22, v138, v139
	v_max_i32_e32 v73, v73, v135
	v_max_i32_e32 v19, v19, v25
	v_max_i32_e32 v20, v20, v27
	v_max_i32_e32 v27, v70, v71
	v_min_i32_e32 v137, v72, v136
	v_min_i32_e32 v144, v140, v143
	v_max_i32_e32 v31, v24, v26
	v_max_i32_e32 v30, v29, v28
	v_min_i32_e32 v24, v24, v26
	v_min_i32_e32 v26, v29, v28
	v_max_i32_e32 v29, v72, v136
	v_max_i32_e32 v72, v140, v143
	v_min_i32_e32 v23, v141, v18
	v_min_i32_e32 v138, v21, v22
	v_max_i32_e32 v18, v141, v18
	v_max_i32_e32 v21, v21, v22
	v_min_i32_e32 v25, v73, v19
	v_min_i32_e32 v70, v20, v27
	v_max_i32_e32 v19, v73, v19
	v_max_i32_e32 v20, v20, v27
	v_min_i32_e32 v32, v31, v30
	v_max_i32_e32 v28, v24, v26
	v_min_i32_e32 v136, v29, v72
	v_min_i32_e32 v24, v24, v26
	v_min_i32_e32 v26, v137, v144
	v_max_i32_e32 v139, v23, v138
	v_min_i32_e32 v22, v18, v21
	v_min_i32_e32 v71, v25, v70
	v_max_i32_e32 v25, v25, v70
	v_min_i32_e32 v27, v19, v20
	v_max_i32_e32 v29, v29, v72
	v_max_i32_e32 v30, v31, v30
	v_max_i32_e32 v145, v137, v144
	v_max_i32_e32 v137, v24, v26
	v_max_i32_e32 v141, v139, v22
	v_max_i32_e32 v18, v18, v21
	v_min_i32_e32 v70, v25, v27
	v_min_i32_e32 v31, v29, v30
	v_min_i32_e32 v33, v145, v32
	v_min_i32_e32 v140, v28, v136
	v_max_i32_e32 v142, v137, v141
	v_min_i32_e32 v21, v71, v18
	v_max_i32_e32 v18, v71, v18
	v_min_i32_e32 v71, v70, v31
; #define LAS __attribute__((address_space(3)))
; #define MFMA32(a, b, c) __builtin_amdgcn_mfma_f32_32x32x16_bf16((a), (b), (c), 0, 0, 0)
; __device__ __forceinline__ void route_task(int task, int tl0, const bf16* QP  , const LAS bf16* KHL, LAS unsigned short* EL, LAS float* GL, int lane) {
;     ...
;         for (int kt = 0; kt < 4; ++kt) {
;             f32x16 X;
; #pragma unroll
;             for (int i = 0; i < 16; ++i) X[i] = 8.f;
;             const LAS bf16* khp = KHL + (half * 128 + 32 * kt + r) * 72 + 8 * hi;
; #pragma unroll
;             for (int ks = 0; ks < 4; ++ks) {
;                 const bf16x8 kh = lds8(khp + 16 * ks);
;                 X = MFMA32(kh, qa[half][ks], X);
;             }
;             int grp[16];
; #pragma unroll
;             for (int i = 0; i < 16; ++i) grp[i] = (int)((__float_as_uint(X[i]) | 127u) - (unsigned)(32 * kt + (i & 3) + 8 * (i >> 2)));
;             sort16_desc(grp);
;             if (kt == 0) {
; #pragma unroll
;                 for (int i = 0; i < 16; ++i) cur[i] = grp[i];
;             } else merge16_desc(cur, grp);
	v_max_i32_e32 v32, v145, v32
	v_max_i32_e32 v28, v28, v136
	v_max_i32_e32 v143, v33, v140
	v_max_i32_e32 v135, v142, v21
	v_min_i32_e32 v72, v18, v71
	v_min_i32_e32 v73, v32, v28
	v_min_i32_e32 v33, v33, v140
	v_min_i32_e32 v21, v142, v21
	v_max_i32_e32 v18, v18, v71
	v_max_i32_e32 v28, v32, v28
	v_min_i32_e32 v24, v24, v26
	v_min_i32_e32 v22, v139, v22
	v_max_i32_e32 v25, v25, v27
	v_max_i32_e32 v27, v29, v30
	v_max_i32_e32 v144, v143, v135
	v_min_i32_e32 v136, v72, v73
	v_min_i32_e32 v135, v143, v135
	v_max_i32_e32 v140, v33, v21
	v_min_i32_e32 v32, v18, v28
	v_max_i32_e32 v71, v72, v73
	v_max_i32_e32 v26, v24, v22
	v_min_i32_e32 v137, v137, v141
	v_max_i32_e32 v18, v18, v28
	v_max_i32_e32 v28, v70, v31
	v_min_i32_e32 v29, v25, v27
	v_min_i32_e32 v145, v144, v136
	v_max_i32_e32 v142, v135, v140
	v_min_i32_e32 v72, v32, v71
	v_max_i32_e32 v73, v144, v136
	v_max_i32_e32 v139, v26, v137
	v_min_i32_e32 v21, v33, v21
	v_min_i32_e32 v30, v28, v29
	v_min_i32_e32 v143, v145, v142
	v_min_i32_e32 v136, v72, v73
	v_min_i32_e32 v33, v139, v21
	v_max_i32_e32 v21, v139, v21
	v_min_i32_e32 v135, v135, v140
	v_max_i32_e32 v32, v32, v71
	v_min_i32_e32 v31, v18, v30
	v_max_i32_e32 v18, v18, v30
	v_min_i32_e32 v26, v26, v137
	v_min_i32_e32 v22, v24, v22
	v_max_i32_e32 v24, v25, v27
	v_min_i32_e32 v23, v23, v138
	v_max3_i32 v23, v127, v129, v23
	v_max_i32_e32 v22, v126, v22
	v_max3_i32 v25, v128, v130, v26
	v_max_i32_e32 v26, v66, v33
	v_max3_i32 v21, v131, v76, v21
	v_max_i32_e32 v27, v67, v135
	v_max3_i32 v30, v74, v75, v143
	v_max3_i32 v66, v77, v82, v136
	v_max3_i32 v67, v69, v72, v73
	v_max3_i32 v32, v78, v80, v32
	v_max_i32_e32 v31, v132, v31
	v_max3_i32 v18, v125, v124, v18
	v_max3_i32 v28, v133, v28, v29
	v_max3_i32 v24, v79, v81, v24
	v_max3_i32 v33, v68, v145, v142
	v_max3_i32 v19, v134, v19, v20
	v_max_i32_e32 v20, v23, v66
	v_min_i32_e32 v23, v23, v66
	v_max_i32_e32 v29, v22, v67
	v_max_i32_e32 v66, v25, v32
	v_min_i32_e32 v25, v25, v32
	v_max_i32_e32 v32, v26, v31
	v_min_i32_e32 v26, v26, v31
	v_max_i32_e32 v31, v21, v18
	v_min_i32_e32 v18, v21, v18
	v_max_i32_e32 v21, v27, v28
	v_min_i32_e32 v27, v27, v28
	v_max_i32_e32 v28, v30, v24
	v_min_i32_e32 v22, v22, v67
	v_min_i32_e32 v24, v30, v24
	v_max_i32_e32 v30, v33, v19
	v_min_i32_e32 v19, v33, v19
	v_max_i32_e32 v33, v20, v31
	v_min_i32_e32 v74, v20, v31
	v_max_i32_e32 v20, v29, v21
	v_min_i32_e32 v75, v29, v21
	v_max_i32_e32 v21, v66, v28
	v_min_i32_e32 v76, v66, v28
	ds_read_b128 v[66:69], v98
	ds_read_b128 v[70:73], v98 offset:32
	v_max_i32_e32 v28, v32, v30
	v_min_i32_e32 v77, v32, v30
	v_max_i32_e32 v78, v23, v18
	v_min_i32_e32 v79, v23, v18
	v_max_i32_e32 v80, v22, v27
	v_min_i32_e32 v81, v22, v27
	v_max_i32_e32 v82, v25, v24
	v_min_i32_e32 v124, v25, v24
	v_max_i32_e32 v125, v26, v19
	v_min_i32_e32 v126, v26, v19
	v_max_i32_e32 v127, v33, v21
	v_min_i32_e32 v128, v33, v21
	v_max_i32_e32 v129, v20, v28
	v_min_i32_e32 v130, v20, v28
	s_waitcnt lgkmcnt(1)
	v_mfma_f32_32x32x16_bf16 v[18:33], v[66:69], v[46:49], v[2:17]
	ds_read_b128 v[46:49], v98 offset:64
	v_max_i32_e32 v67, v75, v77
	v_min_i32_e32 v68, v75, v77
	v_max_i32_e32 v75, v80, v125
	v_max_i32_e32 v131, v74, v76
	v_min_i32_e32 v66, v74, v76
	v_max_i32_e32 v69, v78, v82
	s_waitcnt lgkmcnt(1)
	v_mfma_f32_32x32x16_bf16 v[18:33], v[70:73], v[42:45], v[18:33]
	ds_read_b128 v[42:45], v98 offset:96
	v_min_i32_e32 v70, v80, v125
	v_max_i32_e32 v71, v79, v124
	v_min_i32_e32 v72, v79, v124
	v_min_i32_e32 v74, v78, v82
	v_max_i32_e32 v73, v81, v126
	v_min_i32_e32 v76, v81, v126
	s_waitcnt lgkmcnt(1)
	v_mfma_f32_32x32x16_bf16 v[18:33], v[46:49], v[38:41], v[18:33]
	v_min_i32_e32 v77, v127, v129
	v_min_i32_e32 v38, v128, v130
	v_min_i32_e32 v39, v131, v67
	v_min_i32_e32 v40, v66, v68
	v_min_i32_e32 v41, v69, v75
	v_min_i32_e32 v46, v74, v70
	v_min_i32_e32 v47, v71, v73
	s_waitcnt lgkmcnt(0)
	v_mfma_f32_32x32x16_bf16 v[18:33], v[42:45], v[34:37], v[18:33]
	v_min_i32_e32 v48, v72, v76
	s_nop 10
	v_or_b32_e32 v25, 0x7f, v25
	v_or_b32_e32 v29, 0x7f, v29
	v_or_b32_e32 v19, 0x7f, v19
	v_or_b32_e32 v30, 0x7f, v30
	v_or_b32_e32 v23, 0x7f, v23
	v_or_b32_e32 v24, 0x7f, v24
	v_or_b32_e32 v18, 0x7f, v18
	v_or_b32_e32 v31, 0x7f, v31
	v_or_b32_e32 v22, 0x7f, v22
	v_or_b32_e32 v26, 0x7f, v26
	v_or_b32_e32 v21, 0x7f, v21
	v_or_b32_e32 v32, 0x7f, v32
	v_or_b32_e32 v27, 0x7f, v27
	v_or_b32_e32 v28, 0x7f, v28
	v_or_b32_e32 v20, 0x7f, v20
	v_or_b32_e32 v33, 0x7f, v33
	v_add_u32_e32 v25, 0xffffff95, v25
	v_add_u32_e32 v29, 0xffffff8d, v29
	v_add_u32_e32 v19, 0xffffff9f, v19
	v_add_u32_e32 v30, 0xffffff88, v30
	v_add_u32_e32 v23, 0xffffff97, v23
	v_add_u32_e32 v24, 0xffffff96, v24
	v_add_u32_e32 v18, 0xffffffa0, v18
	v_add_u32_e32 v31, 0xffffff87, v31
	v_add_u32_e32 v22, 0xffffff98, v22
	v_add_u32_e32 v26, 0xffffff90, v26
	v_add_u32_e32 v21, 0xffffff9d, v21
	v_add_u32_e32 v32, 0xffffff86, v32
	v_add_u32_e32 v27, 0xffffff8f, v27
	v_add_u32_e32 v28, 0xffffff8e, v28
	v_add_u32_e32 v20, 0xffffff9e, v20
	v_add_u32_e32 v33, 0xffffff85, v33
	v_min_i32_e32 v34, v25, v29
	v_min_i32_e32 v35, v19, v30
	v_min_i32_e32 v37, v23, v24
	v_min_i32_e32 v42, v18, v31
	v_min_i32_e32 v45, v22, v26
	v_min_i32_e32 v49, v21, v32
	v_min_i32_e32 v79, v27, v28
	v_min_i32_e32 v80, v20, v33
	v_max_i32_e32 v18, v18, v31
	v_max_i32_e32 v23, v23, v24
	v_max_i32_e32 v19, v19, v30
	v_max_i32_e32 v25, v25, v29
	v_max_i32_e32 v20, v20, v33
	v_max_i32_e32 v27, v27, v28
	v_max_i32_e32 v21, v21, v32
	v_max_i32_e32 v22, v22, v26
	v_max_i32_e32 v24, v18, v23
	v_max_i32_e32 v29, v19, v25
	v_max_i32_e32 v28, v20, v27
	v_max_i32_e32 v26, v21, v22
	v_min_i32_e32 v30, v24, v29
	v_min_i32_e32 v31, v28, v26
; __device__ __forceinline__ void route_task(int task, int tl0, const bf16* QP  , const LAS bf16* KHL, LAS unsigned short* EL, LAS float* GL, int lane) {
;     ...
;             sort16_desc(grp);
;             if (kt == 0) {
; #pragma unroll
;                 for (int i = 0; i < 16; ++i) cur[i] = grp[i];
;             } else merge16_desc(cur, grp);
;         }
;         { const unsigned h4 = 4u * (unsigned)hi;
; #pragma unroll
;           for (int i = 0; i < 16; ++i) cur[i] -= (int)h4; }
;         int oth[16];
; #pragma unroll
;         for (int i = 0; i < 16; ++i) oth[i] = __shfl_xor(cur[i], 32);
;         merge16_desc(cur, oth);
; #pragma unroll
;         for (int i = 0; i < 16; ++i) top[half][i] = cur[i];
	v_min_i32_e32 v43, v37, v42
	v_min_i32_e32 v32, v30, v31
	v_max_i32_e32 v30, v30, v31
	v_min_i32_e32 v21, v21, v22
	v_min_i32_e32 v18, v18, v23
	v_max_i32_e32 v23, v79, v80
	v_max_i32_e32 v31, v34, v35
	v_max_i32_e32 v37, v37, v42
	v_max_i32_e32 v42, v45, v49
	v_min_i32_e32 v19, v19, v25
	v_min_i32_e32 v20, v20, v27
	v_min_i32_e32 v36, v34, v35
	v_min_i32_e32 v78, v45, v49
	v_min_i32_e32 v81, v79, v80
	v_max_i32_e32 v22, v21, v18
	v_max_i32_e32 v45, v37, v42
	v_max_i32_e32 v25, v19, v20
	v_min_i32_e32 v18, v21, v18
	v_min_i32_e32 v21, v23, v31
	v_min_i32_e32 v44, v36, v43
	v_min_i32_e32 v82, v78, v81
	v_max_i32_e32 v33, v36, v43
	v_max_i32_e32 v36, v78, v81
	v_max_i32_e32 v24, v24, v29
	v_max_i32_e32 v26, v28, v26
	v_max_i32_e32 v34, v23, v31
	v_max_i32_e32 v27, v45, v25
	v_max_i32_e32 v23, v18, v21
	v_min_i32_e32 v25, v45, v25
	v_min_i32_e32 v37, v37, v42
	v_min_i32_e32 v19, v19, v20
	v_max_i32_e32 v43, v33, v36
	v_min_i32_e32 v28, v24, v26
	v_max_i32_e32 v35, v22, v34
	v_max_i32_e32 v31, v23, v25
	v_max_i32_e32 v20, v37, v19
	v_min_i32_e32 v23, v23, v25
	v_min_i32_e32 v19, v37, v19
	v_min_i32_e32 v18, v18, v21
	v_max_i32_e32 v25, v44, v82
	v_min_i32_e32 v33, v33, v36
	v_min_i32_e32 v29, v30, v28
	v_min_i32_e32 v49, v35, v27
	v_min_i32_e32 v22, v22, v34
	v_max_i32_e32 v21, v19, v18
	v_max_i32_e32 v36, v25, v33
	v_max_i32_e32 v78, v32, v43
	v_min_i32_e32 v79, v29, v49
	v_max_i32_e32 v34, v20, v22
	v_min_i32_e32 v20, v20, v22
	v_max_i32_e32 v37, v21, v36
	v_min_i32_e32 v32, v32, v43
	v_max_i32_e32 v80, v78, v79
	v_max_i32_e32 v42, v31, v34
	v_min_i32_e32 v78, v78, v79
	v_min_i32_e32 v31, v31, v34
	v_max_i32_e32 v22, v23, v20
	v_max_i32_e32 v43, v37, v32
	v_min_i32_e32 v18, v19, v18
	v_min_i32_e32 v19, v25, v33
	v_min_i32_e32 v20, v23, v20
	v_min_i32_e32 v23, v37, v32
	v_max_i32_e32 v28, v30, v28
	v_max_i32_e32 v27, v35, v27
	v_min_i32_e32 v124, v44, v82
	v_min_i32_e32 v45, v80, v42
	v_max_i32_e32 v34, v78, v31
	v_max_i32_e32 v44, v22, v43
	v_min_i32_e32 v31, v78, v31
	v_max_i32_e32 v25, v18, v19
	v_min_i32_e32 v21, v21, v36
	v_min_i32_e32 v32, v20, v23
	v_max_i32_e32 v29, v29, v49
	v_min_i32_e32 v30, v28, v27
	v_min_i32_e32 v22, v22, v43
	v_max_i32_e32 v20, v20, v23
	v_min_i32_e32 v79, v45, v34
	v_max_i32_e32 v78, v44, v31
	v_max_i32_e32 v33, v25, v21
	v_max_i32_e32 v37, v80, v42
	v_min_i32_e32 v35, v29, v30
	v_min_i32_e32 v31, v44, v31
	v_max_i32_e32 v23, v22, v20
	v_min_i32_e32 v81, v79, v78
	v_max_i32_e32 v36, v33, v32
	v_max_i32_e32 v42, v37, v35
	v_min_i32_e32 v21, v25, v21
	v_max_i32_e32 v25, v45, v34
	v_min_i32_e32 v43, v31, v23
	v_max_i32_e32 v27, v28, v27
	v_min_i32_e32 v18, v18, v19
	v_min_i32_e32 v20, v22, v20
	v_min_i32_e32 v32, v33, v32
	v_min_i32_e32 v33, v37, v35
	v_max3_i32 v124, v127, v129, v124
	v_max3_i32 v69, v69, v75, v81
	v_max3_i32 v36, v131, v67, v36
	v_max3_i32 v42, v71, v73, v42
	v_max3_i32 v21, v128, v130, v21
	v_max3_i32 v25, v74, v70, v25
	v_max3_i32 v43, v66, v68, v43
	v_max3_i32 v27, v72, v76, v27
	v_max_i32_e32 v18, v77, v18
	v_max3_i32 v19, v41, v79, v78
	v_max_i32_e32 v20, v39, v20
	v_max3_i32 v22, v47, v29, v30
	v_max_i32_e32 v32, v38, v32
	v_max_i32_e32 v33, v46, v33
	v_max3_i32 v23, v40, v31, v23
	v_max3_i32 v24, v48, v24, v26
	v_min_i32_e32 v49, v36, v42
	v_min_i32_e32 v34, v21, v25
	v_min_i32_e32 v41, v18, v19
	v_min_i32_e32 v29, v20, v22
	v_min_i32_e32 v26, v23, v24
	v_max_i32_e32 v39, v124, v69
	v_max_i32_e32 v36, v36, v42
	v_max_i32_e32 v21, v21, v25
	v_max_i32_e32 v25, v43, v27
	v_max_i32_e32 v18, v18, v19
	v_max_i32_e32 v19, v20, v22
	v_max_i32_e32 v22, v32, v33
	v_max_i32_e32 v23, v23, v24
	v_min_i32_e32 v28, v43, v27
	v_max_i32_e32 v40, v39, v36
	v_max_i32_e32 v27, v21, v25
	v_max_i32_e32 v20, v18, v19
	v_max_i32_e32 v24, v22, v23
	v_min_i32_e32 v35, v32, v33
	v_max_i32_e32 v42, v40, v27
	v_max_i32_e32 v32, v20, v24
	v_min_i32_e32 v27, v40, v27
	v_min_i32_e32 v20, v20, v24
	v_max_i32_e32 v24, v27, v20
	v_min_i32_e32 v20, v27, v20
	v_min_i32_e32 v27, v39, v36
	v_min_i32_e32 v21, v21, v25
	v_min_i32_e32 v18, v18, v19
	v_min_i32_e32 v19, v22, v23
	v_min_i32_e32 v75, v124, v69
	v_max_i32_e32 v25, v27, v21
	v_max_i32_e32 v22, v18, v19
	v_min_i32_e32 v21, v27, v21
	v_min_i32_e32 v18, v18, v19
	v_min_i32_e32 v44, v34, v28
	v_min_i32_e32 v31, v35, v26
	v_max_i32_e32 v23, v25, v22
	v_min_i32_e32 v22, v25, v22
	v_max_i32_e32 v19, v21, v18
	v_min_i32_e32 v18, v21, v18
	v_max_i32_e32 v21, v75, v49
	v_max_i32_e32 v25, v34, v28
	v_max_i32_e32 v28, v41, v29
	v_max_i32_e32 v26, v35, v26
	v_min_i32_e32 v67, v75, v49
	v_min_i32_e32 v30, v41, v29
	v_max_i32_e32 v27, v21, v25
	v_min_i32_e32 v21, v21, v25
	v_min_i32_e32 v25, v28, v26
	v_min_i32_e32 v45, v67, v44
	v_min_i32_e32 v37, v30, v31
	v_max_i32_e32 v29, v28, v26
	v_max_i32_e32 v26, v21, v25
	v_min_i32_e32 v21, v21, v25
	v_max_i32_e32 v25, v67, v44
	v_max_i32_e32 v28, v30, v31
	v_min_i32_e32 v38, v45, v37
	v_max_i32_e32 v33, v42, v32
	v_min_i32_e32 v32, v42, v32
	v_max_i32_e32 v34, v27, v29
	v_min_i32_e32 v27, v27, v29
	v_max_i32_e32 v29, v25, v28
	v_min_i32_e32 v25, v25, v28
	v_max_i32_e32 v28, v45, v37
	v_sub_u32_e32 v30, v33, v87
	v_sub_u32_e32 v31, v32, v87
	v_sub_u32_e32 v24, v24, v87
	v_sub_u32_e32 v20, v20, v87
	v_sub_u32_e32 v23, v23, v87
	v_sub_u32_e32 v22, v22, v87
	v_sub_u32_e32 v19, v19, v87
	v_sub_u32_e32 v18, v18, v87
	v_sub_u32_e32 v32, v34, v87
	v_sub_u32_e32 v27, v27, v87
	v_sub_u32_e32 v26, v26, v87
	v_sub_u32_e32 v21, v21, v87
	v_sub_u32_e32 v29, v29, v87
	v_sub_u32_e32 v25, v25, v87
	v_sub_u32_e32 v28, v28, v87
	v_sub_u32_e32 v33, v38, v87
	ds_bpermute_b32 v34, v123, v30
	ds_bpermute_b32 v35, v123, v31
	ds_bpermute_b32 v36, v123, v24
	ds_bpermute_b32 v37, v123, v20
	ds_bpermute_b32 v38, v123, v23
	ds_bpermute_b32 v39, v123, v22
	ds_bpermute_b32 v40, v123, v19
	ds_bpermute_b32 v41, v123, v18
	ds_bpermute_b32 v42, v123, v32
	ds_bpermute_b32 v43, v123, v27
	ds_bpermute_b32 v44, v123, v26
	ds_bpermute_b32 v45, v123, v33
	ds_bpermute_b32 v46, v123, v28
	ds_bpermute_b32 v47, v123, v25
	ds_bpermute_b32 v48, v123, v29
	ds_bpermute_b32 v49, v123, v21
	s_waitcnt lgkmcnt(4)
; __device__ __forceinline__ void route_task(int task, int tl0, const bf16* QP  , const LAS bf16* KHL, LAS unsigned short* EL, LAS float* GL, int lane) {
;     ...
;         merge16_desc(cur, oth);
; #pragma unroll
;         for (int i = 0; i < 16; ++i) top[half][i] = cur[i];
;     }
;     unsigned P1[4], P2[4];
; #pragma unroll
;     for (int q = 0; q < 4; ++q) { P1[q] = 0u; P2[q] = 0u;
; #pragma unroll
;         for (int s = 0; s < 4; ++s) { P1[q] |= (127u - ((unsigned)top[0][4 * q + s] & 127u)) << (8 * s); P2[q] |= (127u - ((unsigned)top[1][4 * q + s] & 127u)) << (8 * s); } }
;     int bk[16];
;     {
;         int hi2 = hi; asm volatile("" : "+v"(hi2));
;         const bool h1 = hi2 != 0;
;         constexpr int A1[16] = {1, 1, 1, 1, 1, 1, 1, 1, 2, 2, 2, 2, 2, 3, 3, 3}, B1[16] = {0, 1, 2, 3, 4, 5, 6, 7, 0, 1, 2, 3, 4, 0, 1, 2};
; #pragma unroll
;         for (int i = 0; i < 16; ++i) { const float ta = __int_as_float(h1 ? top[0][A1[i]] : top[0][0]), tb = __int_as_float(h1 ? top[1][B1[i]] : top[1][i]); const unsigned code = h1 ? (unsigned)(A1[i] * 16 + B1[i]) : (unsigned)i;
;             bk[i] = (int)((__float_as_uint(ta + tb) | 255u) - code); }
	v_max_i32_e32 v30, v30, v45
	s_waitcnt lgkmcnt(3)
	v_max_i32_e32 v31, v31, v46
	s_waitcnt lgkmcnt(2)
	v_max_i32_e32 v24, v24, v47
	s_waitcnt lgkmcnt(1)
	v_max_i32_e32 v20, v20, v48
	s_waitcnt lgkmcnt(0)
	v_max_i32_e32 v23, v23, v49
	v_max_i32_e32 v22, v22, v44
	v_max_i32_e32 v19, v19, v43
	v_max_i32_e32 v18, v18, v42
	v_max_i32_e32 v32, v32, v41
	v_max_i32_e32 v27, v27, v40
	v_max_i32_e32 v26, v26, v39
	v_max_i32_e32 v21, v21, v38
	v_max_i32_e32 v29, v29, v37
	v_max_i32_e32 v25, v25, v36
	v_max_i32_e32 v28, v28, v35
	v_max_i32_e32 v33, v33, v34
	v_max_i32_e32 v34, v30, v32
	v_min_i32_e32 v30, v30, v32
	v_max_i32_e32 v32, v31, v27
	v_min_i32_e32 v27, v31, v27
	v_max_i32_e32 v31, v24, v26
	v_min_i32_e32 v24, v24, v26
	v_max_i32_e32 v26, v20, v21
	v_min_i32_e32 v20, v20, v21
	v_max_i32_e32 v21, v23, v29
	v_min_i32_e32 v23, v23, v29
	v_max_i32_e32 v29, v22, v25
	v_min_i32_e32 v22, v22, v25
	v_max_i32_e32 v25, v19, v28
	v_min_i32_e32 v19, v19, v28
	v_max_i32_e32 v28, v18, v33
	v_min_i32_e32 v18, v18, v33
	v_max_i32_e32 v33, v34, v21
	v_min_i32_e32 v21, v34, v21
	v_max_i32_e32 v34, v32, v29
	v_min_i32_e32 v29, v32, v29
	v_max_i32_e32 v32, v31, v25
	v_min_i32_e32 v25, v31, v25
	v_max_i32_e32 v31, v26, v28
	v_min_i32_e32 v26, v26, v28
	v_max_i32_e32 v28, v30, v23
	v_min_i32_e32 v23, v30, v23
	v_max_i32_e32 v30, v27, v22
	v_min_i32_e32 v22, v27, v22
	v_max_i32_e32 v27, v24, v19
	v_min_i32_e32 v19, v24, v19
	v_max_i32_e32 v24, v20, v18
	v_min_i32_e32 v18, v20, v18
	v_max_i32_e32 v20, v33, v32
	v_min_i32_e32 v32, v33, v32
	v_max_i32_e32 v33, v34, v31
	v_min_i32_e32 v31, v34, v31
	v_max_i32_e32 v34, v21, v25
	v_min_i32_e32 v21, v21, v25
	v_max_i32_e32 v25, v29, v26
	v_min_i32_e32 v29, v29, v26
	v_max_i32_e32 v35, v28, v27
	v_min_i32_e32 v27, v28, v27
	v_max_i32_e32 v28, v30, v24
	v_min_i32_e32 v24, v30, v24
	v_max_i32_e32 v30, v23, v19
	v_min_i32_e32 v19, v23, v19
	v_max_i32_e32 v23, v22, v18
	v_min_i32_e32 v18, v22, v18
	v_max_i32_e32 v26, v20, v33
	v_min_i32_e32 v33, v20, v33
	v_lshlrev_b32_e32 v20, 8, v65
	v_lshlrev_b32_e32 v22, 16, v64
	v_max_i32_e32 v36, v32, v31
	v_max_i32_e32 v40, v19, v18
	v_min_i32_e32 v41, v19, v18
	v_and_b32_e32 v18, 0x7f, v63
	v_and_b32_e32 v20, 0x7f00, v20
	v_and_b32_e32 v22, 0x7f0000, v22
	v_max_i32_e32 v37, v21, v29
	v_min_i32_e32 v29, v21, v29
	v_lshlrev_b32_e32 v21, 8, v33
	v_or3_b32 v18, v20, v18, v22
	v_lshlrev_b32_e32 v20, 16, v36
	v_and_b32_e32 v19, 0x7f, v26
	v_and_b32_e32 v21, 0x7f00, v21
	v_and_b32_e32 v20, 0x7f0000, v20
	v_or3_b32 v20, v21, v19, v20
	v_lshlrev_b32_e32 v19, 24, v62
	v_min_i32_e32 v31, v32, v31
	v_and_b32_e32 v19, 0x7f000000, v19
	v_bitop3_b32 v19, v18, s68, v19 bitop3:0x36
	v_lshlrev_b32_e32 v18, 24, v31
	v_max_i32_e32 v38, v35, v28
	v_min_i32_e32 v28, v35, v28
	v_max_i32_e32 v35, v27, v24
	v_min_i32_e32 v27, v27, v24
	v_and_b32_e32 v18, 0x7f000000, v18
	v_lshlrev_b32_e32 v22, 8, v60
	v_lshlrev_b32_e32 v24, 16, v59
	v_max_i32_e32 v32, v34, v25
	v_min_i32_e32 v34, v34, v25
	v_bitop3_b32 v18, v20, s68, v18 bitop3:0x36
	v_and_b32_e32 v20, 0x7f, v61
	v_and_b32_e32 v22, 0x7f00, v22
	v_and_b32_e32 v24, 0x7f0000, v24
	v_max_i32_e32 v39, v30, v23
	v_min_i32_e32 v30, v30, v23
	v_lshlrev_b32_e32 v23, 8, v34
	v_or3_b32 v20, v22, v20, v24
	v_lshlrev_b32_e32 v22, 16, v37
	v_and_b32_e32 v21, 0x7f, v32
	v_and_b32_e32 v23, 0x7f00, v23
	v_and_b32_e32 v22, 0x7f0000, v22
	v_or3_b32 v22, v23, v21, v22
	v_lshlrev_b32_e32 v21, 24, v57
	v_and_b32_e32 v21, 0x7f000000, v21
	v_bitop3_b32 v21, v20, s68, v21 bitop3:0x36
	v_lshlrev_b32_e32 v20, 24, v29
	v_and_b32_e32 v20, 0x7f000000, v20
	v_lshlrev_b32_e32 v24, 8, v58
	v_lshlrev_b32_e32 v42, 16, v56
	v_bitop3_b32 v20, v22, s68, v20 bitop3:0x36
	v_and_b32_e32 v22, 0x7f, v55
	v_and_b32_e32 v24, 0x7f00, v24
	v_and_b32_e32 v42, 0x7f0000, v42
	v_lshlrev_b32_e32 v25, 8, v28
	v_or3_b32 v22, v24, v22, v42
	v_lshlrev_b32_e32 v24, 16, v35
	v_and_b32_e32 v23, 0x7f, v38
	v_and_b32_e32 v25, 0x7f00, v25
	v_and_b32_e32 v24, 0x7f0000, v24
	v_or3_b32 v24, v25, v23, v24
	v_lshlrev_b32_e32 v23, 24, v54
	v_and_b32_e32 v23, 0x7f000000, v23
	v_bitop3_b32 v23, v22, s68, v23 bitop3:0x36
	v_lshlrev_b32_e32 v22, 24, v27
	v_and_b32_e32 v22, 0x7f000000, v22
	v_lshlrev_b32_e32 v42, 8, v52
	v_lshlrev_b32_e32 v44, 16, v51
	v_bitop3_b32 v22, v24, s68, v22 bitop3:0x36
	v_and_b32_e32 v24, 0x7f, v53
	v_and_b32_e32 v42, 0x7f00, v42
	v_and_b32_e32 v44, 0x7f0000, v44
	v_lshlrev_b32_e32 v43, 8, v30
	v_or3_b32 v24, v42, v24, v44
	v_lshlrev_b32_e32 v42, 16, v40
	v_and_b32_e32 v25, 0x7f, v39
	v_and_b32_e32 v43, 0x7f00, v43
	v_and_b32_e32 v42, 0x7f0000, v42
	v_or3_b32 v42, v43, v25, v42
	v_lshlrev_b32_e32 v25, 24, v50
	v_and_b32_e32 v25, 0x7f000000, v25
	v_bitop3_b32 v25, v24, s68, v25 bitop3:0x36
	v_lshlrev_b32_e32 v24, 24, v41
	v_and_b32_e32 v24, 0x7f000000, v24
	v_bitop3_b32 v24, v42, s68, v24 bitop3:0x36
	v_mov_b32_e32 v42, v86
	v_add_f32_e32 v55, v55, v26
	v_cmp_eq_u32_e32 vcc, 0, v42
	v_add_f32_e32 v56, v56, v26
	v_add_f32_e32 v54, v54, v26
	v_cndmask_b32_e32 v42, v65, v63, vcc
	v_add_f32_e32 v44, v42, v26
	v_cndmask_b32_e64 v43, -16, 0, vcc
	v_or_b32_e32 v44, 0xff, v44
	v_add_f32_e32 v45, v42, v33
	v_add_u32_e32 v43, v44, v43
	v_cndmask_b32_e64 v44, v99, -1, vcc
	v_or_b32_e32 v45, 0xff, v45
	v_add_f32_e32 v46, v42, v36
	v_add_u32_e32 v44, v45, v44
	v_cndmask_b32_e64 v45, v100, -2, vcc
	v_or_b32_e32 v46, 0xff, v46
	v_add_f32_e32 v47, v42, v31
	v_add_u32_e32 v45, v46, v45
	v_cndmask_b32_e64 v46, v101, -3, vcc
	v_or_b32_e32 v47, 0xff, v47
	v_add_f32_e32 v48, v42, v32
	v_add_u32_e32 v46, v47, v46
	v_cndmask_b32_e64 v47, v102, -4, vcc
	v_or_b32_e32 v48, 0xff, v48
	v_add_f32_e32 v34, v42, v34
	v_add_f32_e32 v37, v42, v37
; __device__ __forceinline__ void route_task(int task, int tl0, const bf16* QP  , const LAS bf16* KHL, LAS unsigned short* EL, LAS float* GL, int lane) {
;     ...
; #pragma unroll
;         for (int i = 0; i < 16; ++i) { const float ta = __int_as_float(h1 ? top[0][A1[i]] : top[0][0]), tb = __int_as_float(h1 ? top[1][B1[i]] : top[1][i]); const unsigned code = h1 ? (unsigned)(A1[i] * 16 + B1[i]) : (unsigned)i;
;             bk[i] = (int)((__float_as_uint(ta + tb) | 255u) - code); }
;         sort16_desc(bk);
;         int oth[16];
; #pragma unroll
;         for (int i = 0; i < 16; ++i) oth[i] = __shfl_xor(bk[i], 32);
;         merge16_desc(bk, oth);
	v_add_f32_e32 v29, v42, v29
	v_cndmask_b32_e32 v42, v64, v63, vcc
	v_cndmask_b32_e32 v32, v32, v39, vcc
	v_add_u32_e32 v47, v48, v47
	v_cndmask_b32_e64 v48, v103, -5, vcc
	v_or_b32_e32 v34, 0xff, v34
	v_add_f32_e32 v32, v42, v32
	v_add_u32_e32 v34, v34, v48
	v_cndmask_b32_e64 v48, v104, -6, vcc
	v_or_b32_e32 v37, 0xff, v37
	v_cndmask_b32_e32 v38, v26, v38, vcc
	v_cndmask_b32_e64 v39, v116, -12, vcc
	v_or_b32_e32 v32, 0xff, v32
	v_add_u32_e32 v37, v37, v48
	v_cndmask_b32_e64 v48, v105, -7, vcc
	v_or_b32_e32 v29, 0xff, v29
	v_add_f32_e32 v38, v42, v38
	v_cndmask_b32_e32 v28, v33, v28, vcc
	v_add_u32_e32 v32, v32, v39
	v_cndmask_b32_e32 v39, v62, v63, vcc
	v_cndmask_b32_e32 v30, v26, v30, vcc
	v_add_u32_e32 v29, v29, v48
	v_cndmask_b32_e64 v48, v106, -8, vcc
	v_or_b32_e32 v38, 0xff, v38
	v_add_f32_e32 v28, v42, v28
	v_cndmask_b32_e32 v35, v36, v35, vcc
	v_cndmask_b32_e32 v27, v31, v27, vcc
	v_add_f32_e32 v30, v39, v30
	v_cndmask_b32_e32 v40, v33, v40, vcc
	v_add_u32_e32 v38, v38, v48
	v_cndmask_b32_e64 v48, v107, -9, vcc
	v_or_b32_e32 v28, 0xff, v28
	v_add_f32_e32 v35, v42, v35
	v_add_f32_e32 v27, v42, v27
	v_cndmask_b32_e64 v42, v117, -13, vcc
	v_or_b32_e32 v30, 0xff, v30
	v_add_f32_e32 v40, v39, v40
	v_cndmask_b32_e32 v41, v36, v41, vcc
	v_add_u32_e32 v28, v28, v48
	v_cndmask_b32_e64 v48, v114, -10, vcc
	v_or_b32_e32 v35, 0xff, v35
	v_add_u32_e32 v30, v30, v42
	v_cndmask_b32_e64 v42, v118, -14, vcc
	v_or_b32_e32 v40, 0xff, v40
	v_add_f32_e32 v39, v39, v41
	v_add_u32_e32 v35, v35, v48
	v_cndmask_b32_e64 v48, v115, -11, vcc
	v_or_b32_e32 v27, 0xff, v27
	v_add_u32_e32 v40, v40, v42
	v_cndmask_b32_e64 v42, v119, -15, vcc
	v_or_b32_e32 v39, 0xff, v39
	v_add_u32_e32 v27, v27, v48
	v_add_u32_e32 v39, v39, v42
	v_max_i32_e32 v41, v43, v30
	v_min_i32_e32 v30, v43, v30
	v_max_i32_e32 v42, v44, v32
	v_min_i32_e32 v32, v44, v32
	v_max_i32_e32 v43, v45, v39
	v_min_i32_e32 v39, v45, v39
	v_max_i32_e32 v44, v46, v40
	v_min_i32_e32 v40, v46, v40
	v_max_i32_e32 v45, v47, v38
	v_min_i32_e32 v38, v47, v38
	v_max_i32_e32 v46, v34, v37
	v_min_i32_e32 v34, v34, v37
	v_max_i32_e32 v37, v29, v27
	v_min_i32_e32 v27, v29, v27
	v_max_i32_e32 v29, v28, v35
	v_min_i32_e32 v28, v28, v35
	v_max_i32_e32 v35, v41, v46
	v_min_i32_e32 v41, v41, v46
	v_max_i32_e32 v46, v42, v37
	v_min_i32_e32 v37, v42, v37
	v_max_i32_e32 v42, v43, v29
	v_min_i32_e32 v29, v43, v29
	v_max_i32_e32 v43, v44, v45
	v_min_i32_e32 v44, v44, v45
	v_max_i32_e32 v45, v34, v30
	v_min_i32_e32 v30, v34, v30
	v_max_i32_e32 v34, v38, v40
	v_min_i32_e32 v38, v38, v40
	v_max_i32_e32 v40, v28, v39
	v_min_i32_e32 v28, v28, v39
	v_max_i32_e32 v39, v27, v32
	v_min_i32_e32 v27, v27, v32
	v_max_i32_e32 v32, v35, v46
	v_min_i32_e32 v35, v35, v46
	v_max_i32_e32 v46, v42, v43
	v_min_i32_e32 v42, v42, v43
	v_max_i32_e32 v43, v44, v41
	v_min_i32_e32 v41, v44, v41
	v_max_i32_e32 v44, v45, v34
	v_min_i32_e32 v34, v45, v34
	v_max_i32_e32 v45, v37, v29
	v_min_i32_e32 v29, v37, v29
	v_max_i32_e32 v37, v40, v39
	v_min_i32_e32 v39, v40, v39
	v_max_i32_e32 v40, v27, v30
	v_min_i32_e32 v27, v27, v30
	v_max_i32_e32 v30, v38, v28
	v_min_i32_e32 v28, v38, v28
	v_max_i32_e32 v38, v32, v46
	v_min_i32_e32 v32, v32, v46
	v_max_i32_e32 v46, v35, v42
	v_min_i32_e32 v35, v35, v42
	v_max_i32_e32 v42, v43, v37
	v_min_i32_e32 v37, v43, v37
	v_max_i32_e32 v43, v41, v39
	v_min_i32_e32 v39, v41, v39
	v_max_i32_e32 v41, v44, v45
	v_min_i32_e32 v44, v44, v45
	v_max_i32_e32 v45, v34, v29
	v_min_i32_e32 v29, v34, v29
	v_max_i32_e32 v34, v40, v30
	v_min_i32_e32 v30, v40, v30
	v_max_i32_e32 v40, v27, v28
	v_min_i32_e32 v27, v27, v28
	v_max_i32_e32 v28, v46, v32
	v_min_i32_e32 v32, v46, v32
	v_max_i32_e32 v46, v35, v34
	v_min_i32_e32 v34, v35, v34
	v_max_i32_e32 v35, v42, v41
	v_min_i32_e32 v41, v42, v41
	v_max_i32_e32 v42, v43, v44
	v_min_i32_e32 v43, v43, v44
	v_max_i32_e32 v44, v45, v37
	v_min_i32_e32 v37, v45, v37
	v_max_i32_e32 v45, v29, v39
	v_min_i32_e32 v29, v29, v39
	v_max_i32_e32 v39, v40, v30
	v_min_i32_e32 v30, v40, v30
	v_max_i32_e32 v40, v28, v35
	v_min_i32_e32 v28, v28, v35
	v_max_i32_e32 v35, v32, v41
	v_min_i32_e32 v32, v32, v41
	v_max_i32_e32 v41, v42, v44
	v_min_i32_e32 v42, v42, v44
	v_max_i32_e32 v44, v43, v37
	v_min_i32_e32 v37, v43, v37
	v_max_i32_e32 v43, v45, v39
	v_min_i32_e32 v39, v45, v39
	v_max_i32_e32 v45, v29, v30
	v_min_i32_e32 v29, v29, v30
	v_max_i32_e32 v30, v35, v28
	v_min_i32_e32 v28, v35, v28
	v_max_i32_e32 v35, v46, v32
	v_min_i32_e32 v32, v46, v32
	v_max_i32_e32 v46, v43, v34
	v_min_i32_e32 v34, v43, v34
	v_max_i32_e32 v43, v45, v39
	v_min_i32_e32 v39, v45, v39
	v_max_i32_e32 v45, v35, v41
	v_min_i32_e32 v35, v35, v41
	v_max_i32_e32 v41, v32, v42
	v_min_i32_e32 v32, v32, v42
	v_max_i32_e32 v42, v44, v46
	v_min_i32_e32 v44, v44, v46
	v_max_i32_e32 v46, v37, v34
	v_min_i32_e32 v34, v37, v34
	v_max_i32_e32 v37, v45, v28
	v_min_i32_e32 v28, v45, v28
	v_max_i32_e32 v45, v35, v41
	v_min_i32_e32 v35, v35, v41
	v_max_i32_e32 v41, v42, v32
	v_min_i32_e32 v32, v42, v32
	v_max_i32_e32 v42, v44, v46
	v_min_i32_e32 v44, v44, v46
	v_max_i32_e32 v46, v43, v34
	v_min_i32_e32 v34, v43, v34
	v_max_i32_e32 v43, v35, v41
	v_min_i32_e32 v35, v35, v41
	v_max_i32_e32 v41, v32, v42
	v_min_i32_e32 v32, v32, v42
	ds_bpermute_b32 v67, v123, v41
	ds_bpermute_b32 v68, v123, v32
	ds_bpermute_b32 v69, v123, v44
	ds_bpermute_b32 v64, v123, v45
	ds_bpermute_b32 v65, v123, v43
	ds_bpermute_b32 v66, v123, v35
	s_waitcnt lgkmcnt(4)
	v_max_i32_e32 v43, v43, v68
	s_waitcnt lgkmcnt(3)
; #define CAND(a, b) (int)((__float_as_uint(__int_as_float(top[0][a]) + __int_as_float(top[1][b])) | 255u) - (unsigned)((a) * 16 + (b)))
; __device__ __forceinline__ void route_task(int task, int tl0, const bf16* QP  , const LAS bf16* KHL, LAS unsigned short* EL, LAS float* GL, int lane) {
;     ...
;         int oth[16];
; #pragma unroll
;         for (int i = 0; i < 16; ++i) oth[i] = __shfl_xor(bk[i], 32);
;         merge16_desc(bk, oth);
;     }
;     ...
;     {
;         int gk[16];
;         gk[0] = CAND(3, 3); gk[1] = CAND(4, 0); gk[2] = CAND(4, 1); gk[3] = CAND(4, 2); gk[4] = CAND(5, 0); gk[5] = CAND(5, 1); gk[6] = CAND(6, 0); gk[7] = CAND(6, 1);
;         gk[8] = CAND(7, 0); gk[9] = CAND(7, 1); gk[10] = CAND(8, 0); gk[11] = CAND(9, 0); gk[12] = CAND(10, 0); gk[13] = CAND(11, 0); gk[14] = CAND(12, 0); gk[15] = CAND(13, 0);
;         sort16_desc(gk);
	v_max_i32_e32 v45, v45, v69
	v_max_i32_e32 v35, v35, v67
	v_add_f32_e32 v31, v62, v31
	v_add_f32_e32 v62, v61, v26
	v_add_f32_e32 v67, v61, v33
	v_add_f32_e32 v36, v61, v36
	v_add_f32_e32 v61, v60, v26
	v_add_f32_e32 v60, v60, v33
	v_add_f32_e32 v68, v59, v26
	v_add_f32_e32 v59, v59, v33
	v_add_f32_e32 v69, v57, v26
	v_add_f32_e32 v33, v57, v33
	v_add_f32_e32 v57, v58, v26
	v_add_f32_e32 v53, v53, v26
	v_add_f32_e32 v52, v52, v26
	ds_bpermute_b32 v70, v123, v27
	v_or_b32_e32 v31, 0xff, v31
	v_or_b32_e32 v62, 0xff, v62
	v_or_b32_e32 v67, 0xff, v67
	v_or_b32_e32 v36, 0xff, v36
	v_or_b32_e32 v61, 0xff, v61
	v_or_b32_e32 v60, 0xff, v60
	v_or_b32_e32 v68, 0xff, v68
	v_or_b32_e32 v59, 0xff, v59
	v_or_b32_e32 v69, 0xff, v69
	v_or_b32_e32 v33, 0xff, v33
	v_or_b32_e32 v55, 0xff, v55
	v_or_b32_e32 v57, 0xff, v57
	v_or_b32_e32 v56, 0xff, v56
	v_or_b32_e32 v54, 0xff, v54
	v_or_b32_e32 v53, 0xff, v53
	v_or_b32_e32 v52, 0xff, v52
	v_subrev_u32_e32 v31, 51, v31
	v_subrev_u32_e32 v62, 64, v62
	v_add_u32_e32 v67, 0xffffffbf, v67
	v_add_u32_e32 v36, 0xffffffbe, v36
	v_add_u32_e32 v61, 0xffffffb0, v61
	v_add_u32_e32 v60, 0xffffffaf, v60
	v_add_u32_e32 v68, 0xffffffa0, v68
	v_add_u32_e32 v59, 0xffffff9f, v59
	v_add_u32_e32 v69, 0xffffff90, v69
	v_add_u32_e32 v33, 0xffffff8f, v33
	v_add_u32_e32 v55, 0xffffff80, v55
	v_add_u32_e32 v57, 0xffffff70, v57
	v_add_u32_e32 v56, 0xffffff60, v56
	v_add_u32_e32 v54, 0xffffff50, v54
	v_add_u32_e32 v53, 0xffffff40, v53
	v_add_u32_e32 v52, 0xffffff30, v52
	ds_bpermute_b32 v42, v123, v38
	ds_bpermute_b32 v47, v123, v40
	ds_bpermute_b32 v48, v123, v30
	ds_bpermute_b32 v49, v123, v37
	ds_bpermute_b32 v63, v123, v28
	ds_bpermute_b32 v71, v123, v29
	ds_bpermute_b32 v72, v123, v39
	ds_bpermute_b32 v73, v123, v34
	ds_bpermute_b32 v74, v123, v46
	v_max_i32_e32 v58, v31, v54
	v_min_i32_e32 v31, v31, v54
	v_max_i32_e32 v54, v62, v56
	v_min_i32_e32 v56, v62, v56
	v_max_i32_e32 v62, v67, v52
	v_min_i32_e32 v52, v67, v52
	v_max_i32_e32 v67, v36, v53
	v_min_i32_e32 v36, v36, v53
	v_max_i32_e32 v53, v61, v69
	v_min_i32_e32 v61, v61, v69
	v_max_i32_e32 v69, v60, v68
	v_min_i32_e32 v60, v60, v68
	v_max_i32_e32 v68, v59, v57
	v_min_i32_e32 v57, v59, v57
	v_max_i32_e32 v59, v33, v55
	v_min_i32_e32 v33, v33, v55
	v_max_i32_e32 v55, v58, v69
	v_min_i32_e32 v58, v58, v69
	v_max_i32_e32 v69, v54, v68
	v_min_i32_e32 v54, v54, v68
	v_max_i32_e32 v68, v62, v59
	v_min_i32_e32 v59, v62, v59
	v_max_i32_e32 v62, v67, v53
	v_min_i32_e32 v53, v67, v53
	v_max_i32_e32 v67, v60, v31
	v_min_i32_e32 v31, v60, v31
	v_max_i32_e32 v60, v61, v36
	v_min_i32_e32 v36, v61, v36
	v_max_i32_e32 v61, v33, v52
	v_min_i32_e32 v33, v33, v52
	v_max_i32_e32 v52, v57, v56
	v_min_i32_e32 v56, v57, v56
	v_max_i32_e32 v57, v55, v69
	v_min_i32_e32 v55, v55, v69
	v_max_i32_e32 v69, v68, v62
	v_min_i32_e32 v62, v68, v62
	v_max_i32_e32 v68, v53, v58
	v_min_i32_e32 v53, v53, v58
	v_max_i32_e32 v58, v67, v60
	v_min_i32_e32 v60, v67, v60
	v_max_i32_e32 v67, v54, v59
	v_min_i32_e32 v54, v54, v59
	v_max_i32_e32 v59, v61, v52
	v_min_i32_e32 v52, v61, v52
	v_max_i32_e32 v61, v56, v31
	v_min_i32_e32 v31, v56, v31
	v_max_i32_e32 v56, v36, v33
	v_min_i32_e32 v33, v36, v33
	s_waitcnt lgkmcnt(9)
	v_max_i32_e32 v38, v38, v70
	v_min_i32_e32 v36, v57, v69
	v_max_i32_e32 v70, v55, v62
	v_min_i32_e32 v55, v55, v62
	v_max_i32_e32 v62, v68, v59
	v_min_i32_e32 v59, v68, v59
	v_max_i32_e32 v68, v53, v52
	v_min_i32_e32 v52, v53, v52
	v_max_i32_e32 v53, v58, v67
	v_min_i32_e32 v58, v58, v67
	v_max_i32_e32 v67, v60, v54
	v_min_i32_e32 v54, v60, v54
	v_max_i32_e32 v60, v61, v56
	v_min_i32_e32 v56, v61, v56
	v_max_i32_e32 v61, v31, v33
	v_min_i32_e32 v31, v31, v33
	v_max_i32_e32 v33, v70, v36
	v_min_i32_e32 v36, v70, v36
	v_max_i32_e32 v70, v55, v60
	v_min_i32_e32 v55, v55, v60
	v_max_i32_e32 v60, v62, v53
	v_min_i32_e32 v53, v62, v53
	v_max_i32_e32 v62, v68, v58
	v_min_i32_e32 v58, v68, v58
	v_max_i32_e32 v68, v67, v59
	v_min_i32_e32 v59, v67, v59
	v_max_i32_e32 v67, v54, v52
	v_min_i32_e32 v52, v54, v52
	v_max_i32_e32 v54, v61, v56
	s_waitcnt lgkmcnt(3)
	v_max_i32_e32 v40, v40, v71
	s_waitcnt lgkmcnt(2)
	v_max_i32_e32 v30, v30, v72
	s_waitcnt lgkmcnt(1)
	v_max_i32_e32 v37, v37, v73
	s_waitcnt lgkmcnt(0)
	v_max_i32_e32 v28, v28, v74
	v_max_i32_e32 v41, v41, v66
	v_max_i32_e32 v32, v32, v65
	v_max_i32_e32 v44, v44, v64
	v_max_i32_e32 v46, v46, v63
	v_max_i32_e32 v34, v34, v49
	v_max_i32_e32 v39, v39, v48
	v_max_i32_e32 v29, v29, v47
	v_max_i32_e32 v27, v27, v42
	v_min_i32_e32 v56, v61, v56
	v_max_i32_e32 v61, v33, v60
	v_min_i32_e32 v33, v33, v60
	v_max_i32_e32 v60, v36, v53
	v_min_i32_e32 v36, v36, v53
	v_max_i32_e32 v53, v62, v68
	v_min_i32_e32 v62, v62, v68
	v_max_i32_e32 v68, v58, v59
	v_min_i32_e32 v58, v58, v59
	v_max_i32_e32 v59, v67, v54
	v_max_i32_e32 v42, v38, v41
	v_min_i32_e32 v38, v38, v41
	v_max_i32_e32 v41, v40, v32
	v_min_i32_e32 v32, v40, v32
	v_max_i32_e32 v40, v30, v44
	v_min_i32_e32 v30, v30, v44
	v_max_i32_e32 v44, v37, v46
	v_min_i32_e32 v37, v37, v46
	v_max_i32_e32 v46, v28, v34
	v_min_i32_e32 v28, v28, v34
	v_max_i32_e32 v34, v45, v39
	v_min_i32_e32 v39, v45, v39
	v_max_i32_e32 v45, v43, v29
	v_min_i32_e32 v29, v43, v29
	v_max_i32_e32 v43, v35, v27
	v_min_i32_e32 v27, v35, v27
	v_min_i32_e32 v54, v67, v54
	v_max_i32_e32 v67, v52, v56
	v_max_i32_e32 v71, v70, v36
	v_min_i32_e32 v36, v70, v36
	v_max_i32_e32 v70, v59, v55
	v_min_i32_e32 v55, v59, v55
	v_max_i32_e32 v35, v42, v46
	v_min_i32_e32 v42, v42, v46
	v_max_i32_e32 v46, v41, v34
	v_min_i32_e32 v34, v41, v34
	v_max_i32_e32 v41, v40, v45
	v_min_i32_e32 v40, v40, v45
	v_max_i32_e32 v45, v44, v43
	v_min_i32_e32 v43, v44, v43
; #define CAND(a, b) (int)((__float_as_uint(__int_as_float(top[0][a]) + __int_as_float(top[1][b])) | 255u) - (unsigned)((a) * 16 + (b)))
; __device__ __forceinline__ void route_task(int task, int tl0, const bf16* QP  , const LAS bf16* KHL, LAS unsigned short* EL, LAS float* GL, int lane) {
;     ...
;         sort16_desc(gk);
;         merge16_desc(bk, gk);
;     }
;     {
;         const int c14 = CAND(14, 0), c15 = CAND(15, 0);
;         const int n14 = max(bk[14], c14), n15 = max(min(bk[14], c14), max(bk[15], c15));
;         bk[14] = n14; bk[15] = n15;
;     }
;     ...
;     int my[8];
; #pragma unroll
;     for (int i = 0; i < 8; ++i) { int lo_ = bk[i], hi_ = bk[8 + i]; asm volatile("" : "+v"(lo_), "+v"(hi_)); my[i] = hi ? hi_ : lo_; }
;     int bv[8];
; #pragma unroll
;     for (int i = 0; i < 8; ++i) {
;         const unsigned cd = 255u - ((unsigned)my[i] & 255u), ca = cd >> 4, cb = cd & 15u;
;         const unsigned wa = (ca >> 2) == 0u ? P1[0] : (ca >> 2) == 1u ? P1[1] : (ca >> 2) == 2u ? P1[2] : P1[3];
;         const unsigned wb = (cb >> 2) == 0u ? P2[0] : (cb >> 2) == 1u ? P2[1] : (cb >> 2) == 2u ? P2[2] : P2[3];
;         bv[i] = (int)((((wa >> (8u * (ca & 3u))) & 255u) << 7) | ((wb >> (8u * (cb & 3u))) & 255u));
	v_max_i32_e32 v44, v38, v28
	v_min_i32_e32 v28, v38, v28
	v_max_i32_e32 v38, v32, v39
	v_min_i32_e32 v32, v32, v39
	v_max_i32_e32 v39, v30, v29
	v_min_i32_e32 v29, v30, v29
	v_max_i32_e32 v30, v37, v27
	v_min_i32_e32 v27, v37, v27
	v_min_i32_e32 v52, v52, v56
	v_min_i32_e32 v56, v60, v33
	v_max_i32_e32 v59, v67, v54
	v_min_i32_e32 v54, v67, v54
	v_max_i32_e32 v67, v71, v53
	v_min_i32_e32 v53, v71, v53
	v_max_i32_e32 v71, v36, v62
	v_min_i32_e32 v36, v36, v62
	v_max_i32_e32 v62, v68, v70
	v_min_i32_e32 v68, v68, v70
	v_max_i32_e32 v70, v58, v55
	v_max_i32_e32 v37, v35, v41
	v_min_i32_e32 v35, v35, v41
	v_max_i32_e32 v41, v46, v45
	v_min_i32_e32 v45, v46, v45
	v_max_i32_e32 v46, v42, v40
	v_min_i32_e32 v40, v42, v40
	v_max_i32_e32 v42, v34, v43
	v_min_i32_e32 v34, v34, v43
	v_max_i32_e32 v43, v44, v39
	v_min_i32_e32 v39, v44, v39
	v_max_i32_e32 v44, v38, v30
	v_min_i32_e32 v30, v38, v30
	v_max_i32_e32 v38, v28, v29
	v_min_i32_e32 v28, v28, v29
	v_max_i32_e32 v29, v32, v27
	v_min_i32_e32 v27, v32, v27
	v_min_i32_e32 v55, v58, v55
	v_max_i32_e32 v58, v67, v56
	v_min_i32_e32 v56, v67, v56
	v_max_i32_e32 v67, v53, v71
	v_min_i32_e32 v53, v53, v71
	v_max_i32_e32 v71, v62, v36
	v_min_i32_e32 v36, v62, v36
	v_max_i32_e32 v62, v68, v70
	v_min_i32_e32 v32, v37, v41
	v_min_i32_e32 v47, v35, v45
	v_min_i32_e32 v48, v46, v42
	v_min_i32_e32 v49, v40, v34
	v_min_i32_e32 v63, v43, v44
	v_min_i32_e32 v64, v39, v30
	v_min_i32_e32 v65, v38, v29
	v_min_i32_e32 v66, v28, v27
	v_min_i32_e32 v68, v68, v70
	v_max_i32_e32 v70, v59, v55
	v_min_i32_e32 v55, v59, v55
	v_min_i32_e32 v59, v53, v71
	v_min_i32_e32 v72, v36, v62
	v_max3_i32 v31, v37, v41, v31
	v_max_i32_e32 v32, v32, v52
	v_max3_i32 v35, v35, v45, v54
	v_max_i32_e32 v37, v47, v55
	v_max3_i32 v41, v46, v42, v70
	v_max_i32_e32 v42, v48, v68
	v_max3_i32 v34, v40, v34, v72
	v_max3_i32 v36, v49, v36, v62
	v_max3_i32 v40, v43, v44, v59
	v_max3_i32 v43, v63, v53, v71
	v_max3_i32 v30, v39, v30, v67
	v_max_i32_e32 v39, v64, v56
	v_max3_i32 v29, v38, v29, v58
	v_max3_i32 v33, v65, v60, v33
	v_max3_i32 v27, v28, v27, v61
	v_max3_i32 v28, v66, v57, v69
	v_max_i32_e32 v38, v31, v40
	v_min_i32_e32 v31, v31, v40
	v_max_i32_e32 v40, v32, v43
	v_min_i32_e32 v32, v32, v43
	v_max_i32_e32 v43, v35, v30
	v_min_i32_e32 v30, v35, v30
	v_max_i32_e32 v35, v37, v39
	v_min_i32_e32 v37, v37, v39
	v_max_i32_e32 v39, v41, v29
	v_min_i32_e32 v29, v41, v29
	v_max_i32_e32 v41, v42, v33
	v_min_i32_e32 v33, v42, v33
	v_max_i32_e32 v42, v34, v27
	v_min_i32_e32 v27, v34, v27
	v_max_i32_e32 v34, v36, v28
	v_min_i32_e32 v28, v36, v28
	v_max_i32_e32 v36, v38, v39
	v_min_i32_e32 v38, v38, v39
	v_max_i32_e32 v39, v40, v41
	v_min_i32_e32 v40, v40, v41
	v_max_i32_e32 v41, v43, v42
	v_min_i32_e32 v42, v43, v42
	v_max_i32_e32 v43, v35, v34
	v_min_i32_e32 v34, v35, v34
	v_max_i32_e32 v35, v31, v29
	v_min_i32_e32 v29, v31, v29
	v_max_i32_e32 v31, v32, v33
	v_min_i32_e32 v32, v32, v33
	v_max_i32_e32 v33, v30, v27
	v_min_i32_e32 v27, v30, v27
	v_max_i32_e32 v30, v37, v28
	v_min_i32_e32 v28, v37, v28
	v_max_i32_e32 v37, v36, v41
	v_min_i32_e32 v36, v36, v41
	v_max_i32_e32 v41, v39, v43
	v_min_i32_e32 v39, v39, v43
	v_max_i32_e32 v43, v38, v42
	v_min_i32_e32 v38, v38, v42
	v_max_i32_e32 v42, v40, v34
	v_min_i32_e32 v34, v40, v34
	v_max_i32_e32 v40, v35, v33
	v_min_i32_e32 v33, v35, v33
	v_max_i32_e32 v35, v31, v30
	v_min_i32_e32 v30, v31, v30
	v_max_i32_e32 v31, v29, v27
	v_min_i32_e32 v27, v29, v27
	v_max_i32_e32 v29, v32, v28
	v_min_i32_e32 v28, v32, v28
	v_max_i32_e32 v32, v37, v41
	v_min_i32_e32 v37, v37, v41
	v_max_i32_e32 v41, v36, v39
	v_min_i32_e32 v36, v36, v39
	v_max_i32_e32 v39, v43, v42
	v_min_i32_e32 v42, v43, v42
	v_max_i32_e32 v43, v38, v34
	v_min_i32_e32 v34, v38, v34
	v_max_i32_e32 v38, v40, v35
	v_min_i32_e32 v35, v40, v35
	v_max_i32_e32 v40, v33, v30
	v_min_i32_e32 v30, v33, v30
	v_max_i32_e32 v33, v31, v29
	v_min_i32_e32 v29, v31, v29
	v_max_i32_e32 v31, v27, v28
	v_min_i32_e32 v27, v27, v28
	v_add_f32_e32 v28, v51, v26
	v_or_b32_e32 v28, 0xff, v28
	v_add_f32_e32 v26, v50, v26
	v_add_u32_e32 v28, 0xffffff20, v28
	v_or_b32_e32 v26, 0xff, v26
	v_add_u32_e32 v26, 0xffffff10, v26
	v_max_i32_e32 v44, v31, v28
	v_min_i32_e32 v28, v31, v28
	v_max3_i32 v26, v28, v27, v26
	v_mov_b32_e32 v27, v32
	s_nop 0
	v_cndmask_b32_e64 v27, v38, v27, s[6:7]
	v_not_b32_e32 v28, v27
	v_bfe_u32 v45, v28, 6, 2
	v_cmp_eq_u32_e32 vcc, 2, v45
	v_cndmask_b32_e64 v34, v26, v34, s[6:7]
	v_bitop3_b32 v26, v27, s3, v27 bitop3:0xc
	v_cndmask_b32_e32 v46, v25, v23, vcc
	v_cmp_eq_u32_e32 vcc, 1, v45
	v_cndmask_b32_e64 v31, v35, v37, s[6:7]
	v_not_b32_e32 v35, v31
	v_cndmask_b32_e32 v45, v46, v21, vcc
	v_cmp_gt_u32_e32 vcc, 64, v26
	v_cndmask_b32_e64 v37, v40, v41, s[6:7]
	v_cndmask_b32_e64 v41, v44, v43, s[6:7]
	v_cndmask_b32_e32 v26, v45, v19, vcc
	v_bfe_u32 v45, v28, 2, 2
	v_cmp_eq_u32_e32 vcc, 2, v45
	v_bitop3_b32 v44, v27, 15, v27 bitop3:0xc
	v_bfe_u32 v47, v35, 6, 2
	v_cndmask_b32_e32 v46, v24, v22, vcc
	v_cmp_eq_u32_e32 vcc, 1, v45
	v_not_b32_e32 v38, v37
	v_bfe_u32 v49, v38, 6, 2
	v_cndmask_b32_e32 v45, v46, v20, vcc
	v_cmp_gt_u32_e32 vcc, 4, v44
	v_bitop3_b32 v46, v31, 15, v31 bitop3:0xc
	v_cndmask_b32_e64 v30, v30, v36, s[6:7]
	v_cndmask_b32_e32 v44, v45, v18, vcc
	v_cmp_eq_u32_e32 vcc, 2, v47
	v_bitop3_b32 v45, v31, s3, v31 bitop3:0xc
	v_not_b32_e32 v36, v30
	v_cndmask_b32_e32 v48, v25, v23, vcc
	v_cmp_eq_u32_e32 vcc, 1, v47
	v_bfe_u32 v51, v36, 6, 2
	v_cndmask_b32_e64 v33, v33, v39, s[6:7]
	v_cndmask_b32_e32 v47, v48, v21, vcc
	v_cmp_gt_u32_e32 vcc, 64, v45
	v_not_b32_e32 v39, v33
	v_bfe_u32 v53, v39, 6, 2
	v_cndmask_b32_e32 v45, v47, v19, vcc
; __device__ __forceinline__ void route_task(int task, int tl0, const bf16* QP  , const LAS bf16* KHL, LAS unsigned short* EL, LAS float* GL, int lane) {
;     ...
;     for (int i = 0; i < 8; ++i) {
;         const unsigned cd = 255u - ((unsigned)my[i] & 255u), ca = cd >> 4, cb = cd & 15u;
;         const unsigned wa = (ca >> 2) == 0u ? P1[0] : (ca >> 2) == 1u ? P1[1] : (ca >> 2) == 2u ? P1[2] : P1[3];
;         const unsigned wb = (cb >> 2) == 0u ? P2[0] : (cb >> 2) == 1u ? P2[1] : (cb >> 2) == 2u ? P2[2] : P2[3];
;         bv[i] = (int)((((wa >> (8u * (ca & 3u))) & 255u) << 7) | ((wb >> (8u * (cb & 3u))) & 255u));
;     }
;     float e[8], se = 0.f;
; #pragma unroll
;     for (int i = 0; i < 8; ++i) { e[i] = __expf(__int_as_float(my[i]) - __int_as_float(bk[0])); se += e[i]; }
;     se += __shfl_xor(se, 32);
	v_bfe_u32 v47, v35, 2, 2
	v_cmp_eq_u32_e32 vcc, 2, v47
	v_cndmask_b32_e64 v29, v29, v42, s[6:7]
	v_not_b32_e32 v40, v29
	v_cndmask_b32_e32 v48, v24, v22, vcc
	v_cmp_eq_u32_e32 vcc, 1, v47
	v_bfe_u32 v55, v40, 6, 2
	v_not_b32_e32 v42, v41
	v_cndmask_b32_e32 v47, v48, v20, vcc
	v_cmp_gt_u32_e32 vcc, 4, v46
	v_bitop3_b32 v48, v37, 15, v37 bitop3:0xc
	v_bfe_u32 v57, v42, 6, 2
	v_cndmask_b32_e32 v46, v47, v18, vcc
	v_cmp_eq_u32_e32 vcc, 2, v49
	v_bitop3_b32 v47, v37, s3, v37 bitop3:0xc
	v_not_b32_e32 v43, v34
	v_cndmask_b32_e32 v50, v25, v23, vcc
	v_cmp_eq_u32_e32 vcc, 1, v49
	v_bfe_u32 v59, v43, 6, 2
	v_or_b32_e32 v82, s10, v88
	v_cndmask_b32_e32 v49, v50, v21, vcc
	v_cmp_gt_u32_e32 vcc, 64, v47
	s_nop 1
	v_cndmask_b32_e32 v47, v49, v19, vcc
	v_bfe_u32 v49, v38, 2, 2
	v_cmp_eq_u32_e32 vcc, 2, v49
	s_nop 1
	v_cndmask_b32_e32 v50, v24, v22, vcc
	v_cmp_eq_u32_e32 vcc, 1, v49
	s_nop 1
	v_cndmask_b32_e32 v49, v50, v20, vcc
	v_cmp_gt_u32_e32 vcc, 4, v48
	v_bitop3_b32 v50, v30, 15, v30 bitop3:0xc
	s_nop 0
	v_cndmask_b32_e32 v48, v49, v18, vcc
	v_cmp_eq_u32_e32 vcc, 2, v51
	v_bitop3_b32 v49, v30, s3, v30 bitop3:0xc
	s_nop 0
	v_cndmask_b32_e32 v52, v25, v23, vcc
	v_cmp_eq_u32_e32 vcc, 1, v51
	s_nop 1
	v_cndmask_b32_e32 v51, v52, v21, vcc
	v_cmp_gt_u32_e32 vcc, 64, v49
	s_nop 1
	v_cndmask_b32_e32 v49, v51, v19, vcc
	v_bfe_u32 v51, v36, 2, 2
	v_cmp_eq_u32_e32 vcc, 2, v51
	s_nop 1
	v_cndmask_b32_e32 v52, v24, v22, vcc
	v_cmp_eq_u32_e32 vcc, 1, v51
	s_nop 1
	v_cndmask_b32_e32 v51, v52, v20, vcc
	v_cmp_gt_u32_e32 vcc, 4, v50
	v_bitop3_b32 v52, v33, 15, v33 bitop3:0xc
	s_nop 0
	v_cndmask_b32_e32 v50, v51, v18, vcc
	v_cmp_eq_u32_e32 vcc, 2, v53
	v_bitop3_b32 v51, v33, s3, v33 bitop3:0xc
	s_nop 0
	v_cndmask_b32_e32 v54, v25, v23, vcc
	v_cmp_eq_u32_e32 vcc, 1, v53
	s_nop 1
	v_cndmask_b32_e32 v53, v54, v21, vcc
	v_cmp_gt_u32_e32 vcc, 64, v51
	s_nop 1
	v_cndmask_b32_e32 v51, v53, v19, vcc
	v_bfe_u32 v53, v39, 2, 2
	v_cmp_eq_u32_e32 vcc, 2, v53
	s_nop 1
	v_cndmask_b32_e32 v54, v24, v22, vcc
	v_cmp_eq_u32_e32 vcc, 1, v53
	s_nop 1
	v_cndmask_b32_e32 v53, v54, v20, vcc
	v_cmp_gt_u32_e32 vcc, 4, v52
	v_bitop3_b32 v54, v29, 15, v29 bitop3:0xc
	s_nop 0
	v_cndmask_b32_e32 v52, v53, v18, vcc
	v_cmp_eq_u32_e32 vcc, 2, v55
	v_bitop3_b32 v53, v29, s3, v29 bitop3:0xc
	s_nop 0
	v_cndmask_b32_e32 v56, v25, v23, vcc
	v_cmp_eq_u32_e32 vcc, 1, v55
	s_nop 1
	v_cndmask_b32_e32 v55, v56, v21, vcc
	v_cmp_gt_u32_e32 vcc, 64, v53
	s_nop 1
	v_cndmask_b32_e32 v53, v55, v19, vcc
	v_bfe_u32 v55, v40, 2, 2
	v_cmp_eq_u32_e32 vcc, 2, v55
	s_nop 1
	v_cndmask_b32_e32 v56, v24, v22, vcc
	v_cmp_eq_u32_e32 vcc, 1, v55
	s_nop 1
	v_cndmask_b32_e32 v55, v56, v20, vcc
	v_cmp_gt_u32_e32 vcc, 4, v54
	v_bitop3_b32 v56, v41, 15, v41 bitop3:0xc
	s_nop 0
	v_cndmask_b32_e32 v54, v55, v18, vcc
	v_cmp_eq_u32_e32 vcc, 2, v57
	v_bitop3_b32 v55, v41, s3, v41 bitop3:0xc
	s_nop 0
	v_cndmask_b32_e32 v58, v25, v23, vcc
	v_cmp_eq_u32_e32 vcc, 1, v57
	s_nop 1
	v_cndmask_b32_e32 v57, v58, v21, vcc
	v_cmp_gt_u32_e32 vcc, 64, v55
	s_nop 1
	v_cndmask_b32_e32 v55, v57, v19, vcc
	v_bfe_u32 v57, v42, 2, 2
	v_cmp_eq_u32_e32 vcc, 2, v57
	s_nop 1
	v_cndmask_b32_e32 v58, v24, v22, vcc
	v_cmp_eq_u32_e32 vcc, 1, v57
	s_nop 1
	v_cndmask_b32_e32 v57, v58, v20, vcc
	v_cmp_gt_u32_e32 vcc, 4, v56
	v_bitop3_b32 v58, v34, 15, v34 bitop3:0xc
	s_nop 0
	v_cndmask_b32_e32 v56, v57, v18, vcc
	v_cmp_eq_u32_e32 vcc, 2, v59
	v_bitop3_b32 v57, v34, s3, v34 bitop3:0xc
	s_nop 0
	v_cndmask_b32_e32 v23, v25, v23, vcc
	v_cmp_eq_u32_e32 vcc, 1, v59
	v_sub_f32_e32 v25, v30, v32
	v_mul_f32_e32 v25, 0x3fb8aa3b, v25
	v_cndmask_b32_e32 v21, v23, v21, vcc
	v_cmp_gt_u32_e32 vcc, 64, v57
	v_lshrrev_b32_e32 v23, 1, v39
	v_and_b32_e32 v23, 24, v23
	v_cndmask_b32_e32 v19, v21, v19, vcc
	v_bfe_u32 v21, v43, 2, 2
	v_cmp_eq_u32_e32 vcc, 2, v21
	v_lshrrev_b32_e32 v23, v23, v51
	v_lshlrev_b32_e32 v23, 7, v23
	v_cndmask_b32_e32 v22, v24, v22, vcc
	v_cmp_eq_u32_e32 vcc, 1, v21
	v_lshrrev_b32_e32 v21, 1, v42
	v_and_b32_e32 v21, 24, v21
	v_cndmask_b32_e32 v20, v22, v20, vcc
	v_cmp_gt_u32_e32 vcc, 4, v58
	v_lshrrev_b32_e32 v21, v21, v55
	v_lshrrev_b32_e32 v22, 1, v40
	v_cndmask_b32_e32 v18, v20, v18, vcc
	v_lshlrev_b32_e32 v20, 3, v42
	v_lshlrev_b32_e32 v21, 7, v21
	v_and_b32_e32 v22, 24, v22
	v_lshrrev_b32_e32 v20, v20, v56
	v_and_b32_e32 v21, 0x7f80, v21
	v_lshrrev_b32_e32 v22, v22, v53
	v_and_or_b32 v21, v20, s3, v21
	v_lshlrev_b32_e32 v20, 3, v40
	v_lshlrev_b32_e32 v22, 7, v22
	v_lshrrev_b32_e32 v20, v20, v54
	v_and_b32_e32 v22, 0x7f80, v22
	v_and_or_b32 v20, v20, s3, v22
	v_lshlrev_b32_e32 v22, 3, v39
	v_lshrrev_b32_e32 v22, v22, v52
	v_and_b32_e32 v23, 0x7f80, v23
	v_and_or_b32 v39, v22, s3, v23
	v_lshrrev_b32_e32 v23, 1, v36
	v_and_b32_e32 v23, 24, v23
	v_lshrrev_b32_e32 v23, v23, v49
	v_lshlrev_b32_e32 v22, 3, v36
	v_lshlrev_b32_e32 v23, 7, v23
	v_lshrrev_b32_e32 v22, v22, v50
	v_and_b32_e32 v23, 0x7f80, v23
	v_and_or_b32 v36, v22, s3, v23
	v_lshrrev_b32_e32 v23, 1, v38
	v_and_b32_e32 v23, 24, v23
	v_lshrrev_b32_e32 v23, v23, v47
	v_lshlrev_b32_e32 v22, 3, v38
	v_lshlrev_b32_e32 v23, 7, v23
	v_lshrrev_b32_e32 v22, v22, v48
	v_and_b32_e32 v23, 0x7f80, v23
	v_and_or_b32 v38, v22, s3, v23
	v_lshrrev_b32_e32 v23, 1, v35
	v_and_b32_e32 v23, 24, v23
	v_lshrrev_b32_e32 v23, v23, v45
	v_lshlrev_b32_e32 v22, 3, v35
	v_lshlrev_b32_e32 v23, 7, v23
	v_lshrrev_b32_e32 v22, v22, v46
	v_and_b32_e32 v23, 0x7f80, v23
	v_and_or_b32 v35, v22, s3, v23
	v_lshrrev_b32_e32 v23, 1, v28
	v_and_b32_e32 v23, 24, v23
	v_lshrrev_b32_e32 v23, v23, v26
	v_lshlrev_b32_e32 v22, 3, v28
	v_lshlrev_b32_e32 v23, 7, v23
	v_lshrrev_b32_e32 v22, v22, v44
	v_and_b32_e32 v23, 0x7f80, v23
	v_and_or_b32 v40, v22, s3, v23
	v_sub_f32_e32 v22, v27, v32
	v_mul_f32_e32 v22, 0x3fb8aa3b, v22
	v_sub_f32_e32 v23, v31, v32
	v_exp_f32_e32 v22, v22
	v_mul_f32_e32 v23, 0x3fb8aa3b, v23
	v_sub_f32_e32 v24, v37, v32
	v_exp_f32_e32 v23, v23
	v_mul_f32_e32 v24, 0x3fb8aa3b, v24
	v_exp_f32_e32 v24, v24
	v_exp_f32_e32 v25, v25
	v_add_f32_e32 v26, 0, v22
	v_add_f32_e32 v26, v23, v26
	v_add_f32_e32 v26, v24, v26
	v_add_f32_e32 v30, v25, v26
	v_sub_f32_e32 v26, v33, v32
	v_mul_f32_e32 v26, 0x3fb8aa3b, v26
	v_sub_f32_e32 v27, v29, v32
	v_exp_f32_e32 v26, v26
	v_mul_f32_e32 v27, 0x3fb8aa3b, v27
	v_sub_f32_e32 v28, v41, v32
	v_exp_f32_e32 v27, v27
	v_mul_f32_e32 v28, 0x3fb8aa3b, v28
	v_sub_f32_e32 v29, v34, v32
	v_exp_f32_e32 v28, v28
	v_mul_f32_e32 v29, 0x3fb8aa3b, v29
	v_exp_f32_e32 v29, v29
	v_add_f32_e32 v30, v26, v30
	v_add_f32_e32 v30, v27, v30
	v_add_f32_e32 v30, v28, v30
	v_add_f32_e32 v30, v29, v30
	ds_bpermute_b32 v31, v123, v30
	v_lshrrev_b32_e32 v42, 1, v43
	v_and_b32_e32 v32, 24, v42
	v_lshrrev_b32_e32 v19, v32, v19
	v_lshlrev_b32_e32 v19, 7, v19
	s_waitcnt lgkmcnt(0)
; #define LAS __attribute__((address_space(3)))
; #define MFMA32(a, b, c) __builtin_amdgcn_mfma_f32_32x32x16_bf16((a), (b), (c), 0, 0, 0)
; __device__ __forceinline__ void route_task(int task, int tl0, const bf16* QP  , const LAS bf16* KHL, LAS unsigned short* EL, LAS float* GL, int lane) {
;     const int r = lane & 31, hi = lane >> 5, t = 4 * task + (r >> 3), head = r & 7;
;     int top[2][16]; bf16x8 qa[2][4];
;     { unsigned qo = (unsigned)t * (unsigned)D + (unsigned)(head * 128 + 8 * hi); asm volatile("" : "+v"(qo)); const bf16* qp = QP + qo;
; #pragma unroll
;       for (int hf = 0; hf < 2; ++hf)
; #pragma unroll
;         for (int ks = 0; ks < 4; ++ks) qa[hf][ks] = ldg8(qp + 64 * hf + 16 * ks); }
; #pragma unroll
;     for (int half = 0; half < 2; ++half) {
;         int cur[16];
; #pragma unroll
;         for (int kt = 0; kt < 4; ++kt) {
;             f32x16 X;
; #pragma unroll
;             for (int i = 0; i < 16; ++i) X[i] = 8.f;
;             const LAS bf16* khp = KHL + (half * 128 + 32 * kt + r) * 72 + 8 * hi;
; #pragma unroll
;             for (int ks = 0; ks < 4; ++ks) {
;                 const bf16x8 kh = lds8(khp + 16 * ks);
;                 X = MFMA32(kh, qa[half][ks], X);
;             }
;             int grp[16];
; #pragma unroll
;             for (int i = 0; i < 16; ++i) grp[i] = (int)((__float_as_uint(X[i]) | 127u) - (unsigned)(32 * kt + (i & 3) + 8 * (i >> 2)));
;             sort16_desc(grp);
;             if (kt == 0) {
; #pragma unroll
;                 for (int i = 0; i < 16; ++i) cur[i] = grp[i];
;             } else merge16_desc(cur, grp);
;     ...
;     const float inv = 1.f / se;
;     {
;         int l2 = lane; asm volatile("" : "+v"(l2));
;         const int o2 = (tl0 + ((l2 & 31) >> 3)) * 128 + (l2 & 7) * 16 + 8 * (l2 >> 5);
;         LAS v4u* ip = (LAS v4u*)(EL + o2); typedef float f4v __attribute__((ext_vector_type(4))); LAS f4v* gp = (LAS f4v*)(GL + o2);
;         ip[0] = (v4u){(unsigned)bv[0] | ((unsigned)bv[1] << 16), (unsigned)bv[2] | ((unsigned)bv[3] << 16), (unsigned)bv[4] | ((unsigned)bv[5] << 16), (unsigned)bv[6] | ((unsigned)bv[7] << 16)};
;         gp[0] = (f4v){e[0] * inv, e[1] * inv, e[2] * inv, e[3] * inv}; gp[1] = (f4v){e[4] * inv, e[5] * inv, e[6] * inv, e[7] * inv};
;     }
	v_add_f32_e32 v30, v30, v31
	v_div_scale_f32 v31, s[12:13], v30, v30, 1.0
	v_rcp_f32_e32 v32, v31
	v_lshlrev_b32_e32 v33, 3, v43
	v_and_b32_e32 v19, 0x7f80, v19
	v_lshrrev_b32_e32 v18, v33, v18
	v_and_or_b32 v33, v18, s3, v19
	v_fma_f32 v18, -v31, v32, 1.0
	v_fmac_f32_e32 v32, v18, v32
	v_div_scale_f32 v18, vcc, 1.0, v30, 1.0
	v_mul_f32_e32 v19, v18, v32
	v_fma_f32 v34, -v31, v19, v18
	v_fmac_f32_e32 v19, v34, v32
	v_fma_f32 v18, -v31, v19, v18
	v_div_fmas_f32 v18, v18, v32, v19
	v_div_fixup_f32 v30, v18, v30, 1.0
	v_mov_b32_e32 v18, v1
	v_lshl_or_b32 v20, v20, 16, v39
	v_lshrrev_b32_e32 v19, 3, v18
	v_and_or_b32 v19, v19, 3, s55
	v_lshlrev_b32_e32 v31, 4, v18
	v_ashrrev_i32_e32 v18, 2, v18
	v_lshlrev_b32_e32 v19, 7, v19
	v_and_b32_e32 v31, 0x70, v31
	v_and_b32_e32 v18, -8, v18
	v_add3_u32 v18, v18, v31, v19
	v_lshl_add_u32 v31, v18, 1, s11
	v_lshl_add_u32 v32, v18, 2, s69
	v_lshl_or_b32 v18, v35, 16, v40
	v_lshl_or_b32 v19, v36, 16, v38
	v_lshl_or_b32 v21, v33, 16, v21
	ds_write_b128 v31, v[18:21]
	v_pk_mul_f32 v[20:21], v[24:25], v[30:31] op_sel_hi:[1,0]
	v_pk_mul_f32 v[18:19], v[22:23], v[30:31] op_sel_hi:[1,0]
	ds_write_b128 v32, v[18:21]
	v_pk_mul_f32 v[20:21], v[28:29], v[30:31] op_sel_hi:[1,0]
	v_pk_mul_f32 v[18:19], v[26:27], v[30:31] op_sel_hi:[1,0]
	ds_write_b128 v32, v[18:21] offset:16
	v_mov_b64_e32 v[32:33], s[30:31]
	v_lshl_add_u64 v[128:129], v[82:83], 1, s[80:81]
	global_load_dwordx4 v[78:81], v[128:129], off
	global_load_dwordx4 v[74:77], v[128:129], off offset:32
	global_load_dwordx4 v[70:73], v[128:129], off offset:64
	global_load_dwordx4 v[66:69], v[128:129], off offset:96
	ds_read_b128 v[50:53], v94
	ds_read_b128 v[54:57], v94 offset:32
	v_mov_b64_e32 v[30:31], s[28:29]
	v_mov_b64_e32 v[28:29], s[26:27]
	v_mov_b64_e32 v[26:27], s[24:25]
	v_mov_b64_e32 v[24:25], s[22:23]
	v_mov_b64_e32 v[22:23], s[20:21]
	v_mov_b64_e32 v[20:21], s[18:19]
	v_mov_b64_e32 v[18:19], s[16:17]
	s_waitcnt vmcnt(3) lgkmcnt(1)
	s_nop 0
	v_mfma_f32_32x32x16_bf16 v[34:49], v[50:53], v[78:81], v[18:33]
	ds_read_b128 v[50:53], v94 offset:64
	ds_read_b128 v[124:127], v94 offset:96
	s_waitcnt vmcnt(2) lgkmcnt(2)
	v_mfma_f32_32x32x16_bf16 v[34:49], v[54:57], v[74:77], v[34:49]
	s_waitcnt vmcnt(1) lgkmcnt(1)
	v_mfma_f32_32x32x16_bf16 v[34:49], v[50:53], v[70:73], v[34:49]
	global_load_dwordx4 v[62:65], v[128:129], off offset:128
	global_load_dwordx4 v[58:61], v[128:129], off offset:160
	global_load_dwordx4 v[54:57], v[128:129], off offset:192
	global_load_dwordx4 v[50:53], v[128:129], off offset:224
	s_waitcnt vmcnt(4) lgkmcnt(0)
	v_mfma_f32_32x32x16_bf16 v[34:49], v[124:127], v[66:69], v[34:49]
	s_nop 11
	v_or_b32_e32 v37, 0x7f, v37
	v_or_b32_e32 v48, 0x7f, v48
	v_or_b32_e32 v38, 0x7f, v38
	v_or_b32_e32 v42, 0x7f, v42
	v_or_b32_e32 v47, 0x7f, v47
	v_or_b32_e32 v39, 0x7f, v39
	v_or_b32_e32 v40, 0x7f, v40
	v_or_b32_e32 v43, 0x7f, v43
	v_or_b32_e32 v44, 0x7f, v44
	v_or_b32_e32 v36, 0x7f, v36
	v_or_b32_e32 v49, 0x7f, v49
	v_or_b32_e32 v41, 0x7f, v41
	v_or_b32_e32 v45, 0x7f, v45
	v_or_b32_e32 v35, 0x7f, v35
	v_or_b32_e32 v46, 0x7f, v46
	v_add_u32_e32 v37, -3, v37
	v_subrev_u32_e32 v48, 26, v48
	v_add_u32_e32 v38, -8, v38
	v_add_u32_e32 v42, -16, v42
	v_or_b32_e32 v34, 0x7f, v34
	v_subrev_u32_e32 v47, 25, v47
	v_add_u32_e32 v39, -9, v39
	v_add_u32_e32 v40, -10, v40
	v_subrev_u32_e32 v43, 17, v43
	v_subrev_u32_e32 v44, 18, v44
	v_add_u32_e32 v36, -2, v36
	v_subrev_u32_e32 v49, 27, v49
	v_add_u32_e32 v41, -11, v41
	v_subrev_u32_e32 v45, 19, v45
	v_add_u32_e32 v35, -1, v35
	v_subrev_u32_e32 v46, 24, v46
	v_max_i32_e32 v82, v37, v48
	v_max_i32_e32 v124, v38, v42
	v_max_i32_e32 v126, v34, v47
	v_max_i32_e32 v127, v39, v40
	v_min_i32_e32 v130, v43, v44
	v_min_i32_e32 v131, v36, v49
	v_min_i32_e32 v133, v41, v45
	v_min_i32_e32 v134, v35, v46
	v_min_i32_e32 v39, v39, v40
	v_min_i32_e32 v34, v34, v47
	v_min_i32_e32 v38, v38, v42
	v_min_i32_e32 v37, v37, v48
	v_max_i32_e32 v35, v35, v46
	v_max_i32_e32 v41, v41, v45
	v_max_i32_e32 v36, v36, v49
	v_max_i32_e32 v43, v43, v44
	v_min_i32_e32 v125, v82, v124
	v_min_i32_e32 v128, v126, v127
	v_max_i32_e32 v132, v130, v131
	v_max_i32_e32 v135, v133, v134
	v_max_i32_e32 v40, v39, v34
	v_max_i32_e32 v42, v38, v37
	v_min_i32_e32 v45, v35, v41
	v_min_i32_e32 v44, v36, v43
	v_min_i32_e32 v129, v125, v128
	v_max_i32_e32 v47, v40, v42
	v_max_i32_e32 v46, v45, v44
	v_min_i32_e32 v40, v40, v42
	v_min_i32_e32 v42, v45, v44
	v_max_i32_e32 v45, v125, v128
	v_max_i32_e32 v125, v132, v135
	v_min_i32_e32 v128, v45, v125
	v_min_i32_e32 v34, v39, v34
	v_max_i32_e32 v39, v126, v127
	v_max_i32_e32 v35, v35, v41
	v_max_i32_e32 v41, v82, v124
	v_max_i32_e32 v148, v45, v125
	ds_read_b128 v[124:127], v95
	v_max_i32_e32 v44, v40, v42
	v_min_i32_e32 v138, v40, v42
	v_min_i32_e32 v40, v133, v134
	v_min_i32_e32 v37, v38, v37
	v_min_i32_e32 v38, v130, v131
	v_max_i32_e32 v36, v36, v43
	v_min_i32_e32 v136, v132, v135
	v_min_i32_e32 v133, v40, v34
	v_min_i32_e32 v134, v37, v38
	v_max_i32_e32 v34, v40, v34
	v_max_i32_e32 v37, v37, v38
	v_min_i32_e32 v40, v39, v35
	v_min_i32_e32 v42, v36, v41
	v_max_i32_e32 v144, v39, v35
	v_max_i32_e32 v145, v36, v41
	v_max_i32_e32 v137, v129, v136
	v_min_i32_e32 v136, v129, v136
	v_max_i32_e32 v140, v133, v134
	v_min_i32_e32 v141, v34, v37
	v_max_i32_e32 v143, v40, v42
	v_min_i32_e32 v146, v144, v145
	v_max_i32_e32 v149, v47, v46
	v_min_i32_e32 v48, v47, v46
	v_max_i32_e32 v139, v138, v136
	v_max_i32_e32 v142, v140, v141
	v_min_i32_e32 v43, v40, v42
	v_max_i32_e32 v34, v34, v37
	v_min_i32_e32 v147, v143, v146
	v_min_i32_e32 v150, v148, v149
	v_min_i32_e32 v49, v137, v48
	v_min_i32_e32 v132, v44, v128
	v_max_i32_e32 v38, v139, v142
	v_min_i32_e32 v37, v43, v34
	v_max_i32_e32 v34, v43, v34
	v_min_i32_e32 v35, v147, v150
	v_max_i32_e32 v39, v137, v48
	v_max_i32_e32 v40, v44, v128
	v_max_i32_e32 v135, v49, v132
	v_max_i32_e32 v82, v38, v37
	v_min_i32_e32 v36, v34, v35
	v_min_i32_e32 v41, v39, v40
	v_max_i32_e32 v129, v135, v82
	v_min_i32_e32 v42, v36, v41
	v_min_i32_e32 v137, v129, v42
	v_max_i32_e32 v159, v129, v42
	ds_read_b128 v[128:131], v95 offset:32
	v_min_i32_e32 v82, v135, v82
	v_min_i32_e32 v132, v49, v132
	v_min_i32_e32 v135, v38, v37
	v_max_i32_e32 v154, v34, v35
	v_max_i32_e32 v155, v39, v40
	v_max_i32_e32 v157, v36, v41
	s_waitcnt lgkmcnt(1)
; #define LAS __attribute__((address_space(3)))
; #define MFMA32(a, b, c) __builtin_amdgcn_mfma_f32_32x32x16_bf16((a), (b), (c), 0, 0, 0)
; __device__ __forceinline__ void route_task(int task, int tl0, const bf16* QP  , const LAS bf16* KHL, LAS unsigned short* EL, LAS float* GL, int lane) {
;     ...
;         for (int kt = 0; kt < 4; ++kt) {
;             f32x16 X;
; #pragma unroll
;             for (int i = 0; i < 16; ++i) X[i] = 8.f;
;             const LAS bf16* khp = KHL + (half * 128 + 32 * kt + r) * 72 + 8 * hi;
; #pragma unroll
;             for (int ks = 0; ks < 4; ++ks) {
;                 const bf16x8 kh = lds8(khp + 16 * ks);
;                 X = MFMA32(kh, qa[half][ks], X);
;             }
;             int grp[16];
; #pragma unroll
;             for (int i = 0; i < 16; ++i) grp[i] = (int)((__float_as_uint(X[i]) | 127u) - (unsigned)(32 * kt + (i & 3) + 8 * (i >> 2)));
;             sort16_desc(grp);
;             if (kt == 0) {
; #pragma unroll
;                 for (int i = 0; i < 16; ++i) cur[i] = grp[i];
;             } else merge16_desc(cur, grp);
	v_mfma_f32_32x32x16_bf16 v[34:49], v[124:127], v[78:81], v[18:33]
	ds_read_b128 v[124:127], v95 offset:64
	v_max_i32_e32 v151, v132, v135
	v_max_i32_e32 v152, v82, v151
	v_min_i32_e32 v136, v138, v136
	v_min_i32_e32 v138, v140, v141
	v_min_i32_e32 v82, v82, v151
	v_max_i32_e32 v147, v147, v150
	s_waitcnt lgkmcnt(1)
	v_mfma_f32_32x32x16_bf16 v[34:49], v[128:131], v[74:77], v[34:49]
	ds_read_b128 v[128:131], v95 offset:96
	v_max_i32_e32 v143, v143, v146
	v_min_i32_e32 v133, v133, v134
	v_min_i32_e32 v156, v154, v155
	v_max_i32_e32 v140, v136, v138
	v_min_i32_e32 v139, v139, v142
	v_max_i32_e32 v142, v154, v155
	s_waitcnt lgkmcnt(1)
	v_mfma_f32_32x32x16_bf16 v[34:49], v[124:127], v[70:73], v[34:49]
	v_max_i32_e32 v124, v148, v149
	v_min_i32_e32 v136, v136, v138
	v_max_i32_e32 v141, v140, v139
	v_min_i32_e32 v139, v140, v139
	v_min_i32_e32 v125, v143, v124
	v_min_i32_e32 v158, v156, v157
	v_min_i32_e32 v132, v132, v135
	s_waitcnt lgkmcnt(0)
	v_mfma_f32_32x32x16_bf16 v[34:49], v[128:131], v[66:69], v[34:49]
	v_min_i32_e32 v126, v147, v125
	v_min_i32_e32 v153, v137, v152
	v_min_i32_e32 v160, v158, v159
	v_min_i32_e32 v135, v141, v132
	v_min_i32_e32 v127, v142, v126
	s_nop 6
	v_or_b32_e32 v37, 0x7f, v37
	v_or_b32_e32 v48, 0x7f, v48
	v_or_b32_e32 v38, 0x7f, v38
	v_or_b32_e32 v42, 0x7f, v42
	v_or_b32_e32 v34, 0x7f, v34
	v_or_b32_e32 v47, 0x7f, v47
	v_or_b32_e32 v39, 0x7f, v39
	v_or_b32_e32 v40, 0x7f, v40
	v_or_b32_e32 v43, 0x7f, v43
	v_or_b32_e32 v44, 0x7f, v44
	v_or_b32_e32 v36, 0x7f, v36
	v_or_b32_e32 v49, 0x7f, v49
	v_or_b32_e32 v41, 0x7f, v41
	v_or_b32_e32 v45, 0x7f, v45
	v_or_b32_e32 v35, 0x7f, v35
	v_or_b32_e32 v46, 0x7f, v46
	v_subrev_u32_e32 v37, 35, v37
	v_subrev_u32_e32 v48, 58, v48
	v_subrev_u32_e32 v38, 40, v38
	v_subrev_u32_e32 v42, 48, v42
	v_subrev_u32_e32 v34, 32, v34
	v_subrev_u32_e32 v47, 57, v47
	v_subrev_u32_e32 v39, 41, v39
	v_subrev_u32_e32 v40, 42, v40
	v_subrev_u32_e32 v43, 49, v43
	v_subrev_u32_e32 v44, 50, v44
	v_subrev_u32_e32 v36, 34, v36
	v_subrev_u32_e32 v49, 59, v49
	v_subrev_u32_e32 v41, 43, v41
	v_subrev_u32_e32 v45, 51, v45
	v_subrev_u32_e32 v35, 33, v35
	v_subrev_u32_e32 v46, 56, v46
	v_max_i32_e32 v128, v37, v48
	v_max_i32_e32 v129, v38, v42
	v_max_i32_e32 v131, v34, v47
	v_max_i32_e32 v134, v39, v40
	v_min_i32_e32 v146, v43, v44
	v_min_i32_e32 v148, v36, v49
	v_min_i32_e32 v150, v41, v45
	v_min_i32_e32 v151, v35, v46
	v_min_i32_e32 v39, v39, v40
	v_min_i32_e32 v34, v34, v47
	v_min_i32_e32 v38, v38, v42
	v_min_i32_e32 v37, v37, v48
	v_max_i32_e32 v35, v35, v46
	v_max_i32_e32 v41, v41, v45
	v_max_i32_e32 v36, v36, v49
	v_max_i32_e32 v43, v43, v44
	v_min_i32_e32 v130, v128, v129
	v_min_i32_e32 v138, v131, v134
	v_max_i32_e32 v149, v146, v148
	v_max_i32_e32 v154, v150, v151
	v_max_i32_e32 v40, v39, v34
	v_max_i32_e32 v42, v38, v37
	v_min_i32_e32 v45, v35, v41
	v_min_i32_e32 v44, v36, v43
	v_min_i32_e32 v150, v150, v151
	v_min_i32_e32 v34, v39, v34
	v_min_i32_e32 v37, v38, v37
	v_min_i32_e32 v38, v146, v148
	v_max_i32_e32 v131, v131, v134
	v_max_i32_e32 v35, v35, v41
	v_max_i32_e32 v36, v36, v43
	v_max_i32_e32 v43, v128, v129
	v_min_i32_e32 v140, v130, v138
	v_min_i32_e32 v155, v149, v154
	v_max_i32_e32 v47, v40, v42
	v_max_i32_e32 v46, v45, v44
	v_min_i32_e32 v40, v40, v42
	v_min_i32_e32 v42, v45, v44
	v_max_i32_e32 v45, v130, v138
	v_max_i32_e32 v130, v149, v154
	v_min_i32_e32 v39, v150, v34
	v_min_i32_e32 v146, v37, v38
	v_max_i32_e32 v34, v150, v34
	v_max_i32_e32 v37, v37, v38
	v_min_i32_e32 v41, v131, v35
	v_min_i32_e32 v128, v36, v43
	v_max_i32_e32 v35, v131, v35
	v_max_i32_e32 v36, v36, v43
	v_min_i32_e32 v48, v47, v46
	v_max_i32_e32 v44, v40, v42
	v_min_i32_e32 v138, v45, v130
	v_min_i32_e32 v40, v40, v42
	v_min_i32_e32 v42, v140, v155
	v_max_i32_e32 v148, v39, v146
	v_min_i32_e32 v38, v34, v37
	v_min_i32_e32 v129, v41, v128
	v_max_i32_e32 v41, v41, v128
	v_min_i32_e32 v43, v35, v36
	v_max_i32_e32 v45, v45, v130
	v_max_i32_e32 v46, v47, v46
	v_max_i32_e32 v161, v140, v155
	v_max_i32_e32 v140, v40, v42
	v_max_i32_e32 v150, v148, v38
	v_max_i32_e32 v34, v34, v37
	v_min_i32_e32 v128, v41, v43
	v_min_i32_e32 v47, v45, v46
	v_min_i32_e32 v49, v161, v48
	v_min_i32_e32 v149, v44, v138
	v_max_i32_e32 v151, v140, v150
	v_min_i32_e32 v37, v129, v34
	v_max_i32_e32 v34, v129, v34
	v_min_i32_e32 v129, v128, v47
	v_max_i32_e32 v48, v161, v48
	v_max_i32_e32 v44, v44, v138
	v_max_i32_e32 v154, v49, v149
	v_max_i32_e32 v134, v151, v37
	v_min_i32_e32 v130, v34, v129
	v_min_i32_e32 v131, v48, v44
	v_min_i32_e32 v49, v49, v149
	v_min_i32_e32 v37, v151, v37
	v_max_i32_e32 v34, v34, v129
	v_max_i32_e32 v44, v48, v44
	v_min_i32_e32 v40, v40, v42
	v_min_i32_e32 v38, v148, v38
	v_max_i32_e32 v41, v41, v43
	v_max_i32_e32 v43, v45, v46
	v_max_i32_e32 v155, v154, v134
	v_min_i32_e32 v138, v130, v131
	v_min_i32_e32 v134, v154, v134
	v_max_i32_e32 v149, v49, v37
	v_min_i32_e32 v48, v34, v44
	v_max_i32_e32 v129, v130, v131
	v_max_i32_e32 v42, v40, v38
	v_min_i32_e32 v140, v140, v150
	v_max_i32_e32 v34, v34, v44
	v_max_i32_e32 v44, v128, v47
	v_min_i32_e32 v45, v41, v43
	v_min_i32_e32 v161, v155, v138
	v_max_i32_e32 v151, v134, v149
	v_min_i32_e32 v130, v48, v129
	v_max_i32_e32 v131, v155, v138
	v_max_i32_e32 v148, v42, v140
	v_min_i32_e32 v37, v49, v37
	v_min_i32_e32 v46, v44, v45
	v_min_i32_e32 v154, v161, v151
	v_min_i32_e32 v138, v130, v131
	v_min_i32_e32 v49, v148, v37
	v_min_i32_e32 v134, v134, v149
	v_min_i32_e32 v47, v34, v46
	v_min_i32_e32 v42, v42, v140
	v_min_i32_e32 v38, v40, v38
	v_min_i32_e32 v39, v39, v146
	v_max3_i32 v39, v144, v145, v39
	v_max3_i32 v38, v143, v124, v38
	v_max3_i32 v40, v147, v125, v42
; #define LAS __attribute__((address_space(3)))
; #define MFMA32(a, b, c) __builtin_amdgcn_mfma_f32_32x32x16_bf16((a), (b), (c), 0, 0, 0)
; __device__ __forceinline__ void route_task(int task, int tl0, const bf16* QP  , const LAS bf16* KHL, LAS unsigned short* EL, LAS float* GL, int lane) {
;     ...
;         for (int kt = 0; kt < 4; ++kt) {
;             f32x16 X;
; #pragma unroll
;             for (int i = 0; i < 16; ++i) X[i] = 8.f;
;             const LAS bf16* khp = KHL + (half * 128 + 32 * kt + r) * 72 + 8 * hi;
; #pragma unroll
;             for (int ks = 0; ks < 4; ++ks) {
;                 const bf16x8 kh = lds8(khp + 16 * ks);
;                 X = MFMA32(kh, qa[half][ks], X);
;             }
;             int grp[16];
; #pragma unroll
;             for (int i = 0; i < 16; ++i) grp[i] = (int)((__float_as_uint(X[i]) | 127u) - (unsigned)(32 * kt + (i & 3) + 8 * (i >> 2)));
;             sort16_desc(grp);
;             if (kt == 0) {
; #pragma unroll
;                 for (int i = 0; i < 16; ++i) cur[i] = grp[i];
;             } else merge16_desc(cur, grp);
	v_max3_i32 v42, v142, v126, v49
	v_max3_i32 v37, v127, v148, v37
	v_max3_i32 v49, v156, v157, v134
	v_max3_i32 v124, v158, v159, v154
	v_max3_i32 v125, v160, v161, v151
	v_max3_i32 v126, v137, v152, v138
	v_max3_i32 v127, v153, v130, v131
	v_max3_i32 v48, v82, v48, v129
	v_max3_i32 v47, v141, v132, v47
	v_max3_i32 v34, v135, v34, v46
	v_max3_i32 v44, v139, v44, v45
	v_max3_i32 v41, v136, v41, v43
	v_max3_i32 v35, v133, v35, v36
	v_max_i32_e32 v36, v39, v126
	v_min_i32_e32 v39, v39, v126
	v_max_i32_e32 v43, v38, v127
	v_min_i32_e32 v38, v38, v127
	v_max_i32_e32 v45, v40, v48
	v_min_i32_e32 v40, v40, v48
	v_max_i32_e32 v46, v42, v47
	v_min_i32_e32 v42, v42, v47
	v_max_i32_e32 v47, v37, v34
	v_min_i32_e32 v34, v37, v34
	v_max_i32_e32 v37, v49, v44
	v_min_i32_e32 v44, v49, v44
	v_max_i32_e32 v48, v124, v41
	v_min_i32_e32 v41, v124, v41
	v_max_i32_e32 v49, v125, v35
	v_min_i32_e32 v35, v125, v35
	ds_read_b128 v[124:127], v94 offset:9216
	ds_read_b128 v[128:131], v94 offset:9248
	v_max_i32_e32 v82, v36, v47
	v_min_i32_e32 v132, v36, v47
	v_max_i32_e32 v36, v43, v37
	v_min_i32_e32 v133, v43, v37
	v_max_i32_e32 v37, v45, v48
	v_max_i32_e32 v43, v46, v49
	v_min_i32_e32 v134, v45, v48
	v_min_i32_e32 v135, v46, v49
	v_max_i32_e32 v136, v39, v34
	v_min_i32_e32 v137, v39, v34
	v_max_i32_e32 v138, v38, v44
	v_min_i32_e32 v139, v38, v44
	v_max_i32_e32 v140, v40, v41
	v_min_i32_e32 v141, v40, v41
	v_max_i32_e32 v142, v42, v35
	v_min_i32_e32 v143, v42, v35
	v_max_i32_e32 v144, v82, v37
	v_min_i32_e32 v82, v82, v37
	v_max_i32_e32 v145, v36, v43
	v_min_i32_e32 v146, v36, v43
	s_waitcnt lgkmcnt(1)
	v_mfma_f32_32x32x16_bf16 v[34:49], v[124:127], v[78:81], v[18:33]
	ds_read_b128 v[124:127], v94 offset:9280
	v_max_i32_e32 v147, v132, v134
	v_min_i32_e32 v132, v132, v134
	v_max_i32_e32 v134, v133, v135
	v_min_i32_e32 v133, v133, v135
	v_max_i32_e32 v135, v136, v140
	v_min_i32_e32 v136, v136, v140
	s_waitcnt lgkmcnt(1)
	v_mfma_f32_32x32x16_bf16 v[34:49], v[128:131], v[74:77], v[34:49]
	ds_read_b128 v[128:131], v94 offset:9312
	v_max_i32_e32 v140, v138, v142
	v_min_i32_e32 v138, v138, v142
	v_max_i32_e32 v142, v137, v141
	v_min_i32_e32 v137, v137, v141
	v_max_i32_e32 v141, v139, v143
	v_min_i32_e32 v139, v139, v143
	s_waitcnt lgkmcnt(1)
	v_mfma_f32_32x32x16_bf16 v[34:49], v[124:127], v[70:73], v[34:49]
	v_min_i32_e32 v143, v144, v145
	v_min_i32_e32 v124, v82, v146
	v_min_i32_e32 v127, v135, v140
	v_min_i32_e32 v125, v147, v134
	v_min_i32_e32 v126, v132, v133
	v_min_i32_e32 v149, v142, v141
	v_min_i32_e32 v148, v136, v138
	s_waitcnt lgkmcnt(0)
	v_mfma_f32_32x32x16_bf16 v[34:49], v[128:131], v[66:69], v[34:49]
	v_min_i32_e32 v150, v137, v139
	s_nop 10
	v_or_b32_e32 v37, 0x7f, v37
	v_or_b32_e32 v48, 0x7f, v48
	v_or_b32_e32 v38, 0x7f, v38
	v_or_b32_e32 v42, 0x7f, v42
	v_or_b32_e32 v34, 0x7f, v34
	v_or_b32_e32 v47, 0x7f, v47
	v_or_b32_e32 v39, 0x7f, v39
	v_or_b32_e32 v40, 0x7f, v40
	v_or_b32_e32 v43, 0x7f, v43
	v_or_b32_e32 v44, 0x7f, v44
	v_or_b32_e32 v36, 0x7f, v36
	v_or_b32_e32 v49, 0x7f, v49
	v_or_b32_e32 v41, 0x7f, v41
	v_or_b32_e32 v45, 0x7f, v45
	v_or_b32_e32 v35, 0x7f, v35
	v_or_b32_e32 v46, 0x7f, v46
	v_add_u32_e32 v37, 0xffffffbd, v37
	v_add_u32_e32 v48, 0xffffffa6, v48
	v_add_u32_e32 v38, 0xffffffb8, v38
	v_add_u32_e32 v42, 0xffffffb0, v42
	v_subrev_u32_e32 v34, 64, v34
	v_add_u32_e32 v47, 0xffffffa7, v47
	v_add_u32_e32 v39, 0xffffffb7, v39
	v_add_u32_e32 v40, 0xffffffb6, v40
	v_add_u32_e32 v43, 0xffffffaf, v43
	v_add_u32_e32 v44, 0xffffffae, v44
	v_add_u32_e32 v36, 0xffffffbe, v36
	v_add_u32_e32 v49, 0xffffffa5, v49
	v_add_u32_e32 v41, 0xffffffb5, v41
	v_add_u32_e32 v45, 0xffffffad, v45
	v_add_u32_e32 v35, 0xffffffbf, v35
	v_add_u32_e32 v46, 0xffffffa8, v46
	v_max_i32_e32 v128, v37, v48
	v_max_i32_e32 v129, v38, v42
	v_max_i32_e32 v131, v34, v47
	v_max_i32_e32 v151, v39, v40
	v_min_i32_e32 v154, v43, v44
	v_min_i32_e32 v155, v36, v49
	v_min_i32_e32 v157, v41, v45
	v_min_i32_e32 v158, v35, v46
	v_min_i32_e32 v39, v39, v40
	v_min_i32_e32 v34, v34, v47
	v_min_i32_e32 v38, v38, v42
	v_min_i32_e32 v37, v37, v48
	v_max_i32_e32 v35, v35, v46
	v_max_i32_e32 v41, v41, v45
	v_max_i32_e32 v36, v36, v49
	v_max_i32_e32 v43, v43, v44
	v_min_i32_e32 v130, v128, v129
	v_min_i32_e32 v152, v131, v151
	v_max_i32_e32 v156, v154, v155
	v_max_i32_e32 v159, v157, v158
	v_max_i32_e32 v40, v39, v34
	v_max_i32_e32 v42, v38, v37
	v_min_i32_e32 v45, v35, v41
	v_min_i32_e32 v44, v36, v43
	v_min_i32_e32 v157, v157, v158
	v_min_i32_e32 v34, v39, v34
	v_min_i32_e32 v37, v38, v37
	v_min_i32_e32 v38, v154, v155
	v_max_i32_e32 v131, v131, v151
	v_max_i32_e32 v35, v35, v41
	v_max_i32_e32 v36, v36, v43
	v_max_i32_e32 v43, v128, v129
	v_min_i32_e32 v153, v130, v152
	v_min_i32_e32 v160, v156, v159
	v_max_i32_e32 v47, v40, v42
	v_max_i32_e32 v46, v45, v44
	v_min_i32_e32 v40, v40, v42
	v_min_i32_e32 v42, v45, v44
	v_max_i32_e32 v45, v130, v152
	v_max_i32_e32 v130, v156, v159
	v_min_i32_e32 v39, v157, v34
	v_min_i32_e32 v154, v37, v38
	v_max_i32_e32 v34, v157, v34
	v_max_i32_e32 v37, v37, v38
	v_min_i32_e32 v41, v131, v35
	v_min_i32_e32 v128, v36, v43
	v_max_i32_e32 v35, v131, v35
	v_max_i32_e32 v36, v36, v43
	v_min_i32_e32 v48, v47, v46
	v_max_i32_e32 v44, v40, v42
	v_min_i32_e32 v152, v45, v130
	v_min_i32_e32 v40, v40, v42
	v_min_i32_e32 v42, v153, v160
	v_max_i32_e32 v155, v39, v154
	v_min_i32_e32 v38, v34, v37
	v_min_i32_e32 v129, v41, v128
	v_max_i32_e32 v41, v41, v128
	v_min_i32_e32 v43, v35, v36
	v_max_i32_e32 v45, v45, v130
	v_max_i32_e32 v46, v47, v46
	v_max_i32_e32 v161, v153, v160
	v_max_i32_e32 v153, v40, v42
	v_max_i32_e32 v157, v155, v38
	v_max_i32_e32 v34, v34, v37
; #define LAS __attribute__((address_space(3)))
; #define MFMA32(a, b, c) __builtin_amdgcn_mfma_f32_32x32x16_bf16((a), (b), (c), 0, 0, 0)
; #define CE_(a, b) ce_desc(v[a], v[b])
; __device__ __forceinline__ void sort16_desc(int (&v)[16]) {
;     ...
;     CE_(0,13); CE_(1,12); CE_(2,15); CE_(3,14); CE_(4,8); CE_(5,6); CE_(7,11); CE_(9,10);
;     CE_(0,5); CE_(1,7); CE_(2,9); CE_(3,4); CE_(6,13); CE_(8,14); CE_(10,15); CE_(11,12);
;     CE_(0,1); CE_(2,3); CE_(4,5); CE_(6,8); CE_(7,9); CE_(10,11); CE_(12,13); CE_(14,15);
;     CE_(0,2); CE_(1,3); CE_(4,10); CE_(5,11); CE_(6,7); CE_(8,9); CE_(12,14); CE_(13,15);
;     CE_(1,2); CE_(3,12); CE_(4,6); CE_(5,7); CE_(8,10); CE_(9,11); CE_(13,14);
;     CE_(1,4); CE_(2,6); CE_(5,8); CE_(7,10); CE_(9,13); CE_(11,14);
;     CE_(2,4); CE_(3,6); CE_(9,12); CE_(11,13);
;     CE_(3,5); CE_(6,8); CE_(7,9); CE_(10,12);
;     CE_(3,4); CE_(5,6); CE_(7,8); CE_(9,10); CE_(11,12);
;     CE_(6,7); CE_(8,9);
;     ...
; }
; __device__ __forceinline__ void merge16_desc(int (&a)[16], const int (&b)[16]) {
; #pragma unroll
;     for (int i = 0; i < 16; ++i) a[i] = a[i] > b[15 - i] ? a[i] : b[15 - i];
; #pragma unroll
;     for (int j = 8; j > 0; j >>= 1)
; #pragma unroll
;         for (int i = 0; i < 16; ++i) { const int l = i ^ j; if (l > i) ce_desc(a[i], a[l]); }
; }
; __device__ __forceinline__ void route_task(int task, int tl0, const bf16* QP  , const LAS bf16* KHL, LAS unsigned short* EL, LAS float* GL, int lane) {
;     ...
;         for (int kt = 0; kt < 4; ++kt) {
;             f32x16 X;
; #pragma unroll
;             for (int i = 0; i < 16; ++i) X[i] = 8.f;
;             const LAS bf16* khp = KHL + (half * 128 + 32 * kt + r) * 72 + 8 * hi;
; #pragma unroll
;             for (int ks = 0; ks < 4; ++ks) {
;                 const bf16x8 kh = lds8(khp + 16 * ks);
;                 X = MFMA32(kh, qa[half][ks], X);
;             }
;             int grp[16];
; #pragma unroll
;             for (int i = 0; i < 16; ++i) grp[i] = (int)((__float_as_uint(X[i]) | 127u) - (unsigned)(32 * kt + (i & 3) + 8 * (i >> 2)));
;             sort16_desc(grp);
;             if (kt == 0) {
; #pragma unroll
;                 for (int i = 0; i < 16; ++i) cur[i] = grp[i];
;             } else merge16_desc(cur, grp);
	v_min_i32_e32 v128, v41, v43
	v_min_i32_e32 v47, v45, v46
	v_min_i32_e32 v49, v161, v48
	v_min_i32_e32 v156, v44, v152
	v_max_i32_e32 v158, v153, v157
	v_min_i32_e32 v37, v129, v34
	v_max_i32_e32 v34, v129, v34
	v_min_i32_e32 v129, v128, v47
	v_max_i32_e32 v48, v161, v48
	v_max_i32_e32 v44, v44, v152
	v_min_i32_e32 v40, v40, v42
	v_min_i32_e32 v38, v155, v38
	v_max_i32_e32 v159, v49, v156
	v_max_i32_e32 v151, v158, v37
	v_min_i32_e32 v130, v34, v129
	v_min_i32_e32 v131, v48, v44
	v_min_i32_e32 v49, v49, v156
	v_min_i32_e32 v37, v158, v37
	v_max_i32_e32 v34, v34, v129
	v_max_i32_e32 v44, v48, v44
	v_max_i32_e32 v42, v40, v38
	v_min_i32_e32 v153, v153, v157
	v_max_i32_e32 v160, v159, v151
	v_min_i32_e32 v152, v130, v131
	v_max_i32_e32 v156, v49, v37
	v_min_i32_e32 v48, v34, v44
	v_max_i32_e32 v129, v130, v131
	v_max_i32_e32 v155, v42, v153
	v_min_i32_e32 v37, v49, v37
	v_min_i32_e32 v151, v159, v151
	v_min_i32_e32 v130, v48, v129
	v_max_i32_e32 v131, v160, v152
	v_min_i32_e32 v49, v155, v37
	v_max_i32_e32 v41, v41, v43
	v_max_i32_e32 v43, v45, v46
	v_min_i32_e32 v42, v42, v153
	v_min_i32_e32 v38, v40, v38
	v_min_i32_e32 v161, v160, v152
	v_max_i32_e32 v158, v151, v156
	v_min_i32_e32 v151, v151, v156
	v_max_i32_e32 v34, v34, v44
	v_max_i32_e32 v44, v128, v47
	v_min_i32_e32 v45, v41, v43
	v_max_i32_e32 v40, v41, v43
	v_max_i32_e32 v38, v143, v38
	v_max3_i32 v41, v82, v146, v42
	v_max_i32_e32 v42, v124, v49
	v_max3_i32 v124, v127, v130, v131
	v_min_i32_e32 v46, v44, v45
	v_max_i32_e32 v43, v125, v151
	v_max3_i32 v49, v126, v161, v158
	v_max3_i32 v44, v149, v44, v45
	v_max_i32_e32 v45, v38, v124
	v_min_i32_e32 v38, v38, v124
	ds_read_b128 v[124:127], v96
	v_min_i32_e32 v159, v161, v158
	v_min_i32_e32 v152, v130, v131
	v_max_i32_e32 v37, v155, v37
	v_max_i32_e32 v48, v48, v129
	v_min_i32_e32 v47, v34, v46
	v_max_i32_e32 v34, v34, v46
	v_min_i32_e32 v39, v39, v154
	v_max3_i32 v39, v144, v145, v39
	v_max3_i32 v37, v147, v134, v37
	v_max3_i32 v46, v132, v133, v159
	v_max3_i32 v82, v135, v140, v152
	v_max3_i32 v48, v136, v138, v48
	v_max_i32_e32 v47, v148, v47
	v_max3_i32 v34, v142, v141, v34
	v_max3_i32 v40, v137, v139, v40
	v_max3_i32 v35, v150, v35, v36
	v_max_i32_e32 v36, v39, v82
	v_min_i32_e32 v39, v39, v82
	v_max_i32_e32 v82, v41, v48
	v_min_i32_e32 v41, v41, v48
	v_max_i32_e32 v48, v42, v47
	v_min_i32_e32 v42, v42, v47
	v_max_i32_e32 v47, v37, v34
	v_min_i32_e32 v34, v37, v34
	v_max_i32_e32 v37, v43, v44
	v_min_i32_e32 v43, v43, v44
	v_max_i32_e32 v44, v46, v40
	v_min_i32_e32 v40, v46, v40
	v_max_i32_e32 v46, v49, v35
	v_min_i32_e32 v35, v49, v35
	v_max_i32_e32 v49, v36, v47
	v_min_i32_e32 v132, v36, v47
	v_max_i32_e32 v36, v45, v37
	v_min_i32_e32 v133, v45, v37
	v_max_i32_e32 v37, v82, v44
	v_min_i32_e32 v82, v82, v44
	v_max_i32_e32 v44, v48, v46
	ds_read_b128 v[128:131], v96 offset:32
	v_min_i32_e32 v134, v48, v46
	v_max_i32_e32 v135, v39, v34
	v_min_i32_e32 v136, v39, v34
	v_max_i32_e32 v137, v38, v43
	v_min_i32_e32 v138, v38, v43
	v_max_i32_e32 v139, v41, v40
	v_min_i32_e32 v140, v41, v40
	v_max_i32_e32 v141, v42, v35
	v_min_i32_e32 v142, v42, v35
	v_max_i32_e32 v143, v49, v37
	v_min_i32_e32 v144, v49, v37
	v_max_i32_e32 v145, v36, v44
	v_min_i32_e32 v146, v36, v44
	s_waitcnt lgkmcnt(1)
	v_mfma_f32_32x32x16_bf16 v[34:49], v[124:127], v[78:81], v[18:33]
	ds_read_b128 v[78:81], v96 offset:64
	v_max_i32_e32 v147, v132, v82
	v_min_i32_e32 v82, v132, v82
	v_max_i32_e32 v132, v137, v141
	v_max_i32_e32 v124, v133, v134
	v_min_i32_e32 v125, v133, v134
	v_max_i32_e32 v126, v135, v139
	s_waitcnt lgkmcnt(1)
	v_mfma_f32_32x32x16_bf16 v[34:49], v[128:131], v[74:77], v[34:49]
	ds_read_b128 v[74:77], v96 offset:96
	v_min_i32_e32 v128, v137, v141
	v_max_i32_e32 v129, v136, v140
	v_min_i32_e32 v130, v136, v140
	v_min_i32_e32 v127, v135, v139
	v_max_i32_e32 v131, v138, v142
	v_min_i32_e32 v133, v138, v142
	s_waitcnt lgkmcnt(1)
	v_mfma_f32_32x32x16_bf16 v[34:49], v[78:81], v[70:73], v[34:49]
	v_min_i32_e32 v134, v143, v145
	v_min_i32_e32 v70, v144, v146
	v_min_i32_e32 v71, v147, v124
	v_min_i32_e32 v72, v82, v125
	v_min_i32_e32 v73, v126, v132
	v_min_i32_e32 v78, v127, v128
	v_min_i32_e32 v79, v129, v131
	s_waitcnt lgkmcnt(0)
	v_mfma_f32_32x32x16_bf16 v[34:49], v[74:77], v[66:69], v[34:49]
	v_min_i32_e32 v80, v130, v133
	s_nop 10
	v_or_b32_e32 v41, 0x7f, v41
	v_or_b32_e32 v45, 0x7f, v45
	v_or_b32_e32 v35, 0x7f, v35
	v_or_b32_e32 v46, 0x7f, v46
	v_or_b32_e32 v39, 0x7f, v39
	v_or_b32_e32 v40, 0x7f, v40
	v_or_b32_e32 v34, 0x7f, v34
	v_or_b32_e32 v47, 0x7f, v47
	v_or_b32_e32 v38, 0x7f, v38
	v_or_b32_e32 v42, 0x7f, v42
	v_or_b32_e32 v37, 0x7f, v37
	v_or_b32_e32 v48, 0x7f, v48
	v_or_b32_e32 v43, 0x7f, v43
	v_or_b32_e32 v44, 0x7f, v44
	v_or_b32_e32 v36, 0x7f, v36
	v_or_b32_e32 v49, 0x7f, v49
	v_add_u32_e32 v41, 0xffffff95, v41
	v_add_u32_e32 v45, 0xffffff8d, v45
	v_add_u32_e32 v35, 0xffffff9f, v35
	v_add_u32_e32 v46, 0xffffff88, v46
	v_add_u32_e32 v39, 0xffffff97, v39
	v_add_u32_e32 v40, 0xffffff96, v40
	v_add_u32_e32 v34, 0xffffffa0, v34
	v_add_u32_e32 v47, 0xffffff87, v47
	v_add_u32_e32 v38, 0xffffff98, v38
	v_add_u32_e32 v42, 0xffffff90, v42
	v_add_u32_e32 v37, 0xffffff9d, v37
	v_add_u32_e32 v48, 0xffffff86, v48
	v_add_u32_e32 v43, 0xffffff8f, v43
	v_add_u32_e32 v44, 0xffffff8e, v44
	v_add_u32_e32 v36, 0xffffff9e, v36
	v_add_u32_e32 v49, 0xffffff85, v49
	v_min_i32_e32 v66, v41, v45
	v_min_i32_e32 v67, v35, v46
	v_min_i32_e32 v69, v39, v40
	v_min_i32_e32 v74, v34, v47
	v_min_i32_e32 v77, v38, v42
	v_min_i32_e32 v81, v37, v48
	v_min_i32_e32 v136, v43, v44
	v_min_i32_e32 v137, v36, v49
	v_max_i32_e32 v34, v34, v47
	v_max_i32_e32 v39, v39, v40
	v_max_i32_e32 v35, v35, v46
; #define CE_(a, b) ce_desc(v[a], v[b])
; __device__ __forceinline__ void sort16_desc(int (&v)[16]) {
;     ...
;     CE_(0,13); CE_(1,12); CE_(2,15); CE_(3,14); CE_(4,8); CE_(5,6); CE_(7,11); CE_(9,10);
;     CE_(0,5); CE_(1,7); CE_(2,9); CE_(3,4); CE_(6,13); CE_(8,14); CE_(10,15); CE_(11,12);
;     CE_(0,1); CE_(2,3); CE_(4,5); CE_(6,8); CE_(7,9); CE_(10,11); CE_(12,13); CE_(14,15);
;     CE_(0,2); CE_(1,3); CE_(4,10); CE_(5,11); CE_(6,7); CE_(8,9); CE_(12,14); CE_(13,15);
;     CE_(1,2); CE_(3,12); CE_(4,6); CE_(5,7); CE_(8,10); CE_(9,11); CE_(13,14);
;     CE_(1,4); CE_(2,6); CE_(5,8); CE_(7,10); CE_(9,13); CE_(11,14);
;     CE_(2,4); CE_(3,6); CE_(9,12); CE_(11,13);
;     CE_(3,5); CE_(6,8); CE_(7,9); CE_(10,12);
;     CE_(3,4); CE_(5,6); CE_(7,8); CE_(9,10); CE_(11,12);
;     CE_(6,7); CE_(8,9);
;     ...
; }
; __device__ __forceinline__ void merge16_desc(int (&a)[16], const int (&b)[16]) {
; #pragma unroll
;     for (int i = 0; i < 16; ++i) a[i] = a[i] > b[15 - i] ? a[i] : b[15 - i];
; #pragma unroll
;     for (int j = 8; j > 0; j >>= 1)
; #pragma unroll
;         for (int i = 0; i < 16; ++i) { const int l = i ^ j; if (l > i) ce_desc(a[i], a[l]); }
; }
; __device__ __forceinline__ void route_task(int task, int tl0, const bf16* QP  , const LAS bf16* KHL, LAS unsigned short* EL, LAS float* GL, int lane) {
;     ...
;         { const unsigned h4 = 4u * (unsigned)hi;
; #pragma unroll
;           for (int i = 0; i < 16; ++i) cur[i] -= (int)h4; }
;         int oth[16];
; #pragma unroll
;         for (int i = 0; i < 16; ++i) oth[i] = __shfl_xor(cur[i], 32);
;         merge16_desc(cur, oth);
	v_max_i32_e32 v41, v41, v45
	v_max_i32_e32 v36, v36, v49
	v_max_i32_e32 v43, v43, v44
	v_max_i32_e32 v37, v37, v48
	v_max_i32_e32 v38, v38, v42
	v_max_i32_e32 v40, v34, v39
	v_max_i32_e32 v45, v35, v41
	v_max_i32_e32 v44, v36, v43
	v_max_i32_e32 v42, v37, v38
	v_min_i32_e32 v46, v40, v45
	v_min_i32_e32 v47, v44, v42
	v_min_i32_e32 v75, v69, v74
	v_min_i32_e32 v48, v46, v47
	v_max_i32_e32 v46, v46, v47
	v_min_i32_e32 v37, v37, v38
	v_min_i32_e32 v34, v34, v39
	v_max_i32_e32 v39, v136, v137
	v_max_i32_e32 v47, v66, v67
	v_max_i32_e32 v69, v69, v74
	v_max_i32_e32 v74, v77, v81
	v_min_i32_e32 v35, v35, v41
	v_min_i32_e32 v36, v36, v43
	v_min_i32_e32 v68, v66, v67
	v_min_i32_e32 v135, v77, v81
	v_min_i32_e32 v138, v136, v137
	v_max_i32_e32 v38, v37, v34
	v_max_i32_e32 v77, v69, v74
	v_max_i32_e32 v41, v35, v36
	v_min_i32_e32 v34, v37, v34
	v_min_i32_e32 v37, v39, v47
	v_min_i32_e32 v76, v68, v75
	v_min_i32_e32 v139, v135, v138
	v_max_i32_e32 v49, v68, v75
	v_max_i32_e32 v68, v135, v138
	v_max_i32_e32 v40, v40, v45
	v_max_i32_e32 v42, v44, v42
	v_max_i32_e32 v66, v39, v47
	v_max_i32_e32 v43, v77, v41
	v_max_i32_e32 v39, v34, v37
	v_min_i32_e32 v41, v77, v41
	v_min_i32_e32 v69, v69, v74
	v_min_i32_e32 v35, v35, v36
	v_max_i32_e32 v75, v49, v68
	v_min_i32_e32 v44, v40, v42
	v_max_i32_e32 v67, v38, v66
	v_max_i32_e32 v47, v39, v41
	v_max_i32_e32 v36, v69, v35
	v_min_i32_e32 v39, v39, v41
	v_min_i32_e32 v35, v69, v35
	v_min_i32_e32 v34, v34, v37
	v_max_i32_e32 v41, v76, v139
	v_min_i32_e32 v49, v49, v68
	v_min_i32_e32 v45, v46, v44
	v_min_i32_e32 v81, v67, v43
	v_min_i32_e32 v38, v38, v66
	v_max_i32_e32 v37, v35, v34
	v_max_i32_e32 v68, v41, v49
	v_max_i32_e32 v135, v48, v75
	v_min_i32_e32 v136, v45, v81
	v_max_i32_e32 v66, v36, v38
	v_min_i32_e32 v36, v36, v38
	v_max_i32_e32 v69, v37, v68
	v_min_i32_e32 v48, v48, v75
	v_max_i32_e32 v137, v135, v136
	v_max_i32_e32 v74, v47, v66
	v_min_i32_e32 v135, v135, v136
	v_min_i32_e32 v47, v47, v66
	v_max_i32_e32 v38, v39, v36
	v_max_i32_e32 v75, v69, v48
	v_min_i32_e32 v34, v35, v34
	v_min_i32_e32 v35, v41, v49
	v_min_i32_e32 v36, v39, v36
	v_min_i32_e32 v39, v69, v48
	v_max_i32_e32 v44, v46, v44
	v_max_i32_e32 v43, v67, v43
	v_min_i32_e32 v140, v76, v139
	v_min_i32_e32 v77, v137, v74
	v_max_i32_e32 v66, v135, v47
	v_max_i32_e32 v76, v38, v75
	v_min_i32_e32 v47, v135, v47
	v_max_i32_e32 v41, v34, v35
	v_min_i32_e32 v37, v37, v68
	v_min_i32_e32 v48, v36, v39
	v_max_i32_e32 v45, v45, v81
	v_min_i32_e32 v46, v44, v43
	v_min_i32_e32 v38, v38, v75
	v_max_i32_e32 v36, v36, v39
	v_min_i32_e32 v136, v77, v66
	v_max_i32_e32 v135, v76, v47
	v_max_i32_e32 v49, v41, v37
	v_max_i32_e32 v69, v137, v74
	v_min_i32_e32 v67, v45, v46
	v_min_i32_e32 v47, v76, v47
	v_max_i32_e32 v39, v38, v36
	v_min_i32_e32 v138, v136, v135
	v_max_i32_e32 v68, v49, v48
	v_max_i32_e32 v74, v69, v67
	v_min_i32_e32 v37, v41, v37
	v_max_i32_e32 v41, v77, v66
	v_min_i32_e32 v75, v47, v39
	v_max_i32_e32 v43, v44, v43
	v_min_i32_e32 v34, v34, v35
	v_min_i32_e32 v36, v38, v36
	v_min_i32_e32 v48, v49, v48
	v_min_i32_e32 v49, v69, v67
	v_max3_i32 v140, v143, v145, v140
	v_max3_i32 v126, v126, v132, v138
	v_max3_i32 v68, v147, v124, v68
	v_max3_i32 v74, v129, v131, v74
	v_max3_i32 v37, v144, v146, v37
	v_max3_i32 v41, v127, v128, v41
	v_max3_i32 v75, v82, v125, v75
	v_max3_i32 v43, v130, v133, v43
	v_max_i32_e32 v34, v134, v34
	v_max3_i32 v35, v73, v136, v135
	v_max_i32_e32 v36, v71, v36
	v_max3_i32 v38, v79, v45, v46
	v_max_i32_e32 v48, v70, v48
	v_max_i32_e32 v49, v78, v49
	v_max3_i32 v39, v72, v47, v39
	v_max3_i32 v40, v80, v40, v42
	v_min_i32_e32 v81, v68, v74
	v_min_i32_e32 v66, v37, v41
	v_min_i32_e32 v73, v34, v35
	v_min_i32_e32 v45, v36, v38
	v_min_i32_e32 v42, v39, v40
	v_max_i32_e32 v71, v140, v126
	v_max_i32_e32 v68, v68, v74
	v_max_i32_e32 v37, v37, v41
	v_max_i32_e32 v41, v75, v43
	v_max_i32_e32 v34, v34, v35
	v_max_i32_e32 v35, v36, v38
	v_max_i32_e32 v38, v48, v49
	v_max_i32_e32 v39, v39, v40
	v_min_i32_e32 v44, v75, v43
	v_max_i32_e32 v72, v71, v68
	v_max_i32_e32 v43, v37, v41
	v_max_i32_e32 v36, v34, v35
	v_max_i32_e32 v40, v38, v39
	v_min_i32_e32 v67, v48, v49
	v_max_i32_e32 v74, v72, v43
	v_max_i32_e32 v48, v36, v40
	v_min_i32_e32 v43, v72, v43
	v_min_i32_e32 v36, v36, v40
	v_max_i32_e32 v40, v43, v36
	v_min_i32_e32 v36, v43, v36
	v_min_i32_e32 v43, v71, v68
	v_min_i32_e32 v37, v37, v41
	v_min_i32_e32 v34, v34, v35
	v_min_i32_e32 v35, v38, v39
	v_min_i32_e32 v132, v140, v126
	v_max_i32_e32 v41, v43, v37
	v_max_i32_e32 v38, v34, v35
	v_min_i32_e32 v37, v43, v37
	v_min_i32_e32 v34, v34, v35
	v_min_i32_e32 v76, v66, v44
	v_min_i32_e32 v47, v67, v42
	v_max_i32_e32 v39, v41, v38
	v_min_i32_e32 v38, v41, v38
	v_max_i32_e32 v35, v37, v34
	v_min_i32_e32 v34, v37, v34
	v_max_i32_e32 v37, v132, v81
	v_max_i32_e32 v41, v66, v44
	v_max_i32_e32 v44, v73, v45
	v_max_i32_e32 v42, v67, v42
	v_min_i32_e32 v124, v132, v81
	v_min_i32_e32 v46, v73, v45
	v_max_i32_e32 v43, v37, v41
	v_min_i32_e32 v37, v37, v41
	v_min_i32_e32 v41, v44, v42
	v_min_i32_e32 v77, v124, v76
	v_min_i32_e32 v69, v46, v47
	v_max_i32_e32 v45, v44, v42
	v_max_i32_e32 v42, v37, v41
	v_min_i32_e32 v37, v37, v41
	v_max_i32_e32 v41, v124, v76
	v_max_i32_e32 v44, v46, v47
	v_min_i32_e32 v70, v77, v69
	v_max_i32_e32 v49, v74, v48
	v_min_i32_e32 v48, v74, v48
	v_max_i32_e32 v66, v43, v45
	v_min_i32_e32 v43, v43, v45
	v_max_i32_e32 v45, v41, v44
	v_min_i32_e32 v41, v41, v44
	v_max_i32_e32 v44, v77, v69
	v_sub_u32_e32 v46, v49, v87
	v_sub_u32_e32 v47, v48, v87
	v_sub_u32_e32 v40, v40, v87
	v_sub_u32_e32 v36, v36, v87
	v_sub_u32_e32 v39, v39, v87
	v_sub_u32_e32 v38, v38, v87
	v_sub_u32_e32 v35, v35, v87
	v_sub_u32_e32 v34, v34, v87
	v_sub_u32_e32 v48, v66, v87
	v_sub_u32_e32 v43, v43, v87
	v_sub_u32_e32 v42, v42, v87
	v_sub_u32_e32 v37, v37, v87
	v_sub_u32_e32 v45, v45, v87
	v_sub_u32_e32 v41, v41, v87
	v_sub_u32_e32 v44, v44, v87
	v_sub_u32_e32 v49, v70, v87
	ds_bpermute_b32 v66, v123, v46
	ds_bpermute_b32 v67, v123, v47
	ds_bpermute_b32 v68, v123, v40
	ds_bpermute_b32 v69, v123, v36
	ds_bpermute_b32 v70, v123, v39
	ds_bpermute_b32 v71, v123, v38
	ds_bpermute_b32 v72, v123, v35
	ds_bpermute_b32 v73, v123, v34
	ds_bpermute_b32 v74, v123, v48
	ds_bpermute_b32 v75, v123, v43
	ds_bpermute_b32 v76, v123, v42
	ds_bpermute_b32 v77, v123, v49
	ds_bpermute_b32 v78, v123, v44
	ds_bpermute_b32 v79, v123, v41
	ds_bpermute_b32 v80, v123, v45
	ds_bpermute_b32 v81, v123, v37
	s_waitcnt lgkmcnt(4)
; #define LAS __attribute__((address_space(3)))
; #define MFMA32(a, b, c) __builtin_amdgcn_mfma_f32_32x32x16_bf16((a), (b), (c), 0, 0, 0)
; #define CE_(a, b) ce_desc(v[a], v[b])
; __device__ __forceinline__ void sort16_desc(int (&v)[16]) {
;     ...
;     CE_(0,13); CE_(1,12); CE_(2,15); CE_(3,14); CE_(4,8); CE_(5,6); CE_(7,11); CE_(9,10);
;     CE_(0,5); CE_(1,7); CE_(2,9); CE_(3,4); CE_(6,13); CE_(8,14); CE_(10,15); CE_(11,12);
;     CE_(0,1); CE_(2,3); CE_(4,5); CE_(6,8); CE_(7,9); CE_(10,11); CE_(12,13); CE_(14,15);
;     CE_(0,2); CE_(1,3); CE_(4,10); CE_(5,11); CE_(6,7); CE_(8,9); CE_(12,14); CE_(13,15);
;     CE_(1,2); CE_(3,12); CE_(4,6); CE_(5,7); CE_(8,10); CE_(9,11); CE_(13,14);
;     CE_(1,4); CE_(2,6); CE_(5,8); CE_(7,10); CE_(9,13); CE_(11,14);
;     CE_(2,4); CE_(3,6); CE_(9,12); CE_(11,13);
;     CE_(3,5); CE_(6,8); CE_(7,9); CE_(10,12);
;     CE_(3,4); CE_(5,6); CE_(7,8); CE_(9,10); CE_(11,12);
;     CE_(6,7); CE_(8,9);
;     ...
; }
; __device__ __forceinline__ void merge16_desc(int (&a)[16], const int (&b)[16]) {
; #pragma unroll
;     for (int i = 0; i < 16; ++i) a[i] = a[i] > b[15 - i] ? a[i] : b[15 - i];
; #pragma unroll
;     for (int j = 8; j > 0; j >>= 1)
; #pragma unroll
;         for (int i = 0; i < 16; ++i) { const int l = i ^ j; if (l > i) ce_desc(a[i], a[l]); }
; }
; __device__ __forceinline__ void route_task(int task, int tl0, const bf16* QP  , const LAS bf16* KHL, LAS unsigned short* EL, LAS float* GL, int lane) {
;     ...
;         for (int kt = 0; kt < 4; ++kt) {
;             f32x16 X;
; #pragma unroll
;             for (int i = 0; i < 16; ++i) X[i] = 8.f;
;             const LAS bf16* khp = KHL + (half * 128 + 32 * kt + r) * 72 + 8 * hi;
; #pragma unroll
;             for (int ks = 0; ks < 4; ++ks) {
;                 const bf16x8 kh = lds8(khp + 16 * ks);
;                 X = MFMA32(kh, qa[half][ks], X);
;             }
;             int grp[16];
; #pragma unroll
;             for (int i = 0; i < 16; ++i) grp[i] = (int)((__float_as_uint(X[i]) | 127u) - (unsigned)(32 * kt + (i & 3) + 8 * (i >> 2)));
;             sort16_desc(grp);
;             if (kt == 0) {
; #pragma unroll
;                 for (int i = 0; i < 16; ++i) cur[i] = grp[i];
;             } else merge16_desc(cur, grp);
	v_max_i32_e32 v46, v46, v77
	s_waitcnt lgkmcnt(3)
	v_max_i32_e32 v47, v47, v78
	s_waitcnt lgkmcnt(2)
	v_max_i32_e32 v40, v40, v79
	s_waitcnt lgkmcnt(1)
	v_max_i32_e32 v36, v36, v80
	s_waitcnt lgkmcnt(0)
	v_max_i32_e32 v39, v39, v81
	v_max_i32_e32 v38, v38, v76
	v_max_i32_e32 v35, v35, v75
	v_max_i32_e32 v34, v34, v74
	v_max_i32_e32 v48, v48, v73
	v_max_i32_e32 v43, v43, v72
	v_max_i32_e32 v42, v42, v71
	v_max_i32_e32 v37, v37, v70
	v_max_i32_e32 v45, v45, v69
	v_max_i32_e32 v41, v41, v68
	v_max_i32_e32 v44, v44, v67
	v_max_i32_e32 v49, v49, v66
	v_max_i32_e32 v66, v46, v48
	v_min_i32_e32 v46, v46, v48
	v_max_i32_e32 v48, v47, v43
	v_min_i32_e32 v43, v47, v43
	v_max_i32_e32 v47, v40, v42
	v_min_i32_e32 v40, v40, v42
	v_max_i32_e32 v42, v36, v37
	v_min_i32_e32 v36, v36, v37
	v_max_i32_e32 v37, v39, v45
	v_min_i32_e32 v39, v39, v45
	v_max_i32_e32 v45, v38, v41
	v_min_i32_e32 v38, v38, v41
	v_max_i32_e32 v41, v35, v44
	v_min_i32_e32 v35, v35, v44
	v_max_i32_e32 v44, v34, v49
	v_min_i32_e32 v34, v34, v49
	v_max_i32_e32 v49, v66, v37
	v_min_i32_e32 v37, v66, v37
	v_max_i32_e32 v66, v48, v45
	v_min_i32_e32 v45, v48, v45
	v_max_i32_e32 v48, v47, v41
	v_min_i32_e32 v41, v47, v41
	v_max_i32_e32 v47, v42, v44
	v_max_i32_e32 v80, v66, v47
	v_min_i32_e32 v124, v66, v47
	ds_read_b128 v[66:69], v94 offset:18432
	ds_read_b128 v[70:73], v94 offset:18464
	v_min_i32_e32 v42, v42, v44
	v_max_i32_e32 v44, v46, v39
	v_min_i32_e32 v74, v46, v39
	v_max_i32_e32 v39, v43, v38
	v_min_i32_e32 v75, v43, v38
	v_max_i32_e32 v38, v40, v35
	v_min_i32_e32 v76, v40, v35
	v_max_i32_e32 v35, v36, v34
	v_min_i32_e32 v77, v36, v34
	v_max_i32_e32 v78, v49, v48
	v_min_i32_e32 v82, v49, v48
	v_max_i32_e32 v125, v37, v41
	v_min_i32_e32 v126, v37, v41
	v_max_i32_e32 v127, v45, v42
	v_min_i32_e32 v128, v45, v42
	v_max_i32_e32 v129, v44, v38
	v_min_i32_e32 v130, v44, v38
	v_max_i32_e32 v131, v39, v35
	v_min_i32_e32 v132, v39, v35
	s_waitcnt vmcnt(3) lgkmcnt(1)
	v_mfma_f32_32x32x16_bf16 v[34:49], v[66:69], v[62:65], v[18:33]
	ds_read_b128 v[66:69], v94 offset:18496
	v_max_i32_e32 v133, v74, v76
	v_min_i32_e32 v134, v74, v76
	v_max_i32_e32 v135, v75, v77
	v_min_i32_e32 v136, v75, v77
	v_max_i32_e32 v79, v78, v80
	v_min_i32_e32 v81, v78, v80
	s_waitcnt vmcnt(2) lgkmcnt(1)
	v_mfma_f32_32x32x16_bf16 v[34:49], v[70:73], v[58:61], v[34:49]
	v_max_i32_e32 v80, v82, v124
	v_min_i32_e32 v78, v82, v124
	v_max_i32_e32 v77, v125, v127
	v_min_i32_e32 v76, v125, v127
	v_max_i32_e32 v75, v126, v128
	v_min_i32_e32 v73, v126, v128
	ds_read_b128 v[124:127], v94 offset:18528
	s_waitcnt vmcnt(1) lgkmcnt(1)
	v_mfma_f32_32x32x16_bf16 v[34:49], v[66:69], v[54:57], v[34:49]
	v_max_i32_e32 v71, v129, v131
	v_min_i32_e32 v74, v129, v131
	v_max_i32_e32 v72, v130, v132
	v_min_i32_e32 v70, v130, v132
	v_max_i32_e32 v69, v133, v135
	v_min_i32_e32 v68, v133, v135
	v_max_i32_e32 v67, v134, v136
	s_waitcnt vmcnt(0) lgkmcnt(0)
	v_mfma_f32_32x32x16_bf16 v[34:49], v[124:127], v[50:53], v[34:49]
	v_min_i32_e32 v66, v134, v136
	s_nop 10
	v_or_b32_e32 v37, 0x7f, v37
	v_or_b32_e32 v48, 0x7f, v48
	v_or_b32_e32 v38, 0x7f, v38
	v_or_b32_e32 v42, 0x7f, v42
	v_or_b32_e32 v47, 0x7f, v47
	v_or_b32_e32 v39, 0x7f, v39
	v_or_b32_e32 v40, 0x7f, v40
	v_or_b32_e32 v43, 0x7f, v43
	v_or_b32_e32 v44, 0x7f, v44
	v_or_b32_e32 v36, 0x7f, v36
	v_or_b32_e32 v49, 0x7f, v49
	v_or_b32_e32 v41, 0x7f, v41
	v_or_b32_e32 v45, 0x7f, v45
	v_or_b32_e32 v35, 0x7f, v35
	v_or_b32_e32 v46, 0x7f, v46
	v_add_u32_e32 v37, -3, v37
	v_subrev_u32_e32 v48, 26, v48
	v_add_u32_e32 v38, -8, v38
	v_add_u32_e32 v42, -16, v42
	v_or_b32_e32 v34, 0x7f, v34
	v_subrev_u32_e32 v47, 25, v47
	v_add_u32_e32 v39, -9, v39
	v_add_u32_e32 v40, -10, v40
	v_subrev_u32_e32 v43, 17, v43
	v_subrev_u32_e32 v44, 18, v44
	v_add_u32_e32 v36, -2, v36
	v_subrev_u32_e32 v49, 27, v49
	v_add_u32_e32 v41, -11, v41
	v_subrev_u32_e32 v45, 19, v45
	v_add_u32_e32 v35, -1, v35
	v_subrev_u32_e32 v46, 24, v46
	v_max_i32_e32 v82, v37, v48
	v_max_i32_e32 v124, v38, v42
	v_max_i32_e32 v126, v34, v47
	v_max_i32_e32 v127, v39, v40
	v_min_i32_e32 v130, v43, v44
	v_min_i32_e32 v131, v36, v49
	v_min_i32_e32 v133, v41, v45
	v_min_i32_e32 v134, v35, v46
	v_min_i32_e32 v39, v39, v40
	v_min_i32_e32 v34, v34, v47
	v_min_i32_e32 v38, v38, v42
	v_min_i32_e32 v37, v37, v48
	v_max_i32_e32 v35, v35, v46
	v_max_i32_e32 v41, v41, v45
	v_max_i32_e32 v36, v36, v49
	v_max_i32_e32 v43, v43, v44
	v_min_i32_e32 v125, v82, v124
	v_min_i32_e32 v128, v126, v127
	v_max_i32_e32 v132, v130, v131
	v_max_i32_e32 v135, v133, v134
	v_max_i32_e32 v40, v39, v34
	v_max_i32_e32 v42, v38, v37
	v_min_i32_e32 v45, v35, v41
	v_min_i32_e32 v44, v36, v43
	v_min_i32_e32 v129, v125, v128
	v_max_i32_e32 v47, v40, v42
	v_max_i32_e32 v46, v45, v44
	v_min_i32_e32 v40, v40, v42
	v_min_i32_e32 v42, v45, v44
	v_max_i32_e32 v45, v125, v128
	v_max_i32_e32 v125, v132, v135
	v_min_i32_e32 v128, v45, v125
	v_min_i32_e32 v34, v39, v34
	v_max_i32_e32 v39, v126, v127
	v_max_i32_e32 v35, v35, v41
	v_max_i32_e32 v41, v82, v124
	v_max_i32_e32 v148, v45, v125
	ds_read_b128 v[124:127], v97
	v_max_i32_e32 v44, v40, v42
	v_min_i32_e32 v138, v40, v42
	v_min_i32_e32 v40, v133, v134
	v_min_i32_e32 v37, v38, v37
	v_min_i32_e32 v38, v130, v131
	v_max_i32_e32 v36, v36, v43
	v_min_i32_e32 v136, v132, v135
	v_min_i32_e32 v133, v40, v34
	v_min_i32_e32 v134, v37, v38
	v_max_i32_e32 v34, v40, v34
	v_max_i32_e32 v37, v37, v38
	v_min_i32_e32 v40, v39, v35
	v_min_i32_e32 v42, v36, v41
	v_max_i32_e32 v144, v39, v35
	v_max_i32_e32 v145, v36, v41
	v_max_i32_e32 v137, v129, v136
	v_min_i32_e32 v136, v129, v136
	v_max_i32_e32 v140, v133, v134
	v_min_i32_e32 v141, v34, v37
	v_max_i32_e32 v143, v40, v42
	v_min_i32_e32 v146, v144, v145
	v_max_i32_e32 v149, v47, v46
	v_min_i32_e32 v48, v47, v46
	v_max_i32_e32 v139, v138, v136
	v_max_i32_e32 v142, v140, v141
	v_min_i32_e32 v43, v40, v42
	v_max_i32_e32 v34, v34, v37
	v_min_i32_e32 v147, v143, v146
	v_min_i32_e32 v150, v148, v149
	v_min_i32_e32 v49, v137, v48
	v_min_i32_e32 v132, v44, v128
	v_max_i32_e32 v38, v139, v142
	v_min_i32_e32 v37, v43, v34
	v_max_i32_e32 v34, v43, v34
	v_min_i32_e32 v35, v147, v150
	v_max_i32_e32 v39, v137, v48
	v_max_i32_e32 v40, v44, v128
	v_max_i32_e32 v135, v49, v132
	v_max_i32_e32 v82, v38, v37
	v_min_i32_e32 v36, v34, v35
	v_min_i32_e32 v41, v39, v40
	v_max_i32_e32 v129, v135, v82
	v_min_i32_e32 v42, v36, v41
	v_min_i32_e32 v137, v129, v42
	v_max_i32_e32 v159, v129, v42
	ds_read_b128 v[128:131], v97 offset:32
	v_min_i32_e32 v82, v135, v82
	v_min_i32_e32 v132, v49, v132
	v_min_i32_e32 v135, v38, v37
	v_max_i32_e32 v154, v34, v35
	v_max_i32_e32 v155, v39, v40
	v_max_i32_e32 v157, v36, v41
	s_waitcnt lgkmcnt(1)
; #define LAS __attribute__((address_space(3)))
; #define MFMA32(a, b, c) __builtin_amdgcn_mfma_f32_32x32x16_bf16((a), (b), (c), 0, 0, 0)
; #define CE_(a, b) ce_desc(v[a], v[b])
; __device__ __forceinline__ void sort16_desc(int (&v)[16]) {
;     ...
;     CE_(0,13); CE_(1,12); CE_(2,15); CE_(3,14); CE_(4,8); CE_(5,6); CE_(7,11); CE_(9,10);
;     CE_(0,5); CE_(1,7); CE_(2,9); CE_(3,4); CE_(6,13); CE_(8,14); CE_(10,15); CE_(11,12);
;     CE_(0,1); CE_(2,3); CE_(4,5); CE_(6,8); CE_(7,9); CE_(10,11); CE_(12,13); CE_(14,15);
;     CE_(0,2); CE_(1,3); CE_(4,10); CE_(5,11); CE_(6,7); CE_(8,9); CE_(12,14); CE_(13,15);
;     CE_(1,2); CE_(3,12); CE_(4,6); CE_(5,7); CE_(8,10); CE_(9,11); CE_(13,14);
;     CE_(1,4); CE_(2,6); CE_(5,8); CE_(7,10); CE_(9,13); CE_(11,14);
;     CE_(2,4); CE_(3,6); CE_(9,12); CE_(11,13);
;     CE_(3,5); CE_(6,8); CE_(7,9); CE_(10,12);
;     CE_(3,4); CE_(5,6); CE_(7,8); CE_(9,10); CE_(11,12);
;     CE_(6,7); CE_(8,9);
;     ...
; }
; __device__ __forceinline__ void merge16_desc(int (&a)[16], const int (&b)[16]) {
; #pragma unroll
;     for (int i = 0; i < 16; ++i) a[i] = a[i] > b[15 - i] ? a[i] : b[15 - i];
; #pragma unroll
;     for (int j = 8; j > 0; j >>= 1)
; #pragma unroll
;         for (int i = 0; i < 16; ++i) { const int l = i ^ j; if (l > i) ce_desc(a[i], a[l]); }
; }
; __device__ __forceinline__ void route_task(int task, int tl0, const bf16* QP  , const LAS bf16* KHL, LAS unsigned short* EL, LAS float* GL, int lane) {
;     ...
;         for (int kt = 0; kt < 4; ++kt) {
;             f32x16 X;
; #pragma unroll
;             for (int i = 0; i < 16; ++i) X[i] = 8.f;
;             const LAS bf16* khp = KHL + (half * 128 + 32 * kt + r) * 72 + 8 * hi;
; #pragma unroll
;             for (int ks = 0; ks < 4; ++ks) {
;                 const bf16x8 kh = lds8(khp + 16 * ks);
;                 X = MFMA32(kh, qa[half][ks], X);
;             }
;             int grp[16];
; #pragma unroll
;             for (int i = 0; i < 16; ++i) grp[i] = (int)((__float_as_uint(X[i]) | 127u) - (unsigned)(32 * kt + (i & 3) + 8 * (i >> 2)));
;             sort16_desc(grp);
;             if (kt == 0) {
; #pragma unroll
;                 for (int i = 0; i < 16; ++i) cur[i] = grp[i];
;             } else merge16_desc(cur, grp);
	v_mfma_f32_32x32x16_bf16 v[34:49], v[124:127], v[62:65], v[18:33]
	ds_read_b128 v[124:127], v97 offset:64
	v_max_i32_e32 v151, v132, v135
	v_max_i32_e32 v152, v82, v151
	v_min_i32_e32 v136, v138, v136
	v_min_i32_e32 v138, v140, v141
	v_min_i32_e32 v82, v82, v151
	v_max_i32_e32 v147, v147, v150
	s_waitcnt lgkmcnt(1)
	v_mfma_f32_32x32x16_bf16 v[34:49], v[128:131], v[58:61], v[34:49]
	ds_read_b128 v[128:131], v97 offset:96
	v_max_i32_e32 v143, v143, v146
	v_min_i32_e32 v133, v133, v134
	v_min_i32_e32 v156, v154, v155
	v_max_i32_e32 v140, v136, v138
	v_min_i32_e32 v139, v139, v142
	v_max_i32_e32 v142, v154, v155
	s_waitcnt lgkmcnt(1)
	v_mfma_f32_32x32x16_bf16 v[34:49], v[124:127], v[54:57], v[34:49]
	v_max_i32_e32 v124, v148, v149
	v_min_i32_e32 v136, v136, v138
	v_max_i32_e32 v141, v140, v139
	v_min_i32_e32 v139, v140, v139
	v_min_i32_e32 v125, v143, v124
	v_min_i32_e32 v158, v156, v157
	v_min_i32_e32 v132, v132, v135
	s_waitcnt lgkmcnt(0)
	v_mfma_f32_32x32x16_bf16 v[34:49], v[128:131], v[50:53], v[34:49]
	v_min_i32_e32 v126, v147, v125
	v_min_i32_e32 v153, v137, v152
	v_min_i32_e32 v160, v158, v159
	v_min_i32_e32 v135, v141, v132
	v_min_i32_e32 v127, v142, v126
	s_nop 6
	v_or_b32_e32 v37, 0x7f, v37
	v_or_b32_e32 v48, 0x7f, v48
	v_or_b32_e32 v38, 0x7f, v38
	v_or_b32_e32 v42, 0x7f, v42
	v_or_b32_e32 v34, 0x7f, v34
	v_or_b32_e32 v47, 0x7f, v47
	v_or_b32_e32 v39, 0x7f, v39
	v_or_b32_e32 v40, 0x7f, v40
	v_or_b32_e32 v43, 0x7f, v43
	v_or_b32_e32 v44, 0x7f, v44
	v_or_b32_e32 v36, 0x7f, v36
	v_or_b32_e32 v49, 0x7f, v49
	v_or_b32_e32 v41, 0x7f, v41
	v_or_b32_e32 v45, 0x7f, v45
	v_or_b32_e32 v35, 0x7f, v35
	v_or_b32_e32 v46, 0x7f, v46
	v_subrev_u32_e32 v37, 35, v37
	v_subrev_u32_e32 v48, 58, v48
	v_subrev_u32_e32 v38, 40, v38
	v_subrev_u32_e32 v42, 48, v42
	v_subrev_u32_e32 v34, 32, v34
	v_subrev_u32_e32 v47, 57, v47
	v_subrev_u32_e32 v39, 41, v39
	v_subrev_u32_e32 v40, 42, v40
	v_subrev_u32_e32 v43, 49, v43
	v_subrev_u32_e32 v44, 50, v44
	v_subrev_u32_e32 v36, 34, v36
	v_subrev_u32_e32 v49, 59, v49
	v_subrev_u32_e32 v41, 43, v41
	v_subrev_u32_e32 v45, 51, v45
	v_subrev_u32_e32 v35, 33, v35
	v_subrev_u32_e32 v46, 56, v46
	v_max_i32_e32 v128, v37, v48
	v_max_i32_e32 v129, v38, v42
	v_max_i32_e32 v131, v34, v47
	v_max_i32_e32 v134, v39, v40
	v_min_i32_e32 v146, v43, v44
	v_min_i32_e32 v148, v36, v49
	v_min_i32_e32 v150, v41, v45
	v_min_i32_e32 v151, v35, v46
	v_min_i32_e32 v39, v39, v40
	v_min_i32_e32 v34, v34, v47
	v_min_i32_e32 v38, v38, v42
	v_min_i32_e32 v37, v37, v48
	v_max_i32_e32 v35, v35, v46
	v_max_i32_e32 v41, v41, v45
	v_max_i32_e32 v36, v36, v49
	v_max_i32_e32 v43, v43, v44
	v_min_i32_e32 v130, v128, v129
	v_min_i32_e32 v138, v131, v134
	v_max_i32_e32 v149, v146, v148
	v_max_i32_e32 v154, v150, v151
	v_max_i32_e32 v40, v39, v34
	v_max_i32_e32 v42, v38, v37
	v_min_i32_e32 v45, v35, v41
	v_min_i32_e32 v44, v36, v43
	v_min_i32_e32 v150, v150, v151
	v_min_i32_e32 v34, v39, v34
	v_min_i32_e32 v37, v38, v37
	v_min_i32_e32 v38, v146, v148
	v_max_i32_e32 v131, v131, v134
	v_max_i32_e32 v35, v35, v41
	v_max_i32_e32 v36, v36, v43
	v_max_i32_e32 v43, v128, v129
	v_min_i32_e32 v140, v130, v138
	v_min_i32_e32 v155, v149, v154
	v_max_i32_e32 v47, v40, v42
	v_max_i32_e32 v46, v45, v44
	v_min_i32_e32 v40, v40, v42
	v_min_i32_e32 v42, v45, v44
	v_max_i32_e32 v45, v130, v138
	v_max_i32_e32 v130, v149, v154
	v_min_i32_e32 v39, v150, v34
	v_min_i32_e32 v146, v37, v38
	v_max_i32_e32 v34, v150, v34
	v_max_i32_e32 v37, v37, v38
	v_min_i32_e32 v41, v131, v35
	v_min_i32_e32 v128, v36, v43
	v_max_i32_e32 v35, v131, v35
	v_max_i32_e32 v36, v36, v43
	v_min_i32_e32 v48, v47, v46
	v_max_i32_e32 v44, v40, v42
	v_min_i32_e32 v138, v45, v130
	v_min_i32_e32 v40, v40, v42
	v_min_i32_e32 v42, v140, v155
	v_max_i32_e32 v148, v39, v146
	v_min_i32_e32 v38, v34, v37
	v_min_i32_e32 v129, v41, v128
	v_max_i32_e32 v41, v41, v128
	v_min_i32_e32 v43, v35, v36
	v_max_i32_e32 v45, v45, v130
	v_max_i32_e32 v46, v47, v46
	v_max_i32_e32 v161, v140, v155
	v_max_i32_e32 v140, v40, v42
	v_max_i32_e32 v150, v148, v38
	v_max_i32_e32 v34, v34, v37
	v_min_i32_e32 v128, v41, v43
	v_min_i32_e32 v47, v45, v46
	v_min_i32_e32 v49, v161, v48
	v_min_i32_e32 v149, v44, v138
	v_max_i32_e32 v151, v140, v150
	v_min_i32_e32 v37, v129, v34
	v_max_i32_e32 v34, v129, v34
	v_min_i32_e32 v129, v128, v47
	v_max_i32_e32 v48, v161, v48
	v_max_i32_e32 v44, v44, v138
	v_max_i32_e32 v154, v49, v149
	v_max_i32_e32 v134, v151, v37
	v_min_i32_e32 v130, v34, v129
	v_min_i32_e32 v131, v48, v44
	v_min_i32_e32 v49, v49, v149
	v_min_i32_e32 v37, v151, v37
	v_max_i32_e32 v34, v34, v129
	v_max_i32_e32 v44, v48, v44
	v_min_i32_e32 v40, v40, v42
	v_min_i32_e32 v38, v148, v38
	v_max_i32_e32 v41, v41, v43
	v_max_i32_e32 v43, v45, v46
	v_max_i32_e32 v155, v154, v134
	v_min_i32_e32 v138, v130, v131
	v_min_i32_e32 v134, v154, v134
	v_max_i32_e32 v149, v49, v37
	v_min_i32_e32 v48, v34, v44
	v_max_i32_e32 v129, v130, v131
	v_max_i32_e32 v42, v40, v38
	v_min_i32_e32 v140, v140, v150
	v_max_i32_e32 v34, v34, v44
	v_max_i32_e32 v44, v128, v47
	v_min_i32_e32 v45, v41, v43
	v_min_i32_e32 v161, v155, v138
	v_max_i32_e32 v151, v134, v149
	v_min_i32_e32 v130, v48, v129
	v_max_i32_e32 v131, v155, v138
	v_max_i32_e32 v148, v42, v140
	v_min_i32_e32 v37, v49, v37
	v_min_i32_e32 v46, v44, v45
	v_min_i32_e32 v154, v161, v151
	v_min_i32_e32 v138, v130, v131
	v_min_i32_e32 v49, v148, v37
	v_min_i32_e32 v134, v134, v149
	v_min_i32_e32 v47, v34, v46
	v_min_i32_e32 v42, v42, v140
	v_min_i32_e32 v38, v40, v38
	v_min_i32_e32 v39, v39, v146
	v_max3_i32 v39, v144, v145, v39
	v_max3_i32 v38, v143, v124, v38
	v_max3_i32 v40, v147, v125, v42
; #define LAS __attribute__((address_space(3)))
; #define MFMA32(a, b, c) __builtin_amdgcn_mfma_f32_32x32x16_bf16((a), (b), (c), 0, 0, 0)
; #define CE_(a, b) ce_desc(v[a], v[b])
; __device__ __forceinline__ void sort16_desc(int (&v)[16]) {
;     ...
;     CE_(0,13); CE_(1,12); CE_(2,15); CE_(3,14); CE_(4,8); CE_(5,6); CE_(7,11); CE_(9,10);
;     CE_(0,5); CE_(1,7); CE_(2,9); CE_(3,4); CE_(6,13); CE_(8,14); CE_(10,15); CE_(11,12);
;     CE_(0,1); CE_(2,3); CE_(4,5); CE_(6,8); CE_(7,9); CE_(10,11); CE_(12,13); CE_(14,15);
;     CE_(0,2); CE_(1,3); CE_(4,10); CE_(5,11); CE_(6,7); CE_(8,9); CE_(12,14); CE_(13,15);
;     CE_(1,2); CE_(3,12); CE_(4,6); CE_(5,7); CE_(8,10); CE_(9,11); CE_(13,14);
;     CE_(1,4); CE_(2,6); CE_(5,8); CE_(7,10); CE_(9,13); CE_(11,14);
;     CE_(2,4); CE_(3,6); CE_(9,12); CE_(11,13);
;     CE_(3,5); CE_(6,8); CE_(7,9); CE_(10,12);
;     CE_(3,4); CE_(5,6); CE_(7,8); CE_(9,10); CE_(11,12);
;     CE_(6,7); CE_(8,9);
;     ...
; }
; __device__ __forceinline__ void merge16_desc(int (&a)[16], const int (&b)[16]) {
; #pragma unroll
;     for (int i = 0; i < 16; ++i) a[i] = a[i] > b[15 - i] ? a[i] : b[15 - i];
; #pragma unroll
;     for (int j = 8; j > 0; j >>= 1)
; #pragma unroll
;         for (int i = 0; i < 16; ++i) { const int l = i ^ j; if (l > i) ce_desc(a[i], a[l]); }
; }
; __device__ __forceinline__ void route_task(int task, int tl0, const bf16* QP  , const LAS bf16* KHL, LAS unsigned short* EL, LAS float* GL, int lane) {
;     ...
;         for (int kt = 0; kt < 4; ++kt) {
;             f32x16 X;
; #pragma unroll
;             for (int i = 0; i < 16; ++i) X[i] = 8.f;
;             const LAS bf16* khp = KHL + (half * 128 + 32 * kt + r) * 72 + 8 * hi;
; #pragma unroll
;             for (int ks = 0; ks < 4; ++ks) {
;                 const bf16x8 kh = lds8(khp + 16 * ks);
;                 X = MFMA32(kh, qa[half][ks], X);
;             }
;             int grp[16];
; #pragma unroll
;             for (int i = 0; i < 16; ++i) grp[i] = (int)((__float_as_uint(X[i]) | 127u) - (unsigned)(32 * kt + (i & 3) + 8 * (i >> 2)));
;             sort16_desc(grp);
;             if (kt == 0) {
; #pragma unroll
;                 for (int i = 0; i < 16; ++i) cur[i] = grp[i];
;             } else merge16_desc(cur, grp);
	v_max3_i32 v42, v142, v126, v49
	v_max3_i32 v37, v127, v148, v37
	v_max3_i32 v49, v156, v157, v134
	v_max3_i32 v124, v158, v159, v154
	v_max3_i32 v125, v160, v161, v151
	v_max3_i32 v126, v137, v152, v138
	v_max3_i32 v127, v153, v130, v131
	v_max3_i32 v48, v82, v48, v129
	v_max3_i32 v47, v141, v132, v47
	v_max3_i32 v34, v135, v34, v46
	v_max3_i32 v44, v139, v44, v45
	v_max3_i32 v41, v136, v41, v43
	v_max3_i32 v35, v133, v35, v36
	v_max_i32_e32 v36, v39, v126
	v_min_i32_e32 v39, v39, v126
	v_max_i32_e32 v43, v38, v127
	v_min_i32_e32 v38, v38, v127
	v_max_i32_e32 v45, v40, v48
	v_min_i32_e32 v40, v40, v48
	v_max_i32_e32 v46, v42, v47
	v_min_i32_e32 v42, v42, v47
	v_max_i32_e32 v47, v37, v34
	v_min_i32_e32 v34, v37, v34
	v_max_i32_e32 v37, v49, v44
	v_min_i32_e32 v44, v49, v44
	v_max_i32_e32 v48, v124, v41
	v_min_i32_e32 v41, v124, v41
	v_max_i32_e32 v49, v125, v35
	v_min_i32_e32 v35, v125, v35
	ds_read_b128 v[124:127], v94 offset:27648
	ds_read_b128 v[128:131], v94 offset:27680
	v_max_i32_e32 v82, v36, v47
	v_min_i32_e32 v132, v36, v47
	v_max_i32_e32 v36, v43, v37
	v_min_i32_e32 v133, v43, v37
	v_max_i32_e32 v37, v45, v48
	v_max_i32_e32 v43, v46, v49
	v_min_i32_e32 v134, v45, v48
	v_min_i32_e32 v135, v46, v49
	v_max_i32_e32 v136, v39, v34
	v_min_i32_e32 v137, v39, v34
	v_max_i32_e32 v138, v38, v44
	v_min_i32_e32 v139, v38, v44
	v_max_i32_e32 v140, v40, v41
	v_min_i32_e32 v141, v40, v41
	v_max_i32_e32 v142, v42, v35
	v_min_i32_e32 v143, v42, v35
	v_max_i32_e32 v144, v82, v37
	v_min_i32_e32 v82, v82, v37
	v_max_i32_e32 v145, v36, v43
	v_min_i32_e32 v146, v36, v43
	s_waitcnt lgkmcnt(1)
	v_mfma_f32_32x32x16_bf16 v[34:49], v[124:127], v[62:65], v[18:33]
	ds_read_b128 v[124:127], v94 offset:27712
	v_max_i32_e32 v147, v132, v134
	v_min_i32_e32 v132, v132, v134
	v_max_i32_e32 v134, v133, v135
	v_min_i32_e32 v133, v133, v135
	v_max_i32_e32 v135, v136, v140
	v_min_i32_e32 v136, v136, v140
	s_waitcnt lgkmcnt(1)
	v_mfma_f32_32x32x16_bf16 v[34:49], v[128:131], v[58:61], v[34:49]
	ds_read_b128 v[128:131], v94 offset:27744
	v_max_i32_e32 v140, v138, v142
	v_min_i32_e32 v138, v138, v142
	v_max_i32_e32 v142, v137, v141
	v_min_i32_e32 v137, v137, v141
	v_max_i32_e32 v141, v139, v143
	v_min_i32_e32 v139, v139, v143
	s_waitcnt lgkmcnt(1)
	v_mfma_f32_32x32x16_bf16 v[34:49], v[124:127], v[54:57], v[34:49]
	v_min_i32_e32 v143, v144, v145
	v_min_i32_e32 v124, v82, v146
	v_min_i32_e32 v127, v135, v140
	v_min_i32_e32 v125, v147, v134
	v_min_i32_e32 v126, v132, v133
	v_min_i32_e32 v149, v142, v141
	v_min_i32_e32 v148, v136, v138
	s_waitcnt lgkmcnt(0)
	v_mfma_f32_32x32x16_bf16 v[34:49], v[128:131], v[50:53], v[34:49]
	v_min_i32_e32 v150, v137, v139
	s_nop 10
	v_or_b32_e32 v37, 0x7f, v37
	v_or_b32_e32 v48, 0x7f, v48
	v_or_b32_e32 v38, 0x7f, v38
	v_or_b32_e32 v42, 0x7f, v42
	v_or_b32_e32 v34, 0x7f, v34
	v_or_b32_e32 v47, 0x7f, v47
	v_or_b32_e32 v39, 0x7f, v39
	v_or_b32_e32 v40, 0x7f, v40
	v_or_b32_e32 v43, 0x7f, v43
	v_or_b32_e32 v44, 0x7f, v44
	v_or_b32_e32 v36, 0x7f, v36
	v_or_b32_e32 v49, 0x7f, v49
	v_or_b32_e32 v41, 0x7f, v41
	v_or_b32_e32 v45, 0x7f, v45
	v_or_b32_e32 v35, 0x7f, v35
	v_or_b32_e32 v46, 0x7f, v46
	v_add_u32_e32 v37, 0xffffffbd, v37
	v_add_u32_e32 v48, 0xffffffa6, v48
	v_add_u32_e32 v38, 0xffffffb8, v38
	v_add_u32_e32 v42, 0xffffffb0, v42
	v_subrev_u32_e32 v34, 64, v34
	v_add_u32_e32 v47, 0xffffffa7, v47
	v_add_u32_e32 v39, 0xffffffb7, v39
	v_add_u32_e32 v40, 0xffffffb6, v40
	v_add_u32_e32 v43, 0xffffffaf, v43
	v_add_u32_e32 v44, 0xffffffae, v44
	v_add_u32_e32 v36, 0xffffffbe, v36
	v_add_u32_e32 v49, 0xffffffa5, v49
	v_add_u32_e32 v41, 0xffffffb5, v41
	v_add_u32_e32 v45, 0xffffffad, v45
	v_add_u32_e32 v35, 0xffffffbf, v35
	v_add_u32_e32 v46, 0xffffffa8, v46
	v_max_i32_e32 v128, v37, v48
	v_max_i32_e32 v129, v38, v42
	v_max_i32_e32 v131, v34, v47
	v_max_i32_e32 v151, v39, v40
	v_min_i32_e32 v154, v43, v44
	v_min_i32_e32 v155, v36, v49
	v_min_i32_e32 v157, v41, v45
	v_min_i32_e32 v158, v35, v46
	v_min_i32_e32 v39, v39, v40
	v_min_i32_e32 v34, v34, v47
	v_min_i32_e32 v38, v38, v42
	v_min_i32_e32 v37, v37, v48
	v_max_i32_e32 v35, v35, v46
	v_max_i32_e32 v41, v41, v45
	v_max_i32_e32 v36, v36, v49
	v_max_i32_e32 v43, v43, v44
	v_min_i32_e32 v130, v128, v129
	v_min_i32_e32 v152, v131, v151
	v_max_i32_e32 v156, v154, v155
	v_max_i32_e32 v159, v157, v158
	v_max_i32_e32 v40, v39, v34
	v_max_i32_e32 v42, v38, v37
	v_min_i32_e32 v45, v35, v41
	v_min_i32_e32 v44, v36, v43
	v_min_i32_e32 v157, v157, v158
	v_min_i32_e32 v34, v39, v34
	v_min_i32_e32 v37, v38, v37
	v_min_i32_e32 v38, v154, v155
	v_max_i32_e32 v131, v131, v151
	v_max_i32_e32 v35, v35, v41
	v_max_i32_e32 v36, v36, v43
	v_max_i32_e32 v43, v128, v129
	v_min_i32_e32 v153, v130, v152
	v_min_i32_e32 v160, v156, v159
	v_max_i32_e32 v47, v40, v42
	v_max_i32_e32 v46, v45, v44
	v_min_i32_e32 v40, v40, v42
	v_min_i32_e32 v42, v45, v44
	v_max_i32_e32 v45, v130, v152
	v_max_i32_e32 v130, v156, v159
	v_min_i32_e32 v39, v157, v34
	v_min_i32_e32 v154, v37, v38
	v_max_i32_e32 v34, v157, v34
	v_max_i32_e32 v37, v37, v38
	v_min_i32_e32 v41, v131, v35
	v_min_i32_e32 v128, v36, v43
	v_max_i32_e32 v35, v131, v35
	v_max_i32_e32 v36, v36, v43
	v_min_i32_e32 v48, v47, v46
	v_max_i32_e32 v44, v40, v42
	v_min_i32_e32 v152, v45, v130
	v_min_i32_e32 v40, v40, v42
	v_min_i32_e32 v42, v153, v160
	v_max_i32_e32 v155, v39, v154
	v_min_i32_e32 v38, v34, v37
	v_min_i32_e32 v129, v41, v128
	v_max_i32_e32 v41, v41, v128
	v_min_i32_e32 v43, v35, v36
	v_max_i32_e32 v45, v45, v130
	v_max_i32_e32 v46, v47, v46
	v_max_i32_e32 v161, v153, v160
	v_max_i32_e32 v153, v40, v42
	v_max_i32_e32 v157, v155, v38
	v_max_i32_e32 v34, v34, v37
; #define LAS __attribute__((address_space(3)))
; #define MFMA32(a, b, c) __builtin_amdgcn_mfma_f32_32x32x16_bf16((a), (b), (c), 0, 0, 0)
; #define CE_(a, b) ce_desc(v[a], v[b])
; __device__ __forceinline__ void sort16_desc(int (&v)[16]) {
;     ...
;     CE_(0,13); CE_(1,12); CE_(2,15); CE_(3,14); CE_(4,8); CE_(5,6); CE_(7,11); CE_(9,10);
;     CE_(0,5); CE_(1,7); CE_(2,9); CE_(3,4); CE_(6,13); CE_(8,14); CE_(10,15); CE_(11,12);
;     CE_(0,1); CE_(2,3); CE_(4,5); CE_(6,8); CE_(7,9); CE_(10,11); CE_(12,13); CE_(14,15);
;     CE_(0,2); CE_(1,3); CE_(4,10); CE_(5,11); CE_(6,7); CE_(8,9); CE_(12,14); CE_(13,15);
;     CE_(1,2); CE_(3,12); CE_(4,6); CE_(5,7); CE_(8,10); CE_(9,11); CE_(13,14);
;     CE_(1,4); CE_(2,6); CE_(5,8); CE_(7,10); CE_(9,13); CE_(11,14);
;     CE_(2,4); CE_(3,6); CE_(9,12); CE_(11,13);
;     CE_(3,5); CE_(6,8); CE_(7,9); CE_(10,12);
;     CE_(3,4); CE_(5,6); CE_(7,8); CE_(9,10); CE_(11,12);
;     CE_(6,7); CE_(8,9);
;     ...
; }
; __device__ __forceinline__ void merge16_desc(int (&a)[16], const int (&b)[16]) {
; #pragma unroll
;     for (int i = 0; i < 16; ++i) a[i] = a[i] > b[15 - i] ? a[i] : b[15 - i];
; #pragma unroll
;     for (int j = 8; j > 0; j >>= 1)
; #pragma unroll
;         for (int i = 0; i < 16; ++i) { const int l = i ^ j; if (l > i) ce_desc(a[i], a[l]); }
; }
; __device__ __forceinline__ void route_task(int task, int tl0, const bf16* QP  , const LAS bf16* KHL, LAS unsigned short* EL, LAS float* GL, int lane) {
;     ...
;         for (int kt = 0; kt < 4; ++kt) {
;             f32x16 X;
; #pragma unroll
;             for (int i = 0; i < 16; ++i) X[i] = 8.f;
;             const LAS bf16* khp = KHL + (half * 128 + 32 * kt + r) * 72 + 8 * hi;
; #pragma unroll
;             for (int ks = 0; ks < 4; ++ks) {
;                 const bf16x8 kh = lds8(khp + 16 * ks);
;                 X = MFMA32(kh, qa[half][ks], X);
;             }
;             int grp[16];
; #pragma unroll
;             for (int i = 0; i < 16; ++i) grp[i] = (int)((__float_as_uint(X[i]) | 127u) - (unsigned)(32 * kt + (i & 3) + 8 * (i >> 2)));
;             sort16_desc(grp);
;             if (kt == 0) {
; #pragma unroll
;                 for (int i = 0; i < 16; ++i) cur[i] = grp[i];
;             } else merge16_desc(cur, grp);
	v_min_i32_e32 v128, v41, v43
	v_min_i32_e32 v47, v45, v46
	v_min_i32_e32 v49, v161, v48
	v_min_i32_e32 v156, v44, v152
	v_max_i32_e32 v158, v153, v157
	v_min_i32_e32 v37, v129, v34
	v_max_i32_e32 v34, v129, v34
	v_min_i32_e32 v129, v128, v47
	v_max_i32_e32 v48, v161, v48
	v_max_i32_e32 v44, v44, v152
	v_min_i32_e32 v40, v40, v42
	v_min_i32_e32 v38, v155, v38
	v_max_i32_e32 v159, v49, v156
	v_max_i32_e32 v151, v158, v37
	v_min_i32_e32 v130, v34, v129
	v_min_i32_e32 v131, v48, v44
	v_min_i32_e32 v49, v49, v156
	v_min_i32_e32 v37, v158, v37
	v_max_i32_e32 v34, v34, v129
	v_max_i32_e32 v44, v48, v44
	v_max_i32_e32 v42, v40, v38
	v_min_i32_e32 v153, v153, v157
	v_max_i32_e32 v160, v159, v151
	v_min_i32_e32 v152, v130, v131
	v_max_i32_e32 v156, v49, v37
	v_min_i32_e32 v48, v34, v44
	v_max_i32_e32 v129, v130, v131
	v_max_i32_e32 v155, v42, v153
	v_min_i32_e32 v37, v49, v37
	v_min_i32_e32 v151, v159, v151
	v_min_i32_e32 v130, v48, v129
	v_max_i32_e32 v131, v160, v152
	v_min_i32_e32 v49, v155, v37
	v_max_i32_e32 v41, v41, v43
	v_max_i32_e32 v43, v45, v46
	v_min_i32_e32 v42, v42, v153
	v_min_i32_e32 v38, v40, v38
	v_min_i32_e32 v161, v160, v152
	v_max_i32_e32 v158, v151, v156
	v_min_i32_e32 v151, v151, v156
	v_max_i32_e32 v34, v34, v44
	v_max_i32_e32 v44, v128, v47
	v_min_i32_e32 v45, v41, v43
	v_max_i32_e32 v40, v41, v43
	v_max_i32_e32 v38, v143, v38
	v_max3_i32 v41, v82, v146, v42
	v_max_i32_e32 v42, v124, v49
	v_max3_i32 v124, v127, v130, v131
	v_min_i32_e32 v46, v44, v45
	v_max_i32_e32 v43, v125, v151
	v_max3_i32 v49, v126, v161, v158
	v_max3_i32 v44, v149, v44, v45
	v_max_i32_e32 v45, v38, v124
	v_min_i32_e32 v38, v38, v124
	ds_read_b128 v[124:127], v98
	v_min_i32_e32 v159, v161, v158
	v_min_i32_e32 v152, v130, v131
	v_max_i32_e32 v37, v155, v37
	v_max_i32_e32 v48, v48, v129
	v_min_i32_e32 v47, v34, v46
	v_max_i32_e32 v34, v34, v46
	v_min_i32_e32 v39, v39, v154
	v_max3_i32 v39, v144, v145, v39
	v_max3_i32 v37, v147, v134, v37
	v_max3_i32 v46, v132, v133, v159
	v_max3_i32 v82, v135, v140, v152
	v_max3_i32 v48, v136, v138, v48
	v_max_i32_e32 v47, v148, v47
	v_max3_i32 v34, v142, v141, v34
	v_max3_i32 v40, v137, v139, v40
	v_max3_i32 v35, v150, v35, v36
	v_max_i32_e32 v36, v39, v82
	v_min_i32_e32 v39, v39, v82
	v_max_i32_e32 v82, v41, v48
	v_min_i32_e32 v41, v41, v48
	v_max_i32_e32 v48, v42, v47
	v_min_i32_e32 v42, v42, v47
	v_max_i32_e32 v47, v37, v34
	v_min_i32_e32 v34, v37, v34
	v_max_i32_e32 v37, v43, v44
	v_min_i32_e32 v43, v43, v44
	v_max_i32_e32 v44, v46, v40
	v_min_i32_e32 v40, v46, v40
	v_max_i32_e32 v46, v49, v35
	v_min_i32_e32 v35, v49, v35
	v_max_i32_e32 v49, v36, v47
	v_min_i32_e32 v132, v36, v47
	v_max_i32_e32 v36, v45, v37
	v_min_i32_e32 v133, v45, v37
	v_max_i32_e32 v37, v82, v44
	v_min_i32_e32 v82, v82, v44
	v_max_i32_e32 v44, v48, v46
	ds_read_b128 v[128:131], v98 offset:32
	v_min_i32_e32 v134, v48, v46
	v_max_i32_e32 v135, v39, v34
	v_min_i32_e32 v136, v39, v34
	v_max_i32_e32 v137, v38, v43
	v_min_i32_e32 v138, v38, v43
	v_max_i32_e32 v139, v41, v40
	v_min_i32_e32 v140, v41, v40
	v_max_i32_e32 v141, v42, v35
	v_min_i32_e32 v142, v42, v35
	v_max_i32_e32 v143, v49, v37
	v_min_i32_e32 v144, v49, v37
	v_max_i32_e32 v145, v36, v44
	v_min_i32_e32 v146, v36, v44
	s_waitcnt lgkmcnt(1)
	v_mfma_f32_32x32x16_bf16 v[34:49], v[124:127], v[62:65], v[18:33]
	v_max_i32_e32 v147, v132, v82
	s_nop 5
	ds_read_b128 v[18:21], v98 offset:64
	ds_read_b128 v[22:25], v98 offset:96
	s_waitcnt lgkmcnt(2)
	v_mfma_f32_32x32x16_bf16 v[34:49], v[128:131], v[58:61], v[34:49]
	v_min_i32_e32 v26, v132, v82
	v_max_i32_e32 v27, v133, v134
	v_min_i32_e32 v30, v135, v139
	v_min_i32_e32 v32, v137, v141
	v_max_i32_e32 v33, v136, v140
	v_max_i32_e32 v59, v138, v142
	v_min_i32_e32 v28, v133, v134
	s_waitcnt lgkmcnt(1)
	v_mfma_f32_32x32x16_bf16 v[34:49], v[18:21], v[54:57], v[34:49]
	v_min_i32_e32 v19, v147, v27
	v_min_i32_e32 v54, v30, v32
	v_min_i32_e32 v55, v33, v59
	v_max_i32_e32 v29, v135, v139
	v_max_i32_e32 v31, v137, v141
	v_min_i32_e32 v58, v136, v140
	v_min_i32_e32 v60, v138, v142
	s_waitcnt lgkmcnt(0)
	v_mfma_f32_32x32x16_bf16 v[34:49], v[22:25], v[50:53], v[34:49]
	v_min_i32_e32 v18, v144, v146
	v_min_i32_e32 v61, v143, v145
	v_min_i32_e32 v20, v26, v28
	v_min_i32_e32 v21, v29, v31
	v_min_i32_e32 v56, v58, v60
	s_nop 6
	v_or_b32_e32 v22, 0x7f, v41
	v_or_b32_e32 v23, 0x7f, v45
	v_or_b32_e32 v25, 0x7f, v35
	v_or_b32_e32 v35, 0x7f, v46
	v_or_b32_e32 v39, 0x7f, v39
	v_or_b32_e32 v40, 0x7f, v40
	v_or_b32_e32 v34, 0x7f, v34
	v_or_b32_e32 v47, 0x7f, v47
	v_or_b32_e32 v38, 0x7f, v38
	v_or_b32_e32 v42, 0x7f, v42
	v_or_b32_e32 v37, 0x7f, v37
	v_or_b32_e32 v48, 0x7f, v48
	v_or_b32_e32 v43, 0x7f, v43
	v_or_b32_e32 v44, 0x7f, v44
	v_or_b32_e32 v36, 0x7f, v36
	v_or_b32_e32 v49, 0x7f, v49
	v_add_u32_e32 v22, 0xffffff95, v22
	v_add_u32_e32 v23, 0xffffff8d, v23
	v_add_u32_e32 v25, 0xffffff9f, v25
	v_add_u32_e32 v35, 0xffffff88, v35
	v_add_u32_e32 v39, 0xffffff97, v39
	v_add_u32_e32 v40, 0xffffff96, v40
	v_add_u32_e32 v34, 0xffffffa0, v34
	v_add_u32_e32 v47, 0xffffff87, v47
	v_add_u32_e32 v38, 0xffffff98, v38
	v_add_u32_e32 v42, 0xffffff90, v42
	v_add_u32_e32 v37, 0xffffff9d, v37
	v_add_u32_e32 v48, 0xffffff86, v48
	v_add_u32_e32 v43, 0xffffff8f, v43
	v_add_u32_e32 v44, 0xffffff8e, v44
	v_add_u32_e32 v36, 0xffffff9e, v36
	v_add_u32_e32 v49, 0xffffff85, v49
	v_min_i32_e32 v24, v22, v23
	v_min_i32_e32 v41, v25, v35
	v_min_i32_e32 v46, v39, v40
	v_min_i32_e32 v50, v34, v47
	v_min_i32_e32 v53, v38, v42
	v_min_i32_e32 v57, v37, v48
	v_min_i32_e32 v63, v43, v44
	v_min_i32_e32 v64, v36, v49
	v_max_i32_e32 v34, v34, v47
	v_max_i32_e32 v39, v39, v40
	v_max_i32_e32 v25, v25, v35
; #define CE_(a, b) ce_desc(v[a], v[b])
; __device__ __forceinline__ void sort16_desc(int (&v)[16]) {
;     ...
;     CE_(0,13); CE_(1,12); CE_(2,15); CE_(3,14); CE_(4,8); CE_(5,6); CE_(7,11); CE_(9,10);
;     CE_(0,5); CE_(1,7); CE_(2,9); CE_(3,4); CE_(6,13); CE_(8,14); CE_(10,15); CE_(11,12);
;     CE_(0,1); CE_(2,3); CE_(4,5); CE_(6,8); CE_(7,9); CE_(10,11); CE_(12,13); CE_(14,15);
;     CE_(0,2); CE_(1,3); CE_(4,10); CE_(5,11); CE_(6,7); CE_(8,9); CE_(12,14); CE_(13,15);
;     CE_(1,2); CE_(3,12); CE_(4,6); CE_(5,7); CE_(8,10); CE_(9,11); CE_(13,14);
;     CE_(1,4); CE_(2,6); CE_(5,8); CE_(7,10); CE_(9,13); CE_(11,14);
;     CE_(2,4); CE_(3,6); CE_(9,12); CE_(11,13);
;     CE_(3,5); CE_(6,8); CE_(7,9); CE_(10,12);
;     CE_(3,4); CE_(5,6); CE_(7,8); CE_(9,10); CE_(11,12);
;     CE_(6,7); CE_(8,9);
;     ...
; }
; __device__ __forceinline__ void merge16_desc(int (&a)[16], const int (&b)[16]) {
; #pragma unroll
;     for (int i = 0; i < 16; ++i) a[i] = a[i] > b[15 - i] ? a[i] : b[15 - i];
; #pragma unroll
;     for (int j = 8; j > 0; j >>= 1)
; #pragma unroll
;         for (int i = 0; i < 16; ++i) { const int l = i ^ j; if (l > i) ce_desc(a[i], a[l]); }
; }
; __device__ __forceinline__ void route_task(int task, int tl0, const bf16* QP  , const LAS bf16* KHL, LAS unsigned short* EL, LAS float* GL, int lane) {
;     ...
;         { const unsigned h4 = 4u * (unsigned)hi;
; #pragma unroll
;           for (int i = 0; i < 16; ++i) cur[i] -= (int)h4; }
;         int oth[16];
; #pragma unroll
;         for (int i = 0; i < 16; ++i) oth[i] = __shfl_xor(cur[i], 32);
;         merge16_desc(cur, oth);
; #pragma unroll
;         for (int i = 0; i < 16; ++i) top[half][i] = cur[i];
	v_max_i32_e32 v22, v22, v23
	v_max_i32_e32 v36, v36, v49
	v_max_i32_e32 v43, v43, v44
	v_max_i32_e32 v37, v37, v48
	v_max_i32_e32 v38, v38, v42
	v_min_i32_e32 v45, v24, v41
	v_min_i32_e32 v51, v46, v50
	v_max_i32_e32 v40, v34, v39
	v_max_i32_e32 v23, v25, v22
	v_max_i32_e32 v44, v36, v43
	v_max_i32_e32 v42, v37, v38
	v_min_i32_e32 v37, v37, v38
	v_min_i32_e32 v34, v34, v39
	v_max_i32_e32 v39, v63, v64
	v_max_i32_e32 v24, v24, v41
	v_max_i32_e32 v46, v46, v50
	v_max_i32_e32 v50, v53, v57
	v_min_i32_e32 v22, v25, v22
	v_min_i32_e32 v25, v36, v43
	v_min_i32_e32 v62, v53, v57
	v_min_i32_e32 v65, v63, v64
	v_min_i32_e32 v35, v40, v23
	v_min_i32_e32 v47, v44, v42
	v_max_i32_e32 v23, v40, v23
	v_max_i32_e32 v40, v44, v42
	v_max_i32_e32 v38, v37, v34
	v_max_i32_e32 v41, v39, v24
	v_max_i32_e32 v53, v46, v50
	v_max_i32_e32 v36, v22, v25
	v_min_i32_e32 v46, v46, v50
	v_min_i32_e32 v22, v22, v25
	v_min_i32_e32 v52, v45, v51
	v_min_i32_e32 v82, v62, v65
	v_min_i32_e32 v48, v35, v47
	v_max_i32_e32 v45, v45, v51
	v_max_i32_e32 v49, v62, v65
	v_max_i32_e32 v35, v35, v47
	v_min_i32_e32 v42, v23, v40
	v_max_i32_e32 v47, v38, v41
	v_max_i32_e32 v43, v53, v36
	v_min_i32_e32 v34, v37, v34
	v_min_i32_e32 v24, v39, v24
	v_max_i32_e32 v25, v46, v22
	v_min_i32_e32 v38, v38, v41
	v_max_i32_e32 v51, v45, v49
	v_min_i32_e32 v44, v35, v42
	v_min_i32_e32 v57, v47, v43
	v_max_i32_e32 v37, v34, v24
	v_min_i32_e32 v36, v53, v36
	v_max_i32_e32 v41, v25, v38
	v_min_i32_e32 v25, v25, v38
	v_min_i32_e32 v22, v46, v22
	v_min_i32_e32 v24, v34, v24
	v_max_i32_e32 v38, v52, v82
	v_min_i32_e32 v45, v45, v49
	v_max_i32_e32 v62, v48, v51
	v_min_i32_e32 v63, v44, v57
	v_max_i32_e32 v39, v37, v36
	v_max_i32_e32 v34, v22, v24
	v_max_i32_e32 v46, v38, v45
	v_max_i32_e32 v64, v62, v63
	v_max_i32_e32 v50, v39, v41
	v_min_i32_e32 v62, v62, v63
	v_min_i32_e32 v39, v39, v41
	v_min_i32_e32 v36, v37, v36
	v_max_i32_e32 v49, v34, v46
	v_min_i32_e32 v48, v48, v51
	v_min_i32_e32 v22, v22, v24
	v_min_i32_e32 v24, v38, v45
	v_min_i32_e32 v53, v64, v50
	v_max_i32_e32 v41, v62, v39
	v_max_i32_e32 v37, v36, v25
	v_max_i32_e32 v51, v49, v48
	v_max_i32_e32 v38, v22, v24
	v_min_i32_e32 v34, v34, v46
	v_min_i32_e32 v25, v36, v25
	v_min_i32_e32 v36, v49, v48
	v_min_i32_e32 v124, v52, v82
	v_max_i32_e32 v52, v37, v51
	v_min_i32_e32 v39, v62, v39
	v_max_i32_e32 v45, v38, v34
	v_min_i32_e32 v46, v25, v36
	v_max_i32_e32 v35, v35, v42
	v_max_i32_e32 v42, v47, v43
	v_min_i32_e32 v34, v38, v34
	v_max_i32_e32 v38, v53, v41
	v_min_i32_e32 v37, v37, v51
	v_max_i32_e32 v25, v25, v36
	v_max_i32_e32 v48, v45, v46
	v_max_i32_e32 v44, v44, v57
	v_min_i32_e32 v43, v35, v42
	v_max3_i32 v30, v30, v32, v38
	v_min_i32_e32 v38, v52, v39
	v_max_i32_e32 v36, v37, v25
	v_min_i32_e32 v25, v37, v25
	v_min_i32_e32 v63, v53, v41
	v_max_i32_e32 v62, v52, v39
	v_max3_i32 v27, v147, v27, v48
	v_max_i32_e32 v48, v64, v50
	v_min_i32_e32 v47, v44, v43
	v_min_i32_e32 v39, v38, v36
	v_max_i32_e32 v19, v19, v25
	v_max3_i32 v25, v55, v44, v43
	v_min_i32_e32 v43, v45, v46
	v_min_i32_e32 v65, v63, v62
	v_max_i32_e32 v49, v48, v47
	v_max3_i32 v26, v26, v28, v39
	v_max_i32_e32 v28, v35, v42
	v_min_i32_e32 v22, v22, v24
	v_max_i32_e32 v18, v18, v43
	v_min_i32_e32 v43, v48, v47
	v_max3_i32 v124, v143, v145, v124
	v_max3_i32 v29, v29, v31, v65
	v_max3_i32 v33, v33, v59, v49
	v_max3_i32 v34, v144, v146, v34
	v_max3_i32 v28, v58, v60, v28
	v_max_i32_e32 v22, v61, v22
	v_max3_i32 v21, v21, v63, v62
	v_max_i32_e32 v43, v54, v43
	v_max3_i32 v20, v20, v38, v36
	v_max3_i32 v23, v56, v23, v40
	v_min_i32_e32 v31, v124, v29
	v_min_i32_e32 v49, v27, v33
	v_min_i32_e32 v32, v34, v30
	v_min_i32_e32 v35, v26, v28
	v_min_i32_e32 v24, v22, v21
	v_min_i32_e32 v37, v19, v25
	v_min_i32_e32 v44, v18, v43
	v_min_i32_e32 v36, v20, v23
	v_max_i32_e32 v29, v124, v29
	v_max_i32_e32 v27, v27, v33
	v_max_i32_e32 v30, v34, v30
	v_max_i32_e32 v26, v26, v28
	v_max_i32_e32 v21, v22, v21
	v_max_i32_e32 v19, v19, v25
	v_max_i32_e32 v18, v18, v43
	v_max_i32_e32 v20, v20, v23
	v_max_i32_e32 v33, v29, v27
	v_max_i32_e32 v28, v30, v26
	v_max_i32_e32 v22, v21, v19
	v_max_i32_e32 v23, v18, v20
	v_max_i32_e32 v34, v33, v28
	v_max_i32_e32 v25, v22, v23
	v_min_i32_e32 v28, v33, v28
	v_min_i32_e32 v22, v22, v23
	v_min_i32_e32 v27, v29, v27
	v_min_i32_e32 v26, v30, v26
	v_min_i32_e32 v19, v21, v19
	v_min_i32_e32 v18, v18, v20
	v_max_i32_e32 v23, v28, v22
	v_min_i32_e32 v22, v28, v22
	v_max_i32_e32 v28, v27, v26
	v_max_i32_e32 v20, v19, v18
	v_min_i32_e32 v26, v27, v26
	v_min_i32_e32 v18, v19, v18
	v_min_i32_e32 v42, v24, v37
	v_max_i32_e32 v19, v26, v18
	v_min_i32_e32 v18, v26, v18
	v_max_i32_e32 v26, v31, v49
	v_max_i32_e32 v27, v32, v35
	v_max_i32_e32 v24, v24, v37
	v_max_i32_e32 v29, v44, v36
	v_min_i32_e32 v50, v31, v49
	v_min_i32_e32 v39, v32, v35
	v_min_i32_e32 v38, v44, v36
	v_max_i32_e32 v21, v28, v20
	v_min_i32_e32 v20, v28, v20
	v_max_i32_e32 v28, v26, v27
	v_max_i32_e32 v30, v24, v29
	v_min_i32_e32 v26, v26, v27
	v_min_i32_e32 v24, v24, v29
	v_min_i32_e32 v41, v50, v39
	v_min_i32_e32 v40, v42, v38
	v_max_i32_e32 v27, v26, v24
	v_min_i32_e32 v24, v26, v24
	v_max_i32_e32 v26, v50, v39
	v_max_i32_e32 v29, v42, v38
	v_min_i32_e32 v45, v41, v40
	v_max_i32_e32 v43, v34, v25
	v_min_i32_e32 v25, v34, v25
	v_max_i32_e32 v31, v28, v30
	v_min_i32_e32 v28, v28, v30
	v_max_i32_e32 v30, v26, v29
	v_min_i32_e32 v26, v26, v29
	v_max_i32_e32 v29, v41, v40
	v_sub_u32_e32 v32, v43, v87
	v_sub_u32_e32 v25, v25, v87
	v_sub_u32_e32 v23, v23, v87
	v_sub_u32_e32 v22, v22, v87
	v_sub_u32_e32 v21, v21, v87
	v_sub_u32_e32 v20, v20, v87
	v_sub_u32_e32 v19, v19, v87
	v_sub_u32_e32 v18, v18, v87
	v_sub_u32_e32 v31, v31, v87
	v_sub_u32_e32 v28, v28, v87
	v_sub_u32_e32 v27, v27, v87
	v_sub_u32_e32 v24, v24, v87
	v_sub_u32_e32 v30, v30, v87
	v_sub_u32_e32 v26, v26, v87
	v_sub_u32_e32 v29, v29, v87
	v_sub_u32_e32 v33, v45, v87
	ds_bpermute_b32 v34, v123, v32
	ds_bpermute_b32 v35, v123, v25
	ds_bpermute_b32 v36, v123, v23
	ds_bpermute_b32 v37, v123, v22
	ds_bpermute_b32 v38, v123, v21
	ds_bpermute_b32 v39, v123, v20
	ds_bpermute_b32 v40, v123, v19
	ds_bpermute_b32 v41, v123, v18
	ds_bpermute_b32 v42, v123, v31
	ds_bpermute_b32 v43, v123, v28
	ds_bpermute_b32 v44, v123, v27
	ds_bpermute_b32 v45, v123, v33
	ds_bpermute_b32 v46, v123, v29
	ds_bpermute_b32 v47, v123, v26
	ds_bpermute_b32 v48, v123, v30
	ds_bpermute_b32 v49, v123, v24
	s_waitcnt lgkmcnt(4)
; __device__ __forceinline__ void merge16_desc(int (&a)[16], const int (&b)[16]) {
; #pragma unroll
;     for (int i = 0; i < 16; ++i) a[i] = a[i] > b[15 - i] ? a[i] : b[15 - i];
; #pragma unroll
;     for (int j = 8; j > 0; j >>= 1)
; #pragma unroll
;         for (int i = 0; i < 16; ++i) { const int l = i ^ j; if (l > i) ce_desc(a[i], a[l]); }
; }
; __device__ __forceinline__ void route_task(int task, int tl0, const bf16* QP  , const LAS bf16* KHL, LAS unsigned short* EL, LAS float* GL, int lane) {
;     ...
;     unsigned P1[4], P2[4];
; #pragma unroll
;     for (int q = 0; q < 4; ++q) { P1[q] = 0u; P2[q] = 0u;
; #pragma unroll
;         for (int s = 0; s < 4; ++s) { P1[q] |= (127u - ((unsigned)top[0][4 * q + s] & 127u)) << (8 * s); P2[q] |= (127u - ((unsigned)top[1][4 * q + s] & 127u)) << (8 * s); } }
;     int bk[16];
;     {
;         int hi2 = hi; asm volatile("" : "+v"(hi2));
;         const bool h1 = hi2 != 0;
;         constexpr int A1[16] = {1, 1, 1, 1, 1, 1, 1, 1, 2, 2, 2, 2, 2, 3, 3, 3}, B1[16] = {0, 1, 2, 3, 4, 5, 6, 7, 0, 1, 2, 3, 4, 0, 1, 2};
; #pragma unroll
;         for (int i = 0; i < 16; ++i) { const float ta = __int_as_float(h1 ? top[0][A1[i]] : top[0][0]), tb = __int_as_float(h1 ? top[1][B1[i]] : top[1][i]); const unsigned code = h1 ? (unsigned)(A1[i] * 16 + B1[i]) : (unsigned)i;
;             bk[i] = (int)((__float_as_uint(ta + tb) | 255u) - code); }
	v_max_i32_e32 v32, v32, v45
	s_waitcnt lgkmcnt(3)
	v_max_i32_e32 v25, v25, v46
	s_waitcnt lgkmcnt(2)
	v_max_i32_e32 v23, v23, v47
	s_waitcnt lgkmcnt(1)
	v_max_i32_e32 v22, v22, v48
	s_waitcnt lgkmcnt(0)
	v_max_i32_e32 v21, v21, v49
	v_max_i32_e32 v20, v20, v44
	v_max_i32_e32 v19, v19, v43
	v_max_i32_e32 v18, v18, v42
	v_max_i32_e32 v31, v31, v41
	v_max_i32_e32 v28, v28, v40
	v_max_i32_e32 v27, v27, v39
	v_max_i32_e32 v24, v24, v38
	v_max_i32_e32 v30, v30, v37
	v_max_i32_e32 v26, v26, v36
	v_max_i32_e32 v29, v29, v35
	v_max_i32_e32 v33, v33, v34
	v_max_i32_e32 v34, v32, v31
	v_min_i32_e32 v31, v32, v31
	v_max_i32_e32 v32, v25, v28
	v_min_i32_e32 v25, v25, v28
	v_max_i32_e32 v28, v23, v27
	v_min_i32_e32 v23, v23, v27
	v_max_i32_e32 v27, v22, v24
	v_min_i32_e32 v22, v22, v24
	v_max_i32_e32 v24, v21, v30
	v_min_i32_e32 v21, v21, v30
	v_max_i32_e32 v30, v20, v26
	v_min_i32_e32 v20, v20, v26
	v_max_i32_e32 v26, v19, v29
	v_min_i32_e32 v19, v19, v29
	v_max_i32_e32 v29, v18, v33
	v_min_i32_e32 v18, v18, v33
	v_max_i32_e32 v33, v34, v24
	v_min_i32_e32 v24, v34, v24
	v_max_i32_e32 v34, v32, v30
	v_min_i32_e32 v30, v32, v30
	v_max_i32_e32 v32, v28, v26
	v_min_i32_e32 v26, v28, v26
	v_max_i32_e32 v28, v27, v29
	v_min_i32_e32 v27, v27, v29
	v_max_i32_e32 v29, v31, v21
	v_min_i32_e32 v21, v31, v21
	v_max_i32_e32 v31, v25, v20
	v_min_i32_e32 v20, v25, v20
	v_max_i32_e32 v25, v23, v19
	v_min_i32_e32 v19, v23, v19
	v_max_i32_e32 v23, v22, v18
	v_min_i32_e32 v18, v22, v18
	v_max_i32_e32 v22, v33, v32
	v_min_i32_e32 v32, v33, v32
	v_max_i32_e32 v33, v34, v28
	v_min_i32_e32 v28, v34, v28
	v_max_i32_e32 v34, v24, v26
	v_min_i32_e32 v24, v24, v26
	v_max_i32_e32 v35, v30, v27
	v_min_i32_e32 v27, v30, v27
	v_max_i32_e32 v30, v29, v25
	v_min_i32_e32 v25, v29, v25
	v_max_i32_e32 v29, v31, v23
	v_min_i32_e32 v23, v31, v23
	v_max_i32_e32 v31, v21, v19
	v_min_i32_e32 v19, v21, v19
	v_max_i32_e32 v21, v20, v18
	v_min_i32_e32 v18, v20, v18
	v_max_i32_e32 v26, v22, v33
	v_min_i32_e32 v33, v22, v33
	v_lshlrev_b32_e32 v20, 8, v81
	v_lshlrev_b32_e32 v22, 16, v80
	v_max_i32_e32 v36, v32, v28
	v_max_i32_e32 v40, v19, v18
	v_min_i32_e32 v41, v19, v18
	v_and_b32_e32 v18, 0x7f, v79
	v_and_b32_e32 v20, 0x7f00, v20
	v_and_b32_e32 v22, 0x7f0000, v22
	v_max_i32_e32 v39, v31, v21
	v_min_i32_e32 v31, v31, v21
	v_lshlrev_b32_e32 v21, 8, v33
	v_or3_b32 v18, v20, v18, v22
	v_lshlrev_b32_e32 v20, 16, v36
	v_and_b32_e32 v19, 0x7f, v26
	v_and_b32_e32 v21, 0x7f00, v21
	v_and_b32_e32 v20, 0x7f0000, v20
	v_or3_b32 v20, v21, v19, v20
	v_lshlrev_b32_e32 v19, 24, v78
	v_min_i32_e32 v28, v32, v28
	v_and_b32_e32 v19, 0x7f000000, v19
	v_bitop3_b32 v19, v18, s68, v19 bitop3:0x36
	v_lshlrev_b32_e32 v18, 24, v28
	v_max_i32_e32 v32, v34, v35
	v_min_i32_e32 v34, v34, v35
	v_max_i32_e32 v35, v24, v27
	v_min_i32_e32 v27, v24, v27
	v_and_b32_e32 v18, 0x7f000000, v18
	v_lshlrev_b32_e32 v22, 8, v76
	v_lshlrev_b32_e32 v24, 16, v75
	v_bitop3_b32 v18, v20, s68, v18 bitop3:0x36
	v_and_b32_e32 v20, 0x7f, v77
	v_and_b32_e32 v22, 0x7f00, v22
	v_and_b32_e32 v24, 0x7f0000, v24
	v_max_i32_e32 v37, v30, v29
	v_min_i32_e32 v29, v30, v29
	v_max_i32_e32 v30, v25, v23
	v_min_i32_e32 v38, v25, v23
	v_lshlrev_b32_e32 v23, 8, v34
	v_or3_b32 v20, v22, v20, v24
	v_lshlrev_b32_e32 v22, 16, v35
	v_and_b32_e32 v21, 0x7f, v32
	v_and_b32_e32 v23, 0x7f00, v23
	v_and_b32_e32 v22, 0x7f0000, v22
	v_or3_b32 v22, v23, v21, v22
	v_lshlrev_b32_e32 v21, 24, v73
	v_and_b32_e32 v21, 0x7f000000, v21
	v_bitop3_b32 v21, v20, s68, v21 bitop3:0x36
	v_lshlrev_b32_e32 v20, 24, v27
	v_and_b32_e32 v20, 0x7f000000, v20
	v_lshlrev_b32_e32 v24, 8, v74
	v_lshlrev_b32_e32 v42, 16, v72
	v_bitop3_b32 v20, v22, s68, v20 bitop3:0x36
	v_and_b32_e32 v22, 0x7f, v71
	v_and_b32_e32 v24, 0x7f00, v24
	v_and_b32_e32 v42, 0x7f0000, v42
	v_lshlrev_b32_e32 v25, 8, v29
	v_or3_b32 v22, v24, v22, v42
	v_lshlrev_b32_e32 v24, 16, v30
	v_and_b32_e32 v23, 0x7f, v37
	v_and_b32_e32 v25, 0x7f00, v25
	v_and_b32_e32 v24, 0x7f0000, v24
	v_or3_b32 v24, v25, v23, v24
	v_lshlrev_b32_e32 v23, 24, v70
	v_and_b32_e32 v23, 0x7f000000, v23
	v_bitop3_b32 v23, v22, s68, v23 bitop3:0x36
	v_lshlrev_b32_e32 v22, 24, v38
	v_and_b32_e32 v22, 0x7f000000, v22
	v_lshlrev_b32_e32 v42, 8, v68
	v_lshlrev_b32_e32 v44, 16, v67
	v_bitop3_b32 v22, v24, s68, v22 bitop3:0x36
	v_and_b32_e32 v24, 0x7f, v69
	v_and_b32_e32 v42, 0x7f00, v42
	v_and_b32_e32 v44, 0x7f0000, v44
	v_lshlrev_b32_e32 v43, 8, v31
	v_or3_b32 v24, v42, v24, v44
	v_lshlrev_b32_e32 v42, 16, v40
	v_and_b32_e32 v25, 0x7f, v39
	v_and_b32_e32 v43, 0x7f00, v43
	v_and_b32_e32 v42, 0x7f0000, v42
	v_or3_b32 v42, v43, v25, v42
	v_lshlrev_b32_e32 v25, 24, v66
	v_and_b32_e32 v25, 0x7f000000, v25
	v_bitop3_b32 v25, v24, s68, v25 bitop3:0x36
	v_lshlrev_b32_e32 v24, 24, v41
	v_and_b32_e32 v24, 0x7f000000, v24
	v_bitop3_b32 v24, v42, s68, v24 bitop3:0x36
	v_mov_b32_e32 v42, v86
	v_add_f32_e32 v62, v74, v26
	v_cmp_eq_u32_e32 vcc, 0, v42
	v_add_f32_e32 v63, v72, v26
	v_add_f32_e32 v64, v70, v26
	v_cndmask_b32_e32 v42, v81, v79, vcc
	v_add_f32_e32 v44, v42, v26
	v_cndmask_b32_e64 v43, -16, 0, vcc
	v_or_b32_e32 v44, 0xff, v44
	v_add_f32_e32 v45, v42, v33
	v_add_u32_e32 v43, v44, v43
	v_cndmask_b32_e64 v44, v99, -1, vcc
	v_or_b32_e32 v45, 0xff, v45
	v_add_f32_e32 v46, v42, v36
	v_add_u32_e32 v44, v45, v44
	v_cndmask_b32_e64 v45, v100, -2, vcc
	v_or_b32_e32 v46, 0xff, v46
	v_add_f32_e32 v47, v42, v28
	v_add_u32_e32 v45, v46, v45
	v_cndmask_b32_e64 v46, v101, -3, vcc
	v_or_b32_e32 v47, 0xff, v47
	v_add_f32_e32 v48, v42, v32
	v_add_u32_e32 v46, v47, v46
	v_cndmask_b32_e64 v47, v102, -4, vcc
	v_or_b32_e32 v48, 0xff, v48
	v_add_f32_e32 v34, v42, v34
	v_add_f32_e32 v35, v42, v35
; #define CE_(a, b) ce_desc(v[a], v[b])
; __device__ __forceinline__ void sort16_desc(int (&v)[16]) {
;     ...
;     CE_(0,13); CE_(1,12); CE_(2,15); CE_(3,14); CE_(4,8); CE_(5,6); CE_(7,11); CE_(9,10);
;     CE_(0,5); CE_(1,7); CE_(2,9); CE_(3,4); CE_(6,13); CE_(8,14); CE_(10,15); CE_(11,12);
;     CE_(0,1); CE_(2,3); CE_(4,5); CE_(6,8); CE_(7,9); CE_(10,11); CE_(12,13); CE_(14,15);
;     CE_(0,2); CE_(1,3); CE_(4,10); CE_(5,11); CE_(6,7); CE_(8,9); CE_(12,14); CE_(13,15);
;     CE_(1,2); CE_(3,12); CE_(4,6); CE_(5,7); CE_(8,10); CE_(9,11); CE_(13,14);
;     CE_(1,4); CE_(2,6); CE_(5,8); CE_(7,10); CE_(9,13); CE_(11,14);
;     CE_(2,4); CE_(3,6); CE_(9,12); CE_(11,13);
;     CE_(3,5); CE_(6,8); CE_(7,9); CE_(10,12);
;     CE_(3,4); CE_(5,6); CE_(7,8); CE_(9,10); CE_(11,12);
;     CE_(6,7); CE_(8,9);
;     ...
; }
; __device__ __forceinline__ void route_task(int task, int tl0, const bf16* QP  , const LAS bf16* KHL, LAS unsigned short* EL, LAS float* GL, int lane) {
;     ...
; #pragma unroll
;         for (int i = 0; i < 16; ++i) { const float ta = __int_as_float(h1 ? top[0][A1[i]] : top[0][0]), tb = __int_as_float(h1 ? top[1][B1[i]] : top[1][i]); const unsigned code = h1 ? (unsigned)(A1[i] * 16 + B1[i]) : (unsigned)i;
;             bk[i] = (int)((__float_as_uint(ta + tb) | 255u) - code); }
;         sort16_desc(bk);
;         int oth[16];
; #pragma unroll
;         for (int i = 0; i < 16; ++i) oth[i] = __shfl_xor(bk[i], 32);
;         merge16_desc(bk, oth);
	v_add_f32_e32 v27, v42, v27
	v_cndmask_b32_e32 v42, v80, v79, vcc
	v_cndmask_b32_e32 v32, v32, v39, vcc
	v_add_u32_e32 v47, v48, v47
	v_cndmask_b32_e64 v48, v103, -5, vcc
	v_or_b32_e32 v34, 0xff, v34
	v_add_f32_e32 v32, v42, v32
	v_add_u32_e32 v34, v34, v48
	v_cndmask_b32_e64 v48, v104, -6, vcc
	v_or_b32_e32 v35, 0xff, v35
	v_cndmask_b32_e32 v37, v26, v37, vcc
	v_cndmask_b32_e64 v39, v116, -12, vcc
	v_or_b32_e32 v32, 0xff, v32
	v_add_u32_e32 v35, v35, v48
	v_cndmask_b32_e64 v48, v105, -7, vcc
	v_or_b32_e32 v27, 0xff, v27
	v_add_f32_e32 v37, v42, v37
	v_cndmask_b32_e32 v29, v33, v29, vcc
	v_add_u32_e32 v32, v32, v39
	v_cndmask_b32_e32 v39, v78, v79, vcc
	v_cndmask_b32_e32 v31, v26, v31, vcc
	v_add_u32_e32 v27, v27, v48
	v_cndmask_b32_e64 v48, v106, -8, vcc
	v_or_b32_e32 v37, 0xff, v37
	v_add_f32_e32 v29, v42, v29
	v_cndmask_b32_e32 v30, v36, v30, vcc
	v_cndmask_b32_e32 v38, v28, v38, vcc
	v_add_f32_e32 v31, v39, v31
	v_cndmask_b32_e32 v40, v33, v40, vcc
	v_add_u32_e32 v37, v37, v48
	v_cndmask_b32_e64 v48, v107, -9, vcc
	v_or_b32_e32 v29, 0xff, v29
	v_add_f32_e32 v30, v42, v30
	v_add_f32_e32 v38, v42, v38
	v_cndmask_b32_e64 v42, v117, -13, vcc
	v_or_b32_e32 v31, 0xff, v31
	v_add_f32_e32 v40, v39, v40
	v_cndmask_b32_e32 v41, v36, v41, vcc
	v_add_u32_e32 v29, v29, v48
	v_cndmask_b32_e64 v48, v114, -10, vcc
	v_or_b32_e32 v30, 0xff, v30
	v_add_u32_e32 v31, v31, v42
	v_cndmask_b32_e64 v42, v118, -14, vcc
	v_or_b32_e32 v40, 0xff, v40
	v_add_f32_e32 v39, v39, v41
	v_add_u32_e32 v30, v30, v48
	v_cndmask_b32_e64 v48, v115, -11, vcc
	v_or_b32_e32 v38, 0xff, v38
	v_add_u32_e32 v40, v40, v42
	v_cndmask_b32_e64 v42, v119, -15, vcc
	v_or_b32_e32 v39, 0xff, v39
	v_add_u32_e32 v38, v38, v48
	v_add_u32_e32 v39, v39, v42
	v_max_i32_e32 v41, v43, v31
	v_min_i32_e32 v31, v43, v31
	v_max_i32_e32 v42, v44, v32
	v_min_i32_e32 v32, v44, v32
	v_max_i32_e32 v43, v45, v39
	v_min_i32_e32 v39, v45, v39
	v_max_i32_e32 v44, v46, v40
	v_min_i32_e32 v40, v46, v40
	v_max_i32_e32 v45, v47, v37
	v_min_i32_e32 v37, v47, v37
	v_max_i32_e32 v46, v34, v35
	v_min_i32_e32 v34, v34, v35
	v_max_i32_e32 v35, v27, v38
	v_min_i32_e32 v27, v27, v38
	v_max_i32_e32 v38, v29, v30
	v_min_i32_e32 v29, v29, v30
	v_max_i32_e32 v30, v41, v46
	v_min_i32_e32 v41, v41, v46
	v_max_i32_e32 v46, v42, v35
	v_min_i32_e32 v35, v42, v35
	v_max_i32_e32 v42, v43, v38
	v_min_i32_e32 v38, v43, v38
	v_max_i32_e32 v43, v44, v45
	v_min_i32_e32 v44, v44, v45
	v_max_i32_e32 v45, v34, v31
	v_min_i32_e32 v31, v34, v31
	v_max_i32_e32 v34, v37, v40
	v_min_i32_e32 v37, v37, v40
	v_max_i32_e32 v40, v29, v39
	v_min_i32_e32 v29, v29, v39
	v_max_i32_e32 v39, v27, v32
	v_min_i32_e32 v27, v27, v32
	v_max_i32_e32 v32, v30, v46
	v_min_i32_e32 v30, v30, v46
	v_max_i32_e32 v46, v42, v43
	v_min_i32_e32 v42, v42, v43
	v_max_i32_e32 v43, v44, v41
	v_min_i32_e32 v41, v44, v41
	v_max_i32_e32 v44, v45, v34
	v_min_i32_e32 v34, v45, v34
	v_max_i32_e32 v45, v35, v38
	v_min_i32_e32 v35, v35, v38
	v_max_i32_e32 v38, v40, v39
	v_min_i32_e32 v39, v40, v39
	v_max_i32_e32 v40, v27, v31
	v_min_i32_e32 v27, v27, v31
	v_max_i32_e32 v31, v37, v29
	v_min_i32_e32 v29, v37, v29
	v_max_i32_e32 v37, v32, v46
	v_min_i32_e32 v32, v32, v46
	v_max_i32_e32 v46, v30, v42
	v_min_i32_e32 v30, v30, v42
	v_max_i32_e32 v42, v43, v38
	v_min_i32_e32 v38, v43, v38
	v_max_i32_e32 v43, v41, v39
	v_min_i32_e32 v39, v41, v39
	v_max_i32_e32 v41, v44, v45
	v_min_i32_e32 v44, v44, v45
	v_max_i32_e32 v45, v34, v35
	v_min_i32_e32 v34, v34, v35
	v_max_i32_e32 v35, v40, v31
	v_min_i32_e32 v31, v40, v31
	v_max_i32_e32 v40, v27, v29
	v_min_i32_e32 v27, v27, v29
	v_max_i32_e32 v29, v46, v32
	v_min_i32_e32 v32, v46, v32
	v_max_i32_e32 v46, v30, v35
	v_min_i32_e32 v30, v30, v35
	v_max_i32_e32 v35, v42, v41
	v_min_i32_e32 v41, v42, v41
	v_max_i32_e32 v42, v43, v44
	v_min_i32_e32 v43, v43, v44
	v_max_i32_e32 v44, v45, v38
	v_min_i32_e32 v38, v45, v38
	v_max_i32_e32 v45, v34, v39
	v_min_i32_e32 v34, v34, v39
	v_max_i32_e32 v39, v40, v31
	v_min_i32_e32 v31, v40, v31
	v_max_i32_e32 v40, v29, v35
	v_min_i32_e32 v29, v29, v35
	v_max_i32_e32 v35, v32, v41
	v_min_i32_e32 v32, v32, v41
	v_max_i32_e32 v41, v42, v44
	v_min_i32_e32 v42, v42, v44
	v_max_i32_e32 v44, v43, v38
	v_min_i32_e32 v38, v43, v38
	v_max_i32_e32 v43, v45, v39
	v_min_i32_e32 v39, v45, v39
	v_max_i32_e32 v45, v34, v31
	v_min_i32_e32 v31, v34, v31
	v_max_i32_e32 v34, v35, v29
	v_min_i32_e32 v29, v35, v29
	v_max_i32_e32 v35, v46, v32
	v_min_i32_e32 v32, v46, v32
	v_max_i32_e32 v46, v43, v30
	v_min_i32_e32 v30, v43, v30
	v_max_i32_e32 v43, v45, v39
	v_min_i32_e32 v39, v45, v39
	v_max_i32_e32 v45, v35, v41
	v_min_i32_e32 v35, v35, v41
	v_max_i32_e32 v41, v32, v42
	v_min_i32_e32 v32, v32, v42
	v_max_i32_e32 v42, v44, v46
	v_min_i32_e32 v44, v44, v46
	v_max_i32_e32 v46, v38, v30
	v_min_i32_e32 v30, v38, v30
	v_max_i32_e32 v38, v45, v29
	v_min_i32_e32 v29, v45, v29
	v_max_i32_e32 v45, v35, v41
	v_min_i32_e32 v35, v35, v41
	v_max_i32_e32 v41, v42, v32
	v_min_i32_e32 v32, v42, v32
	v_max_i32_e32 v42, v44, v46
	v_min_i32_e32 v44, v44, v46
	v_max_i32_e32 v46, v43, v30
	v_min_i32_e32 v30, v43, v30
	v_max_i32_e32 v43, v35, v41
	v_min_i32_e32 v35, v35, v41
	v_max_i32_e32 v41, v32, v42
	v_min_i32_e32 v32, v32, v42
	ds_bpermute_b32 v54, v123, v41
	ds_bpermute_b32 v55, v123, v32
	ds_bpermute_b32 v56, v123, v44
	ds_bpermute_b32 v57, v123, v27
	ds_bpermute_b32 v58, v123, v31
	ds_bpermute_b32 v59, v123, v39
	ds_bpermute_b32 v60, v123, v30
	ds_bpermute_b32 v61, v123, v46
	ds_bpermute_b32 v42, v123, v37
	ds_bpermute_b32 v47, v123, v40
	ds_bpermute_b32 v48, v123, v34
	ds_bpermute_b32 v49, v123, v38
	ds_bpermute_b32 v50, v123, v29
	ds_bpermute_b32 v51, v123, v45
	ds_bpermute_b32 v52, v123, v43
	ds_bpermute_b32 v53, v123, v35
	s_waitcnt lgkmcnt(12)
; #define CE_(a, b) ce_desc(v[a], v[b])
; #define CAND(a, b) (int)((__float_as_uint(__int_as_float(top[0][a]) + __int_as_float(top[1][b])) | 255u) - (unsigned)((a) * 16 + (b)))
; __device__ __forceinline__ void sort16_desc(int (&v)[16]) {
;     ...
;     CE_(0,13); CE_(1,12); CE_(2,15); CE_(3,14); CE_(4,8); CE_(5,6); CE_(7,11); CE_(9,10);
;     CE_(0,5); CE_(1,7); CE_(2,9); CE_(3,4); CE_(6,13); CE_(8,14); CE_(10,15); CE_(11,12);
;     CE_(0,1); CE_(2,3); CE_(4,5); CE_(6,8); CE_(7,9); CE_(10,11); CE_(12,13); CE_(14,15);
;     CE_(0,2); CE_(1,3); CE_(4,10); CE_(5,11); CE_(6,7); CE_(8,9); CE_(12,14); CE_(13,15);
;     CE_(1,2); CE_(3,12); CE_(4,6); CE_(5,7); CE_(8,10); CE_(9,11); CE_(13,14);
;     CE_(1,4); CE_(2,6); CE_(5,8); CE_(7,10); CE_(9,13); CE_(11,14);
;     CE_(2,4); CE_(3,6); CE_(9,12); CE_(11,13);
;     CE_(3,5); CE_(6,8); CE_(7,9); CE_(10,12);
;     CE_(3,4); CE_(5,6); CE_(7,8); CE_(9,10); CE_(11,12);
;     CE_(6,7); CE_(8,9);
;     ...
; }
; __device__ __forceinline__ void merge16_desc(int (&a)[16], const int (&b)[16]) {
; #pragma unroll
;     for (int i = 0; i < 16; ++i) a[i] = a[i] > b[15 - i] ? a[i] : b[15 - i];
; #pragma unroll
;     for (int j = 8; j > 0; j >>= 1)
; #pragma unroll
;         for (int i = 0; i < 16; ++i) { const int l = i ^ j; if (l > i) ce_desc(a[i], a[l]); }
; }
; __device__ __forceinline__ void route_task(int task, int tl0, const bf16* QP  , const LAS bf16* KHL, LAS unsigned short* EL, LAS float* GL, int lane) {
;     ...
;         merge16_desc(bk, oth);
;     }
;     ...
;     {
;         int gk[16];
;         gk[0] = CAND(3, 3); gk[1] = CAND(4, 0); gk[2] = CAND(4, 1); gk[3] = CAND(4, 2); gk[4] = CAND(5, 0); gk[5] = CAND(5, 1); gk[6] = CAND(6, 0); gk[7] = CAND(6, 1);
;         gk[8] = CAND(7, 0); gk[9] = CAND(7, 1); gk[10] = CAND(8, 0); gk[11] = CAND(9, 0); gk[12] = CAND(10, 0); gk[13] = CAND(11, 0); gk[14] = CAND(12, 0); gk[15] = CAND(13, 0);
;         sort16_desc(gk);
;         merge16_desc(bk, gk);
	v_max_i32_e32 v37, v37, v57
	s_waitcnt lgkmcnt(11)
	v_max_i32_e32 v40, v40, v58
	s_waitcnt lgkmcnt(10)
	v_max_i32_e32 v34, v34, v59
	s_waitcnt lgkmcnt(9)
	v_max_i32_e32 v38, v38, v60
	s_waitcnt lgkmcnt(8)
	v_max_i32_e32 v29, v29, v61
	v_max_i32_e32 v45, v45, v56
	v_max_i32_e32 v43, v43, v55
	v_max_i32_e32 v35, v35, v54
	v_add_f32_e32 v28, v78, v28
	v_add_f32_e32 v54, v77, v26
	v_add_f32_e32 v55, v77, v33
	v_add_f32_e32 v36, v77, v36
	v_add_f32_e32 v56, v76, v26
	v_add_f32_e32 v57, v76, v33
	v_add_f32_e32 v58, v75, v26
	v_add_f32_e32 v59, v75, v33
	v_add_f32_e32 v60, v73, v26
	v_add_f32_e32 v33, v73, v33
	v_add_f32_e32 v61, v71, v26
	v_add_f32_e32 v65, v69, v26
	v_add_f32_e32 v68, v68, v26
	v_or_b32_e32 v28, 0xff, v28
	v_or_b32_e32 v54, 0xff, v54
	v_or_b32_e32 v55, 0xff, v55
	v_or_b32_e32 v36, 0xff, v36
	v_or_b32_e32 v56, 0xff, v56
	v_or_b32_e32 v57, 0xff, v57
	v_or_b32_e32 v58, 0xff, v58
	v_or_b32_e32 v59, 0xff, v59
	v_or_b32_e32 v60, 0xff, v60
	v_or_b32_e32 v33, 0xff, v33
	v_or_b32_e32 v61, 0xff, v61
	v_or_b32_e32 v62, 0xff, v62
	v_or_b32_e32 v63, 0xff, v63
	v_or_b32_e32 v64, 0xff, v64
	v_or_b32_e32 v65, 0xff, v65
	v_or_b32_e32 v68, 0xff, v68
	v_subrev_u32_e32 v28, 51, v28
	v_subrev_u32_e32 v54, 64, v54
	v_add_u32_e32 v55, 0xffffffbf, v55
	v_add_u32_e32 v36, 0xffffffbe, v36
	v_add_u32_e32 v56, 0xffffffb0, v56
	v_add_u32_e32 v57, 0xffffffaf, v57
	v_add_u32_e32 v58, 0xffffffa0, v58
	v_add_u32_e32 v59, 0xffffff9f, v59
	v_add_u32_e32 v60, 0xffffff90, v60
	v_add_u32_e32 v33, 0xffffff8f, v33
	v_add_u32_e32 v61, 0xffffff80, v61
	v_add_u32_e32 v62, 0xffffff70, v62
	v_add_u32_e32 v63, 0xffffff60, v63
	v_add_u32_e32 v64, 0xffffff50, v64
	v_add_u32_e32 v65, 0xffffff40, v65
	v_add_u32_e32 v68, 0xffffff30, v68
	v_max_i32_e32 v69, v28, v64
	v_min_i32_e32 v28, v28, v64
	v_max_i32_e32 v64, v54, v63
	v_min_i32_e32 v54, v54, v63
	v_max_i32_e32 v63, v55, v68
	v_min_i32_e32 v55, v55, v68
	v_max_i32_e32 v68, v36, v65
	v_min_i32_e32 v36, v36, v65
	v_max_i32_e32 v65, v56, v60
	v_min_i32_e32 v56, v56, v60
	v_max_i32_e32 v60, v57, v58
	v_min_i32_e32 v57, v57, v58
	v_max_i32_e32 v58, v59, v62
	v_min_i32_e32 v59, v59, v62
	v_max_i32_e32 v62, v33, v61
	v_min_i32_e32 v33, v33, v61
	v_max_i32_e32 v61, v69, v60
	v_min_i32_e32 v60, v69, v60
	v_max_i32_e32 v69, v64, v58
	v_min_i32_e32 v58, v64, v58
	v_max_i32_e32 v64, v63, v62
	v_min_i32_e32 v62, v63, v62
	v_max_i32_e32 v63, v68, v65
	v_min_i32_e32 v65, v68, v65
	v_max_i32_e32 v68, v57, v28
	v_min_i32_e32 v28, v57, v28
	v_max_i32_e32 v57, v56, v36
	v_min_i32_e32 v36, v56, v36
	v_max_i32_e32 v56, v33, v55
	v_min_i32_e32 v33, v33, v55
	v_max_i32_e32 v55, v59, v54
	v_min_i32_e32 v54, v59, v54
	v_max_i32_e32 v59, v61, v69
	v_min_i32_e32 v61, v61, v69
	v_max_i32_e32 v69, v64, v63
	v_min_i32_e32 v63, v64, v63
	v_max_i32_e32 v64, v65, v60
	v_min_i32_e32 v60, v65, v60
	v_max_i32_e32 v65, v68, v57
	v_min_i32_e32 v57, v68, v57
	v_max_i32_e32 v68, v58, v62
	v_min_i32_e32 v58, v58, v62
	v_max_i32_e32 v62, v56, v55
	v_min_i32_e32 v55, v56, v55
	v_max_i32_e32 v56, v54, v28
	v_min_i32_e32 v28, v54, v28
	v_max_i32_e32 v54, v36, v33
	v_min_i32_e32 v33, v36, v33
	v_min_i32_e32 v36, v59, v69
	v_max_i32_e32 v70, v61, v63
	v_min_i32_e32 v61, v61, v63
	v_max_i32_e32 v63, v64, v62
	v_min_i32_e32 v62, v64, v62
	v_max_i32_e32 v64, v60, v55
	v_min_i32_e32 v55, v60, v55
	v_max_i32_e32 v60, v65, v68
	v_min_i32_e32 v65, v65, v68
	v_max_i32_e32 v68, v57, v58
	v_min_i32_e32 v57, v57, v58
	v_max_i32_e32 v58, v56, v54
	v_min_i32_e32 v54, v56, v54
	v_max_i32_e32 v56, v28, v33
	v_min_i32_e32 v28, v28, v33
	v_max_i32_e32 v33, v70, v36
	v_min_i32_e32 v36, v70, v36
	v_max_i32_e32 v70, v61, v58
	v_min_i32_e32 v58, v61, v58
	v_max_i32_e32 v61, v63, v60
	v_min_i32_e32 v60, v63, v60
	v_max_i32_e32 v63, v64, v65
	v_min_i32_e32 v64, v64, v65
	v_max_i32_e32 v65, v68, v62
	v_min_i32_e32 v62, v68, v62
	v_max_i32_e32 v68, v57, v55
	v_min_i32_e32 v55, v57, v55
	v_max_i32_e32 v57, v56, v54
	s_waitcnt lgkmcnt(0)
	v_max_i32_e32 v41, v41, v53
	v_max_i32_e32 v32, v32, v52
	v_max_i32_e32 v44, v44, v51
	v_max_i32_e32 v46, v46, v50
	v_max_i32_e32 v30, v30, v49
	v_max_i32_e32 v39, v39, v48
	v_max_i32_e32 v31, v31, v47
	v_max_i32_e32 v27, v27, v42
	v_min_i32_e32 v54, v56, v54
	v_max_i32_e32 v56, v33, v61
	v_min_i32_e32 v33, v33, v61
	v_max_i32_e32 v61, v36, v60
	v_min_i32_e32 v36, v36, v60
	v_max_i32_e32 v60, v63, v65
	v_min_i32_e32 v63, v63, v65
	v_max_i32_e32 v65, v64, v62
	v_min_i32_e32 v62, v64, v62
	v_max_i32_e32 v64, v68, v57
	v_max_i32_e32 v42, v37, v41
	v_min_i32_e32 v37, v37, v41
	v_max_i32_e32 v41, v40, v32
	v_min_i32_e32 v32, v40, v32
	v_max_i32_e32 v40, v34, v44
	v_min_i32_e32 v34, v34, v44
	v_max_i32_e32 v44, v38, v46
	v_min_i32_e32 v38, v38, v46
	v_max_i32_e32 v46, v29, v30
	v_min_i32_e32 v29, v29, v30
	v_max_i32_e32 v30, v45, v39
	v_min_i32_e32 v39, v45, v39
	v_max_i32_e32 v45, v43, v31
	v_min_i32_e32 v31, v43, v31
	v_max_i32_e32 v43, v35, v27
	v_min_i32_e32 v27, v35, v27
	v_min_i32_e32 v57, v68, v57
	v_max_i32_e32 v68, v55, v54
	v_max_i32_e32 v71, v70, v36
	v_min_i32_e32 v36, v70, v36
	v_max_i32_e32 v70, v64, v58
	v_min_i32_e32 v58, v64, v58
	v_max_i32_e32 v35, v42, v46
	v_min_i32_e32 v42, v42, v46
	v_max_i32_e32 v46, v41, v30
	v_min_i32_e32 v30, v41, v30
	v_max_i32_e32 v41, v40, v45
	v_min_i32_e32 v40, v40, v45
	v_max_i32_e32 v45, v44, v43
	v_min_i32_e32 v43, v44, v43
	v_max_i32_e32 v44, v37, v29
	v_min_i32_e32 v29, v37, v29
	v_max_i32_e32 v37, v32, v39
	v_min_i32_e32 v32, v32, v39
	v_max_i32_e32 v39, v34, v31
	v_min_i32_e32 v31, v34, v31
	v_max_i32_e32 v34, v38, v27
	v_min_i32_e32 v27, v38, v27
	v_min_i32_e32 v54, v55, v54
	v_min_i32_e32 v55, v61, v33
; #define CAND(a, b) (int)((__float_as_uint(__int_as_float(top[0][a]) + __int_as_float(top[1][b])) | 255u) - (unsigned)((a) * 16 + (b)))
; __device__ __forceinline__ void route_task(int task, int tl0, const bf16* QP  , const LAS bf16* KHL, LAS unsigned short* EL, LAS float* GL, int lane) {
;     ...
;         merge16_desc(bk, gk);
;     }
;     {
;         const int c14 = CAND(14, 0), c15 = CAND(15, 0);
;         const int n14 = max(bk[14], c14), n15 = max(min(bk[14], c14), max(bk[15], c15));
;         bk[14] = n14; bk[15] = n15;
;     }
;     ...
;     int my[8];
; #pragma unroll
;     for (int i = 0; i < 8; ++i) { int lo_ = bk[i], hi_ = bk[8 + i]; asm volatile("" : "+v"(lo_), "+v"(hi_)); my[i] = hi ? hi_ : lo_; }
;     int bv[8];
; #pragma unroll
;     for (int i = 0; i < 8; ++i) {
;         const unsigned cd = 255u - ((unsigned)my[i] & 255u), ca = cd >> 4, cb = cd & 15u;
;         const unsigned wa = (ca >> 2) == 0u ? P1[0] : (ca >> 2) == 1u ? P1[1] : (ca >> 2) == 2u ? P1[2] : P1[3];
;         const unsigned wb = (cb >> 2) == 0u ? P2[0] : (cb >> 2) == 1u ? P2[1] : (cb >> 2) == 2u ? P2[2] : P2[3];
;         bv[i] = (int)((((wa >> (8u * (ca & 3u))) & 255u) << 7) | ((wb >> (8u * (cb & 3u))) & 255u));
;     }
	v_max_i32_e32 v64, v68, v57
	v_min_i32_e32 v57, v68, v57
	v_max_i32_e32 v68, v71, v60
	v_min_i32_e32 v60, v71, v60
	v_max_i32_e32 v71, v36, v63
	v_min_i32_e32 v36, v36, v63
	v_max_i32_e32 v63, v65, v70
	v_min_i32_e32 v65, v65, v70
	v_max_i32_e32 v70, v62, v58
	v_max_i32_e32 v38, v35, v41
	v_min_i32_e32 v35, v35, v41
	v_max_i32_e32 v41, v46, v45
	v_min_i32_e32 v45, v46, v45
	v_max_i32_e32 v46, v42, v40
	v_min_i32_e32 v40, v42, v40
	v_max_i32_e32 v42, v30, v43
	v_min_i32_e32 v30, v30, v43
	v_max_i32_e32 v43, v44, v39
	v_min_i32_e32 v39, v44, v39
	v_max_i32_e32 v44, v37, v34
	v_min_i32_e32 v34, v37, v34
	v_max_i32_e32 v37, v29, v31
	v_min_i32_e32 v29, v29, v31
	v_max_i32_e32 v31, v32, v27
	v_min_i32_e32 v27, v32, v27
	v_min_i32_e32 v58, v62, v58
	v_max_i32_e32 v62, v68, v55
	v_min_i32_e32 v55, v68, v55
	v_max_i32_e32 v68, v60, v71
	v_min_i32_e32 v60, v60, v71
	v_max_i32_e32 v71, v63, v36
	v_min_i32_e32 v36, v63, v36
	v_max_i32_e32 v63, v65, v70
	v_min_i32_e32 v32, v38, v41
	v_min_i32_e32 v47, v35, v45
	v_min_i32_e32 v48, v46, v42
	v_min_i32_e32 v49, v40, v30
	v_min_i32_e32 v50, v43, v44
	v_min_i32_e32 v51, v39, v34
	v_min_i32_e32 v52, v37, v31
	v_min_i32_e32 v53, v29, v27
	v_min_i32_e32 v65, v65, v70
	v_max_i32_e32 v70, v64, v58
	v_min_i32_e32 v58, v64, v58
	v_min_i32_e32 v64, v60, v71
	v_min_i32_e32 v72, v36, v63
	v_max3_i32 v28, v38, v41, v28
	v_max_i32_e32 v32, v32, v54
	v_max3_i32 v35, v35, v45, v57
	v_max_i32_e32 v38, v47, v58
	v_max3_i32 v41, v46, v42, v70
	v_max_i32_e32 v42, v48, v65
	v_max3_i32 v30, v40, v30, v72
	v_max3_i32 v36, v49, v36, v63
	v_max3_i32 v40, v43, v44, v64
	v_max3_i32 v43, v50, v60, v71
	v_max3_i32 v34, v39, v34, v68
	v_max_i32_e32 v39, v51, v55
	v_max3_i32 v31, v37, v31, v62
	v_max3_i32 v33, v52, v61, v33
	v_max3_i32 v27, v29, v27, v56
	v_max3_i32 v29, v53, v59, v69
	v_max_i32_e32 v37, v28, v40
	v_min_i32_e32 v28, v28, v40
	v_max_i32_e32 v40, v32, v43
	v_min_i32_e32 v32, v32, v43
	v_max_i32_e32 v43, v35, v34
	v_min_i32_e32 v34, v35, v34
	v_max_i32_e32 v35, v38, v39
	v_min_i32_e32 v38, v38, v39
	v_max_i32_e32 v39, v41, v31
	v_min_i32_e32 v31, v41, v31
	v_max_i32_e32 v41, v42, v33
	v_min_i32_e32 v33, v42, v33
	v_max_i32_e32 v42, v30, v27
	v_min_i32_e32 v27, v30, v27
	v_max_i32_e32 v30, v36, v29
	v_min_i32_e32 v29, v36, v29
	v_max_i32_e32 v36, v37, v39
	v_min_i32_e32 v37, v37, v39
	v_max_i32_e32 v39, v40, v41
	v_min_i32_e32 v40, v40, v41
	v_max_i32_e32 v41, v43, v42
	v_min_i32_e32 v42, v43, v42
	v_max_i32_e32 v43, v35, v30
	v_min_i32_e32 v30, v35, v30
	v_max_i32_e32 v35, v28, v31
	v_min_i32_e32 v28, v28, v31
	v_max_i32_e32 v31, v32, v33
	v_min_i32_e32 v32, v32, v33
	v_max_i32_e32 v33, v34, v27
	v_min_i32_e32 v27, v34, v27
	v_max_i32_e32 v34, v38, v29
	v_min_i32_e32 v29, v38, v29
	v_max_i32_e32 v38, v36, v41
	v_min_i32_e32 v36, v36, v41
	v_max_i32_e32 v41, v39, v43
	v_min_i32_e32 v39, v39, v43
	v_max_i32_e32 v43, v37, v42
	v_min_i32_e32 v37, v37, v42
	v_max_i32_e32 v42, v40, v30
	v_min_i32_e32 v30, v40, v30
	v_max_i32_e32 v40, v35, v33
	v_min_i32_e32 v33, v35, v33
	v_max_i32_e32 v35, v31, v34
	v_min_i32_e32 v31, v31, v34
	v_max_i32_e32 v34, v28, v27
	v_min_i32_e32 v27, v28, v27
	v_max_i32_e32 v28, v32, v29
	v_min_i32_e32 v29, v32, v29
	v_max_i32_e32 v32, v38, v41
	v_min_i32_e32 v38, v38, v41
	v_max_i32_e32 v41, v36, v39
	v_min_i32_e32 v36, v36, v39
	v_max_i32_e32 v39, v43, v42
	v_min_i32_e32 v42, v43, v42
	v_max_i32_e32 v43, v37, v30
	v_min_i32_e32 v30, v37, v30
	v_max_i32_e32 v37, v40, v35
	v_min_i32_e32 v35, v40, v35
	v_max_i32_e32 v40, v33, v31
	v_min_i32_e32 v31, v33, v31
	v_max_i32_e32 v33, v34, v28
	v_min_i32_e32 v28, v34, v28
	v_max_i32_e32 v34, v27, v29
	v_min_i32_e32 v27, v27, v29
	v_add_f32_e32 v29, v67, v26
	v_or_b32_e32 v29, 0xff, v29
	v_add_f32_e32 v26, v66, v26
	v_add_u32_e32 v29, 0xffffff20, v29
	v_or_b32_e32 v26, 0xff, v26
	v_add_u32_e32 v26, 0xffffff10, v26
	v_max_i32_e32 v44, v34, v29
	v_min_i32_e32 v29, v34, v29
	v_max3_i32 v26, v29, v27, v26
	v_mov_b32_e32 v27, v32
	s_nop 0
	v_cndmask_b32_e64 v27, v37, v27, s[6:7]
	v_not_b32_e32 v29, v27
	v_bfe_u32 v45, v29, 6, 2
	v_cmp_eq_u32_e32 vcc, 2, v45
	v_cndmask_b32_e64 v30, v26, v30, s[6:7]
	v_bitop3_b32 v26, v27, s3, v27 bitop3:0xc
	v_cndmask_b32_e32 v46, v25, v23, vcc
	v_cmp_eq_u32_e32 vcc, 1, v45
	v_cndmask_b32_e64 v34, v35, v38, s[6:7]
	v_not_b32_e32 v35, v34
	v_cndmask_b32_e32 v45, v46, v21, vcc
	v_cmp_gt_u32_e32 vcc, 64, v26
	v_cndmask_b32_e64 v37, v40, v41, s[6:7]
	v_cndmask_b32_e64 v41, v44, v43, s[6:7]
	v_cndmask_b32_e32 v26, v45, v19, vcc
	v_bfe_u32 v45, v29, 2, 2
	v_cmp_eq_u32_e32 vcc, 2, v45
	v_bitop3_b32 v44, v27, 15, v27 bitop3:0xc
	v_bfe_u32 v47, v35, 6, 2
	v_cndmask_b32_e32 v46, v24, v22, vcc
	v_cmp_eq_u32_e32 vcc, 1, v45
	v_not_b32_e32 v38, v37
	v_bfe_u32 v49, v38, 6, 2
	v_cndmask_b32_e32 v45, v46, v20, vcc
	v_cmp_gt_u32_e32 vcc, 4, v44
	v_bitop3_b32 v46, v34, 15, v34 bitop3:0xc
	v_cndmask_b32_e64 v31, v31, v36, s[6:7]
	v_cndmask_b32_e32 v44, v45, v18, vcc
	v_cmp_eq_u32_e32 vcc, 2, v47
	v_bitop3_b32 v45, v34, s3, v34 bitop3:0xc
	v_not_b32_e32 v36, v31
	v_cndmask_b32_e32 v48, v25, v23, vcc
	v_cmp_eq_u32_e32 vcc, 1, v47
	v_bfe_u32 v51, v36, 6, 2
	v_cndmask_b32_e64 v33, v33, v39, s[6:7]
	v_cndmask_b32_e32 v47, v48, v21, vcc
	v_cmp_gt_u32_e32 vcc, 64, v45
	v_not_b32_e32 v39, v33
	v_bfe_u32 v53, v39, 6, 2
	v_cndmask_b32_e32 v45, v47, v19, vcc
	v_bfe_u32 v47, v35, 2, 2
	v_cmp_eq_u32_e32 vcc, 2, v47
	v_cndmask_b32_e64 v28, v28, v42, s[6:7]
	v_not_b32_e32 v40, v28
	v_cndmask_b32_e32 v48, v24, v22, vcc
	v_cmp_eq_u32_e32 vcc, 1, v47
	v_bfe_u32 v55, v40, 6, 2
	v_not_b32_e32 v42, v41
	v_cndmask_b32_e32 v47, v48, v20, vcc
	v_cmp_gt_u32_e32 vcc, 4, v46
; __device__ __forceinline__ void route_task(int task, int tl0, const bf16* QP  , const LAS bf16* KHL, LAS unsigned short* EL, LAS float* GL, int lane) {
;     ...
; #pragma unroll
;     for (int i = 0; i < 8; ++i) {
;         const unsigned cd = 255u - ((unsigned)my[i] & 255u), ca = cd >> 4, cb = cd & 15u;
;         const unsigned wa = (ca >> 2) == 0u ? P1[0] : (ca >> 2) == 1u ? P1[1] : (ca >> 2) == 2u ? P1[2] : P1[3];
;         const unsigned wb = (cb >> 2) == 0u ? P2[0] : (cb >> 2) == 1u ? P2[1] : (cb >> 2) == 2u ? P2[2] : P2[3];
;         bv[i] = (int)((((wa >> (8u * (ca & 3u))) & 255u) << 7) | ((wb >> (8u * (cb & 3u))) & 255u));
;     }
;     float e[8], se = 0.f;
; #pragma unroll
;     for (int i = 0; i < 8; ++i) { e[i] = __expf(__int_as_float(my[i]) - __int_as_float(bk[0])); se += e[i]; }
;     se += __shfl_xor(se, 32);
	v_bitop3_b32 v48, v37, 15, v37 bitop3:0xc
	v_bfe_u32 v57, v42, 6, 2
	v_cndmask_b32_e32 v46, v47, v18, vcc
	v_cmp_eq_u32_e32 vcc, 2, v49
	v_bitop3_b32 v47, v37, s3, v37 bitop3:0xc
	v_not_b32_e32 v43, v30
	v_cndmask_b32_e32 v50, v25, v23, vcc
	v_cmp_eq_u32_e32 vcc, 1, v49
	v_bfe_u32 v59, v43, 6, 2
	s_nop 0
	v_cndmask_b32_e32 v49, v50, v21, vcc
	v_cmp_gt_u32_e32 vcc, 64, v47
	s_nop 1
	v_cndmask_b32_e32 v47, v49, v19, vcc
	v_bfe_u32 v49, v38, 2, 2
	v_cmp_eq_u32_e32 vcc, 2, v49
	s_nop 1
	v_cndmask_b32_e32 v50, v24, v22, vcc
	v_cmp_eq_u32_e32 vcc, 1, v49
	s_nop 1
	v_cndmask_b32_e32 v49, v50, v20, vcc
	v_cmp_gt_u32_e32 vcc, 4, v48
	v_bitop3_b32 v50, v31, 15, v31 bitop3:0xc
	s_nop 0
	v_cndmask_b32_e32 v48, v49, v18, vcc
	v_cmp_eq_u32_e32 vcc, 2, v51
	v_bitop3_b32 v49, v31, s3, v31 bitop3:0xc
	s_nop 0
	v_cndmask_b32_e32 v52, v25, v23, vcc
	v_cmp_eq_u32_e32 vcc, 1, v51
	s_nop 1
	v_cndmask_b32_e32 v51, v52, v21, vcc
	v_cmp_gt_u32_e32 vcc, 64, v49
	s_nop 1
	v_cndmask_b32_e32 v49, v51, v19, vcc
	v_bfe_u32 v51, v36, 2, 2
	v_cmp_eq_u32_e32 vcc, 2, v51
	s_nop 1
	v_cndmask_b32_e32 v52, v24, v22, vcc
	v_cmp_eq_u32_e32 vcc, 1, v51
	s_nop 1
	v_cndmask_b32_e32 v51, v52, v20, vcc
	v_cmp_gt_u32_e32 vcc, 4, v50
	v_bitop3_b32 v52, v33, 15, v33 bitop3:0xc
	s_nop 0
	v_cndmask_b32_e32 v50, v51, v18, vcc
	v_cmp_eq_u32_e32 vcc, 2, v53
	v_bitop3_b32 v51, v33, s3, v33 bitop3:0xc
	s_nop 0
	v_cndmask_b32_e32 v54, v25, v23, vcc
	v_cmp_eq_u32_e32 vcc, 1, v53
	s_nop 1
	v_cndmask_b32_e32 v53, v54, v21, vcc
	v_cmp_gt_u32_e32 vcc, 64, v51
	s_nop 1
	v_cndmask_b32_e32 v51, v53, v19, vcc
	v_bfe_u32 v53, v39, 2, 2
	v_cmp_eq_u32_e32 vcc, 2, v53
	s_nop 1
	v_cndmask_b32_e32 v54, v24, v22, vcc
	v_cmp_eq_u32_e32 vcc, 1, v53
	s_nop 1
	v_cndmask_b32_e32 v53, v54, v20, vcc
	v_cmp_gt_u32_e32 vcc, 4, v52
	v_bitop3_b32 v54, v28, 15, v28 bitop3:0xc
	s_nop 0
	v_cndmask_b32_e32 v52, v53, v18, vcc
	v_cmp_eq_u32_e32 vcc, 2, v55
	v_bitop3_b32 v53, v28, s3, v28 bitop3:0xc
	s_nop 0
	v_cndmask_b32_e32 v56, v25, v23, vcc
	v_cmp_eq_u32_e32 vcc, 1, v55
	s_nop 1
	v_cndmask_b32_e32 v55, v56, v21, vcc
	v_cmp_gt_u32_e32 vcc, 64, v53
	s_nop 1
	v_cndmask_b32_e32 v53, v55, v19, vcc
	v_bfe_u32 v55, v40, 2, 2
	v_cmp_eq_u32_e32 vcc, 2, v55
	s_nop 1
	v_cndmask_b32_e32 v56, v24, v22, vcc
	v_cmp_eq_u32_e32 vcc, 1, v55
	s_nop 1
	v_cndmask_b32_e32 v55, v56, v20, vcc
	v_cmp_gt_u32_e32 vcc, 4, v54
	v_bitop3_b32 v56, v41, 15, v41 bitop3:0xc
	s_nop 0
	v_cndmask_b32_e32 v54, v55, v18, vcc
	v_cmp_eq_u32_e32 vcc, 2, v57
	v_bitop3_b32 v55, v41, s3, v41 bitop3:0xc
	s_nop 0
	v_cndmask_b32_e32 v58, v25, v23, vcc
	v_cmp_eq_u32_e32 vcc, 1, v57
	s_nop 1
	v_cndmask_b32_e32 v57, v58, v21, vcc
	v_cmp_gt_u32_e32 vcc, 64, v55
	s_nop 1
	v_cndmask_b32_e32 v55, v57, v19, vcc
	v_bfe_u32 v57, v42, 2, 2
	v_cmp_eq_u32_e32 vcc, 2, v57
	s_nop 1
	v_cndmask_b32_e32 v58, v24, v22, vcc
	v_cmp_eq_u32_e32 vcc, 1, v57
	s_nop 1
	v_cndmask_b32_e32 v57, v58, v20, vcc
	v_cmp_gt_u32_e32 vcc, 4, v56
	v_bitop3_b32 v58, v30, 15, v30 bitop3:0xc
	s_nop 0
	v_cndmask_b32_e32 v56, v57, v18, vcc
	v_cmp_eq_u32_e32 vcc, 2, v59
	v_bitop3_b32 v57, v30, s3, v30 bitop3:0xc
	s_nop 0
	v_cndmask_b32_e32 v23, v25, v23, vcc
	v_cmp_eq_u32_e32 vcc, 1, v59
	v_sub_f32_e32 v25, v31, v32
	v_mul_f32_e32 v25, 0x3fb8aa3b, v25
	v_cndmask_b32_e32 v21, v23, v21, vcc
	v_cmp_gt_u32_e32 vcc, 64, v57
	v_lshrrev_b32_e32 v23, 1, v39
	v_and_b32_e32 v23, 24, v23
	v_cndmask_b32_e32 v19, v21, v19, vcc
	v_bfe_u32 v21, v43, 2, 2
	v_cmp_eq_u32_e32 vcc, 2, v21
	v_lshrrev_b32_e32 v23, v23, v51
	v_lshlrev_b32_e32 v23, 7, v23
	v_cndmask_b32_e32 v22, v24, v22, vcc
	v_cmp_eq_u32_e32 vcc, 1, v21
	v_lshrrev_b32_e32 v21, 1, v42
	v_and_b32_e32 v21, 24, v21
	v_cndmask_b32_e32 v20, v22, v20, vcc
	v_cmp_gt_u32_e32 vcc, 4, v58
	v_lshrrev_b32_e32 v21, v21, v55
	v_lshrrev_b32_e32 v22, 1, v40
	v_cndmask_b32_e32 v18, v20, v18, vcc
	v_lshlrev_b32_e32 v20, 3, v42
	v_lshlrev_b32_e32 v21, 7, v21
	v_and_b32_e32 v22, 24, v22
	v_lshrrev_b32_e32 v20, v20, v56
	v_and_b32_e32 v21, 0x7f80, v21
	v_lshrrev_b32_e32 v22, v22, v53
	v_and_or_b32 v21, v20, s3, v21
	v_lshlrev_b32_e32 v20, 3, v40
	v_lshlrev_b32_e32 v22, 7, v22
	v_lshrrev_b32_e32 v20, v20, v54
	v_and_b32_e32 v22, 0x7f80, v22
	v_and_or_b32 v20, v20, s3, v22
	v_lshlrev_b32_e32 v22, 3, v39
	v_lshrrev_b32_e32 v22, v22, v52
	v_and_b32_e32 v23, 0x7f80, v23
	v_and_or_b32 v39, v22, s3, v23
	v_lshrrev_b32_e32 v23, 1, v36
	v_and_b32_e32 v23, 24, v23
	v_lshrrev_b32_e32 v23, v23, v49
	v_lshlrev_b32_e32 v22, 3, v36
	v_lshlrev_b32_e32 v23, 7, v23
	v_lshrrev_b32_e32 v22, v22, v50
	v_and_b32_e32 v23, 0x7f80, v23
	v_and_or_b32 v36, v22, s3, v23
	v_lshrrev_b32_e32 v23, 1, v38
	v_and_b32_e32 v23, 24, v23
	v_lshrrev_b32_e32 v23, v23, v47
	v_lshlrev_b32_e32 v22, 3, v38
	v_lshlrev_b32_e32 v23, 7, v23
	v_lshrrev_b32_e32 v22, v22, v48
	v_and_b32_e32 v23, 0x7f80, v23
	v_and_or_b32 v38, v22, s3, v23
	v_lshrrev_b32_e32 v23, 1, v35
	v_and_b32_e32 v23, 24, v23
	v_lshrrev_b32_e32 v23, v23, v45
	v_lshlrev_b32_e32 v22, 3, v35
	v_lshlrev_b32_e32 v23, 7, v23
	v_lshrrev_b32_e32 v22, v22, v46
	v_and_b32_e32 v23, 0x7f80, v23
	v_and_or_b32 v35, v22, s3, v23
	v_lshrrev_b32_e32 v23, 1, v29
	v_and_b32_e32 v23, 24, v23
	v_lshrrev_b32_e32 v23, v23, v26
	v_lshlrev_b32_e32 v22, 3, v29
	v_lshlrev_b32_e32 v23, 7, v23
	v_lshrrev_b32_e32 v22, v22, v44
	v_and_b32_e32 v23, 0x7f80, v23
	v_and_or_b32 v40, v22, s3, v23
	v_sub_f32_e32 v22, v27, v32
	v_mul_f32_e32 v22, 0x3fb8aa3b, v22
	v_sub_f32_e32 v23, v34, v32
	v_exp_f32_e32 v22, v22
	v_mul_f32_e32 v23, 0x3fb8aa3b, v23
	v_sub_f32_e32 v24, v37, v32
	v_exp_f32_e32 v23, v23
	v_mul_f32_e32 v24, 0x3fb8aa3b, v24
	v_exp_f32_e32 v24, v24
	v_exp_f32_e32 v25, v25
	v_add_f32_e32 v26, 0, v22
	v_add_f32_e32 v26, v23, v26
	v_add_f32_e32 v26, v24, v26
	v_add_f32_e32 v31, v25, v26
	v_sub_f32_e32 v26, v33, v32
	v_mul_f32_e32 v26, 0x3fb8aa3b, v26
	v_sub_f32_e32 v27, v28, v32
	v_exp_f32_e32 v26, v26
	v_mul_f32_e32 v27, 0x3fb8aa3b, v27
	v_sub_f32_e32 v28, v41, v32
	v_exp_f32_e32 v27, v27
	v_mul_f32_e32 v28, 0x3fb8aa3b, v28
	v_sub_f32_e32 v29, v30, v32
	v_exp_f32_e32 v28, v28
	v_mul_f32_e32 v29, 0x3fb8aa3b, v29
	v_exp_f32_e32 v29, v29
	v_add_f32_e32 v30, v26, v31
	v_add_f32_e32 v30, v27, v30
	v_add_f32_e32 v30, v28, v30
	v_add_f32_e32 v30, v29, v30
	ds_bpermute_b32 v31, v123, v30
	v_lshrrev_b32_e32 v42, 1, v43
	v_and_b32_e32 v32, 24, v42
	v_lshrrev_b32_e32 v19, v32, v19
	v_lshlrev_b32_e32 v19, 7, v19
	s_waitcnt lgkmcnt(0)
; #define LAS __attribute__((address_space(3)))
; __device__ __forceinline__ void peer_u_item(int p, int j, const LAS unsigned short* EL  , const unsigned char* __restrict__ XQ, const unsigned char* __restrict__ U8, LAS int* ACC  , int lane, int wave) {
;     ...
;     const int gidx = lane >> 3; const unsigned coff = (unsigned)(p * 128 + (lane & 7) * 16), toff = (unsigned)(p * (16384 * 128) + (lane & 7) * 16);
; #pragma unroll 1
;     for (int it = 0; it < 8; ++it) {
;         const int t = j * 64 + it * 8 + wave;
;         unsigned E[8];
;         { const LAS v4u* ep = (const LAS v4u*)(EL + (it * 8 + wave) * 128 + 16 * gidx); const v4u e0 = ep[0], e1 = ep[1];
;           E[0] = e0.x; E[1] = e0.y; E[2] = e0.z; E[3] = e0.w; E[4] = e1.x; E[5] = e1.y; E[6] = e1.z; E[7] = e1.w; }
;         uint4 uu[16];
; #pragma unroll
;         for (int i = 0; i < 16; ++i) uu[i] = *(const uint4*)(U8 + (size_t)(PE_ID(E, i) * 128u + toff));
;         const uint4 xh = *(const uint4*)(XQ + (size_t)t * 512 + coff), xl = *(const uint4*)(XQ + 8 * MiB + (size_t)t * 512 + coff);
; __device__ __forceinline__ void route_task(int task, int tl0, const bf16* QP  , const LAS bf16* KHL, LAS unsigned short* EL, LAS float* GL, int lane) {
;     ...
;     const float inv = 1.f / se;
;     {
;         int l2 = lane; asm volatile("" : "+v"(l2));
;         const int o2 = (tl0 + ((l2 & 31) >> 3)) * 128 + (l2 & 7) * 16 + 8 * (l2 >> 5);
;         LAS v4u* ip = (LAS v4u*)(EL + o2); typedef float f4v __attribute__((ext_vector_type(4))); LAS f4v* gp = (LAS f4v*)(GL + o2);
;         ip[0] = (v4u){(unsigned)bv[0] | ((unsigned)bv[1] << 16), (unsigned)bv[2] | ((unsigned)bv[3] << 16), (unsigned)bv[4] | ((unsigned)bv[5] << 16), (unsigned)bv[6] | ((unsigned)bv[7] << 16)};
;         gp[0] = (f4v){e[0] * inv, e[1] * inv, e[2] * inv, e[3] * inv}; gp[1] = (f4v){e[4] * inv, e[5] * inv, e[6] * inv, e[7] * inv};
;     }
	v_add_f32_e32 v30, v30, v31
	v_div_scale_f32 v31, s[12:13], v30, v30, 1.0
	v_rcp_f32_e32 v32, v31
	v_lshlrev_b32_e32 v33, 3, v43
	v_and_b32_e32 v19, 0x7f80, v19
	v_lshrrev_b32_e32 v18, v33, v18
	v_and_or_b32 v33, v18, s3, v19
	v_fma_f32 v18, -v31, v32, 1.0
	v_fmac_f32_e32 v32, v18, v32
	v_div_scale_f32 v18, vcc, 1.0, v30, 1.0
	v_mul_f32_e32 v19, v18, v32
	v_fma_f32 v34, -v31, v19, v18
	v_fmac_f32_e32 v19, v34, v32
	v_fma_f32 v18, -v31, v19, v18
	v_div_fmas_f32 v18, v18, v32, v19
	v_div_fixup_f32 v30, v18, v30, 1.0
	v_mov_b32_e32 v18, v1
	v_lshl_or_b32 v20, v20, 16, v39
	v_lshrrev_b32_e32 v19, 3, v18
	v_and_or_b32 v19, v19, 3, s57
	v_lshlrev_b32_e32 v31, 4, v18
	v_ashrrev_i32_e32 v18, 2, v18
	v_lshlrev_b32_e32 v19, 7, v19
	v_and_b32_e32 v31, 0x70, v31
	v_and_b32_e32 v18, -8, v18
	v_add3_u32 v18, v18, v31, v19
	v_lshl_add_u32 v31, v18, 1, s11
	v_lshl_add_u32 v32, v18, 2, s69
	v_lshl_or_b32 v18, v35, 16, v40
	v_lshl_or_b32 v19, v36, 16, v38
	v_lshl_or_b32 v21, v33, 16, v21
	ds_write_b128 v31, v[18:21]
	v_pk_mul_f32 v[20:21], v[24:25], v[30:31] op_sel_hi:[1,0]
	v_pk_mul_f32 v[18:19], v[22:23], v[30:31] op_sel_hi:[1,0]
	ds_write_b128 v32, v[18:21]
	v_pk_mul_f32 v[20:21], v[28:29], v[30:31] op_sel_hi:[1,0]
	v_pk_mul_f32 v[18:19], v[26:27], v[30:31] op_sel_hi:[1,0]
	ds_write_b128 v32, v[18:21] offset:16
	v_xor_b32_e32 v18, 4, v112
	v_cmp_lt_i32_e32 vcc, v18, v122
	s_waitcnt lgkmcnt(0)
	s_barrier
	v_cndmask_b32_e32 v18, v112, v18, vcc
	v_lshlrev_b32_e32 v30, 2, v18
	v_xor_b32_e32 v18, 2, v112
	v_cmp_lt_i32_e32 vcc, v18, v122
	s_nop 1
	v_cndmask_b32_e32 v18, v112, v18, vcc
	v_lshlrev_b32_e32 v31, 2, v18
	v_xor_b32_e32 v18, 1, v112
	v_cmp_lt_i32_e32 vcc, v18, v122
	s_nop 1
	v_cndmask_b32_e32 v18, v112, v18, vcc
	v_lshlrev_b32_e32 v32, 2, v18
	v_lshlrev_b32_e32 v56, 4, v1
	v_and_b32_e32 v56, 0x70, v56
	v_lshrrev_b32_e32 v59, 3, v1
	v_lshlrev_b32_e32 v59, 5, v59
	v_add_u32_e32 v59, s66, v59
	v_add_u32_e32 v59, -16, v59
	v_lshl_add_u32 v60, v1, 3, s64
	v_and_b32_e32 v38, 4, v1
	v_cmp_ne_u32_e64 s[10:11], 0, v38
	v_and_b32_e32 v38, 2, v1
	v_cmp_ne_u32_e64 s[12:13], 0, v38
	v_and_b32_e32 v38, 1, v1
	v_cmp_ne_u32_e64 s[14:15], 0, v38
	s_mov_b32 s42, 0
	s_mov_b32 s43, 0
	s_mov_b32 s44, 1
	s_mov_b32 s45, 0
	s_lshl_b32 s32, s42, 11
	v_add_u32_e32 v39, s32, v59
	ds_read_b128 v[202:205], v39
	ds_read_b128 v[206:209], v39 offset:16
	s_lshl_b32 s46, s42, 3
	s_add_i32 s46, s46, s40
	s_lshl_b32 s46, s46, 9
	s_lshl_b32 s32, s43, 7
	s_add_i32 s46, s46, s32
	v_add_u32_e32 v57, s46, v56
	global_load_dwordx4 v[186:189], v57, s[34:35]
	global_load_dwordx4 v[190:193], v57, s[36:37]
	v_mov_b32_e32 v58, v56
	s_waitcnt lgkmcnt(0)
	v_and_b32_e32 v38, 0xffff, v202
	v_lshl_add_u32 v38, v38, 7, v58
	global_load_dwordx4 v[122:125], v38, s[96:97]
	v_lshrrev_b32_e32 v38, 16, v202
	v_lshl_add_u32 v38, v38, 7, v58
	global_load_dwordx4 v[126:129], v38, s[96:97]
	v_and_b32_e32 v38, 0xffff, v203
	v_lshl_add_u32 v38, v38, 7, v58
	global_load_dwordx4 v[130:133], v38, s[96:97]
	v_lshrrev_b32_e32 v38, 16, v203
	v_lshl_add_u32 v38, v38, 7, v58
	global_load_dwordx4 v[134:137], v38, s[96:97]
	v_and_b32_e32 v38, 0xffff, v204
	v_lshl_add_u32 v38, v38, 7, v58
	global_load_dwordx4 v[138:141], v38, s[96:97]
	v_lshrrev_b32_e32 v38, 16, v204
	v_lshl_add_u32 v38, v38, 7, v58
	global_load_dwordx4 v[142:145], v38, s[96:97]
	v_and_b32_e32 v38, 0xffff, v205
	v_lshl_add_u32 v38, v38, 7, v58
	global_load_dwordx4 v[146:149], v38, s[96:97]
	v_lshrrev_b32_e32 v38, 16, v205
	v_lshl_add_u32 v38, v38, 7, v58
	global_load_dwordx4 v[150:153], v38, s[96:97]
	v_and_b32_e32 v38, 0xffff, v206
	v_lshl_add_u32 v38, v38, 7, v58
	global_load_dwordx4 v[154:157], v38, s[96:97]
	v_lshrrev_b32_e32 v38, 16, v206
	v_lshl_add_u32 v38, v38, 7, v58
	global_load_dwordx4 v[158:161], v38, s[96:97]
	v_and_b32_e32 v38, 0xffff, v207
	v_lshl_add_u32 v38, v38, 7, v58
	global_load_dwordx4 v[162:165], v38, s[96:97]
	v_lshrrev_b32_e32 v38, 16, v207
	v_lshl_add_u32 v38, v38, 7, v58
	global_load_dwordx4 v[166:169], v38, s[96:97]
	v_and_b32_e32 v38, 0xffff, v208
	v_lshl_add_u32 v38, v38, 7, v58
	global_load_dwordx4 v[170:173], v38, s[96:97]
	v_lshrrev_b32_e32 v38, 16, v208
	v_lshl_add_u32 v38, v38, 7, v58
	global_load_dwordx4 v[174:177], v38, s[96:97]
	v_and_b32_e32 v38, 0xffff, v209
	v_lshl_add_u32 v38, v38, 7, v58
	global_load_dwordx4 v[178:181], v38, s[96:97]
	v_lshrrev_b32_e32 v38, 16, v209
	v_lshl_add_u32 v38, v38, 7, v58
	global_load_dwordx4 v[182:185], v38, s[96:97]
	s_mov_b32 s47, 16
; #define LAS __attribute__((address_space(3)))
; __device__ __forceinline__ void peer_u_item(int p, int j, const LAS unsigned short* EL  , const unsigned char* __restrict__ XQ, const unsigned char* __restrict__ U8, LAS int* ACC  , int lane, int wave) {
;     ...
;     for (int it = 0; it < 8; ++it) {
;         const int t = j * 64 + it * 8 + wave;
;         unsigned E[8];
;         { const LAS v4u* ep = (const LAS v4u*)(EL + (it * 8 + wave) * 128 + 16 * gidx); const v4u e0 = ep[0], e1 = ep[1];
;           E[0] = e0.x; E[1] = e0.y; E[2] = e0.z; E[3] = e0.w; E[4] = e1.x; E[5] = e1.y; E[6] = e1.z; E[7] = e1.w; }
;         uint4 uu[16];
; #pragma unroll
;         for (int i = 0; i < 16; ++i) uu[i] = *(const uint4*)(U8 + (size_t)(PE_ID(E, i) * 128u + toff));
;         const uint4 xh = *(const uint4*)(XQ + (size_t)t * 512 + coff), xl = *(const uint4*)(XQ + 8 * MiB + (size_t)t * 512 + coff);
;         int d[16];
; #pragma unroll
;         for (int i = 0; i < 16; ++i) {
;             int sh = __builtin_amdgcn_sdot8((int)uu[i].x, (int)xh.x, 0, false); sh = __builtin_amdgcn_sdot8((int)uu[i].y, (int)xh.y, sh, false);
;             sh = __builtin_amdgcn_sdot8((int)uu[i].z, (int)xh.z, sh, false); sh = __builtin_amdgcn_sdot8((int)uu[i].w, (int)xh.w, sh, false);
;             int sl = __builtin_amdgcn_sdot8((int)uu[i].x, (int)xl.x, 0, false); sl = __builtin_amdgcn_sdot8((int)uu[i].y, (int)xl.y, sl, false);
;             sl = __builtin_amdgcn_sdot8((int)uu[i].z, (int)xl.z, sl, false); sl = __builtin_amdgcn_sdot8((int)uu[i].w, (int)xl.w, sl, false);
;             d[i] = (sh << 4) + sl;
;         }
;         int r0, r1; treduce16i<4, 2, 1>(d, lane, r0, r1);
.Lpu_trip:
	s_lshl_b32 s32, s44, 11
	v_add_u32_e32 v39, s32, v59
	ds_read_b128 v[210:213], v39
	ds_read_b128 v[214:217], v39 offset:16
	s_lshl_b32 s32, s42, 12
	v_add_u32_e32 v61, s32, v60
	ds_read_b64 v[62:63], v61
	s_lshl_b32 s46, s44, 3
	s_add_i32 s46, s46, s40
	s_lshl_b32 s46, s46, 9
	s_lshl_b32 s32, s45, 7
	s_add_i32 s46, s46, s32
	v_add_u32_e32 v57, s46, v56
	global_load_dwordx4 v[194:197], v57, s[34:35]
	global_load_dwordx4 v[198:201], v57, s[36:37]
	s_lshl_b32 s32, s45, 21
	v_add_u32_e32 v58, s32, v56
	s_waitcnt lgkmcnt(0)
	s_waitcnt vmcnt(17)
	v_dot8_i32_i4 v34, v122, v186, 0
	v_dot8_i32_i4 v35, v122, v190, 0
	v_dot8_i32_i4 v34, v123, v187, v34
	v_dot8_i32_i4 v35, v123, v191, v35
	v_dot8_i32_i4 v34, v124, v188, v34
	v_dot8_i32_i4 v35, v124, v192, v35
	v_dot8_i32_i4 v34, v125, v189, v34
	v_dot8_i32_i4 v35, v125, v193, v35
	v_and_b32_e32 v38, 0xffff, v210
	v_lshl_add_u32 v38, v38, 7, v58
	global_load_dwordx4 v[122:125], v38, s[96:97]
	s_nop 0
	v_lshl_add_u32 v18, v34, 4, v35
	s_waitcnt vmcnt(17)
	v_dot8_i32_i4 v36, v126, v186, 0
	v_dot8_i32_i4 v37, v126, v190, 0
	v_dot8_i32_i4 v36, v127, v187, v36
	v_dot8_i32_i4 v37, v127, v191, v37
	v_dot8_i32_i4 v36, v128, v188, v36
	v_dot8_i32_i4 v37, v128, v192, v37
	v_dot8_i32_i4 v36, v129, v189, v36
	v_dot8_i32_i4 v37, v129, v193, v37
	v_lshrrev_b32_e32 v38, 16, v210
	v_lshl_add_u32 v38, v38, 7, v58
	global_load_dwordx4 v[126:129], v38, s[96:97]
	s_nop 0
	v_lshl_add_u32 v19, v36, 4, v37
	s_waitcnt vmcnt(17)
	v_dot8_i32_i4 v34, v130, v186, 0
	v_dot8_i32_i4 v35, v130, v190, 0
	v_dot8_i32_i4 v34, v131, v187, v34
	v_dot8_i32_i4 v35, v131, v191, v35
	v_dot8_i32_i4 v34, v132, v188, v34
	v_dot8_i32_i4 v35, v132, v192, v35
	v_dot8_i32_i4 v34, v133, v189, v34
	v_dot8_i32_i4 v35, v133, v193, v35
	v_and_b32_e32 v38, 0xffff, v211
	v_lshl_add_u32 v38, v38, 7, v58
	global_load_dwordx4 v[130:133], v38, s[96:97]
	s_nop 0
	v_lshl_add_u32 v20, v34, 4, v35
	s_waitcnt vmcnt(17)
	v_dot8_i32_i4 v36, v134, v186, 0
	v_dot8_i32_i4 v37, v134, v190, 0
	v_dot8_i32_i4 v36, v135, v187, v36
	v_dot8_i32_i4 v37, v135, v191, v37
	v_dot8_i32_i4 v36, v136, v188, v36
	v_dot8_i32_i4 v37, v136, v192, v37
	v_dot8_i32_i4 v36, v137, v189, v36
	v_dot8_i32_i4 v37, v137, v193, v37
	v_lshrrev_b32_e32 v38, 16, v211
	v_lshl_add_u32 v38, v38, 7, v58
	global_load_dwordx4 v[134:137], v38, s[96:97]
	s_nop 0
	v_lshl_add_u32 v21, v36, 4, v37
	s_waitcnt vmcnt(17)
	v_dot8_i32_i4 v34, v138, v186, 0
	v_dot8_i32_i4 v35, v138, v190, 0
	v_dot8_i32_i4 v34, v139, v187, v34
	v_dot8_i32_i4 v35, v139, v191, v35
	v_dot8_i32_i4 v34, v140, v188, v34
	v_dot8_i32_i4 v35, v140, v192, v35
	v_dot8_i32_i4 v34, v141, v189, v34
	v_dot8_i32_i4 v35, v141, v193, v35
	v_and_b32_e32 v38, 0xffff, v212
	v_lshl_add_u32 v38, v38, 7, v58
	global_load_dwordx4 v[138:141], v38, s[96:97]
	s_nop 0
	v_lshl_add_u32 v22, v34, 4, v35
	s_waitcnt vmcnt(17)
	v_dot8_i32_i4 v36, v142, v186, 0
	v_dot8_i32_i4 v37, v142, v190, 0
	v_dot8_i32_i4 v36, v143, v187, v36
	v_dot8_i32_i4 v37, v143, v191, v37
	v_dot8_i32_i4 v36, v144, v188, v36
	v_dot8_i32_i4 v37, v144, v192, v37
	v_dot8_i32_i4 v36, v145, v189, v36
	v_dot8_i32_i4 v37, v145, v193, v37
	v_lshrrev_b32_e32 v38, 16, v212
	v_lshl_add_u32 v38, v38, 7, v58
	global_load_dwordx4 v[142:145], v38, s[96:97]
	s_nop 0
	v_lshl_add_u32 v23, v36, 4, v37
	s_waitcnt vmcnt(17)
	v_dot8_i32_i4 v34, v146, v186, 0
	v_dot8_i32_i4 v35, v146, v190, 0
	v_dot8_i32_i4 v34, v147, v187, v34
	v_dot8_i32_i4 v35, v147, v191, v35
	v_dot8_i32_i4 v34, v148, v188, v34
	v_dot8_i32_i4 v35, v148, v192, v35
	v_dot8_i32_i4 v34, v149, v189, v34
	v_dot8_i32_i4 v35, v149, v193, v35
	v_and_b32_e32 v38, 0xffff, v213
	v_lshl_add_u32 v38, v38, 7, v58
	global_load_dwordx4 v[146:149], v38, s[96:97]
	s_nop 0
	v_lshl_add_u32 v24, v34, 4, v35
	s_waitcnt vmcnt(17)
	v_dot8_i32_i4 v36, v150, v186, 0
	v_dot8_i32_i4 v37, v150, v190, 0
	v_dot8_i32_i4 v36, v151, v187, v36
	v_dot8_i32_i4 v37, v151, v191, v37
	v_dot8_i32_i4 v36, v152, v188, v36
	v_dot8_i32_i4 v37, v152, v192, v37
	v_dot8_i32_i4 v36, v153, v189, v36
	v_dot8_i32_i4 v37, v153, v193, v37
	v_lshrrev_b32_e32 v38, 16, v213
	v_lshl_add_u32 v38, v38, 7, v58
	global_load_dwordx4 v[150:153], v38, s[96:97]
	s_nop 0
	v_lshl_add_u32 v25, v36, 4, v37
	s_waitcnt vmcnt(17)
	v_dot8_i32_i4 v34, v154, v186, 0
	v_dot8_i32_i4 v35, v154, v190, 0
	v_dot8_i32_i4 v34, v155, v187, v34
	v_dot8_i32_i4 v35, v155, v191, v35
	v_dot8_i32_i4 v34, v156, v188, v34
	v_dot8_i32_i4 v35, v156, v192, v35
	v_dot8_i32_i4 v34, v157, v189, v34
	v_dot8_i32_i4 v35, v157, v193, v35
	v_and_b32_e32 v38, 0xffff, v214
	v_lshl_add_u32 v38, v38, 7, v58
	global_load_dwordx4 v[154:157], v38, s[96:97]
	s_nop 0
	v_lshl_add_u32 v26, v34, 4, v35
	s_waitcnt vmcnt(17)
	v_dot8_i32_i4 v36, v158, v186, 0
	v_dot8_i32_i4 v37, v158, v190, 0
	v_dot8_i32_i4 v36, v159, v187, v36
	v_dot8_i32_i4 v37, v159, v191, v37
	v_dot8_i32_i4 v36, v160, v188, v36
	v_dot8_i32_i4 v37, v160, v192, v37
	v_dot8_i32_i4 v36, v161, v189, v36
	v_dot8_i32_i4 v37, v161, v193, v37
	v_lshrrev_b32_e32 v38, 16, v214
	v_lshl_add_u32 v38, v38, 7, v58
	global_load_dwordx4 v[158:161], v38, s[96:97]
	s_nop 0
	v_lshl_add_u32 v27, v36, 4, v37
	s_waitcnt vmcnt(17)
	v_dot8_i32_i4 v34, v162, v186, 0
	v_dot8_i32_i4 v35, v162, v190, 0
	v_dot8_i32_i4 v34, v163, v187, v34
	v_dot8_i32_i4 v35, v163, v191, v35
	v_dot8_i32_i4 v34, v164, v188, v34
	v_dot8_i32_i4 v35, v164, v192, v35
	v_dot8_i32_i4 v34, v165, v189, v34
	v_dot8_i32_i4 v35, v165, v193, v35
	v_and_b32_e32 v38, 0xffff, v215
	v_lshl_add_u32 v38, v38, 7, v58
	global_load_dwordx4 v[162:165], v38, s[96:97]
	s_nop 0
	v_lshl_add_u32 v28, v34, 4, v35
	s_waitcnt vmcnt(17)
; #define LAS __attribute__((address_space(3)))
; __device__ __forceinline__ void peer_u_item(int p, int j, const LAS unsigned short* EL  , const unsigned char* __restrict__ XQ, const unsigned char* __restrict__ U8, LAS int* ACC  , int lane, int wave) {
;     ...
;         int d[16];
; #pragma unroll
;         for (int i = 0; i < 16; ++i) {
;             int sh = __builtin_amdgcn_sdot8((int)uu[i].x, (int)xh.x, 0, false); sh = __builtin_amdgcn_sdot8((int)uu[i].y, (int)xh.y, sh, false);
;             sh = __builtin_amdgcn_sdot8((int)uu[i].z, (int)xh.z, sh, false); sh = __builtin_amdgcn_sdot8((int)uu[i].w, (int)xh.w, sh, false);
;             int sl = __builtin_amdgcn_sdot8((int)uu[i].x, (int)xl.x, 0, false); sl = __builtin_amdgcn_sdot8((int)uu[i].y, (int)xl.y, sl, false);
;             sl = __builtin_amdgcn_sdot8((int)uu[i].z, (int)xl.z, sl, false); sl = __builtin_amdgcn_sdot8((int)uu[i].w, (int)xl.w, sl, false);
;             d[i] = (sh << 4) + sl;
;         }
;         int r0, r1; treduce16i<4, 2, 1>(d, lane, r0, r1);
;         { typedef int i2v __attribute__((ext_vector_type(2))); LAS i2v* ap = (LAS i2v*)(ACC + (it * 8 + wave) * 128 + 2 * lane);
;           i2v a2; if (p == 0) { a2.x = r0; a2.y = r1; } else { a2 = *ap; a2.x += r0; a2.y += r1; } *ap = a2; }
	v_dot8_i32_i4 v36, v166, v186, 0
	v_dot8_i32_i4 v37, v166, v190, 0
	v_dot8_i32_i4 v36, v167, v187, v36
	v_dot8_i32_i4 v37, v167, v191, v37
	v_dot8_i32_i4 v36, v168, v188, v36
	v_dot8_i32_i4 v37, v168, v192, v37
	v_dot8_i32_i4 v36, v169, v189, v36
	v_dot8_i32_i4 v37, v169, v193, v37
	v_lshrrev_b32_e32 v38, 16, v215
	v_lshl_add_u32 v38, v38, 7, v58
	global_load_dwordx4 v[166:169], v38, s[96:97]
	s_nop 0
	v_lshl_add_u32 v29, v36, 4, v37
	s_waitcnt vmcnt(17)
	v_dot8_i32_i4 v34, v170, v186, 0
	v_dot8_i32_i4 v35, v170, v190, 0
	v_dot8_i32_i4 v34, v171, v187, v34
	v_dot8_i32_i4 v35, v171, v191, v35
	v_dot8_i32_i4 v34, v172, v188, v34
	v_dot8_i32_i4 v35, v172, v192, v35
	v_dot8_i32_i4 v34, v173, v189, v34
	v_dot8_i32_i4 v35, v173, v193, v35
	v_and_b32_e32 v38, 0xffff, v216
	v_lshl_add_u32 v38, v38, 7, v58
	global_load_dwordx4 v[170:173], v38, s[96:97]
	s_nop 0
	v_lshl_add_u32 v30, v34, 4, v35
	s_waitcnt vmcnt(17)
	v_dot8_i32_i4 v36, v174, v186, 0
	v_dot8_i32_i4 v37, v174, v190, 0
	v_dot8_i32_i4 v36, v175, v187, v36
	v_dot8_i32_i4 v37, v175, v191, v37
	v_dot8_i32_i4 v36, v176, v188, v36
	v_dot8_i32_i4 v37, v176, v192, v37
	v_dot8_i32_i4 v36, v177, v189, v36
	v_dot8_i32_i4 v37, v177, v193, v37
	v_lshrrev_b32_e32 v38, 16, v216
	v_lshl_add_u32 v38, v38, 7, v58
	global_load_dwordx4 v[174:177], v38, s[96:97]
	s_nop 0
	v_lshl_add_u32 v31, v36, 4, v37
	s_waitcnt vmcnt(17)
	v_dot8_i32_i4 v34, v178, v186, 0
	v_dot8_i32_i4 v35, v178, v190, 0
	v_dot8_i32_i4 v34, v179, v187, v34
	v_dot8_i32_i4 v35, v179, v191, v35
	v_dot8_i32_i4 v34, v180, v188, v34
	v_dot8_i32_i4 v35, v180, v192, v35
	v_dot8_i32_i4 v34, v181, v189, v34
	v_dot8_i32_i4 v35, v181, v193, v35
	v_and_b32_e32 v38, 0xffff, v217
	v_lshl_add_u32 v38, v38, 7, v58
	global_load_dwordx4 v[178:181], v38, s[96:97]
	s_nop 0
	v_lshl_add_u32 v32, v34, 4, v35
	s_waitcnt vmcnt(17)
	v_dot8_i32_i4 v36, v182, v186, 0
	v_dot8_i32_i4 v37, v182, v190, 0
	v_dot8_i32_i4 v36, v183, v187, v36
	v_dot8_i32_i4 v37, v183, v191, v37
	v_dot8_i32_i4 v36, v184, v188, v36
	v_dot8_i32_i4 v37, v184, v192, v37
	v_dot8_i32_i4 v36, v185, v189, v36
	v_dot8_i32_i4 v37, v185, v193, v37
	v_lshrrev_b32_e32 v38, 16, v217
	v_lshl_add_u32 v38, v38, 7, v58
	global_load_dwordx4 v[182:185], v38, s[96:97]
	s_nop 0
	v_lshl_add_u32 v33, v36, 4, v37
	v_cndmask_b32_e64 v40, v26, v18, s[10:11]
	v_cndmask_b32_e64 v48, v18, v26, s[10:11]
	v_cndmask_b32_e64 v41, v27, v19, s[10:11]
	v_cndmask_b32_e64 v49, v19, v27, s[10:11]
	v_cndmask_b32_e64 v42, v28, v20, s[10:11]
	v_cndmask_b32_e64 v50, v20, v28, s[10:11]
	v_cndmask_b32_e64 v43, v29, v21, s[10:11]
	v_cndmask_b32_e64 v51, v21, v29, s[10:11]
	v_cndmask_b32_e64 v44, v30, v22, s[10:11]
	v_cndmask_b32_e64 v52, v22, v30, s[10:11]
	v_cndmask_b32_e64 v45, v31, v23, s[10:11]
	v_cndmask_b32_e64 v53, v23, v31, s[10:11]
	v_cndmask_b32_e64 v46, v32, v24, s[10:11]
	v_cndmask_b32_e64 v54, v24, v32, s[10:11]
	v_cndmask_b32_e64 v47, v33, v25, s[10:11]
	v_cndmask_b32_e64 v55, v25, v33, s[10:11]
	v_add_u32_dpp v18, v40, v48 row_shr:4 row_mask:0xf bank_mask:0xa
	v_add_u32_dpp v18, v40, v48 row_shl:4 row_mask:0xf bank_mask:0x5
	v_add_u32_dpp v19, v41, v49 row_shr:4 row_mask:0xf bank_mask:0xa
	v_add_u32_dpp v19, v41, v49 row_shl:4 row_mask:0xf bank_mask:0x5
	v_add_u32_dpp v20, v42, v50 row_shr:4 row_mask:0xf bank_mask:0xa
	v_add_u32_dpp v20, v42, v50 row_shl:4 row_mask:0xf bank_mask:0x5
	v_add_u32_dpp v21, v43, v51 row_shr:4 row_mask:0xf bank_mask:0xa
	v_add_u32_dpp v21, v43, v51 row_shl:4 row_mask:0xf bank_mask:0x5
	v_add_u32_dpp v22, v44, v52 row_shr:4 row_mask:0xf bank_mask:0xa
	v_add_u32_dpp v22, v44, v52 row_shl:4 row_mask:0xf bank_mask:0x5
	v_add_u32_dpp v23, v45, v53 row_shr:4 row_mask:0xf bank_mask:0xa
	v_add_u32_dpp v23, v45, v53 row_shl:4 row_mask:0xf bank_mask:0x5
	v_add_u32_dpp v24, v46, v54 row_shr:4 row_mask:0xf bank_mask:0xa
	v_add_u32_dpp v24, v46, v54 row_shl:4 row_mask:0xf bank_mask:0x5
	v_add_u32_dpp v25, v47, v55 row_shr:4 row_mask:0xf bank_mask:0xa
	v_add_u32_dpp v25, v47, v55 row_shl:4 row_mask:0xf bank_mask:0x5
	v_cndmask_b32_e64 v40, v22, v18, s[12:13]
	v_cndmask_b32_e64 v48, v18, v22, s[12:13]
	v_cndmask_b32_e64 v41, v23, v19, s[12:13]
	v_cndmask_b32_e64 v49, v19, v23, s[12:13]
	v_cndmask_b32_e64 v42, v24, v20, s[12:13]
	v_cndmask_b32_e64 v50, v20, v24, s[12:13]
	v_cndmask_b32_e64 v43, v25, v21, s[12:13]
	v_cndmask_b32_e64 v51, v21, v25, s[12:13]
	s_nop 0
	v_add_u32_dpp v26, v40, v48 quad_perm:[2,3,0,1] row_mask:0xf bank_mask:0xf
	v_add_u32_dpp v27, v41, v49 quad_perm:[2,3,0,1] row_mask:0xf bank_mask:0xf
	v_add_u32_dpp v28, v42, v50 quad_perm:[2,3,0,1] row_mask:0xf bank_mask:0xf
	v_add_u32_dpp v29, v43, v51 quad_perm:[2,3,0,1] row_mask:0xf bank_mask:0xf
	v_cndmask_b32_e64 v40, v28, v26, s[14:15]
	v_cndmask_b32_e64 v48, v26, v28, s[14:15]
	v_cndmask_b32_e64 v41, v29, v27, s[14:15]
	v_cndmask_b32_e64 v49, v27, v29, s[14:15]
	s_nop 1
	v_add_u32_dpp v44, v40, v48 quad_perm:[1,0,3,2] row_mask:0xf bank_mask:0xf
	v_add_u32_dpp v45, v41, v49 quad_perm:[1,0,3,2] row_mask:0xf bank_mask:0xf
	s_cmp_eq_u32 s43, 0
	s_cselect_b32 s32, 0, -1
	v_and_b32_e32 v62, s32, v62
	v_and_b32_e32 v63, s32, v63
	v_add_u32_e32 v44, v44, v62
	v_add_u32_e32 v45, v45, v63
	ds_write_b64 v61, v[44:45]
	s_mov_b32 s42, s44
	s_mov_b32 s43, s45
	s_add_i32 s44, s44, 1
	s_and_b32 s44, s44, 7
	s_cmp_eq_u32 s44, 0
	s_cselect_b32 s32, 1, 0
	s_add_i32 s45, s45, s32
	s_and_b32 s45, s45, 3
	s_lshl_b32 s32, s44, 11
	v_add_u32_e32 v39, s32, v59
	ds_read_b128 v[202:205], v39
	ds_read_b128 v[206:209], v39 offset:16
	s_lshl_b32 s32, s42, 12
	v_add_u32_e32 v61, s32, v60
	ds_read_b64 v[62:63], v61
	s_lshl_b32 s46, s44, 3
	s_add_i32 s46, s46, s40
	s_lshl_b32 s46, s46, 9
	s_lshl_b32 s32, s45, 7
	s_add_i32 s46, s46, s32
	v_add_u32_e32 v57, s46, v56
	global_load_dwordx4 v[186:189], v57, s[34:35]
	global_load_dwordx4 v[190:193], v57, s[36:37]
	s_lshl_b32 s32, s45, 21
	v_add_u32_e32 v58, s32, v56
	s_waitcnt lgkmcnt(0)
; #define LAS __attribute__((address_space(3)))
; __device__ __forceinline__ void peer_u_item(int p, int j, const LAS unsigned short* EL  , const unsigned char* __restrict__ XQ, const unsigned char* __restrict__ U8, LAS int* ACC  , int lane, int wave) {
;     ...
;     for (int it = 0; it < 8; ++it) {
;         const int t = j * 64 + it * 8 + wave;
;         unsigned E[8];
;         { const LAS v4u* ep = (const LAS v4u*)(EL + (it * 8 + wave) * 128 + 16 * gidx); const v4u e0 = ep[0], e1 = ep[1];
;           E[0] = e0.x; E[1] = e0.y; E[2] = e0.z; E[3] = e0.w; E[4] = e1.x; E[5] = e1.y; E[6] = e1.z; E[7] = e1.w; }
;         uint4 uu[16];
; #pragma unroll
;         for (int i = 0; i < 16; ++i) uu[i] = *(const uint4*)(U8 + (size_t)(PE_ID(E, i) * 128u + toff));
;         const uint4 xh = *(const uint4*)(XQ + (size_t)t * 512 + coff), xl = *(const uint4*)(XQ + 8 * MiB + (size_t)t * 512 + coff);
;         int d[16];
; #pragma unroll
;         for (int i = 0; i < 16; ++i) {
;             int sh = __builtin_amdgcn_sdot8((int)uu[i].x, (int)xh.x, 0, false); sh = __builtin_amdgcn_sdot8((int)uu[i].y, (int)xh.y, sh, false);
;             sh = __builtin_amdgcn_sdot8((int)uu[i].z, (int)xh.z, sh, false); sh = __builtin_amdgcn_sdot8((int)uu[i].w, (int)xh.w, sh, false);
;             int sl = __builtin_amdgcn_sdot8((int)uu[i].x, (int)xl.x, 0, false); sl = __builtin_amdgcn_sdot8((int)uu[i].y, (int)xl.y, sl, false);
;             sl = __builtin_amdgcn_sdot8((int)uu[i].z, (int)xl.z, sl, false); sl = __builtin_amdgcn_sdot8((int)uu[i].w, (int)xl.w, sl, false);
;             d[i] = (sh << 4) + sl;
;         }
	s_waitcnt vmcnt(17)
	v_dot8_i32_i4 v34, v122, v194, 0
	v_dot8_i32_i4 v35, v122, v198, 0
	v_dot8_i32_i4 v34, v123, v195, v34
	v_dot8_i32_i4 v35, v123, v199, v35
	v_dot8_i32_i4 v34, v124, v196, v34
	v_dot8_i32_i4 v35, v124, v200, v35
	v_dot8_i32_i4 v34, v125, v197, v34
	v_dot8_i32_i4 v35, v125, v201, v35
	v_and_b32_e32 v38, 0xffff, v202
	v_lshl_add_u32 v38, v38, 7, v58
	global_load_dwordx4 v[122:125], v38, s[96:97]
	s_nop 0
	v_lshl_add_u32 v18, v34, 4, v35
	s_waitcnt vmcnt(17)
	v_dot8_i32_i4 v36, v126, v194, 0
	v_dot8_i32_i4 v37, v126, v198, 0
	v_dot8_i32_i4 v36, v127, v195, v36
	v_dot8_i32_i4 v37, v127, v199, v37
	v_dot8_i32_i4 v36, v128, v196, v36
	v_dot8_i32_i4 v37, v128, v200, v37
	v_dot8_i32_i4 v36, v129, v197, v36
	v_dot8_i32_i4 v37, v129, v201, v37
	v_lshrrev_b32_e32 v38, 16, v202
	v_lshl_add_u32 v38, v38, 7, v58
	global_load_dwordx4 v[126:129], v38, s[96:97]
	s_nop 0
	v_lshl_add_u32 v19, v36, 4, v37
	s_waitcnt vmcnt(17)
	v_dot8_i32_i4 v34, v130, v194, 0
	v_dot8_i32_i4 v35, v130, v198, 0
	v_dot8_i32_i4 v34, v131, v195, v34
	v_dot8_i32_i4 v35, v131, v199, v35
	v_dot8_i32_i4 v34, v132, v196, v34
	v_dot8_i32_i4 v35, v132, v200, v35
	v_dot8_i32_i4 v34, v133, v197, v34
	v_dot8_i32_i4 v35, v133, v201, v35
	v_and_b32_e32 v38, 0xffff, v203
	v_lshl_add_u32 v38, v38, 7, v58
	global_load_dwordx4 v[130:133], v38, s[96:97]
	s_nop 0
	v_lshl_add_u32 v20, v34, 4, v35
	s_waitcnt vmcnt(17)
	v_dot8_i32_i4 v36, v134, v194, 0
	v_dot8_i32_i4 v37, v134, v198, 0
	v_dot8_i32_i4 v36, v135, v195, v36
	v_dot8_i32_i4 v37, v135, v199, v37
	v_dot8_i32_i4 v36, v136, v196, v36
	v_dot8_i32_i4 v37, v136, v200, v37
	v_dot8_i32_i4 v36, v137, v197, v36
	v_dot8_i32_i4 v37, v137, v201, v37
	v_lshrrev_b32_e32 v38, 16, v203
	v_lshl_add_u32 v38, v38, 7, v58
	global_load_dwordx4 v[134:137], v38, s[96:97]
	s_nop 0
	v_lshl_add_u32 v21, v36, 4, v37
	s_waitcnt vmcnt(17)
	v_dot8_i32_i4 v34, v138, v194, 0
	v_dot8_i32_i4 v35, v138, v198, 0
	v_dot8_i32_i4 v34, v139, v195, v34
	v_dot8_i32_i4 v35, v139, v199, v35
	v_dot8_i32_i4 v34, v140, v196, v34
	v_dot8_i32_i4 v35, v140, v200, v35
	v_dot8_i32_i4 v34, v141, v197, v34
	v_dot8_i32_i4 v35, v141, v201, v35
	v_and_b32_e32 v38, 0xffff, v204
	v_lshl_add_u32 v38, v38, 7, v58
	global_load_dwordx4 v[138:141], v38, s[96:97]
	s_nop 0
	v_lshl_add_u32 v22, v34, 4, v35
	s_waitcnt vmcnt(17)
	v_dot8_i32_i4 v36, v142, v194, 0
	v_dot8_i32_i4 v37, v142, v198, 0
	v_dot8_i32_i4 v36, v143, v195, v36
	v_dot8_i32_i4 v37, v143, v199, v37
	v_dot8_i32_i4 v36, v144, v196, v36
	v_dot8_i32_i4 v37, v144, v200, v37
	v_dot8_i32_i4 v36, v145, v197, v36
	v_dot8_i32_i4 v37, v145, v201, v37
	v_lshrrev_b32_e32 v38, 16, v204
	v_lshl_add_u32 v38, v38, 7, v58
	global_load_dwordx4 v[142:145], v38, s[96:97]
	s_nop 0
	v_lshl_add_u32 v23, v36, 4, v37
	s_waitcnt vmcnt(17)
	v_dot8_i32_i4 v34, v146, v194, 0
	v_dot8_i32_i4 v35, v146, v198, 0
	v_dot8_i32_i4 v34, v147, v195, v34
	v_dot8_i32_i4 v35, v147, v199, v35
	v_dot8_i32_i4 v34, v148, v196, v34
	v_dot8_i32_i4 v35, v148, v200, v35
	v_dot8_i32_i4 v34, v149, v197, v34
	v_dot8_i32_i4 v35, v149, v201, v35
	v_and_b32_e32 v38, 0xffff, v205
	v_lshl_add_u32 v38, v38, 7, v58
	global_load_dwordx4 v[146:149], v38, s[96:97]
	s_nop 0
	v_lshl_add_u32 v24, v34, 4, v35
	s_waitcnt vmcnt(17)
	v_dot8_i32_i4 v36, v150, v194, 0
	v_dot8_i32_i4 v37, v150, v198, 0
	v_dot8_i32_i4 v36, v151, v195, v36
	v_dot8_i32_i4 v37, v151, v199, v37
	v_dot8_i32_i4 v36, v152, v196, v36
	v_dot8_i32_i4 v37, v152, v200, v37
	v_dot8_i32_i4 v36, v153, v197, v36
	v_dot8_i32_i4 v37, v153, v201, v37
	v_lshrrev_b32_e32 v38, 16, v205
	v_lshl_add_u32 v38, v38, 7, v58
	global_load_dwordx4 v[150:153], v38, s[96:97]
	s_nop 0
	v_lshl_add_u32 v25, v36, 4, v37
	s_waitcnt vmcnt(17)
	v_dot8_i32_i4 v34, v154, v194, 0
	v_dot8_i32_i4 v35, v154, v198, 0
	v_dot8_i32_i4 v34, v155, v195, v34
	v_dot8_i32_i4 v35, v155, v199, v35
	v_dot8_i32_i4 v34, v156, v196, v34
	v_dot8_i32_i4 v35, v156, v200, v35
	v_dot8_i32_i4 v34, v157, v197, v34
	v_dot8_i32_i4 v35, v157, v201, v35
	v_and_b32_e32 v38, 0xffff, v206
	v_lshl_add_u32 v38, v38, 7, v58
	global_load_dwordx4 v[154:157], v38, s[96:97]
	s_nop 0
	v_lshl_add_u32 v26, v34, 4, v35
	s_waitcnt vmcnt(17)
	v_dot8_i32_i4 v36, v158, v194, 0
	v_dot8_i32_i4 v37, v158, v198, 0
	v_dot8_i32_i4 v36, v159, v195, v36
	v_dot8_i32_i4 v37, v159, v199, v37
	v_dot8_i32_i4 v36, v160, v196, v36
	v_dot8_i32_i4 v37, v160, v200, v37
	v_dot8_i32_i4 v36, v161, v197, v36
	v_dot8_i32_i4 v37, v161, v201, v37
	v_lshrrev_b32_e32 v38, 16, v206
	v_lshl_add_u32 v38, v38, 7, v58
	global_load_dwordx4 v[158:161], v38, s[96:97]
	s_nop 0
	v_lshl_add_u32 v27, v36, 4, v37
	s_waitcnt vmcnt(17)
	v_dot8_i32_i4 v34, v162, v194, 0
	v_dot8_i32_i4 v35, v162, v198, 0
	v_dot8_i32_i4 v34, v163, v195, v34
	v_dot8_i32_i4 v35, v163, v199, v35
	v_dot8_i32_i4 v34, v164, v196, v34
	v_dot8_i32_i4 v35, v164, v200, v35
	v_dot8_i32_i4 v34, v165, v197, v34
	v_dot8_i32_i4 v35, v165, v201, v35
	v_and_b32_e32 v38, 0xffff, v207
	v_lshl_add_u32 v38, v38, 7, v58
	global_load_dwordx4 v[162:165], v38, s[96:97]
	s_nop 0
	v_lshl_add_u32 v28, v34, 4, v35
	s_waitcnt vmcnt(17)
; #define LAS __attribute__((address_space(3)))
; __device__ __forceinline__ void peer_u_item(int p, int j, const LAS unsigned short* EL  , const unsigned char* __restrict__ XQ, const unsigned char* __restrict__ U8, LAS int* ACC  , int lane, int wave) {
;     ...
;         int d[16];
; #pragma unroll
;         for (int i = 0; i < 16; ++i) {
;             int sh = __builtin_amdgcn_sdot8((int)uu[i].x, (int)xh.x, 0, false); sh = __builtin_amdgcn_sdot8((int)uu[i].y, (int)xh.y, sh, false);
;             sh = __builtin_amdgcn_sdot8((int)uu[i].z, (int)xh.z, sh, false); sh = __builtin_amdgcn_sdot8((int)uu[i].w, (int)xh.w, sh, false);
;             int sl = __builtin_amdgcn_sdot8((int)uu[i].x, (int)xl.x, 0, false); sl = __builtin_amdgcn_sdot8((int)uu[i].y, (int)xl.y, sl, false);
;             sl = __builtin_amdgcn_sdot8((int)uu[i].z, (int)xl.z, sl, false); sl = __builtin_amdgcn_sdot8((int)uu[i].w, (int)xl.w, sl, false);
;             d[i] = (sh << 4) + sl;
;         }
;         int r0, r1; treduce16i<4, 2, 1>(d, lane, r0, r1);
;         { typedef int i2v __attribute__((ext_vector_type(2))); LAS i2v* ap = (LAS i2v*)(ACC + (it * 8 + wave) * 128 + 2 * lane);
;           i2v a2; if (p == 0) { a2.x = r0; a2.y = r1; } else { a2 = *ap; a2.x += r0; a2.y += r1; } *ap = a2; }
	v_dot8_i32_i4 v36, v166, v194, 0
	v_dot8_i32_i4 v37, v166, v198, 0
	v_dot8_i32_i4 v36, v167, v195, v36
	v_dot8_i32_i4 v37, v167, v199, v37
	v_dot8_i32_i4 v36, v168, v196, v36
	v_dot8_i32_i4 v37, v168, v200, v37
	v_dot8_i32_i4 v36, v169, v197, v36
	v_dot8_i32_i4 v37, v169, v201, v37
	v_lshrrev_b32_e32 v38, 16, v207
	v_lshl_add_u32 v38, v38, 7, v58
	global_load_dwordx4 v[166:169], v38, s[96:97]
	s_nop 0
	v_lshl_add_u32 v29, v36, 4, v37
	s_waitcnt vmcnt(17)
	v_dot8_i32_i4 v34, v170, v194, 0
	v_dot8_i32_i4 v35, v170, v198, 0
	v_dot8_i32_i4 v34, v171, v195, v34
	v_dot8_i32_i4 v35, v171, v199, v35
	v_dot8_i32_i4 v34, v172, v196, v34
	v_dot8_i32_i4 v35, v172, v200, v35
	v_dot8_i32_i4 v34, v173, v197, v34
	v_dot8_i32_i4 v35, v173, v201, v35
	v_and_b32_e32 v38, 0xffff, v208
	v_lshl_add_u32 v38, v38, 7, v58
	global_load_dwordx4 v[170:173], v38, s[96:97]
	s_nop 0
	v_lshl_add_u32 v30, v34, 4, v35
	s_waitcnt vmcnt(17)
	v_dot8_i32_i4 v36, v174, v194, 0
	v_dot8_i32_i4 v37, v174, v198, 0
	v_dot8_i32_i4 v36, v175, v195, v36
	v_dot8_i32_i4 v37, v175, v199, v37
	v_dot8_i32_i4 v36, v176, v196, v36
	v_dot8_i32_i4 v37, v176, v200, v37
	v_dot8_i32_i4 v36, v177, v197, v36
	v_dot8_i32_i4 v37, v177, v201, v37
	v_lshrrev_b32_e32 v38, 16, v208
	v_lshl_add_u32 v38, v38, 7, v58
	global_load_dwordx4 v[174:177], v38, s[96:97]
	s_nop 0
	v_lshl_add_u32 v31, v36, 4, v37
	s_waitcnt vmcnt(17)
	v_dot8_i32_i4 v34, v178, v194, 0
	v_dot8_i32_i4 v35, v178, v198, 0
	v_dot8_i32_i4 v34, v179, v195, v34
	v_dot8_i32_i4 v35, v179, v199, v35
	v_dot8_i32_i4 v34, v180, v196, v34
	v_dot8_i32_i4 v35, v180, v200, v35
	v_dot8_i32_i4 v34, v181, v197, v34
	v_dot8_i32_i4 v35, v181, v201, v35
	v_and_b32_e32 v38, 0xffff, v209
	v_lshl_add_u32 v38, v38, 7, v58
	global_load_dwordx4 v[178:181], v38, s[96:97]
	s_nop 0
	v_lshl_add_u32 v32, v34, 4, v35
	s_waitcnt vmcnt(17)
	v_dot8_i32_i4 v36, v182, v194, 0
	v_dot8_i32_i4 v37, v182, v198, 0
	v_dot8_i32_i4 v36, v183, v195, v36
	v_dot8_i32_i4 v37, v183, v199, v37
	v_dot8_i32_i4 v36, v184, v196, v36
	v_dot8_i32_i4 v37, v184, v200, v37
	v_dot8_i32_i4 v36, v185, v197, v36
	v_dot8_i32_i4 v37, v185, v201, v37
	v_lshrrev_b32_e32 v38, 16, v209
	v_lshl_add_u32 v38, v38, 7, v58
	global_load_dwordx4 v[182:185], v38, s[96:97]
	s_nop 0
	v_lshl_add_u32 v33, v36, 4, v37
	v_cndmask_b32_e64 v40, v26, v18, s[10:11]
	v_cndmask_b32_e64 v48, v18, v26, s[10:11]
	v_cndmask_b32_e64 v41, v27, v19, s[10:11]
	v_cndmask_b32_e64 v49, v19, v27, s[10:11]
	v_cndmask_b32_e64 v42, v28, v20, s[10:11]
	v_cndmask_b32_e64 v50, v20, v28, s[10:11]
	v_cndmask_b32_e64 v43, v29, v21, s[10:11]
	v_cndmask_b32_e64 v51, v21, v29, s[10:11]
	v_cndmask_b32_e64 v44, v30, v22, s[10:11]
	v_cndmask_b32_e64 v52, v22, v30, s[10:11]
	v_cndmask_b32_e64 v45, v31, v23, s[10:11]
	v_cndmask_b32_e64 v53, v23, v31, s[10:11]
	v_cndmask_b32_e64 v46, v32, v24, s[10:11]
	v_cndmask_b32_e64 v54, v24, v32, s[10:11]
	v_cndmask_b32_e64 v47, v33, v25, s[10:11]
	v_cndmask_b32_e64 v55, v25, v33, s[10:11]
	v_add_u32_dpp v18, v40, v48 row_shr:4 row_mask:0xf bank_mask:0xa
	v_add_u32_dpp v18, v40, v48 row_shl:4 row_mask:0xf bank_mask:0x5
	v_add_u32_dpp v19, v41, v49 row_shr:4 row_mask:0xf bank_mask:0xa
	v_add_u32_dpp v19, v41, v49 row_shl:4 row_mask:0xf bank_mask:0x5
	v_add_u32_dpp v20, v42, v50 row_shr:4 row_mask:0xf bank_mask:0xa
	v_add_u32_dpp v20, v42, v50 row_shl:4 row_mask:0xf bank_mask:0x5
	v_add_u32_dpp v21, v43, v51 row_shr:4 row_mask:0xf bank_mask:0xa
	v_add_u32_dpp v21, v43, v51 row_shl:4 row_mask:0xf bank_mask:0x5
	v_add_u32_dpp v22, v44, v52 row_shr:4 row_mask:0xf bank_mask:0xa
	v_add_u32_dpp v22, v44, v52 row_shl:4 row_mask:0xf bank_mask:0x5
	v_add_u32_dpp v23, v45, v53 row_shr:4 row_mask:0xf bank_mask:0xa
	v_add_u32_dpp v23, v45, v53 row_shl:4 row_mask:0xf bank_mask:0x5
	v_add_u32_dpp v24, v46, v54 row_shr:4 row_mask:0xf bank_mask:0xa
	v_add_u32_dpp v24, v46, v54 row_shl:4 row_mask:0xf bank_mask:0x5
	v_add_u32_dpp v25, v47, v55 row_shr:4 row_mask:0xf bank_mask:0xa
	v_add_u32_dpp v25, v47, v55 row_shl:4 row_mask:0xf bank_mask:0x5
	v_cndmask_b32_e64 v40, v22, v18, s[12:13]
	v_cndmask_b32_e64 v48, v18, v22, s[12:13]
	v_cndmask_b32_e64 v41, v23, v19, s[12:13]
	v_cndmask_b32_e64 v49, v19, v23, s[12:13]
	v_cndmask_b32_e64 v42, v24, v20, s[12:13]
	v_cndmask_b32_e64 v50, v20, v24, s[12:13]
	v_cndmask_b32_e64 v43, v25, v21, s[12:13]
	v_cndmask_b32_e64 v51, v21, v25, s[12:13]
	s_nop 0
	v_add_u32_dpp v26, v40, v48 quad_perm:[2,3,0,1] row_mask:0xf bank_mask:0xf
	v_add_u32_dpp v27, v41, v49 quad_perm:[2,3,0,1] row_mask:0xf bank_mask:0xf
	v_add_u32_dpp v28, v42, v50 quad_perm:[2,3,0,1] row_mask:0xf bank_mask:0xf
	v_add_u32_dpp v29, v43, v51 quad_perm:[2,3,0,1] row_mask:0xf bank_mask:0xf
	v_cndmask_b32_e64 v40, v28, v26, s[14:15]
	v_cndmask_b32_e64 v48, v26, v28, s[14:15]
	v_cndmask_b32_e64 v41, v29, v27, s[14:15]
	v_cndmask_b32_e64 v49, v27, v29, s[14:15]
	s_nop 1
	v_add_u32_dpp v44, v40, v48 quad_perm:[1,0,3,2] row_mask:0xf bank_mask:0xf
	v_add_u32_dpp v45, v41, v49 quad_perm:[1,0,3,2] row_mask:0xf bank_mask:0xf
	s_cmp_eq_u32 s43, 0
	s_cselect_b32 s32, 0, -1
	v_and_b32_e32 v62, s32, v62
	v_and_b32_e32 v63, s32, v63
	v_add_u32_e32 v44, v44, v62
	v_add_u32_e32 v45, v45, v63
	ds_write_b64 v61, v[44:45]
	s_mov_b32 s42, s44
	s_mov_b32 s43, s45
	s_add_i32 s44, s44, 1
	s_and_b32 s44, s44, 7
	s_cmp_eq_u32 s44, 0
	s_cselect_b32 s32, 1, 0
	s_add_i32 s45, s45, s32
	s_and_b32 s45, s45, 3
	s_add_i32 s47, s47, -1
	s_cmp_lg_u32 s47, 0
	s_cbranch_scc1 .Lpu_trip
	s_waitcnt vmcnt(0) lgkmcnt(0)
